# v14 + Hyena FFT: 987 compiler s_nop 0 pads between packed-f32 producer/consumer pairs removed (no partial-result forwarding on whole-dword packed f32 ops)
# baseline (speedup 1.0000x reference)
.LBB0_414:
	s_or_b64 exec, exec, s[4:5]
	v_lshlrev_b32_e32 v41, 3, v2
	v_lshlrev_b32_e32 v157, 3, v32
	s_waitcnt vmcnt(0)
	ds_write_b64 v35, v[0:1] offset:65280
	s_waitcnt lgkmcnt(0)
	s_barrier
	s_and_saveexec_b64 s[0:1], s[40:41]
	s_xor_b64 s[0:1], exec, s[0:1]
	s_cbranch_execz .LBB0_416
	s_add_i32 s4, 0, 0x11000
	v_add3_u32 v39, s4, v41, v157
	ds_read_b64 v[0:1], v39 offset:2176
	ds_read_b64 v[2:3], v39 offset:4352
	ds_read_b64 v[4:5], v39 offset:6528
	ds_read_b64 v[6:7], v39 offset:8704
	ds_read_b64 v[8:9], v39 offset:10880
	ds_read_b64 v[10:11], v39 offset:13056
	ds_read_b64 v[12:13], v39 offset:15232
	ds_read_b64 v[14:15], v39 offset:17408
	ds_read_b64 v[16:17], v39 offset:19584
	ds_read_b64 v[18:19], v39 offset:21760
	ds_read_b64 v[20:21], v39 offset:23936
	ds_read_b64 v[22:23], v39 offset:26112
	ds_read_b64 v[24:25], v39 offset:34816
	ds_read_b64 v[26:27], v39 offset:36992
	ds_read_b64 v[28:29], v39 offset:39168
	ds_read_b64 v[30:31], v39 offset:41344
	ds_read_b64 v[78:79], v39 offset:43520
	ds_read_b64 v[80:81], v39 offset:45696
	ds_read_b64 v[82:83], v39 offset:47872
	ds_read_b64 v[84:85], v39 offset:50048
	ds_read_b64 v[86:87], v39 offset:52224
	ds_read_b64 v[88:89], v39 offset:54400
	ds_read_b64 v[90:91], v39 offset:56576
	ds_read_b64 v[92:93], v39 offset:58752
	ds_read_b64 v[94:95], v39
	ds_read_b64 v[96:97], v39 offset:60928
	ds_read_b64 v[98:99], v39 offset:63104
	ds_read_b64 v[100:101], v39 offset:65280
	s_mov_b32 s11, s14
	s_waitcnt lgkmcnt(3)
	v_pk_add_f32 v[110:111], v[94:95], v[24:25]
	v_pk_add_f32 v[24:25], v[94:95], v[24:25] neg_lo:[0,1] neg_hi:[0,1]
	v_pk_add_f32 v[94:95], v[0:1], v[26:27]
	v_pk_add_f32 v[0:1], v[0:1], v[26:27] neg_lo:[0,1] neg_hi:[0,1]
	s_mov_b32 s13, s86
	v_pk_mul_f32 v[26:27], v[0:1], s[16:17]
	s_mov_b32 s4, s21
	v_pk_fma_f32 v[0:1], v[0:1], s[6:7], v[26:27] op_sel:[0,0,1] op_sel_hi:[1,0,0]
	v_pk_add_f32 v[26:27], v[2:3], v[28:29]
	v_pk_add_f32 v[2:3], v[2:3], v[28:29] neg_lo:[0,1] neg_hi:[0,1]
	s_mov_b32 s35, s30
	v_pk_mul_f32 v[28:29], v[2:3], s[18:19]
	s_mov_b32 s8, s19
	v_pk_fma_f32 v[2:3], v[2:3], s[30:31], v[28:29] op_sel:[0,0,1] op_sel_hi:[1,0,0]
	v_pk_add_f32 v[28:29], v[4:5], v[30:31]
	v_pk_add_f32 v[4:5], v[4:5], v[30:31] neg_lo:[0,1] neg_hi:[0,1]
	s_mov_b32 s77, s6
	v_pk_mul_f32 v[30:31], v[4:5], s[20:21]
	s_mov_b32 s26, s17
	v_pk_fma_f32 v[4:5], v[4:5], s[86:87], v[30:31] op_sel:[0,0,1] op_sel_hi:[1,0,0]
	v_pk_add_f32 v[30:31], v[6:7], v[78:79]
	v_pk_add_f32 v[6:7], v[6:7], v[78:79] neg_lo:[0,1] neg_hi:[0,1]
	v_add_u32_e32 v108, 0x10780, v39
	v_pk_mul_f32 v[78:79], v[6:7], s[10:11]
	ds_read_b64 v[102:103], v39 offset:28288
	ds_read_b64 v[104:105], v39 offset:30464
	ds_read_b64 v[106:107], v39 offset:32640
	ds_read_b64 v[108:109], v108
	v_pk_fma_f32 v[6:7], v[6:7], s[14:15], v[78:79] op_sel:[0,0,1] op_sel_hi:[1,0,0]
	v_pk_add_f32 v[78:79], v[8:9], v[80:81]
	v_pk_add_f32 v[8:9], v[8:9], v[80:81] neg_lo:[0,1] neg_hi:[0,1]
	v_pk_mul_f32 v[80:81], v[8:9], s[12:13]
	v_pk_fma_f32 v[8:9], v[8:9], s[4:5], v[80:81] op_sel:[0,0,1] op_sel_hi:[1,0,0]
	v_pk_add_f32 v[80:81], v[10:11], v[82:83]
	v_pk_add_f32 v[10:11], v[10:11], v[82:83] neg_lo:[0,1] neg_hi:[0,1]
	v_pk_mul_f32 v[82:83], v[10:11], s[34:35]
	v_pk_fma_f32 v[10:11], v[10:11], s[8:9], v[82:83] op_sel:[0,0,1] op_sel_hi:[1,0,0]
	v_pk_add_f32 v[82:83], v[12:13], v[84:85]
	v_pk_add_f32 v[12:13], v[12:13], v[84:85] neg_lo:[0,1] neg_hi:[0,1]
	v_pk_mul_f32 v[84:85], v[12:13], s[76:77]
	v_pk_fma_f32 v[12:13], v[12:13], s[26:27], v[84:85] op_sel:[0,0,1] op_sel_hi:[1,0,0]
	v_pk_add_f32 v[84:85], v[14:15], v[86:87]
	v_pk_add_f32 v[14:15], v[14:15], v[86:87] neg_lo:[0,1] neg_hi:[0,1]
	v_pk_add_f32 v[86:87], v[16:17], v[88:89]
	v_pk_add_f32 v[16:17], v[16:17], v[88:89] neg_lo:[0,1] neg_hi:[0,1]
	v_pk_mul_f32 v[88:89], v[16:17], s[76:77]
	v_pk_fma_f32 v[16:17], v[16:17], s[26:27], v[88:89] op_sel:[0,0,1] op_sel_hi:[1,0,0] neg_lo:[1,0,0] neg_hi:[1,0,0]
	v_pk_add_f32 v[88:89], v[18:19], v[90:91]
	v_pk_add_f32 v[18:19], v[18:19], v[90:91] neg_lo:[0,1] neg_hi:[0,1]
	v_pk_mul_f32 v[90:91], v[18:19], s[34:35]
	v_pk_fma_f32 v[18:19], v[18:19], s[8:9], v[90:91] op_sel:[0,0,1] op_sel_hi:[1,0,0] neg_lo:[1,0,0] neg_hi:[1,0,0]
	v_pk_add_f32 v[90:91], v[20:21], v[92:93]
	v_pk_add_f32 v[20:21], v[20:21], v[92:93] neg_lo:[0,1] neg_hi:[0,1]
	v_pk_mul_f32 v[92:93], v[20:21], s[12:13]
	v_pk_fma_f32 v[20:21], v[20:21], s[4:5], v[92:93] op_sel:[0,0,1] op_sel_hi:[1,0,0] neg_lo:[1,0,0] neg_hi:[1,0,0]
	s_waitcnt lgkmcnt(6)
	v_pk_add_f32 v[92:93], v[22:23], v[96:97]
	v_pk_add_f32 v[22:23], v[22:23], v[96:97] neg_lo:[0,1] neg_hi:[0,1]
	s_nop 0
	v_pk_mul_f32 v[96:97], v[22:23], s[10:11]
	v_pk_fma_f32 v[22:23], v[22:23], s[14:15], v[96:97] op_sel:[0,0,1] op_sel_hi:[1,0,0] neg_lo:[1,0,0] neg_hi:[1,0,0]
	s_waitcnt lgkmcnt(3)
	v_pk_add_f32 v[96:97], v[102:103], v[98:99]
	v_pk_add_f32 v[98:99], v[102:103], v[98:99] neg_lo:[0,1] neg_hi:[0,1]
	s_nop 0
	v_pk_mul_f32 v[102:103], v[98:99], s[20:21]
	v_pk_fma_f32 v[98:99], v[98:99], s[86:87], v[102:103] op_sel:[0,0,1] op_sel_hi:[1,0,0] neg_lo:[1,0,0] neg_hi:[1,0,0]
	s_waitcnt lgkmcnt(2)
	v_pk_add_f32 v[102:103], v[104:105], v[100:101]
	v_pk_add_f32 v[100:101], v[104:105], v[100:101] neg_lo:[0,1] neg_hi:[0,1]
	s_nop 0
	v_pk_mul_f32 v[104:105], v[100:101], s[18:19]
	v_pk_fma_f32 v[100:101], v[100:101], s[30:31], v[104:105] op_sel:[0,0,1] op_sel_hi:[1,0,0] neg_lo:[1,0,0] neg_hi:[1,0,0]
	s_waitcnt lgkmcnt(0)
	v_pk_add_f32 v[104:105], v[106:107], v[108:109]
	v_pk_add_f32 v[106:107], v[106:107], v[108:109] neg_lo:[0,1] neg_hi:[0,1]
	s_nop 0
	v_pk_mul_f32 v[108:109], v[106:107], s[16:17]
	v_pk_fma_f32 v[106:107], v[106:107], s[6:7], v[108:109] op_sel:[0,0,1] op_sel_hi:[1,0,0] neg_lo:[1,0,0] neg_hi:[1,0,0]
	v_pk_add_f32 v[108:109], v[110:111], v[84:85]
	v_pk_add_f32 v[84:85], v[110:111], v[84:85] neg_lo:[0,1] neg_hi:[0,1]
	v_pk_add_f32 v[110:111], v[94:95], v[86:87]
	v_pk_add_f32 v[86:87], v[94:95], v[86:87] neg_lo:[0,1] neg_hi:[0,1]
	v_pk_mul_f32 v[94:95], v[86:87], s[18:19]
	v_pk_fma_f32 v[86:87], v[86:87], s[30:31], v[94:95] op_sel:[0,0,1] op_sel_hi:[1,0,0]
	v_pk_add_f32 v[94:95], v[26:27], v[88:89]
	v_pk_add_f32 v[26:27], v[26:27], v[88:89] neg_lo:[0,1] neg_hi:[0,1]
	v_pk_mul_f32 v[88:89], v[26:27], s[10:11]
	v_pk_fma_f32 v[26:27], v[26:27], s[14:15], v[88:89] op_sel:[0,0,1] op_sel_hi:[1,0,0]
	v_pk_add_f32 v[88:89], v[28:29], v[90:91]
	v_pk_add_f32 v[28:29], v[28:29], v[90:91] neg_lo:[0,1] neg_hi:[0,1]
	v_pk_mul_f32 v[90:91], v[28:29], s[34:35]
	v_pk_fma_f32 v[28:29], v[28:29], s[8:9], v[90:91] op_sel:[0,0,1] op_sel_hi:[1,0,0]
	v_pk_add_f32 v[90:91], v[30:31], v[92:93]
	v_pk_add_f32 v[30:31], v[30:31], v[92:93] neg_lo:[0,1] neg_hi:[0,1]
	v_pk_add_f32 v[92:93], v[78:79], v[96:97]
	v_pk_add_f32 v[78:79], v[78:79], v[96:97] neg_lo:[0,1] neg_hi:[0,1]
	v_pk_mul_f32 v[96:97], v[78:79], s[34:35]
	v_pk_fma_f32 v[78:79], v[78:79], s[8:9], v[96:97] op_sel:[0,0,1] op_sel_hi:[1,0,0] neg_lo:[1,0,0] neg_hi:[1,0,0]
	v_pk_add_f32 v[96:97], v[80:81], v[102:103]
	v_pk_add_f32 v[80:81], v[80:81], v[102:103] neg_lo:[0,1] neg_hi:[0,1]
	v_pk_mul_f32 v[102:103], v[80:81], s[10:11]
	v_pk_fma_f32 v[80:81], v[80:81], s[14:15], v[102:103] op_sel:[0,0,1] op_sel_hi:[1,0,0] neg_lo:[1,0,0] neg_hi:[1,0,0]
	v_pk_add_f32 v[102:103], v[82:83], v[104:105]
	v_pk_add_f32 v[82:83], v[82:83], v[104:105] neg_lo:[0,1] neg_hi:[0,1]
	v_pk_mul_f32 v[104:105], v[82:83], s[18:19]
	v_pk_fma_f32 v[82:83], v[82:83], s[30:31], v[104:105] op_sel:[0,0,1] op_sel_hi:[1,0,0] neg_lo:[1,0,0] neg_hi:[1,0,0]
	v_pk_add_f32 v[104:105], v[24:25], v[14:15] op_sel:[0,1] op_sel_hi:[1,0] neg_hi:[0,1]
	v_pk_add_f32 v[14:15], v[24:25], v[14:15] op_sel:[0,1] op_sel_hi:[1,0] neg_lo:[0,1]
	v_pk_add_f32 v[24:25], v[0:1], v[16:17]
	v_pk_add_f32 v[0:1], v[0:1], v[16:17] neg_lo:[0,1] neg_hi:[0,1]
	v_pk_mul_f32 v[16:17], v[0:1], s[18:19]
	v_pk_fma_f32 v[0:1], v[0:1], s[30:31], v[16:17] op_sel:[0,0,1] op_sel_hi:[1,0,0]
	v_pk_add_f32 v[16:17], v[2:3], v[18:19]
	v_pk_add_f32 v[2:3], v[2:3], v[18:19] neg_lo:[0,1] neg_hi:[0,1]
	v_pk_mul_f32 v[18:19], v[2:3], s[10:11]
	v_pk_fma_f32 v[2:3], v[2:3], s[14:15], v[18:19] op_sel:[0,0,1] op_sel_hi:[1,0,0]
	v_pk_add_f32 v[18:19], v[4:5], v[20:21]
	v_pk_add_f32 v[4:5], v[4:5], v[20:21] neg_lo:[0,1] neg_hi:[0,1]
	v_pk_mul_f32 v[20:21], v[4:5], s[34:35]
	v_pk_fma_f32 v[4:5], v[4:5], s[8:9], v[20:21] op_sel:[0,0,1] op_sel_hi:[1,0,0]
	v_pk_add_f32 v[20:21], v[6:7], v[22:23]
	v_pk_add_f32 v[6:7], v[6:7], v[22:23] neg_lo:[0,1] neg_hi:[0,1]
	v_pk_add_f32 v[22:23], v[8:9], v[98:99]
	v_pk_add_f32 v[8:9], v[8:9], v[98:99] neg_lo:[0,1] neg_hi:[0,1]
	v_pk_mul_f32 v[98:99], v[8:9], s[34:35]
	v_pk_fma_f32 v[8:9], v[8:9], s[8:9], v[98:99] op_sel:[0,0,1] op_sel_hi:[1,0,0] neg_lo:[1,0,0] neg_hi:[1,0,0]
	v_pk_add_f32 v[98:99], v[10:11], v[100:101]
	v_pk_add_f32 v[10:11], v[10:11], v[100:101] neg_lo:[0,1] neg_hi:[0,1]
	v_pk_mul_f32 v[100:101], v[10:11], s[10:11]
	v_pk_fma_f32 v[10:11], v[10:11], s[14:15], v[100:101] op_sel:[0,0,1] op_sel_hi:[1,0,0] neg_lo:[1,0,0] neg_hi:[1,0,0]
	v_pk_add_f32 v[100:101], v[12:13], v[106:107]
	v_pk_add_f32 v[12:13], v[12:13], v[106:107] neg_lo:[0,1] neg_hi:[0,1]
	v_pk_mul_f32 v[106:107], v[12:13], s[18:19]
	v_pk_fma_f32 v[12:13], v[12:13], s[30:31], v[106:107] op_sel:[0,0,1] op_sel_hi:[1,0,0] neg_lo:[1,0,0] neg_hi:[1,0,0]
	v_pk_add_f32 v[106:107], v[108:109], v[90:91]
	v_pk_add_f32 v[90:91], v[108:109], v[90:91] neg_lo:[0,1] neg_hi:[0,1]
	v_pk_add_f32 v[108:109], v[110:111], v[92:93]
	v_pk_add_f32 v[92:93], v[110:111], v[92:93] neg_lo:[0,1] neg_hi:[0,1]
	v_pk_mul_f32 v[110:111], v[92:93], s[10:11]
	v_pk_fma_f32 v[92:93], v[92:93], s[14:15], v[110:111] op_sel:[0,0,1] op_sel_hi:[1,0,0]
	v_pk_add_f32 v[110:111], v[94:95], v[96:97]
	v_pk_add_f32 v[94:95], v[94:95], v[96:97] neg_lo:[0,1] neg_hi:[0,1]
	v_pk_add_f32 v[96:97], v[88:89], v[102:103]
	v_pk_add_f32 v[88:89], v[88:89], v[102:103] neg_lo:[0,1] neg_hi:[0,1]
	v_pk_mul_f32 v[102:103], v[88:89], s[10:11]
	v_pk_fma_f32 v[88:89], v[88:89], s[14:15], v[102:103] op_sel:[0,0,1] op_sel_hi:[1,0,0] neg_lo:[1,0,0] neg_hi:[1,0,0]
	v_pk_add_f32 v[102:103], v[84:85], v[30:31] op_sel:[0,1] op_sel_hi:[1,0] neg_hi:[0,1]
	v_pk_add_f32 v[30:31], v[84:85], v[30:31] op_sel:[0,1] op_sel_hi:[1,0] neg_lo:[0,1]
	v_pk_add_f32 v[84:85], v[86:87], v[78:79]
	v_pk_add_f32 v[78:79], v[86:87], v[78:79] neg_lo:[0,1] neg_hi:[0,1]
	v_pk_add_f32 v[112:113], v[92:93], v[88:89]
	v_pk_mul_f32 v[86:87], v[78:79], s[10:11]
	v_pk_add_f32 v[88:89], v[92:93], v[88:89] neg_lo:[0,1] neg_hi:[0,1]
	v_pk_fma_f32 v[78:79], v[78:79], s[14:15], v[86:87] op_sel:[0,0,1] op_sel_hi:[1,0,0]
	v_pk_add_f32 v[86:87], v[26:27], v[80:81]
	v_pk_add_f32 v[26:27], v[26:27], v[80:81] neg_lo:[0,1] neg_hi:[0,1]
	v_pk_add_f32 v[80:81], v[28:29], v[82:83]
	v_pk_add_f32 v[28:29], v[28:29], v[82:83] neg_lo:[0,1] neg_hi:[0,1]
	v_pk_mul_f32 v[82:83], v[28:29], s[10:11]
	v_pk_add_f32 v[118:119], v[84:85], v[80:81]
	v_pk_fma_f32 v[28:29], v[28:29], s[14:15], v[82:83] op_sel:[0,0,1] op_sel_hi:[1,0,0] neg_lo:[1,0,0] neg_hi:[1,0,0]
	v_pk_add_f32 v[82:83], v[104:105], v[20:21]
	v_pk_add_f32 v[20:21], v[104:105], v[20:21] neg_lo:[0,1] neg_hi:[0,1]
	v_pk_add_f32 v[104:105], v[24:25], v[22:23]
	v_pk_add_f32 v[22:23], v[24:25], v[22:23] neg_lo:[0,1] neg_hi:[0,1]
	v_pk_add_f32 v[80:81], v[84:85], v[80:81] neg_lo:[0,1] neg_hi:[0,1]
	v_pk_mul_f32 v[24:25], v[22:23], s[10:11]
	v_pk_add_f32 v[120:121], v[30:31], v[26:27] op_sel:[0,1] op_sel_hi:[1,0] neg_hi:[0,1]
	v_pk_fma_f32 v[22:23], v[22:23], s[14:15], v[24:25] op_sel:[0,0,1] op_sel_hi:[1,0,0]
	v_pk_add_f32 v[24:25], v[16:17], v[98:99]
	v_pk_add_f32 v[16:17], v[16:17], v[98:99] neg_lo:[0,1] neg_hi:[0,1]
	v_pk_add_f32 v[98:99], v[18:19], v[100:101]
	v_pk_add_f32 v[18:19], v[18:19], v[100:101] neg_lo:[0,1] neg_hi:[0,1]
	v_pk_mul_f32 v[100:101], v[18:19], s[10:11]
	v_pk_add_f32 v[26:27], v[30:31], v[26:27] op_sel:[0,1] op_sel_hi:[1,0] neg_lo:[0,1]
	v_pk_fma_f32 v[18:19], v[18:19], s[14:15], v[100:101] op_sel:[0,0,1] op_sel_hi:[1,0,0] neg_lo:[1,0,0] neg_hi:[1,0,0]
	v_pk_add_f32 v[100:101], v[14:15], v[6:7] op_sel:[0,1] op_sel_hi:[1,0] neg_hi:[0,1]
	v_pk_add_f32 v[6:7], v[14:15], v[6:7] op_sel:[0,1] op_sel_hi:[1,0] neg_lo:[0,1]
	v_pk_add_f32 v[14:15], v[0:1], v[8:9]
	v_pk_add_f32 v[0:1], v[0:1], v[8:9] neg_lo:[0,1] neg_hi:[0,1]
	v_pk_add_f32 v[30:31], v[78:79], v[28:29]
	v_pk_mul_f32 v[8:9], v[0:1], s[10:11]
	v_pk_add_f32 v[28:29], v[78:79], v[28:29] neg_lo:[0,1] neg_hi:[0,1]
	v_pk_fma_f32 v[0:1], v[0:1], s[14:15], v[8:9] op_sel:[0,0,1] op_sel_hi:[1,0,0]
	v_pk_add_f32 v[8:9], v[2:3], v[10:11]
	v_pk_add_f32 v[2:3], v[2:3], v[10:11] neg_lo:[0,1] neg_hi:[0,1]
	v_pk_add_f32 v[10:11], v[4:5], v[12:13]
	v_pk_add_f32 v[4:5], v[4:5], v[12:13] neg_lo:[0,1] neg_hi:[0,1]
	v_pk_mul_f32 v[12:13], v[4:5], s[10:11]
	v_pk_add_f32 v[122:123], v[82:83], v[24:25]
	v_pk_fma_f32 v[4:5], v[4:5], s[14:15], v[12:13] op_sel:[0,0,1] op_sel_hi:[1,0,0] neg_lo:[1,0,0] neg_hi:[1,0,0]
	v_pk_add_f32 v[12:13], v[106:107], v[110:111]
	v_pk_add_f32 v[106:107], v[106:107], v[110:111] neg_lo:[0,1] neg_hi:[0,1]
	v_pk_add_f32 v[110:111], v[108:109], v[96:97]
	v_pk_add_f32 v[96:97], v[108:109], v[96:97] neg_lo:[0,1] neg_hi:[0,1]
	v_pk_add_f32 v[124:125], v[82:83], v[24:25] neg_lo:[0,1] neg_hi:[0,1]
	v_pk_add_f32 v[126:127], v[104:105], v[98:99]
	v_pk_add_f32 v[24:25], v[104:105], v[98:99] neg_lo:[0,1] neg_hi:[0,1]
	v_pk_add_f32 v[104:105], v[20:21], v[16:17] op_sel:[0,1] op_sel_hi:[1,0] neg_hi:[0,1]
	v_pk_add_f32 v[128:129], v[20:21], v[16:17] op_sel:[0,1] op_sel_hi:[1,0] neg_lo:[0,1]
	v_pk_add_f32 v[16:17], v[22:23], v[18:19] neg_lo:[0,1] neg_hi:[0,1]
	v_pk_add_f32 v[134:135], v[100:101], v[8:9]
	v_pk_add_f32 v[136:137], v[100:101], v[8:9] neg_lo:[0,1] neg_hi:[0,1]
	v_pk_add_f32 v[8:9], v[14:15], v[10:11] neg_lo:[0,1] neg_hi:[0,1]
	v_pk_add_f32 v[140:141], v[6:7], v[2:3] op_sel:[0,1] op_sel_hi:[1,0] neg_hi:[0,1]
	v_pk_add_f32 v[142:143], v[6:7], v[2:3] op_sel:[0,1] op_sel_hi:[1,0] neg_lo:[0,1]
	v_pk_add_f32 v[2:3], v[0:1], v[4:5]
	v_pk_add_f32 v[0:1], v[0:1], v[4:5] neg_lo:[0,1] neg_hi:[0,1]
	v_pk_add_f32 v[108:109], v[90:91], v[94:95] op_sel:[0,1] op_sel_hi:[1,0] neg_hi:[0,1]
	v_pk_add_f32 v[94:95], v[90:91], v[94:95] op_sel:[0,1] op_sel_hi:[1,0] neg_lo:[0,1]
	v_pk_mul_f32 v[114:115], v[88:89], s[22:23]
	v_pk_add_f32 v[116:117], v[102:103], v[86:87]
	v_pk_add_f32 v[102:103], v[102:103], v[86:87] neg_lo:[0,1] neg_hi:[0,1]
	v_pk_mul_f32 v[78:79], v[28:29], s[22:23]
	v_pk_mul_f32 v[98:99], v[24:25], s[22:23]
	v_pk_add_f32 v[130:131], v[22:23], v[18:19]
	v_pk_mul_f32 v[132:133], v[16:17], s[22:23]
	v_pk_add_f32 v[100:101], v[14:15], v[10:11]
	v_pk_mul_f32 v[138:139], v[8:9], s[22:23]
	v_pk_mul_f32 v[144:145], v[0:1], s[22:23]
	v_pk_add_f32 v[28:29], v[12:13], v[110:111]
	v_pk_add_f32 v[92:93], v[12:13], v[110:111] neg_lo:[0,1] neg_hi:[0,1]
	v_pk_add_f32 v[24:25], v[106:107], v[96:97] op_sel:[0,1] op_sel_hi:[1,0] neg_hi:[0,1]
	v_pk_add_f32 v[90:91], v[106:107], v[96:97] op_sel:[0,1] op_sel_hi:[1,0] neg_lo:[0,1]
	v_pk_add_f32 v[20:21], v[108:109], v[112:113]
	v_pk_add_f32 v[88:89], v[108:109], v[112:113] neg_lo:[0,1] neg_hi:[0,1]
	v_pk_add_f32 v[16:17], v[94:95], v[114:115] op_sel:[0,1] op_sel_hi:[1,0]
	v_pk_add_f32 v[86:87], v[94:95], v[114:115] op_sel:[0,1] op_sel_hi:[1,0] neg_lo:[0,1] neg_hi:[0,1]
	v_pk_add_f32 v[12:13], v[116:117], v[118:119]
	v_pk_add_f32 v[84:85], v[116:117], v[118:119] neg_lo:[0,1] neg_hi:[0,1]
	v_pk_add_f32 v[8:9], v[102:103], v[80:81] op_sel:[0,1] op_sel_hi:[1,0] neg_hi:[0,1]
	v_pk_add_f32 v[82:83], v[102:103], v[80:81] op_sel:[0,1] op_sel_hi:[1,0] neg_lo:[0,1]
	v_pk_add_f32 v[4:5], v[120:121], v[30:31]
	v_pk_add_f32 v[80:81], v[120:121], v[30:31] neg_lo:[0,1] neg_hi:[0,1]
	v_pk_add_f32 v[0:1], v[26:27], v[78:79] op_sel:[0,1] op_sel_hi:[1,0]
	v_pk_add_f32 v[78:79], v[26:27], v[78:79] op_sel:[0,1] op_sel_hi:[1,0] neg_lo:[0,1] neg_hi:[0,1]
	v_pk_add_f32 v[30:31], v[122:123], v[126:127]
	v_pk_add_f32 v[108:109], v[122:123], v[126:127] neg_lo:[0,1] neg_hi:[0,1]
	v_pk_add_f32 v[26:27], v[124:125], v[98:99] op_sel:[0,1] op_sel_hi:[1,0]
	v_pk_add_f32 v[106:107], v[124:125], v[98:99] op_sel:[0,1] op_sel_hi:[1,0] neg_lo:[0,1] neg_hi:[0,1]
	v_pk_add_f32 v[22:23], v[104:105], v[130:131]
	v_pk_add_f32 v[104:105], v[104:105], v[130:131] neg_lo:[0,1] neg_hi:[0,1]
	v_pk_add_f32 v[18:19], v[128:129], v[132:133] op_sel:[0,1] op_sel_hi:[1,0]
	v_pk_add_f32 v[102:103], v[128:129], v[132:133] op_sel:[0,1] op_sel_hi:[1,0] neg_lo:[0,1] neg_hi:[0,1]
	v_pk_add_f32 v[14:15], v[134:135], v[100:101]
	v_pk_add_f32 v[100:101], v[134:135], v[100:101] neg_lo:[0,1] neg_hi:[0,1]
	v_pk_add_f32 v[10:11], v[136:137], v[138:139] op_sel:[0,1] op_sel_hi:[1,0]
	v_pk_add_f32 v[98:99], v[136:137], v[138:139] op_sel:[0,1] op_sel_hi:[1,0] neg_lo:[0,1] neg_hi:[0,1]
	v_pk_add_f32 v[6:7], v[140:141], v[2:3]
	v_pk_add_f32 v[96:97], v[140:141], v[2:3] neg_lo:[0,1] neg_hi:[0,1]
	v_pk_add_f32 v[2:3], v[142:143], v[144:145] op_sel:[0,1] op_sel_hi:[1,0]
	v_pk_add_f32 v[94:95], v[142:143], v[144:145] op_sel:[0,1] op_sel_hi:[1,0] neg_lo:[0,1] neg_hi:[0,1]

.LBB0_418:
	s_or_b64 exec, exec, s[0:1]
	v_mov_b32_e32 v39, v32
	s_waitcnt lgkmcnt(0)
	s_barrier
	s_add_i32 s26, 0, 0x11000
	v_and_b32_e32 v86, 31, v39
	v_cvt_f32_ubyte0_e32 v24, v86
	v_mul_f32_e32 v80, 0x3b000000, v24
	v_sin_f32_e32 v24, v80
	v_ashrrev_i32_e32 v0, 4, v39
	v_lshlrev_b32_e32 v0, 3, v0
	v_lshlrev_b32_e32 v1, 3, v39
	v_cos_f32_e32 v80, v80
	v_add3_u32 v25, s26, v0, v1
	ds_read_b64 v[0:1], v25
	ds_read_b64 v[2:3], v25 offset:4352
	ds_read_b64 v[4:5], v25 offset:8704
	ds_read_b64 v[6:7], v25 offset:13056
	ds_read_b64 v[8:9], v25 offset:17408
	ds_read_b64 v[10:11], v25 offset:21760
	ds_read_b64 v[12:13], v25 offset:26112
	ds_read_b64 v[14:15], v25 offset:30464
	ds_read_b64 v[16:17], v25 offset:34816
	ds_read_b64 v[18:19], v25 offset:39168
	ds_read_b64 v[20:21], v25 offset:43520
	ds_read_b64 v[22:23], v25 offset:47872
	v_xor_b32_e32 v81, 0x80000000, v24
	s_waitcnt lgkmcnt(10)
	v_pk_mul_f32 v[82:83], v[2:3], v[24:25] op_sel:[1,0] op_sel_hi:[0,0] neg_hi:[0,1]
	v_pk_fma_f32 v[2:3], v[2:3], v[80:81], v[82:83] op_sel_hi:[1,0,1]
	v_pk_mul_f32 v[82:83], v[24:25], v[80:81] op_sel:[0,1] op_sel_hi:[0,0] neg_hi:[1,0]
	v_pk_fma_f32 v[82:83], v[80:81], v[80:81], v[82:83] op_sel_hi:[0,1,1]
	ds_read_b64 v[26:27], v25 offset:52224
	ds_read_b64 v[28:29], v25 offset:56576
	ds_read_b64 v[30:31], v25 offset:60928
	ds_read_b64 v[78:79], v25 offset:65280
	s_waitcnt lgkmcnt(13)
	v_pk_mul_f32 v[84:85], v[4:5], v[82:83] op_sel:[1,1] op_sel_hi:[0,1] neg_lo:[0,1]
	v_pk_fma_f32 v[4:5], v[4:5], v[82:83], v[84:85] op_sel_hi:[1,0,1]
	v_pk_mul_f32 v[84:85], v[24:25], v[82:83] op_sel:[0,1] op_sel_hi:[0,0] neg_hi:[1,0]
	v_pk_fma_f32 v[82:83], v[80:81], v[82:83], v[84:85] op_sel_hi:[0,1,1]
	s_mov_b32 s11, s14
	s_waitcnt lgkmcnt(12)
	v_pk_mul_f32 v[84:85], v[6:7], v[82:83] op_sel:[1,1] op_sel_hi:[0,1] neg_lo:[0,1]
	v_pk_fma_f32 v[6:7], v[6:7], v[82:83], v[84:85] op_sel_hi:[1,0,1]
	v_pk_mul_f32 v[84:85], v[24:25], v[82:83] op_sel:[0,1] op_sel_hi:[0,0] neg_hi:[1,0]
	v_pk_fma_f32 v[82:83], v[80:81], v[82:83], v[84:85] op_sel_hi:[0,1,1]
	s_mov_b32 s35, s30
	s_waitcnt lgkmcnt(11)
	v_pk_mul_f32 v[84:85], v[8:9], v[82:83] op_sel:[1,1] op_sel_hi:[0,1] neg_lo:[0,1]
	v_pk_fma_f32 v[8:9], v[8:9], v[82:83], v[84:85] op_sel_hi:[1,0,1]
	v_pk_mul_f32 v[84:85], v[24:25], v[82:83] op_sel:[0,1] op_sel_hi:[0,0] neg_hi:[1,0]
	v_pk_fma_f32 v[82:83], v[80:81], v[82:83], v[84:85] op_sel_hi:[0,1,1]
	s_mov_b32 s0, s19
	s_waitcnt lgkmcnt(10)
	v_pk_mul_f32 v[84:85], v[10:11], v[82:83] op_sel:[1,1] op_sel_hi:[0,1] neg_lo:[0,1]
	v_pk_fma_f32 v[10:11], v[10:11], v[82:83], v[84:85] op_sel_hi:[1,0,1]
	v_pk_mul_f32 v[84:85], v[24:25], v[82:83] op_sel:[0,1] op_sel_hi:[0,0] neg_hi:[1,0]
	v_pk_fma_f32 v[82:83], v[80:81], v[82:83], v[84:85] op_sel_hi:[0,1,1]
	s_waitcnt lgkmcnt(0)
	v_pk_mul_f32 v[84:85], v[12:13], v[82:83] op_sel:[1,1] op_sel_hi:[0,1] neg_lo:[0,1]
	v_pk_fma_f32 v[12:13], v[12:13], v[82:83], v[84:85] op_sel_hi:[1,0,1]
	v_pk_mul_f32 v[84:85], v[24:25], v[82:83] op_sel:[0,1] op_sel_hi:[0,0] neg_hi:[1,0]
	v_pk_fma_f32 v[82:83], v[80:81], v[82:83], v[84:85] op_sel_hi:[0,1,1]
	s_barrier
	v_pk_mul_f32 v[84:85], v[14:15], v[82:83] op_sel:[1,1] op_sel_hi:[0,1] neg_lo:[0,1]
	v_pk_fma_f32 v[14:15], v[14:15], v[82:83], v[84:85] op_sel_hi:[1,0,1]
	v_pk_mul_f32 v[84:85], v[24:25], v[82:83] op_sel:[0,1] op_sel_hi:[0,0] neg_hi:[1,0]
	v_pk_fma_f32 v[82:83], v[80:81], v[82:83], v[84:85] op_sel_hi:[0,1,1]
	v_pk_mul_f32 v[84:85], v[16:17], v[82:83] op_sel:[1,1] op_sel_hi:[0,1] neg_lo:[0,1]
	v_pk_fma_f32 v[16:17], v[16:17], v[82:83], v[84:85] op_sel_hi:[1,0,1]
	v_pk_mul_f32 v[84:85], v[24:25], v[82:83] op_sel:[0,1] op_sel_hi:[0,0] neg_hi:[1,0]
	v_pk_fma_f32 v[82:83], v[80:81], v[82:83], v[84:85] op_sel_hi:[0,1,1]
	v_pk_mul_f32 v[84:85], v[18:19], v[82:83] op_sel:[1,1] op_sel_hi:[0,1] neg_lo:[0,1]
	v_pk_fma_f32 v[18:19], v[18:19], v[82:83], v[84:85] op_sel_hi:[1,0,1]
	v_pk_mul_f32 v[84:85], v[24:25], v[82:83] op_sel:[0,1] op_sel_hi:[0,0] neg_hi:[1,0]
	v_pk_fma_f32 v[82:83], v[80:81], v[82:83], v[84:85] op_sel_hi:[0,1,1]
	v_pk_mul_f32 v[84:85], v[20:21], v[82:83] op_sel:[1,1] op_sel_hi:[0,1] neg_lo:[0,1]
	v_pk_fma_f32 v[20:21], v[20:21], v[82:83], v[84:85] op_sel_hi:[1,0,1]
	v_pk_mul_f32 v[84:85], v[24:25], v[82:83] op_sel:[0,1] op_sel_hi:[0,0] neg_hi:[1,0]
	v_pk_fma_f32 v[82:83], v[80:81], v[82:83], v[84:85] op_sel_hi:[0,1,1]
	v_pk_mul_f32 v[84:85], v[22:23], v[82:83] op_sel:[1,1] op_sel_hi:[0,1] neg_lo:[0,1]
	v_pk_fma_f32 v[22:23], v[22:23], v[82:83], v[84:85] op_sel_hi:[1,0,1]
	v_pk_mul_f32 v[84:85], v[24:25], v[82:83] op_sel:[0,1] op_sel_hi:[0,0] neg_hi:[1,0]
	v_pk_fma_f32 v[82:83], v[80:81], v[82:83], v[84:85] op_sel_hi:[0,1,1]
	v_pk_mul_f32 v[84:85], v[26:27], v[82:83] op_sel:[1,1] op_sel_hi:[0,1] neg_lo:[0,1]
	v_pk_fma_f32 v[26:27], v[26:27], v[82:83], v[84:85] op_sel_hi:[1,0,1]
	v_pk_mul_f32 v[84:85], v[24:25], v[82:83] op_sel:[0,1] op_sel_hi:[0,0] neg_hi:[1,0]
	v_pk_fma_f32 v[82:83], v[80:81], v[82:83], v[84:85] op_sel_hi:[0,1,1]
	v_pk_mul_f32 v[84:85], v[28:29], v[82:83] op_sel:[1,1] op_sel_hi:[0,1] neg_lo:[0,1]
	v_pk_fma_f32 v[28:29], v[28:29], v[82:83], v[84:85] op_sel_hi:[1,0,1]
	v_pk_mul_f32 v[84:85], v[24:25], v[82:83] op_sel:[0,1] op_sel_hi:[0,0] neg_hi:[1,0]
	v_pk_fma_f32 v[82:83], v[80:81], v[82:83], v[84:85] op_sel_hi:[0,1,1]
	v_pk_mul_f32 v[24:25], v[24:25], v[82:83] op_sel:[0,1] op_sel_hi:[0,0] neg_hi:[1,0]
	v_pk_fma_f32 v[24:25], v[80:81], v[82:83], v[24:25] op_sel_hi:[0,1,1]
	v_pk_mul_f32 v[80:81], v[78:79], v[24:25] op_sel:[1,1] op_sel_hi:[0,1] neg_lo:[0,1]
	v_pk_fma_f32 v[24:25], v[78:79], v[24:25], v[80:81] op_sel_hi:[1,0,1]
	v_pk_add_f32 v[78:79], v[0:1], v[16:17]
	v_pk_add_f32 v[0:1], v[0:1], v[16:17] neg_lo:[0,1] neg_hi:[0,1]
	v_pk_add_f32 v[16:17], v[2:3], v[18:19]
	v_pk_add_f32 v[2:3], v[2:3], v[18:19] neg_lo:[0,1] neg_hi:[0,1]
	v_pk_mul_f32 v[84:85], v[30:31], v[82:83] op_sel:[1,1] op_sel_hi:[0,1] neg_lo:[0,1]
	v_pk_mul_f32 v[18:19], v[2:3], s[18:19]
	v_pk_fma_f32 v[30:31], v[30:31], v[82:83], v[84:85] op_sel_hi:[1,0,1]
	v_pk_fma_f32 v[2:3], v[2:3], s[30:31], v[18:19] op_sel:[0,0,1] op_sel_hi:[1,0,0]
	v_pk_add_f32 v[18:19], v[4:5], v[20:21]
	v_pk_add_f32 v[4:5], v[4:5], v[20:21] neg_lo:[0,1] neg_hi:[0,1]
	v_pk_mul_f32 v[20:21], v[4:5], s[10:11]
	v_pk_fma_f32 v[4:5], v[4:5], s[14:15], v[20:21] op_sel:[0,0,1] op_sel_hi:[1,0,0]
	v_pk_add_f32 v[20:21], v[6:7], v[22:23]
	v_pk_add_f32 v[6:7], v[6:7], v[22:23] neg_lo:[0,1] neg_hi:[0,1]
	v_pk_mul_f32 v[22:23], v[6:7], s[34:35]
	v_pk_fma_f32 v[6:7], v[6:7], s[0:1], v[22:23] op_sel:[0,0,1] op_sel_hi:[1,0,0]
	v_pk_add_f32 v[22:23], v[8:9], v[26:27]
	v_pk_add_f32 v[8:9], v[8:9], v[26:27] neg_lo:[0,1] neg_hi:[0,1]
	v_pk_add_f32 v[26:27], v[10:11], v[28:29]
	v_pk_add_f32 v[10:11], v[10:11], v[28:29] neg_lo:[0,1] neg_hi:[0,1]
	v_pk_mul_f32 v[28:29], v[10:11], s[34:35]
	v_pk_fma_f32 v[10:11], v[10:11], s[0:1], v[28:29] op_sel:[0,0,1] op_sel_hi:[1,0,0] neg_lo:[1,0,0] neg_hi:[1,0,0]
	v_pk_add_f32 v[28:29], v[12:13], v[30:31]
	v_pk_add_f32 v[12:13], v[12:13], v[30:31] neg_lo:[0,1] neg_hi:[0,1]
	v_pk_mul_f32 v[30:31], v[12:13], s[10:11]
	v_pk_fma_f32 v[12:13], v[12:13], s[14:15], v[30:31] op_sel:[0,0,1] op_sel_hi:[1,0,0] neg_lo:[1,0,0] neg_hi:[1,0,0]
	v_pk_add_f32 v[30:31], v[14:15], v[24:25]
	v_pk_add_f32 v[14:15], v[14:15], v[24:25] neg_lo:[0,1] neg_hi:[0,1]
	v_pk_mul_f32 v[24:25], v[14:15], s[18:19]
	v_pk_fma_f32 v[14:15], v[14:15], s[30:31], v[24:25] op_sel:[0,0,1] op_sel_hi:[1,0,0] neg_lo:[1,0,0] neg_hi:[1,0,0]
	v_pk_add_f32 v[24:25], v[78:79], v[22:23]
	v_pk_add_f32 v[22:23], v[78:79], v[22:23] neg_lo:[0,1] neg_hi:[0,1]
	v_pk_add_f32 v[78:79], v[16:17], v[26:27]
	v_pk_add_f32 v[16:17], v[16:17], v[26:27] neg_lo:[0,1] neg_hi:[0,1]
	v_pk_mul_f32 v[26:27], v[16:17], s[10:11]
	v_pk_fma_f32 v[16:17], v[16:17], s[14:15], v[26:27] op_sel:[0,0,1] op_sel_hi:[1,0,0]
	v_pk_add_f32 v[26:27], v[18:19], v[28:29]
	v_pk_add_f32 v[18:19], v[18:19], v[28:29] neg_lo:[0,1] neg_hi:[0,1]
	v_pk_add_f32 v[28:29], v[20:21], v[30:31]
	v_pk_add_f32 v[20:21], v[20:21], v[30:31] neg_lo:[0,1] neg_hi:[0,1]
	v_pk_mul_f32 v[30:31], v[20:21], s[10:11]
	v_pk_fma_f32 v[20:21], v[20:21], s[14:15], v[30:31] op_sel:[0,0,1] op_sel_hi:[1,0,0] neg_lo:[1,0,0] neg_hi:[1,0,0]
	v_pk_add_f32 v[30:31], v[0:1], v[8:9] op_sel:[0,1] op_sel_hi:[1,0] neg_hi:[0,1]
	v_pk_add_f32 v[0:1], v[0:1], v[8:9] op_sel:[0,1] op_sel_hi:[1,0] neg_lo:[0,1]
	v_pk_add_f32 v[8:9], v[2:3], v[10:11]
	v_pk_add_f32 v[2:3], v[2:3], v[10:11] neg_lo:[0,1] neg_hi:[0,1]
	v_pk_mul_f32 v[10:11], v[2:3], s[10:11]
	v_pk_fma_f32 v[2:3], v[2:3], s[14:15], v[10:11] op_sel:[0,0,1] op_sel_hi:[1,0,0]
	v_pk_add_f32 v[10:11], v[4:5], v[12:13]
	v_pk_add_f32 v[4:5], v[4:5], v[12:13] neg_lo:[0,1] neg_hi:[0,1]
	v_pk_add_f32 v[12:13], v[6:7], v[14:15]
	v_pk_add_f32 v[6:7], v[6:7], v[14:15] neg_lo:[0,1] neg_hi:[0,1]
	v_pk_mul_f32 v[14:15], v[6:7], s[10:11]
	v_pk_fma_f32 v[6:7], v[6:7], s[14:15], v[14:15] op_sel:[0,0,1] op_sel_hi:[1,0,0] neg_lo:[1,0,0] neg_hi:[1,0,0]
	v_pk_add_f32 v[14:15], v[24:25], v[26:27]
	v_pk_add_f32 v[24:25], v[24:25], v[26:27] neg_lo:[0,1] neg_hi:[0,1]
	v_pk_add_f32 v[26:27], v[78:79], v[28:29]
	v_pk_add_f32 v[28:29], v[78:79], v[28:29] neg_lo:[0,1] neg_hi:[0,1]
	v_pk_add_f32 v[78:79], v[22:23], v[18:19] op_sel:[0,1] op_sel_hi:[1,0] neg_hi:[0,1]
	v_pk_add_f32 v[18:19], v[22:23], v[18:19] op_sel:[0,1] op_sel_hi:[1,0] neg_lo:[0,1]
	v_pk_add_f32 v[22:23], v[16:17], v[20:21]
	v_pk_add_f32 v[16:17], v[16:17], v[20:21] neg_lo:[0,1] neg_hi:[0,1]
	v_pk_add_f32 v[20:21], v[30:31], v[10:11]
	v_pk_add_f32 v[10:11], v[30:31], v[10:11] neg_lo:[0,1] neg_hi:[0,1]
	v_pk_add_f32 v[30:31], v[8:9], v[12:13]
	v_pk_add_f32 v[8:9], v[8:9], v[12:13] neg_lo:[0,1] neg_hi:[0,1]
	v_pk_add_f32 v[12:13], v[0:1], v[4:5] op_sel:[0,1] op_sel_hi:[1,0] neg_hi:[0,1]
	v_pk_add_f32 v[0:1], v[0:1], v[4:5] op_sel:[0,1] op_sel_hi:[1,0] neg_lo:[0,1]
	v_pk_add_f32 v[4:5], v[2:3], v[6:7]
	v_pk_add_f32 v[2:3], v[2:3], v[6:7] neg_lo:[0,1] neg_hi:[0,1]
	v_pk_mul_f32 v[2:3], v[2:3], s[22:23]
	v_pk_add_f32 v[6:7], v[14:15], v[26:27]
	v_pk_add_f32 v[14:15], v[14:15], v[26:27] neg_lo:[0,1] neg_hi:[0,1]
	v_pk_add_f32 v[26:27], v[24:25], v[28:29] op_sel:[0,1] op_sel_hi:[1,0] neg_hi:[0,1]
	v_pk_add_f32 v[24:25], v[24:25], v[28:29] op_sel:[0,1] op_sel_hi:[1,0] neg_lo:[0,1]
	v_pk_add_f32 v[28:29], v[78:79], v[22:23]
	v_pk_add_f32 v[22:23], v[78:79], v[22:23] neg_lo:[0,1] neg_hi:[0,1]
	v_pk_add_f32 v[78:79], v[18:19], v[16:17] op_sel:[0,1] op_sel_hi:[1,0] neg_hi:[0,1]
	v_pk_add_f32 v[16:17], v[18:19], v[16:17] op_sel:[0,1] op_sel_hi:[1,0] neg_lo:[0,1]
	v_pk_add_f32 v[18:19], v[20:21], v[30:31]
	v_pk_add_f32 v[20:21], v[20:21], v[30:31] neg_lo:[0,1] neg_hi:[0,1]
	v_pk_add_f32 v[30:31], v[10:11], v[8:9] op_sel:[0,1] op_sel_hi:[1,0] neg_hi:[0,1]
	v_pk_add_f32 v[8:9], v[10:11], v[8:9] op_sel:[0,1] op_sel_hi:[1,0] neg_lo:[0,1]
	v_pk_add_f32 v[10:11], v[12:13], v[4:5]
	v_pk_add_f32 v[4:5], v[12:13], v[4:5] neg_lo:[0,1] neg_hi:[0,1]
	v_pk_add_f32 v[12:13], v[0:1], v[2:3] op_sel:[0,1] op_sel_hi:[1,0]
	v_pk_add_f32 v[0:1], v[0:1], v[2:3] op_sel:[0,1] op_sel_hi:[1,0] neg_lo:[0,1] neg_hi:[0,1]
	v_lshlrev_b32_e32 v2, 4, v39
	v_and_or_b32 v2, v2, s7, v86
	v_ashrrev_i32_e32 v3, 4, v2
	v_lshlrev_b32_e32 v3, 3, v3
	v_lshlrev_b32_e32 v2, 3, v2
	v_add3_u32 v2, s26, v3, v2
	v_add_u32_e32 v3, 0x800, v2
	v_mov_b32_e32 v39, v32
	ds_write2_b64 v2, v[6:7], v[18:19] offset1:34
	ds_write2_b64 v3, v[14:15], v[20:21] offset0:16 offset1:50
	ds_write2_b64 v2, v[26:27], v[30:31] offset0:136 offset1:170
	ds_write2_b64 v3, v[24:25], v[8:9] offset0:152 offset1:186
	ds_write2_b64 v2, v[28:29], v[10:11] offset0:68 offset1:102
	ds_write2_b64 v3, v[22:23], v[4:5] offset0:84 offset1:118
	ds_write2_b64 v2, v[78:79], v[12:13] offset0:204 offset1:238
	ds_write2_b64 v3, v[16:17], v[0:1] offset0:220 offset1:254
	s_waitcnt lgkmcnt(0)
	s_barrier
	s_nop 0
	v_and_b32_e32 v86, 0x1ff, v39
	v_cvt_f32_u32_e32 v24, v86
	v_ashrrev_i32_e32 v0, 4, v39
	v_lshlrev_b32_e32 v0, 3, v0
	v_lshlrev_b32_e32 v1, 3, v39
	v_mul_f32_e32 v80, 0x39000000, v24
	v_sin_f32_e32 v24, v80
	v_cos_f32_e32 v80, v80
	v_add3_u32 v25, s26, v0, v1
	ds_read_b64 v[0:1], v25
	ds_read_b64 v[2:3], v25 offset:4352
	ds_read_b64 v[4:5], v25 offset:8704
	ds_read_b64 v[6:7], v25 offset:13056
	ds_read_b64 v[8:9], v25 offset:17408
	ds_read_b64 v[10:11], v25 offset:21760
	ds_read_b64 v[12:13], v25 offset:26112
	ds_read_b64 v[14:15], v25 offset:30464
	v_xor_b32_e32 v81, 0x80000000, v24
	s_waitcnt lgkmcnt(6)
	v_pk_mul_f32 v[82:83], v[2:3], v[24:25] op_sel:[1,0] op_sel_hi:[0,0] neg_hi:[0,1]
	v_pk_fma_f32 v[2:3], v[2:3], v[80:81], v[82:83] op_sel_hi:[1,0,1]
	v_pk_mul_f32 v[82:83], v[24:25], v[80:81] op_sel:[0,1] op_sel_hi:[0,0] neg_hi:[1,0]
	v_pk_fma_f32 v[82:83], v[80:81], v[80:81], v[82:83] op_sel_hi:[0,1,1]
	ds_read_b64 v[16:17], v25 offset:34816
	ds_read_b64 v[18:19], v25 offset:39168
	ds_read_b64 v[20:21], v25 offset:43520
	ds_read_b64 v[22:23], v25 offset:47872
	s_waitcnt lgkmcnt(9)
	v_pk_mul_f32 v[84:85], v[4:5], v[82:83] op_sel:[1,1] op_sel_hi:[0,1] neg_lo:[0,1]
	v_pk_fma_f32 v[4:5], v[4:5], v[82:83], v[84:85] op_sel_hi:[1,0,1]
	v_pk_mul_f32 v[84:85], v[24:25], v[82:83] op_sel:[0,1] op_sel_hi:[0,0] neg_hi:[1,0]
	v_pk_fma_f32 v[82:83], v[80:81], v[82:83], v[84:85] op_sel_hi:[0,1,1]
	ds_read_b64 v[26:27], v25 offset:52224
	ds_read_b64 v[28:29], v25 offset:56576
	ds_read_b64 v[30:31], v25 offset:60928
	ds_read_b64 v[78:79], v25 offset:65280
	s_waitcnt lgkmcnt(12)
	v_pk_mul_f32 v[84:85], v[6:7], v[82:83] op_sel:[1,1] op_sel_hi:[0,1] neg_lo:[0,1]
	v_pk_fma_f32 v[6:7], v[6:7], v[82:83], v[84:85] op_sel_hi:[1,0,1]
	v_pk_mul_f32 v[84:85], v[24:25], v[82:83] op_sel:[0,1] op_sel_hi:[0,0] neg_hi:[1,0]
	v_pk_fma_f32 v[82:83], v[80:81], v[82:83], v[84:85] op_sel_hi:[0,1,1]
	s_waitcnt lgkmcnt(0)
	v_pk_mul_f32 v[84:85], v[8:9], v[82:83] op_sel:[1,1] op_sel_hi:[0,1] neg_lo:[0,1]
	v_pk_fma_f32 v[8:9], v[8:9], v[82:83], v[84:85] op_sel_hi:[1,0,1]
	v_pk_mul_f32 v[84:85], v[24:25], v[82:83] op_sel:[0,1] op_sel_hi:[0,0] neg_hi:[1,0]
	v_pk_fma_f32 v[82:83], v[80:81], v[82:83], v[84:85] op_sel_hi:[0,1,1]
	s_barrier
	v_pk_mul_f32 v[84:85], v[10:11], v[82:83] op_sel:[1,1] op_sel_hi:[0,1] neg_lo:[0,1]
	v_pk_fma_f32 v[10:11], v[10:11], v[82:83], v[84:85] op_sel_hi:[1,0,1]
	v_pk_mul_f32 v[84:85], v[24:25], v[82:83] op_sel:[0,1] op_sel_hi:[0,0] neg_hi:[1,0]
	v_pk_fma_f32 v[82:83], v[80:81], v[82:83], v[84:85] op_sel_hi:[0,1,1]
	v_pk_mul_f32 v[84:85], v[12:13], v[82:83] op_sel:[1,1] op_sel_hi:[0,1] neg_lo:[0,1]
	v_pk_fma_f32 v[12:13], v[12:13], v[82:83], v[84:85] op_sel_hi:[1,0,1]
	v_pk_mul_f32 v[84:85], v[24:25], v[82:83] op_sel:[0,1] op_sel_hi:[0,0] neg_hi:[1,0]
	v_pk_fma_f32 v[82:83], v[80:81], v[82:83], v[84:85] op_sel_hi:[0,1,1]
	v_pk_mul_f32 v[84:85], v[14:15], v[82:83] op_sel:[1,1] op_sel_hi:[0,1] neg_lo:[0,1]
	v_pk_fma_f32 v[14:15], v[14:15], v[82:83], v[84:85] op_sel_hi:[1,0,1]
	v_pk_mul_f32 v[84:85], v[24:25], v[82:83] op_sel:[0,1] op_sel_hi:[0,0] neg_hi:[1,0]
	v_pk_fma_f32 v[82:83], v[80:81], v[82:83], v[84:85] op_sel_hi:[0,1,1]
	v_pk_mul_f32 v[84:85], v[16:17], v[82:83] op_sel:[1,1] op_sel_hi:[0,1] neg_lo:[0,1]
	v_pk_fma_f32 v[16:17], v[16:17], v[82:83], v[84:85] op_sel_hi:[1,0,1]
	v_pk_mul_f32 v[84:85], v[24:25], v[82:83] op_sel:[0,1] op_sel_hi:[0,0] neg_hi:[1,0]
	v_pk_fma_f32 v[82:83], v[80:81], v[82:83], v[84:85] op_sel_hi:[0,1,1]
	v_pk_mul_f32 v[84:85], v[18:19], v[82:83] op_sel:[1,1] op_sel_hi:[0,1] neg_lo:[0,1]
	v_pk_fma_f32 v[18:19], v[18:19], v[82:83], v[84:85] op_sel_hi:[1,0,1]
	v_pk_mul_f32 v[84:85], v[24:25], v[82:83] op_sel:[0,1] op_sel_hi:[0,0] neg_hi:[1,0]
	v_pk_fma_f32 v[82:83], v[80:81], v[82:83], v[84:85] op_sel_hi:[0,1,1]
	v_pk_mul_f32 v[84:85], v[20:21], v[82:83] op_sel:[1,1] op_sel_hi:[0,1] neg_lo:[0,1]
	v_pk_fma_f32 v[20:21], v[20:21], v[82:83], v[84:85] op_sel_hi:[1,0,1]
	v_pk_mul_f32 v[84:85], v[24:25], v[82:83] op_sel:[0,1] op_sel_hi:[0,0] neg_hi:[1,0]
	v_pk_fma_f32 v[82:83], v[80:81], v[82:83], v[84:85] op_sel_hi:[0,1,1]
	v_pk_mul_f32 v[84:85], v[22:23], v[82:83] op_sel:[1,1] op_sel_hi:[0,1] neg_lo:[0,1]
	v_pk_fma_f32 v[22:23], v[22:23], v[82:83], v[84:85] op_sel_hi:[1,0,1]
	v_pk_mul_f32 v[84:85], v[24:25], v[82:83] op_sel:[0,1] op_sel_hi:[0,0] neg_hi:[1,0]
	v_pk_fma_f32 v[82:83], v[80:81], v[82:83], v[84:85] op_sel_hi:[0,1,1]
	v_pk_mul_f32 v[84:85], v[26:27], v[82:83] op_sel:[1,1] op_sel_hi:[0,1] neg_lo:[0,1]
	v_pk_fma_f32 v[26:27], v[26:27], v[82:83], v[84:85] op_sel_hi:[1,0,1]
	v_pk_mul_f32 v[84:85], v[24:25], v[82:83] op_sel:[0,1] op_sel_hi:[0,0] neg_hi:[1,0]
	v_pk_fma_f32 v[82:83], v[80:81], v[82:83], v[84:85] op_sel_hi:[0,1,1]
	v_pk_mul_f32 v[84:85], v[28:29], v[82:83] op_sel:[1,1] op_sel_hi:[0,1] neg_lo:[0,1]
	v_pk_fma_f32 v[28:29], v[28:29], v[82:83], v[84:85] op_sel_hi:[1,0,1]
	v_pk_mul_f32 v[84:85], v[24:25], v[82:83] op_sel:[0,1] op_sel_hi:[0,0] neg_hi:[1,0]
	v_pk_fma_f32 v[82:83], v[80:81], v[82:83], v[84:85] op_sel_hi:[0,1,1]
	v_pk_mul_f32 v[24:25], v[24:25], v[82:83] op_sel:[0,1] op_sel_hi:[0,0] neg_hi:[1,0]
	v_pk_fma_f32 v[24:25], v[80:81], v[82:83], v[24:25] op_sel_hi:[0,1,1]
	v_pk_mul_f32 v[80:81], v[78:79], v[24:25] op_sel:[1,1] op_sel_hi:[0,1] neg_lo:[0,1]
	v_pk_fma_f32 v[24:25], v[78:79], v[24:25], v[80:81] op_sel_hi:[1,0,1]
	v_pk_add_f32 v[78:79], v[0:1], v[16:17]
	v_pk_add_f32 v[0:1], v[0:1], v[16:17] neg_lo:[0,1] neg_hi:[0,1]
	v_pk_add_f32 v[16:17], v[2:3], v[18:19]
	v_pk_add_f32 v[2:3], v[2:3], v[18:19] neg_lo:[0,1] neg_hi:[0,1]
	v_pk_mul_f32 v[84:85], v[30:31], v[82:83] op_sel:[1,1] op_sel_hi:[0,1] neg_lo:[0,1]
	v_pk_mul_f32 v[18:19], v[2:3], s[18:19]
	v_pk_fma_f32 v[30:31], v[30:31], v[82:83], v[84:85] op_sel_hi:[1,0,1]
	v_pk_fma_f32 v[2:3], v[2:3], s[30:31], v[18:19] op_sel:[0,0,1] op_sel_hi:[1,0,0]
	v_pk_add_f32 v[18:19], v[4:5], v[20:21]
	v_pk_add_f32 v[4:5], v[4:5], v[20:21] neg_lo:[0,1] neg_hi:[0,1]
	v_mov_b32_e32 v81, 0
	v_pk_mul_f32 v[20:21], v[4:5], s[10:11]
	v_mov_b32_e32 v80, 0
	v_pk_fma_f32 v[4:5], v[4:5], s[14:15], v[20:21] op_sel:[0,0,1] op_sel_hi:[1,0,0]
	v_pk_add_f32 v[20:21], v[6:7], v[22:23]
	v_pk_add_f32 v[6:7], v[6:7], v[22:23] neg_lo:[0,1] neg_hi:[0,1]
	v_pk_mul_f32 v[22:23], v[6:7], s[34:35]
	v_pk_fma_f32 v[6:7], v[6:7], s[0:1], v[22:23] op_sel:[0,0,1] op_sel_hi:[1,0,0]
	v_pk_add_f32 v[22:23], v[8:9], v[26:27]
	v_pk_add_f32 v[8:9], v[8:9], v[26:27] neg_lo:[0,1] neg_hi:[0,1]
	v_pk_add_f32 v[26:27], v[10:11], v[28:29]
	v_pk_add_f32 v[10:11], v[10:11], v[28:29] neg_lo:[0,1] neg_hi:[0,1]
	v_pk_mul_f32 v[28:29], v[10:11], s[34:35]
	v_pk_fma_f32 v[10:11], v[10:11], s[0:1], v[28:29] op_sel:[0,0,1] op_sel_hi:[1,0,0] neg_lo:[1,0,0] neg_hi:[1,0,0]
	v_pk_add_f32 v[28:29], v[12:13], v[30:31]
	v_pk_add_f32 v[12:13], v[12:13], v[30:31] neg_lo:[0,1] neg_hi:[0,1]
	s_lshl_b32 s0, s57, 9
	v_pk_mul_f32 v[30:31], v[12:13], s[10:11]
	s_add_u32 s0, s60, s0
	v_pk_fma_f32 v[12:13], v[12:13], s[14:15], v[30:31] op_sel:[0,0,1] op_sel_hi:[1,0,0] neg_lo:[1,0,0] neg_hi:[1,0,0]
	v_pk_add_f32 v[30:31], v[14:15], v[24:25]
	v_pk_add_f32 v[14:15], v[14:15], v[24:25] neg_lo:[0,1] neg_hi:[0,1]
	s_addc_u32 s1, s61, 0
	v_pk_mul_f32 v[24:25], v[14:15], s[18:19]
	s_add_u32 s0, s0, 0x81b2000
	v_pk_fma_f32 v[14:15], v[14:15], s[30:31], v[24:25] op_sel:[0,0,1] op_sel_hi:[1,0,0] neg_lo:[1,0,0] neg_hi:[1,0,0]
	v_pk_add_f32 v[24:25], v[78:79], v[22:23]
	v_pk_add_f32 v[22:23], v[78:79], v[22:23] neg_lo:[0,1] neg_hi:[0,1]
	v_pk_add_f32 v[78:79], v[16:17], v[26:27]
	v_pk_add_f32 v[16:17], v[16:17], v[26:27] neg_lo:[0,1] neg_hi:[0,1]
	s_addc_u32 s1, s1, 0
	v_pk_mul_f32 v[26:27], v[16:17], s[10:11]
	s_nop 0
	v_pk_fma_f32 v[16:17], v[16:17], s[14:15], v[26:27] op_sel:[0,0,1] op_sel_hi:[1,0,0]
	v_pk_add_f32 v[26:27], v[18:19], v[28:29]
	v_pk_add_f32 v[18:19], v[18:19], v[28:29] neg_lo:[0,1] neg_hi:[0,1]
	v_pk_add_f32 v[28:29], v[20:21], v[30:31]
	v_pk_add_f32 v[20:21], v[20:21], v[30:31] neg_lo:[0,1] neg_hi:[0,1]
	v_pk_mul_f32 v[30:31], v[20:21], s[10:11]
	v_pk_fma_f32 v[20:21], v[20:21], s[14:15], v[30:31] op_sel:[0,0,1] op_sel_hi:[1,0,0] neg_lo:[1,0,0] neg_hi:[1,0,0]
	v_pk_add_f32 v[30:31], v[0:1], v[8:9] op_sel:[0,1] op_sel_hi:[1,0] neg_hi:[0,1]
	v_pk_add_f32 v[0:1], v[0:1], v[8:9] op_sel:[0,1] op_sel_hi:[1,0] neg_lo:[0,1]
	v_pk_add_f32 v[8:9], v[2:3], v[10:11]
	v_pk_add_f32 v[2:3], v[2:3], v[10:11] neg_lo:[0,1] neg_hi:[0,1]
	v_pk_mul_f32 v[10:11], v[2:3], s[10:11]
	v_pk_fma_f32 v[2:3], v[2:3], s[14:15], v[10:11] op_sel:[0,0,1] op_sel_hi:[1,0,0]
	v_pk_add_f32 v[10:11], v[4:5], v[12:13]
	v_pk_add_f32 v[4:5], v[4:5], v[12:13] neg_lo:[0,1] neg_hi:[0,1]
	v_pk_add_f32 v[12:13], v[6:7], v[14:15]
	v_pk_add_f32 v[6:7], v[6:7], v[14:15] neg_lo:[0,1] neg_hi:[0,1]
	v_pk_mul_f32 v[14:15], v[6:7], s[10:11]
	v_pk_fma_f32 v[6:7], v[6:7], s[14:15], v[14:15] op_sel:[0,0,1] op_sel_hi:[1,0,0] neg_lo:[1,0,0] neg_hi:[1,0,0]
	v_pk_add_f32 v[14:15], v[24:25], v[26:27]
	v_pk_add_f32 v[24:25], v[24:25], v[26:27] neg_lo:[0,1] neg_hi:[0,1]
	v_pk_add_f32 v[26:27], v[78:79], v[28:29]
	v_pk_add_f32 v[28:29], v[78:79], v[28:29] neg_lo:[0,1] neg_hi:[0,1]
	v_pk_add_f32 v[78:79], v[22:23], v[18:19] op_sel:[0,1] op_sel_hi:[1,0] neg_hi:[0,1]
	v_pk_add_f32 v[18:19], v[22:23], v[18:19] op_sel:[0,1] op_sel_hi:[1,0] neg_lo:[0,1]
	v_pk_add_f32 v[22:23], v[16:17], v[20:21]
	v_pk_add_f32 v[16:17], v[16:17], v[20:21] neg_lo:[0,1] neg_hi:[0,1]
	v_pk_add_f32 v[20:21], v[30:31], v[10:11]
	v_pk_add_f32 v[10:11], v[30:31], v[10:11] neg_lo:[0,1] neg_hi:[0,1]
	v_pk_add_f32 v[30:31], v[8:9], v[12:13]
	v_pk_add_f32 v[8:9], v[8:9], v[12:13] neg_lo:[0,1] neg_hi:[0,1]
	v_pk_add_f32 v[12:13], v[0:1], v[4:5] op_sel:[0,1] op_sel_hi:[1,0] neg_hi:[0,1]
	v_pk_add_f32 v[0:1], v[0:1], v[4:5] op_sel:[0,1] op_sel_hi:[1,0] neg_lo:[0,1]
	v_pk_add_f32 v[4:5], v[2:3], v[6:7]
	v_pk_add_f32 v[2:3], v[2:3], v[6:7] neg_lo:[0,1] neg_hi:[0,1]
	v_pk_mul_f32 v[2:3], v[2:3], s[22:23]
	v_pk_add_f32 v[6:7], v[14:15], v[26:27]
	v_pk_add_f32 v[14:15], v[14:15], v[26:27] neg_lo:[0,1] neg_hi:[0,1]
	v_pk_add_f32 v[26:27], v[24:25], v[28:29] op_sel:[0,1] op_sel_hi:[1,0] neg_hi:[0,1]
	v_pk_add_f32 v[24:25], v[24:25], v[28:29] op_sel:[0,1] op_sel_hi:[1,0] neg_lo:[0,1]
	v_pk_add_f32 v[28:29], v[78:79], v[22:23]
	v_pk_add_f32 v[22:23], v[78:79], v[22:23] neg_lo:[0,1] neg_hi:[0,1]
	v_pk_add_f32 v[78:79], v[18:19], v[16:17] op_sel:[0,1] op_sel_hi:[1,0] neg_hi:[0,1]
	v_pk_add_f32 v[16:17], v[18:19], v[16:17] op_sel:[0,1] op_sel_hi:[1,0] neg_lo:[0,1]
	v_pk_add_f32 v[18:19], v[20:21], v[30:31]
	v_pk_add_f32 v[20:21], v[20:21], v[30:31] neg_lo:[0,1] neg_hi:[0,1]
	v_pk_add_f32 v[30:31], v[10:11], v[8:9] op_sel:[0,1] op_sel_hi:[1,0] neg_hi:[0,1]
	v_pk_add_f32 v[8:9], v[10:11], v[8:9] op_sel:[0,1] op_sel_hi:[1,0] neg_lo:[0,1]
	v_pk_add_f32 v[10:11], v[12:13], v[4:5]
	v_pk_add_f32 v[4:5], v[12:13], v[4:5] neg_lo:[0,1] neg_hi:[0,1]
	v_pk_add_f32 v[12:13], v[0:1], v[2:3] op_sel:[0,1] op_sel_hi:[1,0]
	v_pk_add_f32 v[0:1], v[0:1], v[2:3] op_sel:[0,1] op_sel_hi:[1,0] neg_lo:[0,1] neg_hi:[0,1]
	v_lshlrev_b32_e32 v2, 4, v39
	v_and_or_b32 v2, v2, s15, v86
	v_ashrrev_i32_e32 v3, 4, v2
	v_lshlrev_b32_e32 v3, 3, v3
	v_lshlrev_b32_e32 v2, 3, v2
	v_add3_u32 v2, s26, v3, v2
	v_and_b32_e32 v39, 31, v32
	ds_write_b64 v2, v[6:7]
	ds_write_b64 v2, v[14:15] offset:34816
	ds_write_b64 v2, v[26:27] offset:17408
	ds_write_b64 v2, v[24:25] offset:52224
	ds_write_b64 v2, v[28:29] offset:8704
	ds_write_b64 v2, v[22:23] offset:43520
	ds_write_b64 v2, v[78:79] offset:26112
	ds_write_b64 v2, v[16:17] offset:60928
	ds_write_b64 v2, v[18:19] offset:4352
	ds_write_b64 v2, v[20:21] offset:39168
	ds_write_b64 v2, v[30:31] offset:21760
	ds_write_b64 v2, v[8:9] offset:56576
	ds_write_b64 v2, v[10:11] offset:13056
	ds_write_b64 v2, v[4:5] offset:47872
	ds_write_b64 v2, v[12:13] offset:30464
	ds_write_b64 v2, v[0:1] offset:65280
	v_lshlrev_b32_e32 v2, 4, v39
	v_ashrrev_i32_e32 v3, 5, v32
	v_mov_b64_e32 v[0:1], s[0:1]
	s_mov_b32 s0, 0x180000
	v_cmp_gt_u32_e64 s[42:43], 16, v39
	v_mad_i64_i32 v[78:79], s[0:1], v3, s0, v[0:1]
	v_mov_b32_e32 v9, 0
	v_lshlrev_b32_e32 v172, 1, v2
	v_mov_b32_e32 v8, 0
	v_mov_b32_e32 v11, 0
	v_mov_b32_e32 v10, 0
	v_mov_b32_e32 v13, 0
	v_mov_b32_e32 v12, 0
	v_mov_b32_e32 v15, 0
	v_mov_b32_e32 v14, 0
	v_mov_b32_e32 v17, 0
	v_mov_b32_e32 v16, 0
	v_mov_b32_e32 v21, 0
	v_mov_b32_e32 v20, 0
	v_mov_b32_e32 v23, 0
	v_mov_b32_e32 v22, 0
	v_mov_b32_e32 v25, 0
	v_mov_b32_e32 v24, 0
	v_mov_b32_e32 v1, 0
	v_mov_b32_e32 v0, 0
	v_mov_b32_e32 v3, 0
	v_mov_b32_e32 v2, 0
	v_mov_b32_e32 v5, 0
	v_mov_b32_e32 v4, 0
	v_mov_b32_e32 v7, 0
	v_mov_b32_e32 v6, 0
	v_mov_b32_e32 v27, 0
	v_mov_b32_e32 v26, 0
	v_mov_b32_e32 v29, 0
	v_mov_b32_e32 v28, 0
	v_mov_b32_e32 v31, 0
	v_mov_b32_e32 v30, 0
	s_waitcnt lgkmcnt(0)
	s_barrier
	s_and_saveexec_b64 s[0:1], s[42:43]
	s_cbranch_execz .LBB0_428
	v_lshl_add_u64 v[0:1], v[78:79], 0, v[172:173]
	global_load_dwordx4 v[8:11], v[0:1], off offset:16
	global_load_dwordx4 v[12:15], v[0:1], off
	v_cmp_ne_u32_e64 s[44:45], 0, v39
	v_mov_b32_e32 v27, 0
	v_mov_b32_e32 v16, 0
	s_and_saveexec_b64 s[4:5], s[44:45]
	s_cbranch_execz .LBB0_421
	global_load_ushort v2, v[0:1], off offset:-2
	s_waitcnt vmcnt(0)
	v_lshlrev_b32_e32 v16, 16, v2

.LBB0_428:
	s_or_b64 exec, exec, s[0:1]
	s_movk_i32 s0, 0x88
	v_mul_lo_u32 v18, v32, s0
	v_add_u32_e32 v152, 0, v18
	v_cndmask_b32_e64 v95, 0, v80, s[42:43]
	v_cndmask_b32_e64 v94, 0, v24, s[42:43]
	v_cndmask_b32_e64 v89, 0, v81, s[42:43]
	v_cndmask_b32_e64 v88, 0, v25, s[42:43]
	v_cndmask_b32_e64 v113, 0, v30, s[42:43]
	v_cndmask_b32_e64 v112, 0, v22, s[42:43]
	v_cndmask_b32_e64 v105, 0, v31, s[42:43]
	v_cndmask_b32_e64 v104, 0, v23, s[42:43]
	v_cndmask_b32_e64 v97, 0, v28, s[42:43]
	v_cndmask_b32_e64 v96, 0, v20, s[42:43]
	v_cndmask_b32_e64 v91, 0, v29, s[42:43]
	v_cndmask_b32_e64 v90, 0, v21, s[42:43]
	v_cndmask_b32_e64 v115, 0, v26, s[42:43]
	v_cndmask_b32_e64 v114, 0, v16, s[42:43]
	v_cndmask_b32_e64 v107, 0, v27, s[42:43]
	v_cndmask_b32_e64 v106, 0, v17, s[42:43]
	v_cndmask_b32_e64 v99, 0, v6, s[42:43]
	v_cndmask_b32_e64 v98, 0, v14, s[42:43]
	v_cndmask_b32_e64 v93, 0, v7, s[42:43]
	v_cndmask_b32_e64 v92, 0, v15, s[42:43]
	v_cndmask_b32_e64 v117, 0, v4, s[42:43]
	v_cndmask_b32_e64 v116, 0, v12, s[42:43]
	v_cndmask_b32_e64 v109, 0, v5, s[42:43]
	v_cndmask_b32_e64 v108, 0, v13, s[42:43]
	v_cndmask_b32_e64 v101, 0, v2, s[42:43]
	v_cndmask_b32_e64 v100, 0, v10, s[42:43]
	v_cndmask_b32_e64 v87, 0, v3, s[42:43]
	v_cndmask_b32_e64 v86, 0, v11, s[42:43]
	v_cndmask_b32_e64 v85, 0, v0, s[42:43]
	v_cndmask_b32_e64 v84, 0, v8, s[42:43]
	v_cndmask_b32_e64 v83, 0, v1, s[42:43]
	v_cndmask_b32_e64 v82, 0, v9, s[42:43]
	v_add3_u32 v153, 0, v41, v157
	ds_write2_b64 v152, v[94:95], v[88:89] offset1:1
	ds_write2_b64 v152, v[112:113], v[104:105] offset0:2 offset1:3
	ds_write2_b64 v152, v[96:97], v[90:91] offset0:4 offset1:5
	ds_write2_b64 v152, v[114:115], v[106:107] offset0:6 offset1:7
	ds_write2_b64 v152, v[98:99], v[92:93] offset0:8 offset1:9
	ds_write2_b64 v152, v[116:117], v[108:109] offset0:10 offset1:11
	ds_write2_b64 v152, v[100:101], v[86:87] offset0:12 offset1:13
	ds_write2_b64 v152, v[84:85], v[82:83] offset0:14 offset1:15
	s_waitcnt lgkmcnt(0)
	s_barrier
	s_and_saveexec_b64 s[0:1], s[40:41]
	s_cbranch_execz .LBB0_430
	v_add_u32_e32 v142, 0x10780, v153
	ds_read_b64 v[0:1], v153
	ds_read_b64 v[2:3], v153 offset:2176
	ds_read_b64 v[4:5], v153 offset:4352
	ds_read_b64 v[6:7], v153 offset:6528
	ds_read_b64 v[8:9], v153 offset:8704
	ds_read_b64 v[10:11], v153 offset:10880
	ds_read_b64 v[12:13], v153 offset:13056
	ds_read_b64 v[14:15], v153 offset:15232
	ds_read_b64 v[16:17], v153 offset:17408
	ds_read_b64 v[18:19], v153 offset:19584
	ds_read_b64 v[20:21], v153 offset:21760
	ds_read_b64 v[22:23], v153 offset:23936
	ds_read_b64 v[24:25], v153 offset:26112
	ds_read_b64 v[26:27], v153 offset:28288
	ds_read_b64 v[28:29], v153 offset:30464
	ds_read_b64 v[30:31], v153 offset:32640
	ds_read_b64 v[80:81], v153 offset:34816
	ds_read_b64 v[102:103], v153 offset:41344
	ds_read_b64 v[110:111], v153 offset:43520
	ds_read_b64 v[118:119], v153 offset:45696
	ds_read_b64 v[120:121], v153 offset:47872
	ds_read_b64 v[122:123], v153 offset:50048
	ds_read_b64 v[124:125], v153 offset:52224
	ds_read_b64 v[126:127], v153 offset:54400
	ds_read_b64 v[128:129], v153 offset:56576
	ds_read_b64 v[130:131], v153 offset:58752
	ds_read_b64 v[132:133], v153 offset:60928
	ds_read_b64 v[134:135], v153 offset:63104
	ds_read_b64 v[136:137], v153 offset:65280
	ds_read_b64 v[138:139], v153 offset:36992
	ds_read_b64 v[140:141], v153 offset:39168
	ds_read_b64 v[142:143], v142
	s_waitcnt lgkmcnt(14)
	v_pk_add_f32 v[144:145], v[0:1], v[80:81]
	v_pk_add_f32 v[0:1], v[0:1], v[80:81] neg_lo:[0,1] neg_hi:[0,1]
	s_waitcnt lgkmcnt(2)
	v_pk_add_f32 v[80:81], v[2:3], v[138:139]
	v_pk_add_f32 v[2:3], v[2:3], v[138:139] neg_lo:[0,1] neg_hi:[0,1]
	s_mov_b32 s11, s14
	v_pk_mul_f32 v[138:139], v[2:3], s[16:17]
	s_mov_b32 s13, s86
	v_pk_fma_f32 v[2:3], v[2:3], s[6:7], v[138:139] op_sel:[0,0,1] op_sel_hi:[1,0,0]
	s_waitcnt lgkmcnt(1)
	v_pk_add_f32 v[138:139], v[4:5], v[140:141]
	v_pk_add_f32 v[4:5], v[4:5], v[140:141] neg_lo:[0,1] neg_hi:[0,1]
	s_mov_b32 s4, s21
	v_pk_mul_f32 v[140:141], v[4:5], s[18:19]
	s_mov_b32 s35, s30
	v_pk_fma_f32 v[4:5], v[4:5], s[30:31], v[140:141] op_sel:[0,0,1] op_sel_hi:[1,0,0]
	v_pk_add_f32 v[140:141], v[6:7], v[102:103]
	v_pk_add_f32 v[6:7], v[6:7], v[102:103] neg_lo:[0,1] neg_hi:[0,1]
	s_mov_b32 s8, s19
	v_pk_mul_f32 v[102:103], v[6:7], s[20:21]
	s_mov_b32 s77, s6
	v_pk_fma_f32 v[6:7], v[6:7], s[86:87], v[102:103] op_sel:[0,0,1] op_sel_hi:[1,0,0]
	v_pk_add_f32 v[102:103], v[8:9], v[110:111]
	v_pk_add_f32 v[8:9], v[8:9], v[110:111] neg_lo:[0,1] neg_hi:[0,1]
	s_mov_b32 s28, s17
	v_pk_mul_f32 v[110:111], v[8:9], s[10:11]
	s_nop 0
	v_pk_fma_f32 v[8:9], v[8:9], s[14:15], v[110:111] op_sel:[0,0,1] op_sel_hi:[1,0,0]
	v_pk_add_f32 v[110:111], v[10:11], v[118:119]
	v_pk_add_f32 v[10:11], v[10:11], v[118:119] neg_lo:[0,1] neg_hi:[0,1]
	v_pk_mul_f32 v[118:119], v[10:11], s[12:13]
	v_pk_fma_f32 v[10:11], v[10:11], s[4:5], v[118:119] op_sel:[0,0,1] op_sel_hi:[1,0,0]
	v_pk_add_f32 v[118:119], v[12:13], v[120:121]
	v_pk_add_f32 v[12:13], v[12:13], v[120:121] neg_lo:[0,1] neg_hi:[0,1]
	v_pk_mul_f32 v[120:121], v[12:13], s[34:35]
	v_pk_fma_f32 v[12:13], v[12:13], s[8:9], v[120:121] op_sel:[0,0,1] op_sel_hi:[1,0,0]
	v_pk_add_f32 v[120:121], v[14:15], v[122:123]
	v_pk_add_f32 v[14:15], v[14:15], v[122:123] neg_lo:[0,1] neg_hi:[0,1]
	v_pk_mul_f32 v[122:123], v[14:15], s[76:77]
	v_pk_fma_f32 v[14:15], v[14:15], s[28:29], v[122:123] op_sel:[0,0,1] op_sel_hi:[1,0,0]
	v_pk_add_f32 v[122:123], v[16:17], v[124:125]
	v_pk_add_f32 v[16:17], v[16:17], v[124:125] neg_lo:[0,1] neg_hi:[0,1]
	v_pk_add_f32 v[124:125], v[18:19], v[126:127]
	v_pk_add_f32 v[18:19], v[18:19], v[126:127] neg_lo:[0,1] neg_hi:[0,1]
	v_pk_mul_f32 v[126:127], v[18:19], s[76:77]
	v_pk_fma_f32 v[18:19], v[18:19], s[28:29], v[126:127] op_sel:[0,0,1] op_sel_hi:[1,0,0] neg_lo:[1,0,0] neg_hi:[1,0,0]
	v_pk_add_f32 v[126:127], v[20:21], v[128:129]
	v_pk_add_f32 v[20:21], v[20:21], v[128:129] neg_lo:[0,1] neg_hi:[0,1]
	v_pk_mul_f32 v[128:129], v[20:21], s[34:35]
	v_pk_fma_f32 v[20:21], v[20:21], s[8:9], v[128:129] op_sel:[0,0,1] op_sel_hi:[1,0,0] neg_lo:[1,0,0] neg_hi:[1,0,0]
	v_pk_add_f32 v[128:129], v[22:23], v[130:131]
	v_pk_add_f32 v[22:23], v[22:23], v[130:131] neg_lo:[0,1] neg_hi:[0,1]
	v_pk_mul_f32 v[130:131], v[22:23], s[12:13]
	v_pk_fma_f32 v[22:23], v[22:23], s[4:5], v[130:131] op_sel:[0,0,1] op_sel_hi:[1,0,0] neg_lo:[1,0,0] neg_hi:[1,0,0]
	v_pk_add_f32 v[130:131], v[24:25], v[132:133]
	v_pk_add_f32 v[24:25], v[24:25], v[132:133] neg_lo:[0,1] neg_hi:[0,1]
	v_pk_mul_f32 v[132:133], v[24:25], s[10:11]
	v_pk_fma_f32 v[24:25], v[24:25], s[14:15], v[132:133] op_sel:[0,0,1] op_sel_hi:[1,0,0] neg_lo:[1,0,0] neg_hi:[1,0,0]
	v_pk_add_f32 v[132:133], v[26:27], v[134:135]
	v_pk_add_f32 v[26:27], v[26:27], v[134:135] neg_lo:[0,1] neg_hi:[0,1]
	v_pk_mul_f32 v[134:135], v[26:27], s[20:21]
	v_pk_fma_f32 v[26:27], v[26:27], s[86:87], v[134:135] op_sel:[0,0,1] op_sel_hi:[1,0,0] neg_lo:[1,0,0] neg_hi:[1,0,0]
	v_pk_add_f32 v[134:135], v[28:29], v[136:137]
	v_pk_add_f32 v[28:29], v[28:29], v[136:137] neg_lo:[0,1] neg_hi:[0,1]
	v_pk_mul_f32 v[136:137], v[28:29], s[18:19]
	v_pk_fma_f32 v[28:29], v[28:29], s[30:31], v[136:137] op_sel:[0,0,1] op_sel_hi:[1,0,0] neg_lo:[1,0,0] neg_hi:[1,0,0]
	s_waitcnt lgkmcnt(0)
	v_pk_add_f32 v[136:137], v[30:31], v[142:143]
	v_pk_add_f32 v[30:31], v[30:31], v[142:143] neg_lo:[0,1] neg_hi:[0,1]
	s_nop 0
	v_pk_mul_f32 v[142:143], v[30:31], s[16:17]
	v_pk_fma_f32 v[30:31], v[30:31], s[6:7], v[142:143] op_sel:[0,0,1] op_sel_hi:[1,0,0] neg_lo:[1,0,0] neg_hi:[1,0,0]
	v_pk_add_f32 v[142:143], v[144:145], v[122:123]
	v_pk_add_f32 v[122:123], v[144:145], v[122:123] neg_lo:[0,1] neg_hi:[0,1]
	v_pk_add_f32 v[144:145], v[80:81], v[124:125]
	v_pk_add_f32 v[80:81], v[80:81], v[124:125] neg_lo:[0,1] neg_hi:[0,1]
	v_pk_mul_f32 v[124:125], v[80:81], s[18:19]
	v_pk_fma_f32 v[80:81], v[80:81], s[30:31], v[124:125] op_sel:[0,0,1] op_sel_hi:[1,0,0]
	v_pk_add_f32 v[124:125], v[138:139], v[126:127]
	v_pk_add_f32 v[126:127], v[138:139], v[126:127] neg_lo:[0,1] neg_hi:[0,1]
	v_pk_mul_f32 v[138:139], v[126:127], s[10:11]
	v_pk_fma_f32 v[126:127], v[126:127], s[14:15], v[138:139] op_sel:[0,0,1] op_sel_hi:[1,0,0]
	v_pk_add_f32 v[138:139], v[140:141], v[128:129]
	v_pk_add_f32 v[128:129], v[140:141], v[128:129] neg_lo:[0,1] neg_hi:[0,1]
	v_pk_mul_f32 v[140:141], v[128:129], s[34:35]
	v_pk_fma_f32 v[128:129], v[128:129], s[8:9], v[140:141] op_sel:[0,0,1] op_sel_hi:[1,0,0]
	v_pk_add_f32 v[140:141], v[102:103], v[130:131]
	v_pk_add_f32 v[102:103], v[102:103], v[130:131] neg_lo:[0,1] neg_hi:[0,1]
	v_pk_add_f32 v[130:131], v[110:111], v[132:133]
	v_pk_add_f32 v[110:111], v[110:111], v[132:133] neg_lo:[0,1] neg_hi:[0,1]
	v_pk_mul_f32 v[132:133], v[110:111], s[34:35]
	v_pk_fma_f32 v[110:111], v[110:111], s[8:9], v[132:133] op_sel:[0,0,1] op_sel_hi:[1,0,0] neg_lo:[1,0,0] neg_hi:[1,0,0]
	v_pk_add_f32 v[132:133], v[118:119], v[134:135]
	v_pk_add_f32 v[118:119], v[118:119], v[134:135] neg_lo:[0,1] neg_hi:[0,1]
	v_pk_mul_f32 v[134:135], v[118:119], s[10:11]
	v_pk_fma_f32 v[118:119], v[118:119], s[14:15], v[134:135] op_sel:[0,0,1] op_sel_hi:[1,0,0] neg_lo:[1,0,0] neg_hi:[1,0,0]
	v_pk_add_f32 v[134:135], v[120:121], v[136:137]
	v_pk_add_f32 v[120:121], v[120:121], v[136:137] neg_lo:[0,1] neg_hi:[0,1]
	v_pk_mul_f32 v[136:137], v[120:121], s[18:19]
	v_pk_fma_f32 v[120:121], v[120:121], s[30:31], v[136:137] op_sel:[0,0,1] op_sel_hi:[1,0,0] neg_lo:[1,0,0] neg_hi:[1,0,0]
	v_pk_add_f32 v[136:137], v[0:1], v[16:17] op_sel:[0,1] op_sel_hi:[1,0] neg_hi:[0,1]
	v_pk_add_f32 v[0:1], v[0:1], v[16:17] op_sel:[0,1] op_sel_hi:[1,0] neg_lo:[0,1]
	v_pk_add_f32 v[16:17], v[2:3], v[18:19]
	v_pk_add_f32 v[2:3], v[2:3], v[18:19] neg_lo:[0,1] neg_hi:[0,1]
	v_pk_mul_f32 v[18:19], v[2:3], s[18:19]
	v_pk_fma_f32 v[2:3], v[2:3], s[30:31], v[18:19] op_sel:[0,0,1] op_sel_hi:[1,0,0]
	v_pk_add_f32 v[18:19], v[4:5], v[20:21]
	v_pk_add_f32 v[4:5], v[4:5], v[20:21] neg_lo:[0,1] neg_hi:[0,1]
	v_pk_mul_f32 v[20:21], v[4:5], s[10:11]
	v_pk_fma_f32 v[4:5], v[4:5], s[14:15], v[20:21] op_sel:[0,0,1] op_sel_hi:[1,0,0]
	v_pk_add_f32 v[20:21], v[6:7], v[22:23]
	v_pk_add_f32 v[6:7], v[6:7], v[22:23] neg_lo:[0,1] neg_hi:[0,1]
	v_pk_mul_f32 v[22:23], v[6:7], s[34:35]
	v_pk_fma_f32 v[6:7], v[6:7], s[8:9], v[22:23] op_sel:[0,0,1] op_sel_hi:[1,0,0]
	v_pk_add_f32 v[22:23], v[8:9], v[24:25]
	v_pk_add_f32 v[8:9], v[8:9], v[24:25] neg_lo:[0,1] neg_hi:[0,1]
	v_pk_add_f32 v[24:25], v[10:11], v[26:27]
	v_pk_add_f32 v[10:11], v[10:11], v[26:27] neg_lo:[0,1] neg_hi:[0,1]
	v_pk_mul_f32 v[26:27], v[10:11], s[34:35]
	v_pk_fma_f32 v[10:11], v[10:11], s[8:9], v[26:27] op_sel:[0,0,1] op_sel_hi:[1,0,0] neg_lo:[1,0,0] neg_hi:[1,0,0]
	v_pk_add_f32 v[26:27], v[12:13], v[28:29]
	v_pk_add_f32 v[12:13], v[12:13], v[28:29] neg_lo:[0,1] neg_hi:[0,1]
	v_pk_mul_f32 v[28:29], v[12:13], s[10:11]
	v_pk_fma_f32 v[12:13], v[12:13], s[14:15], v[28:29] op_sel:[0,0,1] op_sel_hi:[1,0,0] neg_lo:[1,0,0] neg_hi:[1,0,0]
	v_pk_add_f32 v[28:29], v[14:15], v[30:31]
	v_pk_add_f32 v[14:15], v[14:15], v[30:31] neg_lo:[0,1] neg_hi:[0,1]
	v_pk_mul_f32 v[30:31], v[14:15], s[18:19]
	v_pk_fma_f32 v[14:15], v[14:15], s[30:31], v[30:31] op_sel:[0,0,1] op_sel_hi:[1,0,0] neg_lo:[1,0,0] neg_hi:[1,0,0]
	v_pk_add_f32 v[30:31], v[142:143], v[140:141]
	v_pk_add_f32 v[140:141], v[142:143], v[140:141] neg_lo:[0,1] neg_hi:[0,1]
	v_pk_add_f32 v[142:143], v[144:145], v[130:131]
	v_pk_add_f32 v[130:131], v[144:145], v[130:131] neg_lo:[0,1] neg_hi:[0,1]
	v_pk_mul_f32 v[144:145], v[130:131], s[10:11]
	v_pk_fma_f32 v[130:131], v[130:131], s[14:15], v[144:145] op_sel:[0,0,1] op_sel_hi:[1,0,0]
	v_pk_add_f32 v[144:145], v[124:125], v[132:133]
	v_pk_add_f32 v[124:125], v[124:125], v[132:133] neg_lo:[0,1] neg_hi:[0,1]
	v_pk_add_f32 v[132:133], v[138:139], v[134:135]
	v_pk_add_f32 v[134:135], v[138:139], v[134:135] neg_lo:[0,1] neg_hi:[0,1]
	v_pk_mul_f32 v[138:139], v[134:135], s[10:11]
	v_pk_fma_f32 v[134:135], v[134:135], s[14:15], v[138:139] op_sel:[0,0,1] op_sel_hi:[1,0,0] neg_lo:[1,0,0] neg_hi:[1,0,0]
	v_pk_add_f32 v[138:139], v[122:123], v[102:103] op_sel:[0,1] op_sel_hi:[1,0] neg_hi:[0,1]
	v_pk_add_f32 v[102:103], v[122:123], v[102:103] op_sel:[0,1] op_sel_hi:[1,0] neg_lo:[0,1]
	v_pk_add_f32 v[122:123], v[80:81], v[110:111]
	v_pk_add_f32 v[80:81], v[80:81], v[110:111] neg_lo:[0,1] neg_hi:[0,1]
	v_pk_add_f32 v[154:155], v[130:131], v[134:135]
	v_pk_mul_f32 v[110:111], v[80:81], s[10:11]
	v_pk_fma_f32 v[80:81], v[80:81], s[14:15], v[110:111] op_sel:[0,0,1] op_sel_hi:[1,0,0]
	v_pk_add_f32 v[110:111], v[126:127], v[118:119]
	v_pk_add_f32 v[118:119], v[126:127], v[118:119] neg_lo:[0,1] neg_hi:[0,1]
	v_pk_add_f32 v[126:127], v[128:129], v[120:121]
	v_pk_add_f32 v[120:121], v[128:129], v[120:121] neg_lo:[0,1] neg_hi:[0,1]
	v_pk_mul_f32 v[128:129], v[120:121], s[10:11]
	v_pk_add_f32 v[160:161], v[102:103], v[118:119] op_sel:[0,1] op_sel_hi:[1,0] neg_hi:[0,1]
	v_pk_fma_f32 v[120:121], v[120:121], s[14:15], v[128:129] op_sel:[0,0,1] op_sel_hi:[1,0,0] neg_lo:[1,0,0] neg_hi:[1,0,0]
	v_pk_add_f32 v[128:129], v[136:137], v[22:23]
	v_pk_add_f32 v[22:23], v[136:137], v[22:23] neg_lo:[0,1] neg_hi:[0,1]
	v_pk_add_f32 v[136:137], v[16:17], v[24:25]
	v_pk_add_f32 v[16:17], v[16:17], v[24:25] neg_lo:[0,1] neg_hi:[0,1]
	v_pk_add_f32 v[162:163], v[102:103], v[118:119] op_sel:[0,1] op_sel_hi:[1,0] neg_lo:[0,1]
	v_pk_mul_f32 v[24:25], v[16:17], s[10:11]
	v_pk_add_f32 v[102:103], v[80:81], v[120:121]
	v_pk_fma_f32 v[16:17], v[16:17], s[14:15], v[24:25] op_sel:[0,0,1] op_sel_hi:[1,0,0]
	v_pk_add_f32 v[24:25], v[18:19], v[26:27]
	v_pk_add_f32 v[18:19], v[18:19], v[26:27] neg_lo:[0,1] neg_hi:[0,1]
	v_pk_add_f32 v[26:27], v[20:21], v[28:29]
	v_pk_add_f32 v[20:21], v[20:21], v[28:29] neg_lo:[0,1] neg_hi:[0,1]
	v_pk_mul_f32 v[28:29], v[20:21], s[10:11]
	v_pk_add_f32 v[80:81], v[80:81], v[120:121] neg_lo:[0,1] neg_hi:[0,1]
	v_pk_fma_f32 v[20:21], v[20:21], s[14:15], v[28:29] op_sel:[0,0,1] op_sel_hi:[1,0,0] neg_lo:[1,0,0] neg_hi:[1,0,0]
	v_pk_add_f32 v[28:29], v[0:1], v[8:9] op_sel:[0,1] op_sel_hi:[1,0] neg_hi:[0,1]
	v_pk_add_f32 v[0:1], v[0:1], v[8:9] op_sel:[0,1] op_sel_hi:[1,0] neg_lo:[0,1]
	v_pk_add_f32 v[8:9], v[2:3], v[10:11]
	v_pk_add_f32 v[2:3], v[2:3], v[10:11] neg_lo:[0,1] neg_hi:[0,1]
	v_pk_add_f32 v[164:165], v[128:129], v[24:25]
	v_pk_mul_f32 v[10:11], v[2:3], s[10:11]
	v_pk_add_f32 v[128:129], v[128:129], v[24:25] neg_lo:[0,1] neg_hi:[0,1]
	v_pk_fma_f32 v[2:3], v[2:3], s[14:15], v[10:11] op_sel:[0,0,1] op_sel_hi:[1,0,0]
	v_pk_add_f32 v[10:11], v[4:5], v[12:13]
	v_pk_add_f32 v[4:5], v[4:5], v[12:13] neg_lo:[0,1] neg_hi:[0,1]
	v_pk_add_f32 v[12:13], v[6:7], v[14:15]
	v_pk_add_f32 v[6:7], v[6:7], v[14:15] neg_lo:[0,1] neg_hi:[0,1]
	v_pk_mul_f32 v[14:15], v[6:7], s[10:11]
	v_pk_add_f32 v[24:25], v[136:137], v[26:27] neg_lo:[0,1] neg_hi:[0,1]
	v_pk_fma_f32 v[6:7], v[6:7], s[14:15], v[14:15] op_sel:[0,0,1] op_sel_hi:[1,0,0] neg_lo:[1,0,0] neg_hi:[1,0,0]
	v_pk_add_f32 v[14:15], v[30:31], v[144:145]
	v_pk_add_f32 v[30:31], v[30:31], v[144:145] neg_lo:[0,1] neg_hi:[0,1]
	v_pk_add_f32 v[144:145], v[142:143], v[132:133]
	v_pk_add_f32 v[132:133], v[142:143], v[132:133] neg_lo:[0,1] neg_hi:[0,1]
	v_pk_add_f32 v[142:143], v[140:141], v[124:125] op_sel:[0,1] op_sel_hi:[1,0] neg_hi:[0,1]
	v_pk_add_f32 v[140:141], v[140:141], v[124:125] op_sel:[0,1] op_sel_hi:[1,0] neg_lo:[0,1]
	v_pk_add_f32 v[124:125], v[130:131], v[134:135] neg_lo:[0,1] neg_hi:[0,1]
	v_pk_add_f32 v[134:135], v[138:139], v[110:111]
	v_pk_add_f32 v[110:111], v[138:139], v[110:111] neg_lo:[0,1] neg_hi:[0,1]
	v_pk_add_f32 v[138:139], v[122:123], v[126:127]
	v_pk_add_f32 v[122:123], v[122:123], v[126:127] neg_lo:[0,1] neg_hi:[0,1]
	v_pk_add_f32 v[168:169], v[22:23], v[18:19] op_sel:[0,1] op_sel_hi:[1,0] neg_hi:[0,1]
	v_pk_add_f32 v[170:171], v[22:23], v[18:19] op_sel:[0,1] op_sel_hi:[1,0] neg_lo:[0,1]
	v_pk_add_f32 v[18:19], v[16:17], v[20:21]
	v_pk_add_f32 v[16:17], v[16:17], v[20:21] neg_lo:[0,1] neg_hi:[0,1]
	v_pk_add_f32 v[184:185], v[28:29], v[10:11]
	v_pk_add_f32 v[186:187], v[28:29], v[10:11] neg_lo:[0,1] neg_hi:[0,1]
	v_pk_add_f32 v[10:11], v[8:9], v[12:13]
	v_pk_add_f32 v[8:9], v[8:9], v[12:13] neg_lo:[0,1] neg_hi:[0,1]
	v_pk_add_f32 v[190:191], v[0:1], v[4:5] op_sel:[0,1] op_sel_hi:[1,0] neg_hi:[0,1]
	v_pk_add_f32 v[192:193], v[0:1], v[4:5] op_sel:[0,1] op_sel_hi:[1,0] neg_lo:[0,1]
	v_pk_add_f32 v[0:1], v[2:3], v[6:7] neg_lo:[0,1] neg_hi:[0,1]
	v_pk_mul_f32 v[130:131], v[124:125], s[22:23]
	v_pk_mul_f32 v[158:159], v[122:123], s[22:23]
	v_pk_add_f32 v[166:167], v[136:137], v[26:27]
	v_pk_mul_f32 v[136:137], v[24:25], s[22:23]
	v_pk_mul_f32 v[182:183], v[16:17], s[22:23]
	v_pk_mul_f32 v[188:189], v[8:9], s[22:23]
	v_pk_add_f32 v[194:195], v[2:3], v[6:7]
	v_pk_mul_f32 v[196:197], v[0:1], s[22:23]
	v_pk_add_f32 v[28:29], v[14:15], v[144:145]
	v_pk_add_f32 v[126:127], v[14:15], v[144:145] neg_lo:[0,1] neg_hi:[0,1]
	v_pk_add_f32 v[24:25], v[30:31], v[132:133] op_sel:[0,1] op_sel_hi:[1,0] neg_hi:[0,1]
	v_pk_add_f32 v[124:125], v[30:31], v[132:133] op_sel:[0,1] op_sel_hi:[1,0] neg_lo:[0,1]
	v_pk_add_f32 v[20:21], v[142:143], v[154:155]
	v_pk_add_f32 v[122:123], v[142:143], v[154:155] neg_lo:[0,1] neg_hi:[0,1]
	v_pk_add_f32 v[16:17], v[140:141], v[130:131] op_sel:[0,1] op_sel_hi:[1,0]
	v_pk_add_f32 v[120:121], v[140:141], v[130:131] op_sel:[0,1] op_sel_hi:[1,0] neg_lo:[0,1] neg_hi:[0,1]
	v_pk_add_f32 v[12:13], v[134:135], v[138:139]
	v_pk_add_f32 v[118:119], v[134:135], v[138:139] neg_lo:[0,1] neg_hi:[0,1]
	v_pk_add_f32 v[8:9], v[110:111], v[158:159] op_sel:[0,1] op_sel_hi:[1,0]
	v_pk_add_f32 v[110:111], v[110:111], v[158:159] op_sel:[0,1] op_sel_hi:[1,0] neg_lo:[0,1] neg_hi:[0,1]
	v_pk_add_f32 v[4:5], v[160:161], v[102:103]
	v_pk_add_f32 v[102:103], v[160:161], v[102:103] neg_lo:[0,1] neg_hi:[0,1]
	v_pk_add_f32 v[0:1], v[162:163], v[80:81] op_sel:[0,1] op_sel_hi:[1,0] neg_hi:[0,1]
	v_pk_add_f32 v[80:81], v[162:163], v[80:81] op_sel:[0,1] op_sel_hi:[1,0] neg_lo:[0,1]
	v_pk_add_f32 v[30:31], v[164:165], v[166:167]
	v_pk_add_f32 v[142:143], v[164:165], v[166:167] neg_lo:[0,1] neg_hi:[0,1]
	v_pk_add_f32 v[26:27], v[128:129], v[136:137] op_sel:[0,1] op_sel_hi:[1,0]
	v_pk_add_f32 v[140:141], v[128:129], v[136:137] op_sel:[0,1] op_sel_hi:[1,0] neg_lo:[0,1] neg_hi:[0,1]
	v_pk_add_f32 v[22:23], v[168:169], v[18:19]
	v_pk_add_f32 v[138:139], v[168:169], v[18:19] neg_lo:[0,1] neg_hi:[0,1]
	v_pk_add_f32 v[18:19], v[170:171], v[182:183] op_sel:[0,1] op_sel_hi:[1,0]
	v_pk_add_f32 v[136:137], v[170:171], v[182:183] op_sel:[0,1] op_sel_hi:[1,0] neg_lo:[0,1] neg_hi:[0,1]
	v_pk_add_f32 v[14:15], v[184:185], v[10:11]
	v_pk_add_f32 v[134:135], v[184:185], v[10:11] neg_lo:[0,1] neg_hi:[0,1]
	v_pk_add_f32 v[10:11], v[186:187], v[188:189] op_sel:[0,1] op_sel_hi:[1,0]
	v_pk_add_f32 v[132:133], v[186:187], v[188:189] op_sel:[0,1] op_sel_hi:[1,0] neg_lo:[0,1] neg_hi:[0,1]
	v_pk_add_f32 v[6:7], v[190:191], v[194:195]
	v_pk_add_f32 v[130:131], v[190:191], v[194:195] neg_lo:[0,1] neg_hi:[0,1]
	v_pk_add_f32 v[2:3], v[192:193], v[196:197] op_sel:[0,1] op_sel_hi:[1,0]
	v_pk_add_f32 v[128:129], v[192:193], v[196:197] op_sel:[0,1] op_sel_hi:[1,0] neg_lo:[0,1] neg_hi:[0,1]

.LBB0_432:
	s_or_b64 exec, exec, s[0:1]
	v_mov_b32_e32 v120, v32
	s_waitcnt lgkmcnt(0)
	s_barrier
	s_mov_b32 s11, s14
	v_and_b32_e32 v121, 31, v120
	v_cvt_f32_ubyte0_e32 v24, v121
	v_mul_f32_e32 v102, 0x3b000000, v24
	v_sin_f32_e32 v24, v102
	v_ashrrev_i32_e32 v0, 4, v120
	v_lshlrev_b32_e32 v0, 3, v0
	v_lshlrev_b32_e32 v1, 3, v120
	v_cos_f32_e32 v102, v102
	v_add3_u32 v25, 0, v0, v1
	ds_read_b64 v[0:1], v25
	ds_read_b64 v[2:3], v25 offset:4352
	ds_read_b64 v[4:5], v25 offset:8704
	ds_read_b64 v[6:7], v25 offset:13056
	ds_read_b64 v[8:9], v25 offset:17408
	ds_read_b64 v[10:11], v25 offset:21760
	ds_read_b64 v[12:13], v25 offset:26112
	ds_read_b64 v[14:15], v25 offset:30464
	ds_read_b64 v[16:17], v25 offset:34816
	ds_read_b64 v[18:19], v25 offset:39168
	ds_read_b64 v[20:21], v25 offset:43520
	ds_read_b64 v[22:23], v25 offset:47872
	v_xor_b32_e32 v103, 0x80000000, v24
	s_waitcnt lgkmcnt(10)
	v_pk_mul_f32 v[110:111], v[2:3], v[24:25] op_sel:[1,0] op_sel_hi:[0,0] neg_hi:[0,1]
	v_pk_fma_f32 v[2:3], v[2:3], v[102:103], v[110:111] op_sel_hi:[1,0,1]
	v_pk_mul_f32 v[110:111], v[24:25], v[102:103] op_sel:[0,1] op_sel_hi:[0,0] neg_hi:[1,0]
	v_pk_fma_f32 v[110:111], v[102:103], v[102:103], v[110:111] op_sel_hi:[0,1,1]
	ds_read_b64 v[26:27], v25 offset:52224
	ds_read_b64 v[28:29], v25 offset:56576
	ds_read_b64 v[30:31], v25 offset:60928
	ds_read_b64 v[80:81], v25 offset:65280
	s_waitcnt lgkmcnt(13)
	v_pk_mul_f32 v[118:119], v[4:5], v[110:111] op_sel:[1,1] op_sel_hi:[0,1] neg_lo:[0,1]
	v_pk_fma_f32 v[4:5], v[4:5], v[110:111], v[118:119] op_sel_hi:[1,0,1]
	v_pk_mul_f32 v[118:119], v[24:25], v[110:111] op_sel:[0,1] op_sel_hi:[0,0] neg_hi:[1,0]
	v_pk_fma_f32 v[110:111], v[102:103], v[110:111], v[118:119] op_sel_hi:[0,1,1]
	s_mov_b32 s35, s30
	s_waitcnt lgkmcnt(12)
	v_pk_mul_f32 v[118:119], v[6:7], v[110:111] op_sel:[1,1] op_sel_hi:[0,1] neg_lo:[0,1]
	v_pk_fma_f32 v[6:7], v[6:7], v[110:111], v[118:119] op_sel_hi:[1,0,1]
	v_pk_mul_f32 v[118:119], v[24:25], v[110:111] op_sel:[0,1] op_sel_hi:[0,0] neg_hi:[1,0]
	v_pk_fma_f32 v[110:111], v[102:103], v[110:111], v[118:119] op_sel_hi:[0,1,1]
	s_mov_b32 s0, s19
	s_waitcnt lgkmcnt(11)
	v_pk_mul_f32 v[118:119], v[8:9], v[110:111] op_sel:[1,1] op_sel_hi:[0,1] neg_lo:[0,1]
	v_pk_fma_f32 v[8:9], v[8:9], v[110:111], v[118:119] op_sel_hi:[1,0,1]
	v_pk_mul_f32 v[118:119], v[24:25], v[110:111] op_sel:[0,1] op_sel_hi:[0,0] neg_hi:[1,0]
	v_pk_fma_f32 v[110:111], v[102:103], v[110:111], v[118:119] op_sel_hi:[0,1,1]
	s_waitcnt lgkmcnt(0)
	v_pk_mul_f32 v[118:119], v[10:11], v[110:111] op_sel:[1,1] op_sel_hi:[0,1] neg_lo:[0,1]
	v_pk_fma_f32 v[10:11], v[10:11], v[110:111], v[118:119] op_sel_hi:[1,0,1]
	v_pk_mul_f32 v[118:119], v[24:25], v[110:111] op_sel:[0,1] op_sel_hi:[0,0] neg_hi:[1,0]
	v_pk_fma_f32 v[110:111], v[102:103], v[110:111], v[118:119] op_sel_hi:[0,1,1]
	s_barrier
	v_pk_mul_f32 v[118:119], v[12:13], v[110:111] op_sel:[1,1] op_sel_hi:[0,1] neg_lo:[0,1]
	v_pk_fma_f32 v[12:13], v[12:13], v[110:111], v[118:119] op_sel_hi:[1,0,1]
	v_pk_mul_f32 v[118:119], v[24:25], v[110:111] op_sel:[0,1] op_sel_hi:[0,0] neg_hi:[1,0]
	v_pk_fma_f32 v[110:111], v[102:103], v[110:111], v[118:119] op_sel_hi:[0,1,1]
	v_pk_mul_f32 v[118:119], v[14:15], v[110:111] op_sel:[1,1] op_sel_hi:[0,1] neg_lo:[0,1]
	v_pk_fma_f32 v[14:15], v[14:15], v[110:111], v[118:119] op_sel_hi:[1,0,1]
	v_pk_mul_f32 v[118:119], v[24:25], v[110:111] op_sel:[0,1] op_sel_hi:[0,0] neg_hi:[1,0]
	v_pk_fma_f32 v[110:111], v[102:103], v[110:111], v[118:119] op_sel_hi:[0,1,1]
	v_lshlrev_b32_e32 v155, 3, v47
	v_pk_mul_f32 v[118:119], v[16:17], v[110:111] op_sel:[1,1] op_sel_hi:[0,1] neg_lo:[0,1]
	v_pk_fma_f32 v[16:17], v[16:17], v[110:111], v[118:119] op_sel_hi:[1,0,1]
	v_pk_mul_f32 v[118:119], v[24:25], v[110:111] op_sel:[0,1] op_sel_hi:[0,0] neg_hi:[1,0]
	v_pk_fma_f32 v[110:111], v[102:103], v[110:111], v[118:119] op_sel_hi:[0,1,1]
	v_pk_mul_f32 v[118:119], v[18:19], v[110:111] op_sel:[1,1] op_sel_hi:[0,1] neg_lo:[0,1]
	v_pk_fma_f32 v[18:19], v[18:19], v[110:111], v[118:119] op_sel_hi:[1,0,1]
	v_pk_mul_f32 v[118:119], v[24:25], v[110:111] op_sel:[0,1] op_sel_hi:[0,0] neg_hi:[1,0]
	v_pk_fma_f32 v[110:111], v[102:103], v[110:111], v[118:119] op_sel_hi:[0,1,1]
	v_pk_mul_f32 v[118:119], v[20:21], v[110:111] op_sel:[1,1] op_sel_hi:[0,1] neg_lo:[0,1]
	v_pk_fma_f32 v[20:21], v[20:21], v[110:111], v[118:119] op_sel_hi:[1,0,1]
	v_pk_mul_f32 v[118:119], v[24:25], v[110:111] op_sel:[0,1] op_sel_hi:[0,0] neg_hi:[1,0]
	v_pk_fma_f32 v[110:111], v[102:103], v[110:111], v[118:119] op_sel_hi:[0,1,1]
	v_pk_mul_f32 v[118:119], v[22:23], v[110:111] op_sel:[1,1] op_sel_hi:[0,1] neg_lo:[0,1]
	v_pk_fma_f32 v[22:23], v[22:23], v[110:111], v[118:119] op_sel_hi:[1,0,1]
	v_pk_mul_f32 v[118:119], v[24:25], v[110:111] op_sel:[0,1] op_sel_hi:[0,0] neg_hi:[1,0]
	v_pk_fma_f32 v[110:111], v[102:103], v[110:111], v[118:119] op_sel_hi:[0,1,1]
	v_pk_mul_f32 v[118:119], v[26:27], v[110:111] op_sel:[1,1] op_sel_hi:[0,1] neg_lo:[0,1]
	v_pk_fma_f32 v[26:27], v[26:27], v[110:111], v[118:119] op_sel_hi:[1,0,1]
	v_pk_mul_f32 v[118:119], v[24:25], v[110:111] op_sel:[0,1] op_sel_hi:[0,0] neg_hi:[1,0]
	v_pk_fma_f32 v[110:111], v[102:103], v[110:111], v[118:119] op_sel_hi:[0,1,1]
	v_pk_mul_f32 v[118:119], v[28:29], v[110:111] op_sel:[1,1] op_sel_hi:[0,1] neg_lo:[0,1]
	v_pk_fma_f32 v[28:29], v[28:29], v[110:111], v[118:119] op_sel_hi:[1,0,1]
	v_pk_mul_f32 v[118:119], v[24:25], v[110:111] op_sel:[0,1] op_sel_hi:[0,0] neg_hi:[1,0]
	v_pk_fma_f32 v[110:111], v[102:103], v[110:111], v[118:119] op_sel_hi:[0,1,1]
	v_pk_mul_f32 v[24:25], v[24:25], v[110:111] op_sel:[0,1] op_sel_hi:[0,0] neg_hi:[1,0]
	v_pk_fma_f32 v[24:25], v[102:103], v[110:111], v[24:25] op_sel_hi:[0,1,1]
	v_pk_mul_f32 v[102:103], v[80:81], v[24:25] op_sel:[1,1] op_sel_hi:[0,1] neg_lo:[0,1]
	v_pk_fma_f32 v[24:25], v[80:81], v[24:25], v[102:103] op_sel_hi:[1,0,1]
	v_pk_add_f32 v[80:81], v[0:1], v[16:17]
	v_pk_add_f32 v[0:1], v[0:1], v[16:17] neg_lo:[0,1] neg_hi:[0,1]
	v_pk_add_f32 v[16:17], v[2:3], v[18:19]
	v_pk_add_f32 v[2:3], v[2:3], v[18:19] neg_lo:[0,1] neg_hi:[0,1]
	v_pk_mul_f32 v[118:119], v[30:31], v[110:111] op_sel:[1,1] op_sel_hi:[0,1] neg_lo:[0,1]
	v_pk_mul_f32 v[18:19], v[2:3], s[18:19]
	v_pk_fma_f32 v[30:31], v[30:31], v[110:111], v[118:119] op_sel_hi:[1,0,1]
	v_pk_fma_f32 v[2:3], v[2:3], s[30:31], v[18:19] op_sel:[0,0,1] op_sel_hi:[1,0,0]
	v_pk_add_f32 v[18:19], v[4:5], v[20:21]
	v_pk_add_f32 v[4:5], v[4:5], v[20:21] neg_lo:[0,1] neg_hi:[0,1]
	v_pk_mul_f32 v[20:21], v[4:5], s[10:11]
	v_pk_fma_f32 v[4:5], v[4:5], s[14:15], v[20:21] op_sel:[0,0,1] op_sel_hi:[1,0,0]
	v_pk_add_f32 v[20:21], v[6:7], v[22:23]
	v_pk_add_f32 v[6:7], v[6:7], v[22:23] neg_lo:[0,1] neg_hi:[0,1]
	v_pk_mul_f32 v[22:23], v[6:7], s[34:35]
	v_pk_fma_f32 v[6:7], v[6:7], s[0:1], v[22:23] op_sel:[0,0,1] op_sel_hi:[1,0,0]
	v_pk_add_f32 v[22:23], v[8:9], v[26:27]
	v_pk_add_f32 v[8:9], v[8:9], v[26:27] neg_lo:[0,1] neg_hi:[0,1]
	v_pk_add_f32 v[26:27], v[10:11], v[28:29]
	v_pk_add_f32 v[10:11], v[10:11], v[28:29] neg_lo:[0,1] neg_hi:[0,1]
	v_pk_mul_f32 v[28:29], v[10:11], s[34:35]
	v_pk_fma_f32 v[10:11], v[10:11], s[0:1], v[28:29] op_sel:[0,0,1] op_sel_hi:[1,0,0] neg_lo:[1,0,0] neg_hi:[1,0,0]
	v_pk_add_f32 v[28:29], v[12:13], v[30:31]
	v_pk_add_f32 v[12:13], v[12:13], v[30:31] neg_lo:[0,1] neg_hi:[0,1]
	v_pk_mul_f32 v[30:31], v[12:13], s[10:11]
	v_pk_fma_f32 v[12:13], v[12:13], s[14:15], v[30:31] op_sel:[0,0,1] op_sel_hi:[1,0,0] neg_lo:[1,0,0] neg_hi:[1,0,0]
	v_pk_add_f32 v[30:31], v[14:15], v[24:25]
	v_pk_add_f32 v[14:15], v[14:15], v[24:25] neg_lo:[0,1] neg_hi:[0,1]
	v_pk_mul_f32 v[24:25], v[14:15], s[18:19]
	v_pk_fma_f32 v[14:15], v[14:15], s[30:31], v[24:25] op_sel:[0,0,1] op_sel_hi:[1,0,0] neg_lo:[1,0,0] neg_hi:[1,0,0]
	v_pk_add_f32 v[24:25], v[80:81], v[22:23]
	v_pk_add_f32 v[22:23], v[80:81], v[22:23] neg_lo:[0,1] neg_hi:[0,1]
	v_pk_add_f32 v[80:81], v[16:17], v[26:27]
	v_pk_add_f32 v[16:17], v[16:17], v[26:27] neg_lo:[0,1] neg_hi:[0,1]
	v_pk_mul_f32 v[26:27], v[16:17], s[10:11]
	v_pk_fma_f32 v[16:17], v[16:17], s[14:15], v[26:27] op_sel:[0,0,1] op_sel_hi:[1,0,0]
	v_pk_add_f32 v[26:27], v[18:19], v[28:29]
	v_pk_add_f32 v[18:19], v[18:19], v[28:29] neg_lo:[0,1] neg_hi:[0,1]
	v_pk_add_f32 v[28:29], v[20:21], v[30:31]
	v_pk_add_f32 v[20:21], v[20:21], v[30:31] neg_lo:[0,1] neg_hi:[0,1]
	v_pk_mul_f32 v[30:31], v[20:21], s[10:11]
	v_pk_fma_f32 v[20:21], v[20:21], s[14:15], v[30:31] op_sel:[0,0,1] op_sel_hi:[1,0,0] neg_lo:[1,0,0] neg_hi:[1,0,0]
	v_pk_add_f32 v[30:31], v[0:1], v[8:9] op_sel:[0,1] op_sel_hi:[1,0] neg_hi:[0,1]
	v_pk_add_f32 v[0:1], v[0:1], v[8:9] op_sel:[0,1] op_sel_hi:[1,0] neg_lo:[0,1]
	v_pk_add_f32 v[8:9], v[2:3], v[10:11]
	v_pk_add_f32 v[2:3], v[2:3], v[10:11] neg_lo:[0,1] neg_hi:[0,1]
	v_pk_mul_f32 v[10:11], v[2:3], s[10:11]
	v_pk_fma_f32 v[2:3], v[2:3], s[14:15], v[10:11] op_sel:[0,0,1] op_sel_hi:[1,0,0]
	v_pk_add_f32 v[10:11], v[4:5], v[12:13]
	v_pk_add_f32 v[4:5], v[4:5], v[12:13] neg_lo:[0,1] neg_hi:[0,1]
	v_pk_add_f32 v[12:13], v[6:7], v[14:15]
	v_pk_add_f32 v[6:7], v[6:7], v[14:15] neg_lo:[0,1] neg_hi:[0,1]
	v_pk_mul_f32 v[14:15], v[6:7], s[10:11]
	v_pk_fma_f32 v[6:7], v[6:7], s[14:15], v[14:15] op_sel:[0,0,1] op_sel_hi:[1,0,0] neg_lo:[1,0,0] neg_hi:[1,0,0]
	v_pk_add_f32 v[14:15], v[24:25], v[26:27]
	v_pk_add_f32 v[24:25], v[24:25], v[26:27] neg_lo:[0,1] neg_hi:[0,1]
	v_pk_add_f32 v[26:27], v[80:81], v[28:29]
	v_pk_add_f32 v[28:29], v[80:81], v[28:29] neg_lo:[0,1] neg_hi:[0,1]
	v_pk_add_f32 v[80:81], v[22:23], v[18:19] op_sel:[0,1] op_sel_hi:[1,0] neg_hi:[0,1]
	v_pk_add_f32 v[18:19], v[22:23], v[18:19] op_sel:[0,1] op_sel_hi:[1,0] neg_lo:[0,1]
	v_pk_add_f32 v[22:23], v[16:17], v[20:21]
	v_pk_add_f32 v[16:17], v[16:17], v[20:21] neg_lo:[0,1] neg_hi:[0,1]
	v_pk_add_f32 v[20:21], v[30:31], v[10:11]
	v_pk_add_f32 v[10:11], v[30:31], v[10:11] neg_lo:[0,1] neg_hi:[0,1]
	v_pk_add_f32 v[30:31], v[8:9], v[12:13]
	v_pk_add_f32 v[8:9], v[8:9], v[12:13] neg_lo:[0,1] neg_hi:[0,1]
	v_pk_add_f32 v[12:13], v[0:1], v[4:5] op_sel:[0,1] op_sel_hi:[1,0] neg_hi:[0,1]
	v_pk_add_f32 v[0:1], v[0:1], v[4:5] op_sel:[0,1] op_sel_hi:[1,0] neg_lo:[0,1]
	v_pk_add_f32 v[4:5], v[2:3], v[6:7]
	v_pk_add_f32 v[2:3], v[2:3], v[6:7] neg_lo:[0,1] neg_hi:[0,1]
	v_pk_mul_f32 v[2:3], v[2:3], s[22:23]
	v_pk_add_f32 v[6:7], v[14:15], v[26:27]
	v_pk_add_f32 v[14:15], v[14:15], v[26:27] neg_lo:[0,1] neg_hi:[0,1]
	v_pk_add_f32 v[26:27], v[24:25], v[28:29] op_sel:[0,1] op_sel_hi:[1,0] neg_hi:[0,1]
	v_pk_add_f32 v[24:25], v[24:25], v[28:29] op_sel:[0,1] op_sel_hi:[1,0] neg_lo:[0,1]
	v_pk_add_f32 v[28:29], v[80:81], v[22:23]
	v_pk_add_f32 v[22:23], v[80:81], v[22:23] neg_lo:[0,1] neg_hi:[0,1]
	v_pk_add_f32 v[80:81], v[18:19], v[16:17] op_sel:[0,1] op_sel_hi:[1,0] neg_hi:[0,1]
	v_pk_add_f32 v[16:17], v[18:19], v[16:17] op_sel:[0,1] op_sel_hi:[1,0] neg_lo:[0,1]
	v_pk_add_f32 v[18:19], v[20:21], v[30:31]
	v_pk_add_f32 v[20:21], v[20:21], v[30:31] neg_lo:[0,1] neg_hi:[0,1]
	v_pk_add_f32 v[30:31], v[10:11], v[8:9] op_sel:[0,1] op_sel_hi:[1,0] neg_hi:[0,1]
	v_pk_add_f32 v[8:9], v[10:11], v[8:9] op_sel:[0,1] op_sel_hi:[1,0] neg_lo:[0,1]
	v_pk_add_f32 v[10:11], v[12:13], v[4:5]
	v_pk_add_f32 v[4:5], v[12:13], v[4:5] neg_lo:[0,1] neg_hi:[0,1]
	v_pk_add_f32 v[12:13], v[0:1], v[2:3] op_sel:[0,1] op_sel_hi:[1,0]
	v_pk_add_f32 v[0:1], v[0:1], v[2:3] op_sel:[0,1] op_sel_hi:[1,0] neg_lo:[0,1] neg_hi:[0,1]
	v_lshlrev_b32_e32 v2, 4, v120
	v_and_or_b32 v2, v2, s7, v121
	v_ashrrev_i32_e32 v3, 4, v2
	v_lshlrev_b32_e32 v3, 3, v3
	v_lshlrev_b32_e32 v2, 3, v2
	v_add3_u32 v2, 0, v3, v2
	v_add_u32_e32 v3, 0x800, v2
	v_mov_b32_e32 v120, v32
	ds_write2_b64 v2, v[6:7], v[18:19] offset1:34
	ds_write2_b64 v3, v[14:15], v[20:21] offset0:16 offset1:50
	ds_write2_b64 v2, v[26:27], v[30:31] offset0:136 offset1:170
	ds_write2_b64 v3, v[24:25], v[8:9] offset0:152 offset1:186
	ds_write2_b64 v2, v[28:29], v[10:11] offset0:68 offset1:102
	ds_write2_b64 v3, v[22:23], v[4:5] offset0:84 offset1:118
	ds_write2_b64 v2, v[80:81], v[12:13] offset0:204 offset1:238
	ds_write2_b64 v3, v[16:17], v[0:1] offset0:220 offset1:254
	s_waitcnt lgkmcnt(0)
	s_barrier
	s_nop 0
	v_and_b32_e32 v121, 0x1ff, v120
	v_cvt_f32_u32_e32 v24, v121
	v_ashrrev_i32_e32 v0, 4, v120
	v_lshlrev_b32_e32 v0, 3, v0
	v_lshlrev_b32_e32 v1, 3, v120
	v_mul_f32_e32 v102, 0x39000000, v24
	v_sin_f32_e32 v24, v102
	v_cos_f32_e32 v102, v102
	v_add3_u32 v25, 0, v0, v1
	ds_read_b64 v[0:1], v25
	ds_read_b64 v[2:3], v25 offset:4352
	ds_read_b64 v[4:5], v25 offset:8704
	ds_read_b64 v[6:7], v25 offset:13056
	ds_read_b64 v[8:9], v25 offset:17408
	ds_read_b64 v[10:11], v25 offset:21760
	ds_read_b64 v[12:13], v25 offset:26112
	ds_read_b64 v[14:15], v25 offset:30464
	v_xor_b32_e32 v103, 0x80000000, v24
	s_waitcnt lgkmcnt(6)
	v_pk_mul_f32 v[110:111], v[2:3], v[24:25] op_sel:[1,0] op_sel_hi:[0,0] neg_hi:[0,1]
	v_pk_fma_f32 v[2:3], v[2:3], v[102:103], v[110:111] op_sel_hi:[1,0,1]
	v_pk_mul_f32 v[110:111], v[24:25], v[102:103] op_sel:[0,1] op_sel_hi:[0,0] neg_hi:[1,0]
	v_pk_fma_f32 v[110:111], v[102:103], v[102:103], v[110:111] op_sel_hi:[0,1,1]
	ds_read_b64 v[16:17], v25 offset:34816
	ds_read_b64 v[18:19], v25 offset:39168
	ds_read_b64 v[20:21], v25 offset:43520
	ds_read_b64 v[22:23], v25 offset:47872
	s_waitcnt lgkmcnt(9)
	v_pk_mul_f32 v[118:119], v[4:5], v[110:111] op_sel:[1,1] op_sel_hi:[0,1] neg_lo:[0,1]
	v_pk_fma_f32 v[4:5], v[4:5], v[110:111], v[118:119] op_sel_hi:[1,0,1]
	v_pk_mul_f32 v[118:119], v[24:25], v[110:111] op_sel:[0,1] op_sel_hi:[0,0] neg_hi:[1,0]
	v_pk_fma_f32 v[110:111], v[102:103], v[110:111], v[118:119] op_sel_hi:[0,1,1]
	ds_read_b64 v[26:27], v25 offset:52224
	ds_read_b64 v[28:29], v25 offset:56576
	ds_read_b64 v[30:31], v25 offset:60928
	ds_read_b64 v[80:81], v25 offset:65280
	s_waitcnt lgkmcnt(12)
	v_pk_mul_f32 v[118:119], v[6:7], v[110:111] op_sel:[1,1] op_sel_hi:[0,1] neg_lo:[0,1]
	v_pk_fma_f32 v[6:7], v[6:7], v[110:111], v[118:119] op_sel_hi:[1,0,1]
	v_pk_mul_f32 v[118:119], v[24:25], v[110:111] op_sel:[0,1] op_sel_hi:[0,0] neg_hi:[1,0]
	v_pk_fma_f32 v[110:111], v[102:103], v[110:111], v[118:119] op_sel_hi:[0,1,1]
	s_waitcnt lgkmcnt(0)
	v_pk_mul_f32 v[118:119], v[8:9], v[110:111] op_sel:[1,1] op_sel_hi:[0,1] neg_lo:[0,1]
	v_pk_fma_f32 v[8:9], v[8:9], v[110:111], v[118:119] op_sel_hi:[1,0,1]
	v_pk_mul_f32 v[118:119], v[24:25], v[110:111] op_sel:[0,1] op_sel_hi:[0,0] neg_hi:[1,0]
	v_pk_fma_f32 v[110:111], v[102:103], v[110:111], v[118:119] op_sel_hi:[0,1,1]
	s_barrier
	v_pk_mul_f32 v[118:119], v[10:11], v[110:111] op_sel:[1,1] op_sel_hi:[0,1] neg_lo:[0,1]
	v_pk_fma_f32 v[10:11], v[10:11], v[110:111], v[118:119] op_sel_hi:[1,0,1]
	v_pk_mul_f32 v[118:119], v[24:25], v[110:111] op_sel:[0,1] op_sel_hi:[0,0] neg_hi:[1,0]
	v_pk_fma_f32 v[110:111], v[102:103], v[110:111], v[118:119] op_sel_hi:[0,1,1]
	v_pk_mul_f32 v[118:119], v[12:13], v[110:111] op_sel:[1,1] op_sel_hi:[0,1] neg_lo:[0,1]
	v_pk_fma_f32 v[12:13], v[12:13], v[110:111], v[118:119] op_sel_hi:[1,0,1]
	v_pk_mul_f32 v[118:119], v[24:25], v[110:111] op_sel:[0,1] op_sel_hi:[0,0] neg_hi:[1,0]
	v_pk_fma_f32 v[110:111], v[102:103], v[110:111], v[118:119] op_sel_hi:[0,1,1]
	v_pk_mul_f32 v[118:119], v[14:15], v[110:111] op_sel:[1,1] op_sel_hi:[0,1] neg_lo:[0,1]
	v_pk_fma_f32 v[14:15], v[14:15], v[110:111], v[118:119] op_sel_hi:[1,0,1]
	v_pk_mul_f32 v[118:119], v[24:25], v[110:111] op_sel:[0,1] op_sel_hi:[0,0] neg_hi:[1,0]
	v_pk_fma_f32 v[110:111], v[102:103], v[110:111], v[118:119] op_sel_hi:[0,1,1]
	v_pk_mul_f32 v[118:119], v[16:17], v[110:111] op_sel:[1,1] op_sel_hi:[0,1] neg_lo:[0,1]
	v_pk_fma_f32 v[16:17], v[16:17], v[110:111], v[118:119] op_sel_hi:[1,0,1]
	v_pk_mul_f32 v[118:119], v[24:25], v[110:111] op_sel:[0,1] op_sel_hi:[0,0] neg_hi:[1,0]
	v_pk_fma_f32 v[110:111], v[102:103], v[110:111], v[118:119] op_sel_hi:[0,1,1]
	v_pk_mul_f32 v[118:119], v[18:19], v[110:111] op_sel:[1,1] op_sel_hi:[0,1] neg_lo:[0,1]
	v_pk_fma_f32 v[18:19], v[18:19], v[110:111], v[118:119] op_sel_hi:[1,0,1]
	v_pk_mul_f32 v[118:119], v[24:25], v[110:111] op_sel:[0,1] op_sel_hi:[0,0] neg_hi:[1,0]
	v_pk_fma_f32 v[110:111], v[102:103], v[110:111], v[118:119] op_sel_hi:[0,1,1]
	v_pk_mul_f32 v[118:119], v[20:21], v[110:111] op_sel:[1,1] op_sel_hi:[0,1] neg_lo:[0,1]
	v_pk_fma_f32 v[20:21], v[20:21], v[110:111], v[118:119] op_sel_hi:[1,0,1]
	v_pk_mul_f32 v[118:119], v[24:25], v[110:111] op_sel:[0,1] op_sel_hi:[0,0] neg_hi:[1,0]
	v_pk_fma_f32 v[110:111], v[102:103], v[110:111], v[118:119] op_sel_hi:[0,1,1]
	v_pk_mul_f32 v[118:119], v[22:23], v[110:111] op_sel:[1,1] op_sel_hi:[0,1] neg_lo:[0,1]
	v_pk_fma_f32 v[22:23], v[22:23], v[110:111], v[118:119] op_sel_hi:[1,0,1]
	v_pk_mul_f32 v[118:119], v[24:25], v[110:111] op_sel:[0,1] op_sel_hi:[0,0] neg_hi:[1,0]
	v_pk_fma_f32 v[110:111], v[102:103], v[110:111], v[118:119] op_sel_hi:[0,1,1]
	v_pk_mul_f32 v[118:119], v[26:27], v[110:111] op_sel:[1,1] op_sel_hi:[0,1] neg_lo:[0,1]
	v_pk_fma_f32 v[26:27], v[26:27], v[110:111], v[118:119] op_sel_hi:[1,0,1]
	v_pk_mul_f32 v[118:119], v[24:25], v[110:111] op_sel:[0,1] op_sel_hi:[0,0] neg_hi:[1,0]
	v_pk_fma_f32 v[110:111], v[102:103], v[110:111], v[118:119] op_sel_hi:[0,1,1]
	v_pk_mul_f32 v[118:119], v[28:29], v[110:111] op_sel:[1,1] op_sel_hi:[0,1] neg_lo:[0,1]
	v_pk_fma_f32 v[28:29], v[28:29], v[110:111], v[118:119] op_sel_hi:[1,0,1]
	v_pk_mul_f32 v[118:119], v[24:25], v[110:111] op_sel:[0,1] op_sel_hi:[0,0] neg_hi:[1,0]
	v_pk_fma_f32 v[110:111], v[102:103], v[110:111], v[118:119] op_sel_hi:[0,1,1]
	v_pk_mul_f32 v[24:25], v[24:25], v[110:111] op_sel:[0,1] op_sel_hi:[0,0] neg_hi:[1,0]
	v_pk_fma_f32 v[24:25], v[102:103], v[110:111], v[24:25] op_sel_hi:[0,1,1]
	v_pk_mul_f32 v[102:103], v[80:81], v[24:25] op_sel:[1,1] op_sel_hi:[0,1] neg_lo:[0,1]
	v_pk_fma_f32 v[24:25], v[80:81], v[24:25], v[102:103] op_sel_hi:[1,0,1]
	v_pk_add_f32 v[80:81], v[0:1], v[16:17]
	v_pk_add_f32 v[0:1], v[0:1], v[16:17] neg_lo:[0,1] neg_hi:[0,1]
	v_pk_add_f32 v[16:17], v[2:3], v[18:19]
	v_pk_add_f32 v[2:3], v[2:3], v[18:19] neg_lo:[0,1] neg_hi:[0,1]
	v_pk_mul_f32 v[118:119], v[30:31], v[110:111] op_sel:[1,1] op_sel_hi:[0,1] neg_lo:[0,1]
	v_pk_mul_f32 v[18:19], v[2:3], s[18:19]
	v_pk_fma_f32 v[30:31], v[30:31], v[110:111], v[118:119] op_sel_hi:[1,0,1]
	v_pk_fma_f32 v[2:3], v[2:3], s[30:31], v[18:19] op_sel:[0,0,1] op_sel_hi:[1,0,0]
	v_pk_add_f32 v[18:19], v[4:5], v[20:21]
	v_pk_add_f32 v[4:5], v[4:5], v[20:21] neg_lo:[0,1] neg_hi:[0,1]
	v_pk_mul_f32 v[20:21], v[4:5], s[10:11]
	v_pk_fma_f32 v[4:5], v[4:5], s[14:15], v[20:21] op_sel:[0,0,1] op_sel_hi:[1,0,0]
	v_pk_add_f32 v[20:21], v[6:7], v[22:23]
	v_pk_add_f32 v[6:7], v[6:7], v[22:23] neg_lo:[0,1] neg_hi:[0,1]
	v_pk_mul_f32 v[22:23], v[6:7], s[34:35]
	v_pk_fma_f32 v[6:7], v[6:7], s[0:1], v[22:23] op_sel:[0,0,1] op_sel_hi:[1,0,0]
	v_pk_add_f32 v[22:23], v[8:9], v[26:27]
	v_pk_add_f32 v[8:9], v[8:9], v[26:27] neg_lo:[0,1] neg_hi:[0,1]
	v_pk_add_f32 v[26:27], v[10:11], v[28:29]
	v_pk_add_f32 v[10:11], v[10:11], v[28:29] neg_lo:[0,1] neg_hi:[0,1]
	v_pk_mul_f32 v[28:29], v[10:11], s[34:35]
	v_pk_fma_f32 v[10:11], v[10:11], s[0:1], v[28:29] op_sel:[0,0,1] op_sel_hi:[1,0,0] neg_lo:[1,0,0] neg_hi:[1,0,0]
	v_pk_add_f32 v[28:29], v[12:13], v[30:31]
	v_pk_add_f32 v[12:13], v[12:13], v[30:31] neg_lo:[0,1] neg_hi:[0,1]
	s_mov_b32 s0, 0
	v_pk_mul_f32 v[30:31], v[12:13], s[10:11]
	s_nop 0
	v_pk_fma_f32 v[12:13], v[12:13], s[14:15], v[30:31] op_sel:[0,0,1] op_sel_hi:[1,0,0] neg_lo:[1,0,0] neg_hi:[1,0,0]
	v_pk_add_f32 v[30:31], v[14:15], v[24:25]
	v_pk_add_f32 v[14:15], v[14:15], v[24:25] neg_lo:[0,1] neg_hi:[0,1]
	v_pk_mul_f32 v[24:25], v[14:15], s[18:19]
	v_pk_fma_f32 v[14:15], v[14:15], s[30:31], v[24:25] op_sel:[0,0,1] op_sel_hi:[1,0,0] neg_lo:[1,0,0] neg_hi:[1,0,0]
	v_pk_add_f32 v[24:25], v[80:81], v[22:23]
	v_pk_add_f32 v[22:23], v[80:81], v[22:23] neg_lo:[0,1] neg_hi:[0,1]
	v_pk_add_f32 v[80:81], v[16:17], v[26:27]
	v_pk_add_f32 v[16:17], v[16:17], v[26:27] neg_lo:[0,1] neg_hi:[0,1]
	v_pk_mul_f32 v[26:27], v[16:17], s[10:11]
	v_pk_fma_f32 v[16:17], v[16:17], s[14:15], v[26:27] op_sel:[0,0,1] op_sel_hi:[1,0,0]
	v_pk_add_f32 v[26:27], v[18:19], v[28:29]
	v_pk_add_f32 v[18:19], v[18:19], v[28:29] neg_lo:[0,1] neg_hi:[0,1]
	v_pk_add_f32 v[28:29], v[20:21], v[30:31]
	v_pk_add_f32 v[20:21], v[20:21], v[30:31] neg_lo:[0,1] neg_hi:[0,1]
	v_pk_mul_f32 v[30:31], v[20:21], s[10:11]
	v_pk_fma_f32 v[20:21], v[20:21], s[14:15], v[30:31] op_sel:[0,0,1] op_sel_hi:[1,0,0] neg_lo:[1,0,0] neg_hi:[1,0,0]
	v_pk_add_f32 v[30:31], v[0:1], v[8:9] op_sel:[0,1] op_sel_hi:[1,0] neg_hi:[0,1]
	v_pk_add_f32 v[0:1], v[0:1], v[8:9] op_sel:[0,1] op_sel_hi:[1,0] neg_lo:[0,1]
	v_pk_add_f32 v[8:9], v[2:3], v[10:11]
	v_pk_add_f32 v[2:3], v[2:3], v[10:11] neg_lo:[0,1] neg_hi:[0,1]
	v_pk_mul_f32 v[10:11], v[2:3], s[10:11]
	v_pk_fma_f32 v[2:3], v[2:3], s[14:15], v[10:11] op_sel:[0,0,1] op_sel_hi:[1,0,0]
	v_pk_add_f32 v[10:11], v[4:5], v[12:13]
	v_pk_add_f32 v[4:5], v[4:5], v[12:13] neg_lo:[0,1] neg_hi:[0,1]
	v_pk_add_f32 v[12:13], v[6:7], v[14:15]
	v_pk_add_f32 v[6:7], v[6:7], v[14:15] neg_lo:[0,1] neg_hi:[0,1]
	v_pk_mul_f32 v[14:15], v[6:7], s[10:11]
	v_pk_fma_f32 v[6:7], v[6:7], s[14:15], v[14:15] op_sel:[0,0,1] op_sel_hi:[1,0,0] neg_lo:[1,0,0] neg_hi:[1,0,0]
	v_pk_add_f32 v[14:15], v[24:25], v[26:27]
	v_pk_add_f32 v[24:25], v[24:25], v[26:27] neg_lo:[0,1] neg_hi:[0,1]
	v_pk_add_f32 v[26:27], v[80:81], v[28:29]
	v_pk_add_f32 v[28:29], v[80:81], v[28:29] neg_lo:[0,1] neg_hi:[0,1]
	v_pk_add_f32 v[80:81], v[22:23], v[18:19] op_sel:[0,1] op_sel_hi:[1,0] neg_hi:[0,1]
	v_pk_add_f32 v[18:19], v[22:23], v[18:19] op_sel:[0,1] op_sel_hi:[1,0] neg_lo:[0,1]
	v_pk_add_f32 v[22:23], v[16:17], v[20:21]
	v_pk_add_f32 v[16:17], v[16:17], v[20:21] neg_lo:[0,1] neg_hi:[0,1]
	v_pk_add_f32 v[20:21], v[30:31], v[10:11]
	v_pk_add_f32 v[10:11], v[30:31], v[10:11] neg_lo:[0,1] neg_hi:[0,1]
	v_pk_add_f32 v[30:31], v[8:9], v[12:13]
	v_pk_add_f32 v[8:9], v[8:9], v[12:13] neg_lo:[0,1] neg_hi:[0,1]
	v_pk_add_f32 v[12:13], v[0:1], v[4:5] op_sel:[0,1] op_sel_hi:[1,0] neg_hi:[0,1]
	v_pk_add_f32 v[0:1], v[0:1], v[4:5] op_sel:[0,1] op_sel_hi:[1,0] neg_lo:[0,1]
	v_pk_add_f32 v[4:5], v[2:3], v[6:7]
	v_pk_add_f32 v[2:3], v[2:3], v[6:7] neg_lo:[0,1] neg_hi:[0,1]
	v_pk_mul_f32 v[2:3], v[2:3], s[22:23]
	v_pk_add_f32 v[6:7], v[14:15], v[26:27]
	v_pk_add_f32 v[14:15], v[14:15], v[26:27] neg_lo:[0,1] neg_hi:[0,1]
	v_pk_add_f32 v[26:27], v[24:25], v[28:29] op_sel:[0,1] op_sel_hi:[1,0] neg_hi:[0,1]
	v_pk_add_f32 v[24:25], v[24:25], v[28:29] op_sel:[0,1] op_sel_hi:[1,0] neg_lo:[0,1]
	v_pk_add_f32 v[28:29], v[80:81], v[22:23]
	v_pk_add_f32 v[22:23], v[80:81], v[22:23] neg_lo:[0,1] neg_hi:[0,1]
	v_pk_add_f32 v[80:81], v[18:19], v[16:17] op_sel:[0,1] op_sel_hi:[1,0] neg_hi:[0,1]
	v_pk_add_f32 v[16:17], v[18:19], v[16:17] op_sel:[0,1] op_sel_hi:[1,0] neg_lo:[0,1]
	v_pk_add_f32 v[18:19], v[20:21], v[30:31]
	v_pk_add_f32 v[20:21], v[20:21], v[30:31] neg_lo:[0,1] neg_hi:[0,1]
	v_pk_add_f32 v[30:31], v[10:11], v[8:9] op_sel:[0,1] op_sel_hi:[1,0] neg_hi:[0,1]
	v_pk_add_f32 v[8:9], v[10:11], v[8:9] op_sel:[0,1] op_sel_hi:[1,0] neg_lo:[0,1]
	v_pk_add_f32 v[10:11], v[12:13], v[4:5]
	v_pk_add_f32 v[4:5], v[12:13], v[4:5] neg_lo:[0,1] neg_hi:[0,1]
	v_pk_add_f32 v[12:13], v[0:1], v[2:3] op_sel:[0,1] op_sel_hi:[1,0]
	v_pk_add_f32 v[0:1], v[0:1], v[2:3] op_sel:[0,1] op_sel_hi:[1,0] neg_lo:[0,1] neg_hi:[0,1]
	v_lshlrev_b32_e32 v2, 4, v120
	v_and_or_b32 v2, v2, s15, v121
	v_ashrrev_i32_e32 v3, 4, v2
	v_lshlrev_b32_e32 v3, 3, v3
	v_lshlrev_b32_e32 v2, 3, v2
	v_add3_u32 v2, 0, v3, v2
	ds_write_b64 v2, v[6:7]
	ds_write_b64 v2, v[14:15] offset:34816
	ds_write_b64 v2, v[26:27] offset:17408
	ds_write_b64 v2, v[24:25] offset:52224
	ds_write_b64 v2, v[28:29] offset:8704
	ds_write_b64 v2, v[22:23] offset:43520
	ds_write_b64 v2, v[80:81] offset:26112
	ds_write_b64 v2, v[16:17] offset:60928
	ds_write_b64 v2, v[18:19] offset:4352
	ds_write_b64 v2, v[20:21] offset:39168
	ds_write_b64 v2, v[30:31] offset:21760
	ds_write_b64 v2, v[8:9] offset:56576
	ds_write_b64 v2, v[10:11] offset:13056
	ds_write_b64 v2, v[4:5] offset:47872
	ds_write_b64 v2, v[12:13] offset:30464
	ds_write_b64 v2, v[0:1] offset:65280
	v_sub_u32_e32 v80, 0x2000, v32
	v_ashrrev_i32_e32 v0, 4, v80
	v_add_u32_e32 v154, v0, v80
	v_lshlrev_b32_e32 v0, 3, v0
	v_sub_u32_e32 v156, v0, v157
	v_mov_b32_e32 v0, v154
	v_mov_b32_e32 v1, v156
	v_mov_b32_e32 v2, v155
	s_waitcnt lgkmcnt(0)
	s_barrier
.LBB0_433:
	v_or_b32_e32 v3, s0, v32
	v_cmp_ne_u32_e32 vcc, 0, v3
	v_add_u32_e32 v12, 0, v2
	v_add_u32_e32 v4, 0x11000, v12
	v_cndmask_b32_e32 v3, 0, v0, vcc
	v_lshl_add_u32 v3, v3, 3, 0
	v_add_u32_e32 v3, 0x11000, v3
	ds_read_b64 v[4:5], v4
	ds_read_b64 v[8:9], v12
	ds_read_b64 v[6:7], v3
	s_add_i32 s0, s0, 2
	v_add_u32_e32 v2, 0x2200, v2
	v_add_u32_e32 v0, 0xfffffbc0, v0
	s_cmp_lg_u32 s0, 16
	s_waitcnt lgkmcnt(0)
	v_add_f32_e32 v3, v4, v6
	v_mul_f32_e32 v4, 0.5, v3
	v_sub_f32_e32 v3, v5, v7
	v_mul_f32_e32 v6, 0.5, v3
	v_pk_mul_f32 v[6:7], v[8:9], v[6:7] op_sel:[1,0] op_sel_hi:[0,0]
	v_pk_fma_f32 v[10:11], v[8:9], v[4:5], v[6:7] neg_lo:[0,0,1] neg_hi:[0,0,1]
	v_pk_fma_f32 v[4:5], v[8:9], v[4:5], v[6:7] op_sel_hi:[1,0,1]
	v_add_u32_e32 v3, 0x12100, v12
	v_mov_b32_e32 v11, v5
	v_pk_mul_f32 v[4:5], v[10:11], s[24:25]
	ds_write_b64 v12, v[4:5]
	ds_read_b64 v[4:5], v3
	ds_read_b64 v[8:9], v12 offset:4352
	v_add_u32_e32 v3, 0, v1
	v_add_u32_e32 v3, 0x1ff00, v3
	ds_read_b64 v[6:7], v3
	v_add_u32_e32 v1, 0xffffde00, v1
	s_waitcnt lgkmcnt(0)
	v_add_f32_e32 v3, v4, v6
	v_mul_f32_e32 v4, 0.5, v3
	v_sub_f32_e32 v3, v5, v7
	v_mul_f32_e32 v6, 0.5, v3
	v_pk_mul_f32 v[6:7], v[8:9], v[6:7] op_sel:[1,0] op_sel_hi:[0,0]
	v_pk_fma_f32 v[10:11], v[8:9], v[4:5], v[6:7] neg_lo:[0,0,1] neg_hi:[0,0,1]
	v_pk_fma_f32 v[4:5], v[8:9], v[4:5], v[6:7] op_sel_hi:[1,0,1]
	s_nop 0
	v_mov_b32_e32 v11, v5
	v_pk_mul_f32 v[4:5], v[10:11], s[24:25]
	ds_write_b64 v12, v[4:5] offset:4352
	s_cbranch_scc1 .LBB0_433
	s_waitcnt lgkmcnt(0)
	s_barrier
	s_and_saveexec_b64 s[0:1], s[40:41]
	s_cbranch_execz .LBB0_436
	ds_read_b64 v[0:1], v37 offset:2176
	ds_read_b64 v[2:3], v37 offset:4352
	ds_read_b64 v[4:5], v37 offset:6528
	ds_read_b64 v[6:7], v37 offset:8704
	ds_read_b64 v[8:9], v37 offset:10880
	ds_read_b64 v[10:11], v37 offset:13056
	ds_read_b64 v[12:13], v37 offset:15232
	ds_read_b64 v[14:15], v37 offset:17408
	ds_read_b64 v[16:17], v37 offset:19584
	ds_read_b64 v[18:19], v37 offset:21760
	ds_read_b64 v[20:21], v37 offset:23936
	ds_read_b64 v[22:23], v37 offset:26112
	ds_read_b64 v[24:25], v37 offset:34816
	ds_read_b64 v[26:27], v37 offset:36992
	ds_read_b64 v[28:29], v37 offset:39168
	ds_read_b64 v[30:31], v37 offset:41344
	ds_read_b64 v[102:103], v37 offset:43520
	ds_read_b64 v[110:111], v37 offset:45696
	ds_read_b64 v[118:119], v37 offset:47872
	ds_read_b64 v[120:121], v37 offset:50048
	ds_read_b64 v[122:123], v37 offset:52224
	ds_read_b64 v[124:125], v37 offset:54400
	ds_read_b64 v[126:127], v37 offset:56576
	ds_read_b64 v[128:129], v37 offset:58752
	ds_read_b64 v[130:131], v37
	ds_read_b64 v[132:133], v37 offset:60928
	ds_read_b64 v[134:135], v37 offset:63104
	ds_read_b64 v[136:137], v37 offset:65280
	s_mov_b32 s11, s14
	s_waitcnt lgkmcnt(3)
	v_pk_add_f32 v[158:159], v[130:131], v[24:25]
	v_pk_add_f32 v[24:25], v[130:131], v[24:25] neg_lo:[0,1] neg_hi:[0,1]
	v_pk_add_f32 v[130:131], v[0:1], v[26:27]
	v_pk_add_f32 v[0:1], v[0:1], v[26:27] neg_lo:[0,1] neg_hi:[0,1]
	s_mov_b32 s13, s86
	v_pk_mul_f32 v[26:27], v[0:1], s[16:17]
	s_mov_b32 s4, s21
	v_pk_fma_f32 v[0:1], v[0:1], s[6:7], v[26:27] op_sel:[0,0,1] op_sel_hi:[1,0,0]
	v_pk_add_f32 v[26:27], v[2:3], v[28:29]
	v_pk_add_f32 v[2:3], v[2:3], v[28:29] neg_lo:[0,1] neg_hi:[0,1]
	s_mov_b32 s35, s30
	v_pk_mul_f32 v[28:29], v[2:3], s[18:19]
	s_mov_b32 s8, s19
	v_pk_fma_f32 v[2:3], v[2:3], s[30:31], v[28:29] op_sel:[0,0,1] op_sel_hi:[1,0,0]
	v_pk_add_f32 v[28:29], v[4:5], v[30:31]
	v_pk_add_f32 v[4:5], v[4:5], v[30:31] neg_lo:[0,1] neg_hi:[0,1]
	s_mov_b32 s77, s6
	v_pk_mul_f32 v[30:31], v[4:5], s[20:21]
	s_mov_b32 s28, s17
	v_pk_fma_f32 v[4:5], v[4:5], s[86:87], v[30:31] op_sel:[0,0,1] op_sel_hi:[1,0,0]
	v_pk_add_f32 v[30:31], v[6:7], v[102:103]
	v_pk_add_f32 v[6:7], v[6:7], v[102:103] neg_lo:[0,1] neg_hi:[0,1]
	v_add_u32_e32 v47, 0x10780, v37
	v_pk_mul_f32 v[102:103], v[6:7], s[10:11]
	ds_read_b64 v[138:139], v37 offset:28288
	ds_read_b64 v[140:141], v37 offset:30464
	ds_read_b64 v[142:143], v37 offset:32640
	ds_read_b64 v[144:145], v47
	v_pk_fma_f32 v[6:7], v[6:7], s[14:15], v[102:103] op_sel:[0,0,1] op_sel_hi:[1,0,0]
	v_pk_add_f32 v[102:103], v[8:9], v[110:111]
	v_pk_add_f32 v[8:9], v[8:9], v[110:111] neg_lo:[0,1] neg_hi:[0,1]
	v_pk_mul_f32 v[110:111], v[8:9], s[12:13]
	v_pk_fma_f32 v[8:9], v[8:9], s[4:5], v[110:111] op_sel:[0,0,1] op_sel_hi:[1,0,0]
	v_pk_add_f32 v[110:111], v[10:11], v[118:119]
	v_pk_add_f32 v[10:11], v[10:11], v[118:119] neg_lo:[0,1] neg_hi:[0,1]
	v_pk_mul_f32 v[118:119], v[10:11], s[34:35]
	v_pk_fma_f32 v[10:11], v[10:11], s[8:9], v[118:119] op_sel:[0,0,1] op_sel_hi:[1,0,0]
	v_pk_add_f32 v[118:119], v[12:13], v[120:121]
	v_pk_add_f32 v[12:13], v[12:13], v[120:121] neg_lo:[0,1] neg_hi:[0,1]
	v_pk_mul_f32 v[120:121], v[12:13], s[76:77]
	v_pk_fma_f32 v[12:13], v[12:13], s[28:29], v[120:121] op_sel:[0,0,1] op_sel_hi:[1,0,0]
	v_pk_add_f32 v[120:121], v[14:15], v[122:123]
	v_pk_add_f32 v[14:15], v[14:15], v[122:123] neg_lo:[0,1] neg_hi:[0,1]
	v_pk_add_f32 v[122:123], v[16:17], v[124:125]
	v_pk_add_f32 v[16:17], v[16:17], v[124:125] neg_lo:[0,1] neg_hi:[0,1]
	v_pk_mul_f32 v[124:125], v[16:17], s[76:77]
	v_pk_fma_f32 v[16:17], v[16:17], s[28:29], v[124:125] op_sel:[0,0,1] op_sel_hi:[1,0,0] neg_lo:[1,0,0] neg_hi:[1,0,0]
	v_pk_add_f32 v[124:125], v[18:19], v[126:127]
	v_pk_add_f32 v[18:19], v[18:19], v[126:127] neg_lo:[0,1] neg_hi:[0,1]
	v_pk_mul_f32 v[126:127], v[18:19], s[34:35]
	v_pk_fma_f32 v[18:19], v[18:19], s[8:9], v[126:127] op_sel:[0,0,1] op_sel_hi:[1,0,0] neg_lo:[1,0,0] neg_hi:[1,0,0]
	v_pk_add_f32 v[126:127], v[20:21], v[128:129]
	v_pk_add_f32 v[20:21], v[20:21], v[128:129] neg_lo:[0,1] neg_hi:[0,1]
	v_pk_mul_f32 v[128:129], v[20:21], s[12:13]
	v_pk_fma_f32 v[20:21], v[20:21], s[4:5], v[128:129] op_sel:[0,0,1] op_sel_hi:[1,0,0] neg_lo:[1,0,0] neg_hi:[1,0,0]
	s_waitcnt lgkmcnt(6)
	v_pk_add_f32 v[128:129], v[22:23], v[132:133]
	v_pk_add_f32 v[22:23], v[22:23], v[132:133] neg_lo:[0,1] neg_hi:[0,1]
	s_nop 0
	v_pk_mul_f32 v[132:133], v[22:23], s[10:11]
	v_pk_fma_f32 v[22:23], v[22:23], s[14:15], v[132:133] op_sel:[0,0,1] op_sel_hi:[1,0,0] neg_lo:[1,0,0] neg_hi:[1,0,0]
	s_waitcnt lgkmcnt(3)
	v_pk_add_f32 v[132:133], v[138:139], v[134:135]
	v_pk_add_f32 v[134:135], v[138:139], v[134:135] neg_lo:[0,1] neg_hi:[0,1]
	s_nop 0
	v_pk_mul_f32 v[138:139], v[134:135], s[20:21]
	v_pk_fma_f32 v[134:135], v[134:135], s[86:87], v[138:139] op_sel:[0,0,1] op_sel_hi:[1,0,0] neg_lo:[1,0,0] neg_hi:[1,0,0]
	s_waitcnt lgkmcnt(2)
	v_pk_add_f32 v[138:139], v[140:141], v[136:137]
	v_pk_add_f32 v[136:137], v[140:141], v[136:137] neg_lo:[0,1] neg_hi:[0,1]
	s_nop 0
	v_pk_mul_f32 v[140:141], v[136:137], s[18:19]
	v_pk_fma_f32 v[136:137], v[136:137], s[30:31], v[140:141] op_sel:[0,0,1] op_sel_hi:[1,0,0] neg_lo:[1,0,0] neg_hi:[1,0,0]
	s_waitcnt lgkmcnt(0)
	v_pk_add_f32 v[140:141], v[142:143], v[144:145]
	v_pk_add_f32 v[142:143], v[142:143], v[144:145] neg_lo:[0,1] neg_hi:[0,1]
	s_nop 0
	v_pk_mul_f32 v[144:145], v[142:143], s[16:17]
	v_pk_fma_f32 v[142:143], v[142:143], s[6:7], v[144:145] op_sel:[0,0,1] op_sel_hi:[1,0,0] neg_lo:[1,0,0] neg_hi:[1,0,0]
	v_pk_add_f32 v[144:145], v[158:159], v[120:121]
	v_pk_add_f32 v[120:121], v[158:159], v[120:121] neg_lo:[0,1] neg_hi:[0,1]
	v_pk_add_f32 v[158:159], v[130:131], v[122:123]
	v_pk_add_f32 v[122:123], v[130:131], v[122:123] neg_lo:[0,1] neg_hi:[0,1]
	v_pk_mul_f32 v[130:131], v[122:123], s[18:19]
	v_pk_fma_f32 v[122:123], v[122:123], s[30:31], v[130:131] op_sel:[0,0,1] op_sel_hi:[1,0,0]
	v_pk_add_f32 v[130:131], v[26:27], v[124:125]
	v_pk_add_f32 v[26:27], v[26:27], v[124:125] neg_lo:[0,1] neg_hi:[0,1]
	v_pk_mul_f32 v[124:125], v[26:27], s[10:11]
	v_pk_fma_f32 v[26:27], v[26:27], s[14:15], v[124:125] op_sel:[0,0,1] op_sel_hi:[1,0,0]
	v_pk_add_f32 v[124:125], v[28:29], v[126:127]
	v_pk_add_f32 v[28:29], v[28:29], v[126:127] neg_lo:[0,1] neg_hi:[0,1]
	v_pk_mul_f32 v[126:127], v[28:29], s[34:35]
	v_pk_fma_f32 v[28:29], v[28:29], s[8:9], v[126:127] op_sel:[0,0,1] op_sel_hi:[1,0,0]
	v_pk_add_f32 v[126:127], v[30:31], v[128:129]
	v_pk_add_f32 v[30:31], v[30:31], v[128:129] neg_lo:[0,1] neg_hi:[0,1]
	v_pk_add_f32 v[128:129], v[102:103], v[132:133]
	v_pk_add_f32 v[102:103], v[102:103], v[132:133] neg_lo:[0,1] neg_hi:[0,1]
	v_pk_mul_f32 v[132:133], v[102:103], s[34:35]
	v_pk_fma_f32 v[102:103], v[102:103], s[8:9], v[132:133] op_sel:[0,0,1] op_sel_hi:[1,0,0] neg_lo:[1,0,0] neg_hi:[1,0,0]
	v_pk_add_f32 v[132:133], v[110:111], v[138:139]
	v_pk_add_f32 v[110:111], v[110:111], v[138:139] neg_lo:[0,1] neg_hi:[0,1]
	v_pk_mul_f32 v[138:139], v[110:111], s[10:11]
	v_pk_fma_f32 v[110:111], v[110:111], s[14:15], v[138:139] op_sel:[0,0,1] op_sel_hi:[1,0,0] neg_lo:[1,0,0] neg_hi:[1,0,0]
	v_pk_add_f32 v[138:139], v[118:119], v[140:141]
	v_pk_add_f32 v[118:119], v[118:119], v[140:141] neg_lo:[0,1] neg_hi:[0,1]
	v_pk_mul_f32 v[140:141], v[118:119], s[18:19]
	v_pk_fma_f32 v[118:119], v[118:119], s[30:31], v[140:141] op_sel:[0,0,1] op_sel_hi:[1,0,0] neg_lo:[1,0,0] neg_hi:[1,0,0]
	v_pk_add_f32 v[140:141], v[24:25], v[14:15] op_sel:[0,1] op_sel_hi:[1,0] neg_hi:[0,1]
	v_pk_add_f32 v[14:15], v[24:25], v[14:15] op_sel:[0,1] op_sel_hi:[1,0] neg_lo:[0,1]
	v_pk_add_f32 v[24:25], v[0:1], v[16:17]
	v_pk_add_f32 v[0:1], v[0:1], v[16:17] neg_lo:[0,1] neg_hi:[0,1]
	v_pk_mul_f32 v[16:17], v[0:1], s[18:19]
	v_pk_fma_f32 v[0:1], v[0:1], s[30:31], v[16:17] op_sel:[0,0,1] op_sel_hi:[1,0,0]
	v_pk_add_f32 v[16:17], v[2:3], v[18:19]
	v_pk_add_f32 v[2:3], v[2:3], v[18:19] neg_lo:[0,1] neg_hi:[0,1]
	v_pk_mul_f32 v[18:19], v[2:3], s[10:11]
	v_pk_fma_f32 v[2:3], v[2:3], s[14:15], v[18:19] op_sel:[0,0,1] op_sel_hi:[1,0,0]
	v_pk_add_f32 v[18:19], v[4:5], v[20:21]
	v_pk_add_f32 v[4:5], v[4:5], v[20:21] neg_lo:[0,1] neg_hi:[0,1]
	v_pk_mul_f32 v[20:21], v[4:5], s[34:35]
	v_pk_fma_f32 v[4:5], v[4:5], s[8:9], v[20:21] op_sel:[0,0,1] op_sel_hi:[1,0,0]
	v_pk_add_f32 v[20:21], v[6:7], v[22:23]
	v_pk_add_f32 v[6:7], v[6:7], v[22:23] neg_lo:[0,1] neg_hi:[0,1]
	v_pk_add_f32 v[22:23], v[8:9], v[134:135]
	v_pk_add_f32 v[8:9], v[8:9], v[134:135] neg_lo:[0,1] neg_hi:[0,1]
	v_pk_mul_f32 v[134:135], v[8:9], s[34:35]
	v_pk_fma_f32 v[8:9], v[8:9], s[8:9], v[134:135] op_sel:[0,0,1] op_sel_hi:[1,0,0] neg_lo:[1,0,0] neg_hi:[1,0,0]
	v_pk_add_f32 v[134:135], v[10:11], v[136:137]
	v_pk_add_f32 v[10:11], v[10:11], v[136:137] neg_lo:[0,1] neg_hi:[0,1]
	v_pk_mul_f32 v[136:137], v[10:11], s[10:11]
	v_pk_fma_f32 v[10:11], v[10:11], s[14:15], v[136:137] op_sel:[0,0,1] op_sel_hi:[1,0,0] neg_lo:[1,0,0] neg_hi:[1,0,0]
	v_pk_add_f32 v[136:137], v[12:13], v[142:143]
	v_pk_add_f32 v[12:13], v[12:13], v[142:143] neg_lo:[0,1] neg_hi:[0,1]
	v_pk_mul_f32 v[142:143], v[12:13], s[18:19]
	v_pk_fma_f32 v[12:13], v[12:13], s[30:31], v[142:143] op_sel:[0,0,1] op_sel_hi:[1,0,0] neg_lo:[1,0,0] neg_hi:[1,0,0]
	v_pk_add_f32 v[142:143], v[144:145], v[126:127]
	v_pk_add_f32 v[126:127], v[144:145], v[126:127] neg_lo:[0,1] neg_hi:[0,1]
	v_pk_add_f32 v[144:145], v[158:159], v[128:129]
	v_pk_add_f32 v[128:129], v[158:159], v[128:129] neg_lo:[0,1] neg_hi:[0,1]
	v_pk_mul_f32 v[158:159], v[128:129], s[10:11]
	v_pk_fma_f32 v[128:129], v[128:129], s[14:15], v[158:159] op_sel:[0,0,1] op_sel_hi:[1,0,0]
	v_pk_add_f32 v[158:159], v[130:131], v[132:133]
	v_pk_add_f32 v[130:131], v[130:131], v[132:133] neg_lo:[0,1] neg_hi:[0,1]
	v_pk_add_f32 v[132:133], v[124:125], v[138:139]
	v_pk_add_f32 v[124:125], v[124:125], v[138:139] neg_lo:[0,1] neg_hi:[0,1]
	v_pk_mul_f32 v[138:139], v[124:125], s[10:11]
	v_pk_fma_f32 v[124:125], v[124:125], s[14:15], v[138:139] op_sel:[0,0,1] op_sel_hi:[1,0,0] neg_lo:[1,0,0] neg_hi:[1,0,0]
	v_pk_add_f32 v[138:139], v[120:121], v[30:31] op_sel:[0,1] op_sel_hi:[1,0] neg_hi:[0,1]
	v_pk_add_f32 v[30:31], v[120:121], v[30:31] op_sel:[0,1] op_sel_hi:[1,0] neg_lo:[0,1]
	v_pk_add_f32 v[120:121], v[122:123], v[102:103]
	v_pk_add_f32 v[102:103], v[122:123], v[102:103] neg_lo:[0,1] neg_hi:[0,1]
	v_pk_add_f32 v[160:161], v[128:129], v[124:125]
	v_pk_mul_f32 v[122:123], v[102:103], s[10:11]
	v_pk_add_f32 v[124:125], v[128:129], v[124:125] neg_lo:[0,1] neg_hi:[0,1]
	v_pk_fma_f32 v[102:103], v[102:103], s[14:15], v[122:123] op_sel:[0,0,1] op_sel_hi:[1,0,0]
	v_pk_add_f32 v[122:123], v[26:27], v[110:111]
	v_pk_add_f32 v[26:27], v[26:27], v[110:111] neg_lo:[0,1] neg_hi:[0,1]
	v_pk_add_f32 v[110:111], v[28:29], v[118:119]
	v_pk_add_f32 v[28:29], v[28:29], v[118:119] neg_lo:[0,1] neg_hi:[0,1]
	v_pk_mul_f32 v[118:119], v[28:29], s[10:11]
	v_pk_add_f32 v[166:167], v[120:121], v[110:111]
	v_pk_fma_f32 v[28:29], v[28:29], s[14:15], v[118:119] op_sel:[0,0,1] op_sel_hi:[1,0,0] neg_lo:[1,0,0] neg_hi:[1,0,0]
	v_pk_add_f32 v[118:119], v[140:141], v[20:21]
	v_pk_add_f32 v[20:21], v[140:141], v[20:21] neg_lo:[0,1] neg_hi:[0,1]
	v_pk_add_f32 v[140:141], v[24:25], v[22:23]
	v_pk_add_f32 v[22:23], v[24:25], v[22:23] neg_lo:[0,1] neg_hi:[0,1]
	v_pk_add_f32 v[110:111], v[120:121], v[110:111] neg_lo:[0,1] neg_hi:[0,1]
	v_pk_mul_f32 v[24:25], v[22:23], s[10:11]
	v_pk_add_f32 v[168:169], v[30:31], v[26:27] op_sel:[0,1] op_sel_hi:[1,0] neg_hi:[0,1]
	v_pk_fma_f32 v[22:23], v[22:23], s[14:15], v[24:25] op_sel:[0,0,1] op_sel_hi:[1,0,0]
	v_pk_add_f32 v[24:25], v[16:17], v[134:135]
	v_pk_add_f32 v[16:17], v[16:17], v[134:135] neg_lo:[0,1] neg_hi:[0,1]
	v_pk_add_f32 v[134:135], v[18:19], v[136:137]
	v_pk_add_f32 v[18:19], v[18:19], v[136:137] neg_lo:[0,1] neg_hi:[0,1]
	v_pk_mul_f32 v[136:137], v[18:19], s[10:11]
	v_pk_add_f32 v[26:27], v[30:31], v[26:27] op_sel:[0,1] op_sel_hi:[1,0] neg_lo:[0,1]
	v_pk_fma_f32 v[18:19], v[18:19], s[14:15], v[136:137] op_sel:[0,0,1] op_sel_hi:[1,0,0] neg_lo:[1,0,0] neg_hi:[1,0,0]
	v_pk_add_f32 v[136:137], v[14:15], v[6:7] op_sel:[0,1] op_sel_hi:[1,0] neg_hi:[0,1]
	v_pk_add_f32 v[6:7], v[14:15], v[6:7] op_sel:[0,1] op_sel_hi:[1,0] neg_lo:[0,1]
	v_pk_add_f32 v[14:15], v[0:1], v[8:9]
	v_pk_add_f32 v[0:1], v[0:1], v[8:9] neg_lo:[0,1] neg_hi:[0,1]
	v_pk_add_f32 v[30:31], v[102:103], v[28:29]
	v_pk_mul_f32 v[8:9], v[0:1], s[10:11]
	v_pk_add_f32 v[28:29], v[102:103], v[28:29] neg_lo:[0,1] neg_hi:[0,1]
	v_pk_fma_f32 v[0:1], v[0:1], s[14:15], v[8:9] op_sel:[0,0,1] op_sel_hi:[1,0,0]
	v_pk_add_f32 v[8:9], v[2:3], v[10:11]
	v_pk_add_f32 v[2:3], v[2:3], v[10:11] neg_lo:[0,1] neg_hi:[0,1]
	v_pk_add_f32 v[10:11], v[4:5], v[12:13]
	v_pk_add_f32 v[4:5], v[4:5], v[12:13] neg_lo:[0,1] neg_hi:[0,1]
	v_pk_mul_f32 v[12:13], v[4:5], s[10:11]
	v_pk_add_f32 v[170:171], v[118:119], v[24:25]
	v_pk_fma_f32 v[4:5], v[4:5], s[14:15], v[12:13] op_sel:[0,0,1] op_sel_hi:[1,0,0] neg_lo:[1,0,0] neg_hi:[1,0,0]
	v_pk_add_f32 v[12:13], v[142:143], v[158:159]
	v_pk_add_f32 v[142:143], v[142:143], v[158:159] neg_lo:[0,1] neg_hi:[0,1]
	v_pk_add_f32 v[158:159], v[144:145], v[132:133]
	v_pk_add_f32 v[132:133], v[144:145], v[132:133] neg_lo:[0,1] neg_hi:[0,1]
	v_pk_add_f32 v[182:183], v[118:119], v[24:25] neg_lo:[0,1] neg_hi:[0,1]
	v_pk_add_f32 v[184:185], v[140:141], v[134:135]
	v_pk_add_f32 v[24:25], v[140:141], v[134:135] neg_lo:[0,1] neg_hi:[0,1]
	v_pk_add_f32 v[140:141], v[20:21], v[16:17] op_sel:[0,1] op_sel_hi:[1,0] neg_hi:[0,1]
	v_pk_add_f32 v[186:187], v[20:21], v[16:17] op_sel:[0,1] op_sel_hi:[1,0] neg_lo:[0,1]
	v_pk_add_f32 v[16:17], v[22:23], v[18:19] neg_lo:[0,1] neg_hi:[0,1]
	v_pk_add_f32 v[192:193], v[136:137], v[8:9]
	v_pk_add_f32 v[194:195], v[136:137], v[8:9] neg_lo:[0,1] neg_hi:[0,1]
	v_pk_add_f32 v[8:9], v[14:15], v[10:11] neg_lo:[0,1] neg_hi:[0,1]
	v_pk_add_f32 v[198:199], v[6:7], v[2:3] op_sel:[0,1] op_sel_hi:[1,0] neg_hi:[0,1]
	v_pk_add_f32 v[200:201], v[6:7], v[2:3] op_sel:[0,1] op_sel_hi:[1,0] neg_lo:[0,1]
	v_pk_add_f32 v[2:3], v[0:1], v[4:5]
	v_pk_add_f32 v[0:1], v[0:1], v[4:5] neg_lo:[0,1] neg_hi:[0,1]
	v_pk_add_f32 v[144:145], v[126:127], v[130:131] op_sel:[0,1] op_sel_hi:[1,0] neg_hi:[0,1]
	v_pk_add_f32 v[130:131], v[126:127], v[130:131] op_sel:[0,1] op_sel_hi:[1,0] neg_lo:[0,1]
	v_pk_mul_f32 v[162:163], v[124:125], s[22:23]
	v_pk_add_f32 v[164:165], v[138:139], v[122:123]
	v_pk_add_f32 v[138:139], v[138:139], v[122:123] neg_lo:[0,1] neg_hi:[0,1]
	v_pk_mul_f32 v[102:103], v[28:29], s[22:23]
	v_pk_mul_f32 v[134:135], v[24:25], s[22:23]
	v_pk_add_f32 v[188:189], v[22:23], v[18:19]
	v_pk_mul_f32 v[190:191], v[16:17], s[22:23]
	v_pk_add_f32 v[136:137], v[14:15], v[10:11]
	v_pk_mul_f32 v[196:197], v[8:9], s[22:23]
	v_pk_mul_f32 v[202:203], v[0:1], s[22:23]
	v_pk_add_f32 v[28:29], v[12:13], v[158:159]
	v_pk_add_f32 v[128:129], v[12:13], v[158:159] neg_lo:[0,1] neg_hi:[0,1]
	v_pk_add_f32 v[24:25], v[142:143], v[132:133] op_sel:[0,1] op_sel_hi:[1,0] neg_hi:[0,1]
	v_pk_add_f32 v[126:127], v[142:143], v[132:133] op_sel:[0,1] op_sel_hi:[1,0] neg_lo:[0,1]
	v_pk_add_f32 v[20:21], v[144:145], v[160:161]
	v_pk_add_f32 v[124:125], v[144:145], v[160:161] neg_lo:[0,1] neg_hi:[0,1]
	v_pk_add_f32 v[16:17], v[130:131], v[162:163] op_sel:[0,1] op_sel_hi:[1,0]
	v_pk_add_f32 v[122:123], v[130:131], v[162:163] op_sel:[0,1] op_sel_hi:[1,0] neg_lo:[0,1] neg_hi:[0,1]
	v_pk_add_f32 v[12:13], v[164:165], v[166:167]
	v_pk_add_f32 v[120:121], v[164:165], v[166:167] neg_lo:[0,1] neg_hi:[0,1]
	v_pk_add_f32 v[8:9], v[138:139], v[110:111] op_sel:[0,1] op_sel_hi:[1,0] neg_hi:[0,1]
	v_pk_add_f32 v[118:119], v[138:139], v[110:111] op_sel:[0,1] op_sel_hi:[1,0] neg_lo:[0,1]
	v_pk_add_f32 v[4:5], v[168:169], v[30:31]
	v_pk_add_f32 v[110:111], v[168:169], v[30:31] neg_lo:[0,1] neg_hi:[0,1]
	v_pk_add_f32 v[0:1], v[26:27], v[102:103] op_sel:[0,1] op_sel_hi:[1,0]
	v_pk_add_f32 v[102:103], v[26:27], v[102:103] op_sel:[0,1] op_sel_hi:[1,0] neg_lo:[0,1] neg_hi:[0,1]
	v_pk_add_f32 v[30:31], v[170:171], v[184:185]
	v_pk_add_f32 v[144:145], v[170:171], v[184:185] neg_lo:[0,1] neg_hi:[0,1]
	v_pk_add_f32 v[26:27], v[182:183], v[134:135] op_sel:[0,1] op_sel_hi:[1,0]
	v_pk_add_f32 v[142:143], v[182:183], v[134:135] op_sel:[0,1] op_sel_hi:[1,0] neg_lo:[0,1] neg_hi:[0,1]
	v_pk_add_f32 v[22:23], v[140:141], v[188:189]
	v_pk_add_f32 v[140:141], v[140:141], v[188:189] neg_lo:[0,1] neg_hi:[0,1]
	v_pk_add_f32 v[18:19], v[186:187], v[190:191] op_sel:[0,1] op_sel_hi:[1,0]
	v_pk_add_f32 v[138:139], v[186:187], v[190:191] op_sel:[0,1] op_sel_hi:[1,0] neg_lo:[0,1] neg_hi:[0,1]
	v_pk_add_f32 v[14:15], v[192:193], v[136:137]
	v_pk_add_f32 v[136:137], v[192:193], v[136:137] neg_lo:[0,1] neg_hi:[0,1]
	v_pk_add_f32 v[10:11], v[194:195], v[196:197] op_sel:[0,1] op_sel_hi:[1,0]
	v_pk_add_f32 v[134:135], v[194:195], v[196:197] op_sel:[0,1] op_sel_hi:[1,0] neg_lo:[0,1] neg_hi:[0,1]
	v_pk_add_f32 v[6:7], v[198:199], v[2:3]
	v_pk_add_f32 v[132:133], v[198:199], v[2:3] neg_lo:[0,1] neg_hi:[0,1]
	v_pk_add_f32 v[2:3], v[200:201], v[202:203] op_sel:[0,1] op_sel_hi:[1,0]
	v_pk_add_f32 v[130:131], v[200:201], v[202:203] op_sel:[0,1] op_sel_hi:[1,0] neg_lo:[0,1] neg_hi:[0,1]

.LBB0_438:
	s_or_b64 exec, exec, s[0:1]
	v_mov_b32_e32 v47, v32
	s_waitcnt lgkmcnt(0)
	s_barrier
	s_mov_b32 s11, s14
	v_and_b32_e32 v81, 31, v47
	v_cvt_f32_ubyte0_e32 v24, v81
	v_mul_f32_e32 v110, 0x3b000000, v24
	v_sin_f32_e32 v24, v110
	v_ashrrev_i32_e32 v0, 4, v47
	v_lshlrev_b32_e32 v0, 3, v0
	v_lshlrev_b32_e32 v1, 3, v47
	v_cos_f32_e32 v110, v110
	v_add3_u32 v25, 0, v0, v1
	ds_read_b64 v[0:1], v25
	ds_read_b64 v[2:3], v25 offset:4352
	ds_read_b64 v[4:5], v25 offset:8704
	ds_read_b64 v[6:7], v25 offset:13056
	ds_read_b64 v[8:9], v25 offset:17408
	ds_read_b64 v[10:11], v25 offset:21760
	ds_read_b64 v[12:13], v25 offset:26112
	ds_read_b64 v[14:15], v25 offset:30464
	ds_read_b64 v[16:17], v25 offset:34816
	ds_read_b64 v[18:19], v25 offset:39168
	ds_read_b64 v[20:21], v25 offset:43520
	ds_read_b64 v[22:23], v25 offset:47872
	v_xor_b32_e32 v111, 0x80000000, v24
	s_waitcnt lgkmcnt(10)
	v_pk_mul_f32 v[118:119], v[2:3], v[24:25] op_sel:[1,0] op_sel_hi:[0,0] neg_hi:[0,1]
	v_pk_fma_f32 v[2:3], v[2:3], v[110:111], v[118:119] op_sel_hi:[1,0,1]
	v_pk_mul_f32 v[118:119], v[24:25], v[110:111] op_sel:[0,1] op_sel_hi:[0,0] neg_hi:[1,0]
	v_pk_fma_f32 v[118:119], v[110:111], v[110:111], v[118:119] op_sel_hi:[0,1,1]
	ds_read_b64 v[26:27], v25 offset:52224
	ds_read_b64 v[28:29], v25 offset:56576
	ds_read_b64 v[30:31], v25 offset:60928
	ds_read_b64 v[102:103], v25 offset:65280
	s_waitcnt lgkmcnt(13)
	v_pk_mul_f32 v[120:121], v[4:5], v[118:119] op_sel:[1,1] op_sel_hi:[0,1] neg_lo:[0,1]
	v_pk_fma_f32 v[4:5], v[4:5], v[118:119], v[120:121] op_sel_hi:[1,0,1]
	v_pk_mul_f32 v[120:121], v[24:25], v[118:119] op_sel:[0,1] op_sel_hi:[0,0] neg_hi:[1,0]
	v_pk_fma_f32 v[118:119], v[110:111], v[118:119], v[120:121] op_sel_hi:[0,1,1]
	s_mov_b32 s35, s30
	s_waitcnt lgkmcnt(12)
	v_pk_mul_f32 v[120:121], v[6:7], v[118:119] op_sel:[1,1] op_sel_hi:[0,1] neg_lo:[0,1]
	v_pk_fma_f32 v[6:7], v[6:7], v[118:119], v[120:121] op_sel_hi:[1,0,1]
	v_pk_mul_f32 v[120:121], v[24:25], v[118:119] op_sel:[0,1] op_sel_hi:[0,0] neg_hi:[1,0]
	v_pk_fma_f32 v[118:119], v[110:111], v[118:119], v[120:121] op_sel_hi:[0,1,1]
	s_mov_b32 s0, s19
	s_waitcnt lgkmcnt(11)
	v_pk_mul_f32 v[120:121], v[8:9], v[118:119] op_sel:[1,1] op_sel_hi:[0,1] neg_lo:[0,1]
	v_pk_fma_f32 v[8:9], v[8:9], v[118:119], v[120:121] op_sel_hi:[1,0,1]
	v_pk_mul_f32 v[120:121], v[24:25], v[118:119] op_sel:[0,1] op_sel_hi:[0,0] neg_hi:[1,0]
	v_pk_fma_f32 v[118:119], v[110:111], v[118:119], v[120:121] op_sel_hi:[0,1,1]
	s_waitcnt lgkmcnt(0)
	v_pk_mul_f32 v[120:121], v[10:11], v[118:119] op_sel:[1,1] op_sel_hi:[0,1] neg_lo:[0,1]
	v_pk_fma_f32 v[10:11], v[10:11], v[118:119], v[120:121] op_sel_hi:[1,0,1]
	v_pk_mul_f32 v[120:121], v[24:25], v[118:119] op_sel:[0,1] op_sel_hi:[0,0] neg_hi:[1,0]
	v_pk_fma_f32 v[118:119], v[110:111], v[118:119], v[120:121] op_sel_hi:[0,1,1]
	s_barrier
	v_pk_mul_f32 v[120:121], v[12:13], v[118:119] op_sel:[1,1] op_sel_hi:[0,1] neg_lo:[0,1]
	v_pk_fma_f32 v[12:13], v[12:13], v[118:119], v[120:121] op_sel_hi:[1,0,1]
	v_pk_mul_f32 v[120:121], v[24:25], v[118:119] op_sel:[0,1] op_sel_hi:[0,0] neg_hi:[1,0]
	v_pk_fma_f32 v[118:119], v[110:111], v[118:119], v[120:121] op_sel_hi:[0,1,1]
	v_pk_mul_f32 v[120:121], v[14:15], v[118:119] op_sel:[1,1] op_sel_hi:[0,1] neg_lo:[0,1]
	v_pk_fma_f32 v[14:15], v[14:15], v[118:119], v[120:121] op_sel_hi:[1,0,1]
	v_pk_mul_f32 v[120:121], v[24:25], v[118:119] op_sel:[0,1] op_sel_hi:[0,0] neg_hi:[1,0]
	v_pk_fma_f32 v[118:119], v[110:111], v[118:119], v[120:121] op_sel_hi:[0,1,1]
	v_pk_mul_f32 v[120:121], v[16:17], v[118:119] op_sel:[1,1] op_sel_hi:[0,1] neg_lo:[0,1]
	v_pk_fma_f32 v[16:17], v[16:17], v[118:119], v[120:121] op_sel_hi:[1,0,1]
	v_pk_mul_f32 v[120:121], v[24:25], v[118:119] op_sel:[0,1] op_sel_hi:[0,0] neg_hi:[1,0]
	v_pk_fma_f32 v[118:119], v[110:111], v[118:119], v[120:121] op_sel_hi:[0,1,1]
	v_pk_mul_f32 v[120:121], v[18:19], v[118:119] op_sel:[1,1] op_sel_hi:[0,1] neg_lo:[0,1]
	v_pk_fma_f32 v[18:19], v[18:19], v[118:119], v[120:121] op_sel_hi:[1,0,1]
	v_pk_mul_f32 v[120:121], v[24:25], v[118:119] op_sel:[0,1] op_sel_hi:[0,0] neg_hi:[1,0]
	v_pk_fma_f32 v[118:119], v[110:111], v[118:119], v[120:121] op_sel_hi:[0,1,1]
	v_pk_mul_f32 v[120:121], v[20:21], v[118:119] op_sel:[1,1] op_sel_hi:[0,1] neg_lo:[0,1]
	v_pk_fma_f32 v[20:21], v[20:21], v[118:119], v[120:121] op_sel_hi:[1,0,1]
	v_pk_mul_f32 v[120:121], v[24:25], v[118:119] op_sel:[0,1] op_sel_hi:[0,0] neg_hi:[1,0]
	v_pk_fma_f32 v[118:119], v[110:111], v[118:119], v[120:121] op_sel_hi:[0,1,1]
	v_pk_mul_f32 v[120:121], v[22:23], v[118:119] op_sel:[1,1] op_sel_hi:[0,1] neg_lo:[0,1]
	v_pk_fma_f32 v[22:23], v[22:23], v[118:119], v[120:121] op_sel_hi:[1,0,1]
	v_pk_mul_f32 v[120:121], v[24:25], v[118:119] op_sel:[0,1] op_sel_hi:[0,0] neg_hi:[1,0]
	v_pk_fma_f32 v[118:119], v[110:111], v[118:119], v[120:121] op_sel_hi:[0,1,1]
	v_pk_mul_f32 v[120:121], v[26:27], v[118:119] op_sel:[1,1] op_sel_hi:[0,1] neg_lo:[0,1]
	v_pk_fma_f32 v[26:27], v[26:27], v[118:119], v[120:121] op_sel_hi:[1,0,1]
	v_pk_mul_f32 v[120:121], v[24:25], v[118:119] op_sel:[0,1] op_sel_hi:[0,0] neg_hi:[1,0]
	v_pk_fma_f32 v[118:119], v[110:111], v[118:119], v[120:121] op_sel_hi:[0,1,1]
	v_pk_mul_f32 v[120:121], v[28:29], v[118:119] op_sel:[1,1] op_sel_hi:[0,1] neg_lo:[0,1]
	v_pk_fma_f32 v[28:29], v[28:29], v[118:119], v[120:121] op_sel_hi:[1,0,1]
	v_pk_mul_f32 v[120:121], v[24:25], v[118:119] op_sel:[0,1] op_sel_hi:[0,0] neg_hi:[1,0]
	v_pk_fma_f32 v[118:119], v[110:111], v[118:119], v[120:121] op_sel_hi:[0,1,1]
	v_pk_mul_f32 v[24:25], v[24:25], v[118:119] op_sel:[0,1] op_sel_hi:[0,0] neg_hi:[1,0]
	v_pk_fma_f32 v[24:25], v[110:111], v[118:119], v[24:25] op_sel_hi:[0,1,1]
	v_pk_mul_f32 v[110:111], v[102:103], v[24:25] op_sel:[1,1] op_sel_hi:[0,1] neg_lo:[0,1]
	v_pk_fma_f32 v[24:25], v[102:103], v[24:25], v[110:111] op_sel_hi:[1,0,1]
	v_pk_add_f32 v[102:103], v[0:1], v[16:17]
	v_pk_add_f32 v[0:1], v[0:1], v[16:17] neg_lo:[0,1] neg_hi:[0,1]
	v_pk_add_f32 v[16:17], v[2:3], v[18:19]
	v_pk_add_f32 v[2:3], v[2:3], v[18:19] neg_lo:[0,1] neg_hi:[0,1]
	v_pk_mul_f32 v[120:121], v[30:31], v[118:119] op_sel:[1,1] op_sel_hi:[0,1] neg_lo:[0,1]
	v_pk_mul_f32 v[18:19], v[2:3], s[18:19]
	v_pk_fma_f32 v[30:31], v[30:31], v[118:119], v[120:121] op_sel_hi:[1,0,1]
	v_pk_fma_f32 v[2:3], v[2:3], s[30:31], v[18:19] op_sel:[0,0,1] op_sel_hi:[1,0,0]
	v_pk_add_f32 v[18:19], v[4:5], v[20:21]
	v_pk_add_f32 v[4:5], v[4:5], v[20:21] neg_lo:[0,1] neg_hi:[0,1]
	v_pk_mul_f32 v[20:21], v[4:5], s[10:11]
	v_pk_fma_f32 v[4:5], v[4:5], s[14:15], v[20:21] op_sel:[0,0,1] op_sel_hi:[1,0,0]
	v_pk_add_f32 v[20:21], v[6:7], v[22:23]
	v_pk_add_f32 v[6:7], v[6:7], v[22:23] neg_lo:[0,1] neg_hi:[0,1]
	v_pk_mul_f32 v[22:23], v[6:7], s[34:35]
	v_pk_fma_f32 v[6:7], v[6:7], s[0:1], v[22:23] op_sel:[0,0,1] op_sel_hi:[1,0,0]
	v_pk_add_f32 v[22:23], v[8:9], v[26:27]
	v_pk_add_f32 v[8:9], v[8:9], v[26:27] neg_lo:[0,1] neg_hi:[0,1]
	v_pk_add_f32 v[26:27], v[10:11], v[28:29]
	v_pk_add_f32 v[10:11], v[10:11], v[28:29] neg_lo:[0,1] neg_hi:[0,1]
	v_pk_mul_f32 v[28:29], v[10:11], s[34:35]
	v_pk_fma_f32 v[10:11], v[10:11], s[0:1], v[28:29] op_sel:[0,0,1] op_sel_hi:[1,0,0] neg_lo:[1,0,0] neg_hi:[1,0,0]
	v_pk_add_f32 v[28:29], v[12:13], v[30:31]
	v_pk_add_f32 v[12:13], v[12:13], v[30:31] neg_lo:[0,1] neg_hi:[0,1]
	v_pk_mul_f32 v[30:31], v[12:13], s[10:11]
	v_pk_fma_f32 v[12:13], v[12:13], s[14:15], v[30:31] op_sel:[0,0,1] op_sel_hi:[1,0,0] neg_lo:[1,0,0] neg_hi:[1,0,0]
	v_pk_add_f32 v[30:31], v[14:15], v[24:25]
	v_pk_add_f32 v[14:15], v[14:15], v[24:25] neg_lo:[0,1] neg_hi:[0,1]
	v_pk_mul_f32 v[24:25], v[14:15], s[18:19]
	v_pk_fma_f32 v[14:15], v[14:15], s[30:31], v[24:25] op_sel:[0,0,1] op_sel_hi:[1,0,0] neg_lo:[1,0,0] neg_hi:[1,0,0]
	v_pk_add_f32 v[24:25], v[102:103], v[22:23]
	v_pk_add_f32 v[22:23], v[102:103], v[22:23] neg_lo:[0,1] neg_hi:[0,1]
	v_pk_add_f32 v[102:103], v[16:17], v[26:27]
	v_pk_add_f32 v[16:17], v[16:17], v[26:27] neg_lo:[0,1] neg_hi:[0,1]
	v_pk_mul_f32 v[26:27], v[16:17], s[10:11]
	v_pk_fma_f32 v[16:17], v[16:17], s[14:15], v[26:27] op_sel:[0,0,1] op_sel_hi:[1,0,0]
	v_pk_add_f32 v[26:27], v[18:19], v[28:29]
	v_pk_add_f32 v[18:19], v[18:19], v[28:29] neg_lo:[0,1] neg_hi:[0,1]
	v_pk_add_f32 v[28:29], v[20:21], v[30:31]
	v_pk_add_f32 v[20:21], v[20:21], v[30:31] neg_lo:[0,1] neg_hi:[0,1]
	v_pk_mul_f32 v[30:31], v[20:21], s[10:11]
	v_pk_fma_f32 v[20:21], v[20:21], s[14:15], v[30:31] op_sel:[0,0,1] op_sel_hi:[1,0,0] neg_lo:[1,0,0] neg_hi:[1,0,0]
	v_pk_add_f32 v[30:31], v[0:1], v[8:9] op_sel:[0,1] op_sel_hi:[1,0] neg_hi:[0,1]
	v_pk_add_f32 v[0:1], v[0:1], v[8:9] op_sel:[0,1] op_sel_hi:[1,0] neg_lo:[0,1]
	v_pk_add_f32 v[8:9], v[2:3], v[10:11]
	v_pk_add_f32 v[2:3], v[2:3], v[10:11] neg_lo:[0,1] neg_hi:[0,1]
	v_pk_mul_f32 v[10:11], v[2:3], s[10:11]
	v_pk_fma_f32 v[2:3], v[2:3], s[14:15], v[10:11] op_sel:[0,0,1] op_sel_hi:[1,0,0]
	v_pk_add_f32 v[10:11], v[4:5], v[12:13]
	v_pk_add_f32 v[4:5], v[4:5], v[12:13] neg_lo:[0,1] neg_hi:[0,1]
	v_pk_add_f32 v[12:13], v[6:7], v[14:15]
	v_pk_add_f32 v[6:7], v[6:7], v[14:15] neg_lo:[0,1] neg_hi:[0,1]
	v_pk_mul_f32 v[14:15], v[6:7], s[10:11]
	v_pk_fma_f32 v[6:7], v[6:7], s[14:15], v[14:15] op_sel:[0,0,1] op_sel_hi:[1,0,0] neg_lo:[1,0,0] neg_hi:[1,0,0]
	v_pk_add_f32 v[14:15], v[24:25], v[26:27]
	v_pk_add_f32 v[24:25], v[24:25], v[26:27] neg_lo:[0,1] neg_hi:[0,1]
	v_pk_add_f32 v[26:27], v[102:103], v[28:29]
	v_pk_add_f32 v[28:29], v[102:103], v[28:29] neg_lo:[0,1] neg_hi:[0,1]
	v_pk_add_f32 v[102:103], v[22:23], v[18:19] op_sel:[0,1] op_sel_hi:[1,0] neg_hi:[0,1]
	v_pk_add_f32 v[18:19], v[22:23], v[18:19] op_sel:[0,1] op_sel_hi:[1,0] neg_lo:[0,1]
	v_pk_add_f32 v[22:23], v[16:17], v[20:21]
	v_pk_add_f32 v[16:17], v[16:17], v[20:21] neg_lo:[0,1] neg_hi:[0,1]
	v_pk_add_f32 v[20:21], v[30:31], v[10:11]
	v_pk_add_f32 v[10:11], v[30:31], v[10:11] neg_lo:[0,1] neg_hi:[0,1]
	v_pk_add_f32 v[30:31], v[8:9], v[12:13]
	v_pk_add_f32 v[8:9], v[8:9], v[12:13] neg_lo:[0,1] neg_hi:[0,1]
	v_pk_add_f32 v[12:13], v[0:1], v[4:5] op_sel:[0,1] op_sel_hi:[1,0] neg_hi:[0,1]
	v_pk_add_f32 v[0:1], v[0:1], v[4:5] op_sel:[0,1] op_sel_hi:[1,0] neg_lo:[0,1]
	v_pk_add_f32 v[4:5], v[2:3], v[6:7]
	v_pk_add_f32 v[2:3], v[2:3], v[6:7] neg_lo:[0,1] neg_hi:[0,1]
	v_pk_mul_f32 v[2:3], v[2:3], s[22:23]
	v_pk_add_f32 v[6:7], v[14:15], v[26:27]
	v_pk_add_f32 v[14:15], v[14:15], v[26:27] neg_lo:[0,1] neg_hi:[0,1]
	v_pk_add_f32 v[26:27], v[24:25], v[28:29] op_sel:[0,1] op_sel_hi:[1,0] neg_hi:[0,1]
	v_pk_add_f32 v[24:25], v[24:25], v[28:29] op_sel:[0,1] op_sel_hi:[1,0] neg_lo:[0,1]
	v_pk_add_f32 v[28:29], v[102:103], v[22:23]
	v_pk_add_f32 v[22:23], v[102:103], v[22:23] neg_lo:[0,1] neg_hi:[0,1]
	v_pk_add_f32 v[102:103], v[18:19], v[16:17] op_sel:[0,1] op_sel_hi:[1,0] neg_hi:[0,1]
	v_pk_add_f32 v[16:17], v[18:19], v[16:17] op_sel:[0,1] op_sel_hi:[1,0] neg_lo:[0,1]
	v_pk_add_f32 v[18:19], v[20:21], v[30:31]
	v_pk_add_f32 v[20:21], v[20:21], v[30:31] neg_lo:[0,1] neg_hi:[0,1]
	v_pk_add_f32 v[30:31], v[10:11], v[8:9] op_sel:[0,1] op_sel_hi:[1,0] neg_hi:[0,1]
	v_pk_add_f32 v[8:9], v[10:11], v[8:9] op_sel:[0,1] op_sel_hi:[1,0] neg_lo:[0,1]
	v_pk_add_f32 v[10:11], v[12:13], v[4:5]
	v_pk_add_f32 v[4:5], v[12:13], v[4:5] neg_lo:[0,1] neg_hi:[0,1]
	v_pk_add_f32 v[12:13], v[0:1], v[2:3] op_sel:[0,1] op_sel_hi:[1,0]
	v_pk_add_f32 v[0:1], v[0:1], v[2:3] op_sel:[0,1] op_sel_hi:[1,0] neg_lo:[0,1] neg_hi:[0,1]
	v_lshlrev_b32_e32 v2, 4, v47
	v_and_or_b32 v2, v2, s7, v81
	v_ashrrev_i32_e32 v3, 4, v2
	v_lshlrev_b32_e32 v3, 3, v3
	v_lshlrev_b32_e32 v2, 3, v2
	v_add3_u32 v2, 0, v3, v2
	v_add_u32_e32 v3, 0x800, v2
	v_mov_b32_e32 v47, v32
	ds_write2_b64 v2, v[6:7], v[18:19] offset1:34
	ds_write2_b64 v3, v[14:15], v[20:21] offset0:16 offset1:50
	ds_write2_b64 v2, v[26:27], v[30:31] offset0:136 offset1:170
	ds_write2_b64 v3, v[24:25], v[8:9] offset0:152 offset1:186
	ds_write2_b64 v2, v[28:29], v[10:11] offset0:68 offset1:102
	ds_write2_b64 v3, v[22:23], v[4:5] offset0:84 offset1:118
	ds_write2_b64 v2, v[102:103], v[12:13] offset0:204 offset1:238
	ds_write2_b64 v3, v[16:17], v[0:1] offset0:220 offset1:254
	s_waitcnt lgkmcnt(0)
	s_barrier
	s_nop 0
	v_and_b32_e32 v81, 0x1ff, v47
	v_cvt_f32_u32_e32 v24, v81
	v_ashrrev_i32_e32 v0, 4, v47
	v_lshlrev_b32_e32 v0, 3, v0
	v_lshlrev_b32_e32 v1, 3, v47
	v_mul_f32_e32 v110, 0x39000000, v24
	v_sin_f32_e32 v24, v110
	v_cos_f32_e32 v110, v110
	v_add3_u32 v25, 0, v0, v1
	ds_read_b64 v[0:1], v25
	ds_read_b64 v[2:3], v25 offset:4352
	ds_read_b64 v[4:5], v25 offset:8704
	ds_read_b64 v[6:7], v25 offset:13056
	ds_read_b64 v[8:9], v25 offset:17408
	ds_read_b64 v[10:11], v25 offset:21760
	ds_read_b64 v[12:13], v25 offset:26112
	ds_read_b64 v[14:15], v25 offset:30464
	v_xor_b32_e32 v111, 0x80000000, v24
	s_waitcnt lgkmcnt(6)
	v_pk_mul_f32 v[118:119], v[2:3], v[24:25] op_sel:[1,0] op_sel_hi:[0,0] neg_hi:[0,1]
	v_pk_fma_f32 v[2:3], v[2:3], v[110:111], v[118:119] op_sel_hi:[1,0,1]
	v_pk_mul_f32 v[118:119], v[24:25], v[110:111] op_sel:[0,1] op_sel_hi:[0,0] neg_hi:[1,0]
	v_pk_fma_f32 v[118:119], v[110:111], v[110:111], v[118:119] op_sel_hi:[0,1,1]
	ds_read_b64 v[16:17], v25 offset:34816
	ds_read_b64 v[18:19], v25 offset:39168
	ds_read_b64 v[20:21], v25 offset:43520
	ds_read_b64 v[22:23], v25 offset:47872
	s_waitcnt lgkmcnt(9)
	v_pk_mul_f32 v[120:121], v[4:5], v[118:119] op_sel:[1,1] op_sel_hi:[0,1] neg_lo:[0,1]
	v_pk_fma_f32 v[4:5], v[4:5], v[118:119], v[120:121] op_sel_hi:[1,0,1]
	v_pk_mul_f32 v[120:121], v[24:25], v[118:119] op_sel:[0,1] op_sel_hi:[0,0] neg_hi:[1,0]
	v_pk_fma_f32 v[118:119], v[110:111], v[118:119], v[120:121] op_sel_hi:[0,1,1]
	ds_read_b64 v[26:27], v25 offset:52224
	ds_read_b64 v[28:29], v25 offset:56576
	ds_read_b64 v[30:31], v25 offset:60928
	ds_read_b64 v[102:103], v25 offset:65280
	s_waitcnt lgkmcnt(12)
	v_pk_mul_f32 v[120:121], v[6:7], v[118:119] op_sel:[1,1] op_sel_hi:[0,1] neg_lo:[0,1]
	v_pk_fma_f32 v[6:7], v[6:7], v[118:119], v[120:121] op_sel_hi:[1,0,1]
	v_pk_mul_f32 v[120:121], v[24:25], v[118:119] op_sel:[0,1] op_sel_hi:[0,0] neg_hi:[1,0]
	v_pk_fma_f32 v[118:119], v[110:111], v[118:119], v[120:121] op_sel_hi:[0,1,1]
	s_waitcnt lgkmcnt(0)
	v_pk_mul_f32 v[120:121], v[8:9], v[118:119] op_sel:[1,1] op_sel_hi:[0,1] neg_lo:[0,1]
	v_pk_fma_f32 v[8:9], v[8:9], v[118:119], v[120:121] op_sel_hi:[1,0,1]
	v_pk_mul_f32 v[120:121], v[24:25], v[118:119] op_sel:[0,1] op_sel_hi:[0,0] neg_hi:[1,0]
	v_pk_fma_f32 v[118:119], v[110:111], v[118:119], v[120:121] op_sel_hi:[0,1,1]
	s_barrier
	v_pk_mul_f32 v[120:121], v[10:11], v[118:119] op_sel:[1,1] op_sel_hi:[0,1] neg_lo:[0,1]
	v_pk_fma_f32 v[10:11], v[10:11], v[118:119], v[120:121] op_sel_hi:[1,0,1]
	v_pk_mul_f32 v[120:121], v[24:25], v[118:119] op_sel:[0,1] op_sel_hi:[0,0] neg_hi:[1,0]
	v_pk_fma_f32 v[118:119], v[110:111], v[118:119], v[120:121] op_sel_hi:[0,1,1]
	v_pk_mul_f32 v[120:121], v[12:13], v[118:119] op_sel:[1,1] op_sel_hi:[0,1] neg_lo:[0,1]
	v_pk_fma_f32 v[12:13], v[12:13], v[118:119], v[120:121] op_sel_hi:[1,0,1]
	v_pk_mul_f32 v[120:121], v[24:25], v[118:119] op_sel:[0,1] op_sel_hi:[0,0] neg_hi:[1,0]
	v_pk_fma_f32 v[118:119], v[110:111], v[118:119], v[120:121] op_sel_hi:[0,1,1]
	v_pk_mul_f32 v[120:121], v[14:15], v[118:119] op_sel:[1,1] op_sel_hi:[0,1] neg_lo:[0,1]
	v_pk_fma_f32 v[14:15], v[14:15], v[118:119], v[120:121] op_sel_hi:[1,0,1]
	v_pk_mul_f32 v[120:121], v[24:25], v[118:119] op_sel:[0,1] op_sel_hi:[0,0] neg_hi:[1,0]
	v_pk_fma_f32 v[118:119], v[110:111], v[118:119], v[120:121] op_sel_hi:[0,1,1]
	v_pk_mul_f32 v[120:121], v[16:17], v[118:119] op_sel:[1,1] op_sel_hi:[0,1] neg_lo:[0,1]
	v_pk_fma_f32 v[16:17], v[16:17], v[118:119], v[120:121] op_sel_hi:[1,0,1]
	v_pk_mul_f32 v[120:121], v[24:25], v[118:119] op_sel:[0,1] op_sel_hi:[0,0] neg_hi:[1,0]
	v_pk_fma_f32 v[118:119], v[110:111], v[118:119], v[120:121] op_sel_hi:[0,1,1]
	v_pk_mul_f32 v[120:121], v[18:19], v[118:119] op_sel:[1,1] op_sel_hi:[0,1] neg_lo:[0,1]
	v_pk_fma_f32 v[18:19], v[18:19], v[118:119], v[120:121] op_sel_hi:[1,0,1]
	v_pk_mul_f32 v[120:121], v[24:25], v[118:119] op_sel:[0,1] op_sel_hi:[0,0] neg_hi:[1,0]
	v_pk_fma_f32 v[118:119], v[110:111], v[118:119], v[120:121] op_sel_hi:[0,1,1]
	v_pk_mul_f32 v[120:121], v[20:21], v[118:119] op_sel:[1,1] op_sel_hi:[0,1] neg_lo:[0,1]
	v_pk_fma_f32 v[20:21], v[20:21], v[118:119], v[120:121] op_sel_hi:[1,0,1]
	v_pk_mul_f32 v[120:121], v[24:25], v[118:119] op_sel:[0,1] op_sel_hi:[0,0] neg_hi:[1,0]
	v_pk_fma_f32 v[118:119], v[110:111], v[118:119], v[120:121] op_sel_hi:[0,1,1]
	v_pk_mul_f32 v[120:121], v[22:23], v[118:119] op_sel:[1,1] op_sel_hi:[0,1] neg_lo:[0,1]
	v_pk_fma_f32 v[22:23], v[22:23], v[118:119], v[120:121] op_sel_hi:[1,0,1]
	v_pk_mul_f32 v[120:121], v[24:25], v[118:119] op_sel:[0,1] op_sel_hi:[0,0] neg_hi:[1,0]
	v_pk_fma_f32 v[118:119], v[110:111], v[118:119], v[120:121] op_sel_hi:[0,1,1]
	v_pk_mul_f32 v[120:121], v[26:27], v[118:119] op_sel:[1,1] op_sel_hi:[0,1] neg_lo:[0,1]
	v_pk_fma_f32 v[26:27], v[26:27], v[118:119], v[120:121] op_sel_hi:[1,0,1]
	v_pk_mul_f32 v[120:121], v[24:25], v[118:119] op_sel:[0,1] op_sel_hi:[0,0] neg_hi:[1,0]
	v_pk_fma_f32 v[118:119], v[110:111], v[118:119], v[120:121] op_sel_hi:[0,1,1]
	v_pk_mul_f32 v[120:121], v[28:29], v[118:119] op_sel:[1,1] op_sel_hi:[0,1] neg_lo:[0,1]
	v_pk_fma_f32 v[28:29], v[28:29], v[118:119], v[120:121] op_sel_hi:[1,0,1]
	v_pk_mul_f32 v[120:121], v[24:25], v[118:119] op_sel:[0,1] op_sel_hi:[0,0] neg_hi:[1,0]
	v_pk_fma_f32 v[118:119], v[110:111], v[118:119], v[120:121] op_sel_hi:[0,1,1]
	v_pk_mul_f32 v[24:25], v[24:25], v[118:119] op_sel:[0,1] op_sel_hi:[0,0] neg_hi:[1,0]
	v_pk_fma_f32 v[24:25], v[110:111], v[118:119], v[24:25] op_sel_hi:[0,1,1]
	v_pk_mul_f32 v[110:111], v[102:103], v[24:25] op_sel:[1,1] op_sel_hi:[0,1] neg_lo:[0,1]
	v_pk_fma_f32 v[24:25], v[102:103], v[24:25], v[110:111] op_sel_hi:[1,0,1]
	v_pk_add_f32 v[102:103], v[0:1], v[16:17]
	v_pk_add_f32 v[0:1], v[0:1], v[16:17] neg_lo:[0,1] neg_hi:[0,1]
	v_pk_add_f32 v[16:17], v[2:3], v[18:19]
	v_pk_add_f32 v[2:3], v[2:3], v[18:19] neg_lo:[0,1] neg_hi:[0,1]
	v_pk_mul_f32 v[120:121], v[30:31], v[118:119] op_sel:[1,1] op_sel_hi:[0,1] neg_lo:[0,1]
	v_pk_mul_f32 v[18:19], v[2:3], s[18:19]
	v_pk_fma_f32 v[30:31], v[30:31], v[118:119], v[120:121] op_sel_hi:[1,0,1]
	v_pk_fma_f32 v[2:3], v[2:3], s[30:31], v[18:19] op_sel:[0,0,1] op_sel_hi:[1,0,0]
	v_pk_add_f32 v[18:19], v[4:5], v[20:21]
	v_pk_add_f32 v[4:5], v[4:5], v[20:21] neg_lo:[0,1] neg_hi:[0,1]
	v_pk_mul_f32 v[20:21], v[4:5], s[10:11]
	v_pk_fma_f32 v[4:5], v[4:5], s[14:15], v[20:21] op_sel:[0,0,1] op_sel_hi:[1,0,0]
	v_pk_add_f32 v[20:21], v[6:7], v[22:23]
	v_pk_add_f32 v[6:7], v[6:7], v[22:23] neg_lo:[0,1] neg_hi:[0,1]
	v_pk_mul_f32 v[22:23], v[6:7], s[34:35]
	v_pk_fma_f32 v[6:7], v[6:7], s[0:1], v[22:23] op_sel:[0,0,1] op_sel_hi:[1,0,0]
	v_pk_add_f32 v[22:23], v[8:9], v[26:27]
	v_pk_add_f32 v[8:9], v[8:9], v[26:27] neg_lo:[0,1] neg_hi:[0,1]
	v_pk_add_f32 v[26:27], v[10:11], v[28:29]
	v_pk_add_f32 v[10:11], v[10:11], v[28:29] neg_lo:[0,1] neg_hi:[0,1]
	v_pk_mul_f32 v[28:29], v[10:11], s[34:35]
	v_pk_fma_f32 v[10:11], v[10:11], s[0:1], v[28:29] op_sel:[0,0,1] op_sel_hi:[1,0,0] neg_lo:[1,0,0] neg_hi:[1,0,0]
	v_pk_add_f32 v[28:29], v[12:13], v[30:31]
	v_pk_add_f32 v[12:13], v[12:13], v[30:31] neg_lo:[0,1] neg_hi:[0,1]
	v_pk_mul_f32 v[30:31], v[12:13], s[10:11]
	v_pk_fma_f32 v[12:13], v[12:13], s[14:15], v[30:31] op_sel:[0,0,1] op_sel_hi:[1,0,0] neg_lo:[1,0,0] neg_hi:[1,0,0]
	v_pk_add_f32 v[30:31], v[14:15], v[24:25]
	v_pk_add_f32 v[14:15], v[14:15], v[24:25] neg_lo:[0,1] neg_hi:[0,1]
	v_pk_mul_f32 v[24:25], v[14:15], s[18:19]
	v_pk_fma_f32 v[14:15], v[14:15], s[30:31], v[24:25] op_sel:[0,0,1] op_sel_hi:[1,0,0] neg_lo:[1,0,0] neg_hi:[1,0,0]
	v_pk_add_f32 v[24:25], v[102:103], v[22:23]
	v_pk_add_f32 v[22:23], v[102:103], v[22:23] neg_lo:[0,1] neg_hi:[0,1]
	v_pk_add_f32 v[102:103], v[16:17], v[26:27]
	v_pk_add_f32 v[16:17], v[16:17], v[26:27] neg_lo:[0,1] neg_hi:[0,1]
	v_pk_mul_f32 v[26:27], v[16:17], s[10:11]
	v_pk_fma_f32 v[16:17], v[16:17], s[14:15], v[26:27] op_sel:[0,0,1] op_sel_hi:[1,0,0]
	v_pk_add_f32 v[26:27], v[18:19], v[28:29]
	v_pk_add_f32 v[18:19], v[18:19], v[28:29] neg_lo:[0,1] neg_hi:[0,1]
	v_pk_add_f32 v[28:29], v[20:21], v[30:31]
	v_pk_add_f32 v[20:21], v[20:21], v[30:31] neg_lo:[0,1] neg_hi:[0,1]
	v_pk_mul_f32 v[30:31], v[20:21], s[10:11]
	v_pk_fma_f32 v[20:21], v[20:21], s[14:15], v[30:31] op_sel:[0,0,1] op_sel_hi:[1,0,0] neg_lo:[1,0,0] neg_hi:[1,0,0]
	v_pk_add_f32 v[30:31], v[0:1], v[8:9] op_sel:[0,1] op_sel_hi:[1,0] neg_hi:[0,1]
	v_pk_add_f32 v[0:1], v[0:1], v[8:9] op_sel:[0,1] op_sel_hi:[1,0] neg_lo:[0,1]
	v_pk_add_f32 v[8:9], v[2:3], v[10:11]
	v_pk_add_f32 v[2:3], v[2:3], v[10:11] neg_lo:[0,1] neg_hi:[0,1]
	v_pk_mul_f32 v[10:11], v[2:3], s[10:11]
	v_pk_fma_f32 v[2:3], v[2:3], s[14:15], v[10:11] op_sel:[0,0,1] op_sel_hi:[1,0,0]
	v_pk_add_f32 v[10:11], v[4:5], v[12:13]
	v_pk_add_f32 v[4:5], v[4:5], v[12:13] neg_lo:[0,1] neg_hi:[0,1]
	v_pk_add_f32 v[12:13], v[6:7], v[14:15]
	v_pk_add_f32 v[6:7], v[6:7], v[14:15] neg_lo:[0,1] neg_hi:[0,1]
	v_pk_mul_f32 v[14:15], v[6:7], s[10:11]
	v_pk_fma_f32 v[6:7], v[6:7], s[14:15], v[14:15] op_sel:[0,0,1] op_sel_hi:[1,0,0] neg_lo:[1,0,0] neg_hi:[1,0,0]
	v_pk_add_f32 v[14:15], v[24:25], v[26:27]
	v_pk_add_f32 v[24:25], v[24:25], v[26:27] neg_lo:[0,1] neg_hi:[0,1]
	v_pk_add_f32 v[26:27], v[102:103], v[28:29]
	v_pk_add_f32 v[28:29], v[102:103], v[28:29] neg_lo:[0,1] neg_hi:[0,1]
	v_pk_add_f32 v[102:103], v[22:23], v[18:19] op_sel:[0,1] op_sel_hi:[1,0] neg_hi:[0,1]
	v_pk_add_f32 v[18:19], v[22:23], v[18:19] op_sel:[0,1] op_sel_hi:[1,0] neg_lo:[0,1]
	v_pk_add_f32 v[22:23], v[16:17], v[20:21]
	v_pk_add_f32 v[16:17], v[16:17], v[20:21] neg_lo:[0,1] neg_hi:[0,1]
	v_pk_add_f32 v[20:21], v[30:31], v[10:11]
	v_pk_add_f32 v[10:11], v[30:31], v[10:11] neg_lo:[0,1] neg_hi:[0,1]
	v_pk_add_f32 v[30:31], v[8:9], v[12:13]
	v_pk_add_f32 v[8:9], v[8:9], v[12:13] neg_lo:[0,1] neg_hi:[0,1]
	v_pk_add_f32 v[12:13], v[0:1], v[4:5] op_sel:[0,1] op_sel_hi:[1,0] neg_hi:[0,1]
	v_pk_add_f32 v[0:1], v[0:1], v[4:5] op_sel:[0,1] op_sel_hi:[1,0] neg_lo:[0,1]
	v_pk_add_f32 v[4:5], v[2:3], v[6:7]
	v_pk_add_f32 v[2:3], v[2:3], v[6:7] neg_lo:[0,1] neg_hi:[0,1]
	v_pk_mul_f32 v[2:3], v[2:3], s[22:23]
	v_pk_add_f32 v[6:7], v[14:15], v[26:27]
	v_pk_add_f32 v[14:15], v[14:15], v[26:27] neg_lo:[0,1] neg_hi:[0,1]
	v_pk_add_f32 v[26:27], v[24:25], v[28:29] op_sel:[0,1] op_sel_hi:[1,0] neg_hi:[0,1]
	v_pk_add_f32 v[24:25], v[24:25], v[28:29] op_sel:[0,1] op_sel_hi:[1,0] neg_lo:[0,1]
	v_pk_add_f32 v[28:29], v[102:103], v[22:23]
	v_pk_add_f32 v[22:23], v[102:103], v[22:23] neg_lo:[0,1] neg_hi:[0,1]
	v_pk_add_f32 v[102:103], v[18:19], v[16:17] op_sel:[0,1] op_sel_hi:[1,0] neg_hi:[0,1]
	v_pk_add_f32 v[16:17], v[18:19], v[16:17] op_sel:[0,1] op_sel_hi:[1,0] neg_lo:[0,1]
	v_pk_add_f32 v[18:19], v[20:21], v[30:31]
	v_pk_add_f32 v[20:21], v[20:21], v[30:31] neg_lo:[0,1] neg_hi:[0,1]
	v_pk_add_f32 v[30:31], v[10:11], v[8:9] op_sel:[0,1] op_sel_hi:[1,0] neg_hi:[0,1]
	v_pk_add_f32 v[8:9], v[10:11], v[8:9] op_sel:[0,1] op_sel_hi:[1,0] neg_lo:[0,1]
	v_pk_add_f32 v[10:11], v[12:13], v[4:5]
	v_pk_add_f32 v[4:5], v[12:13], v[4:5] neg_lo:[0,1] neg_hi:[0,1]
	v_pk_add_f32 v[12:13], v[0:1], v[2:3] op_sel:[0,1] op_sel_hi:[1,0]
	v_pk_add_f32 v[0:1], v[0:1], v[2:3] op_sel:[0,1] op_sel_hi:[1,0] neg_lo:[0,1] neg_hi:[0,1]
	v_lshlrev_b32_e32 v2, 4, v47
	v_and_or_b32 v2, v2, s15, v81
	v_ashrrev_i32_e32 v3, 4, v2
	v_lshlrev_b32_e32 v3, 3, v3
	v_lshlrev_b32_e32 v2, 3, v2
	v_add3_u32 v2, 0, v3, v2
	ds_write_b64 v2, v[6:7]
	ds_write_b64 v2, v[14:15] offset:34816
	ds_write_b64 v2, v[26:27] offset:17408
	ds_write_b64 v2, v[24:25] offset:52224
	ds_write_b64 v2, v[28:29] offset:8704
	ds_write_b64 v2, v[22:23] offset:43520
	ds_write_b64 v2, v[102:103] offset:26112
	ds_write_b64 v2, v[16:17] offset:60928
	ds_write_b64 v2, v[18:19] offset:4352
	ds_write_b64 v2, v[20:21] offset:39168
	ds_write_b64 v2, v[30:31] offset:21760
	ds_write_b64 v2, v[8:9] offset:56576
	ds_write_b64 v2, v[10:11] offset:13056
	ds_write_b64 v2, v[4:5] offset:47872
	ds_write_b64 v2, v[12:13] offset:30464
	ds_write_b64 v2, v[0:1] offset:65280
	s_waitcnt lgkmcnt(0)
	s_barrier
	s_and_saveexec_b64 s[0:1], s[42:43]
	s_cbranch_execz .LBB0_448
	v_lshl_add_u64 v[2:3], v[78:79], 0, v[172:173]
	s_mov_b64 s[4:5], 0x40000
	v_lshl_add_u64 v[0:1], v[2:3], 0, s[4:5]
	v_add_co_u32_e32 v2, vcc, 0x40000, v2
	v_cmp_ne_u32_e64 s[44:45], 0, v39
	s_nop 0
	v_addc_co_u32_e32 v3, vcc, 0, v3, vcc
	global_load_dwordx4 v[12:15], v[2:3], off
	global_load_dwordx4 v[8:11], v[0:1], off offset:16
	v_mov_b32_e32 v19, 0
	v_mov_b32_e32 v18, 0
	s_and_saveexec_b64 s[4:5], s[44:45]
	s_cbranch_execz .LBB0_441
	global_load_ushort v2, v[0:1], off offset:-2
	s_waitcnt vmcnt(0)
	v_lshlrev_b32_e32 v18, 16, v2

.LBB0_480:
	s_or_b64 exec, exec, s[0:1]
	s_barrier
	ds_write2_b64 v152, v[110:111], v[102:103] offset1:1
	ds_write2_b64 v152, v[94:95], v[88:89] offset0:2 offset1:3
	ds_write2_b64 v152, v[112:113], v[104:105] offset0:4 offset1:5
	ds_write2_b64 v152, v[96:97], v[90:91] offset0:6 offset1:7
	ds_write2_b64 v152, v[114:115], v[106:107] offset0:8 offset1:9
	ds_write2_b64 v152, v[98:99], v[92:93] offset0:10 offset1:11
	ds_write2_b64 v152, v[116:117], v[108:109] offset0:12 offset1:13
	ds_write2_b64 v152, v[100:101], v[86:87] offset0:14 offset1:15
	s_waitcnt lgkmcnt(0)
	s_barrier
	s_and_saveexec_b64 s[0:1], s[40:41]
	s_cbranch_execz .LBB0_482
	ds_read_b64 v[0:1], v37 offset:2176
	ds_read_b64 v[2:3], v37 offset:4352
	ds_read_b64 v[4:5], v37 offset:6528
	ds_read_b64 v[6:7], v37 offset:8704
	ds_read_b64 v[8:9], v37 offset:10880
	ds_read_b64 v[10:11], v37 offset:13056
	ds_read_b64 v[12:13], v37 offset:15232
	ds_read_b64 v[14:15], v37 offset:17408
	ds_read_b64 v[16:17], v37 offset:19584
	ds_read_b64 v[18:19], v37 offset:21760
	ds_read_b64 v[20:21], v37 offset:23936
	ds_read_b64 v[22:23], v37 offset:26112
	ds_read_b64 v[24:25], v37 offset:34816
	ds_read_b64 v[26:27], v37 offset:36992
	ds_read_b64 v[28:29], v37 offset:39168
	ds_read_b64 v[30:31], v37 offset:41344
	ds_read_b64 v[82:83], v37 offset:43520
	ds_read_b64 v[84:85], v37 offset:45696
	ds_read_b64 v[118:119], v37 offset:47872
	ds_read_b64 v[120:121], v37 offset:50048
	ds_read_b64 v[122:123], v37 offset:52224
	ds_read_b64 v[124:125], v37 offset:54400
	ds_read_b64 v[126:127], v37 offset:56576
	ds_read_b64 v[128:129], v37 offset:58752
	ds_read_b64 v[130:131], v37
	ds_read_b64 v[132:133], v37 offset:60928
	ds_read_b64 v[134:135], v37 offset:63104
	ds_read_b64 v[136:137], v37 offset:65280
	s_mov_b32 s11, s14
	s_waitcnt lgkmcnt(3)
	v_pk_add_f32 v[158:159], v[130:131], v[24:25]
	v_pk_add_f32 v[24:25], v[130:131], v[24:25] neg_lo:[0,1] neg_hi:[0,1]
	v_pk_add_f32 v[130:131], v[0:1], v[26:27]
	v_pk_add_f32 v[0:1], v[0:1], v[26:27] neg_lo:[0,1] neg_hi:[0,1]
	s_mov_b32 s13, s86
	v_pk_mul_f32 v[26:27], v[0:1], s[16:17]
	s_mov_b32 s4, s21
	v_pk_fma_f32 v[0:1], v[0:1], s[6:7], v[26:27] op_sel:[0,0,1] op_sel_hi:[1,0,0]
	v_pk_add_f32 v[26:27], v[2:3], v[28:29]
	v_pk_add_f32 v[2:3], v[2:3], v[28:29] neg_lo:[0,1] neg_hi:[0,1]
	s_mov_b32 s35, s30
	v_pk_mul_f32 v[28:29], v[2:3], s[18:19]
	s_mov_b32 s8, s19
	v_pk_fma_f32 v[2:3], v[2:3], s[30:31], v[28:29] op_sel:[0,0,1] op_sel_hi:[1,0,0]
	v_pk_add_f32 v[28:29], v[4:5], v[30:31]
	v_pk_add_f32 v[4:5], v[4:5], v[30:31] neg_lo:[0,1] neg_hi:[0,1]
	s_mov_b32 s77, s6
	v_pk_mul_f32 v[30:31], v[4:5], s[20:21]
	s_mov_b32 s28, s17
	v_pk_fma_f32 v[4:5], v[4:5], s[86:87], v[30:31] op_sel:[0,0,1] op_sel_hi:[1,0,0]
	v_pk_add_f32 v[30:31], v[6:7], v[82:83]
	v_pk_add_f32 v[6:7], v[6:7], v[82:83] neg_lo:[0,1] neg_hi:[0,1]
	v_add_u32_e32 v47, 0x10780, v37
	v_pk_mul_f32 v[82:83], v[6:7], s[10:11]
	ds_read_b64 v[138:139], v37 offset:28288
	ds_read_b64 v[140:141], v37 offset:30464
	ds_read_b64 v[142:143], v37 offset:32640
	ds_read_b64 v[144:145], v47
	v_pk_fma_f32 v[6:7], v[6:7], s[14:15], v[82:83] op_sel:[0,0,1] op_sel_hi:[1,0,0]
	v_pk_add_f32 v[82:83], v[8:9], v[84:85]
	v_pk_add_f32 v[8:9], v[8:9], v[84:85] neg_lo:[0,1] neg_hi:[0,1]
	v_pk_mul_f32 v[84:85], v[8:9], s[12:13]
	v_pk_fma_f32 v[8:9], v[8:9], s[4:5], v[84:85] op_sel:[0,0,1] op_sel_hi:[1,0,0]
	v_pk_add_f32 v[84:85], v[10:11], v[118:119]
	v_pk_add_f32 v[10:11], v[10:11], v[118:119] neg_lo:[0,1] neg_hi:[0,1]
	v_pk_mul_f32 v[118:119], v[10:11], s[34:35]
	v_pk_fma_f32 v[10:11], v[10:11], s[8:9], v[118:119] op_sel:[0,0,1] op_sel_hi:[1,0,0]
	v_pk_add_f32 v[118:119], v[12:13], v[120:121]
	v_pk_add_f32 v[12:13], v[12:13], v[120:121] neg_lo:[0,1] neg_hi:[0,1]
	v_pk_mul_f32 v[120:121], v[12:13], s[76:77]
	v_pk_fma_f32 v[12:13], v[12:13], s[28:29], v[120:121] op_sel:[0,0,1] op_sel_hi:[1,0,0]
	v_pk_add_f32 v[120:121], v[14:15], v[122:123]
	v_pk_add_f32 v[14:15], v[14:15], v[122:123] neg_lo:[0,1] neg_hi:[0,1]
	v_pk_add_f32 v[122:123], v[16:17], v[124:125]
	v_pk_add_f32 v[16:17], v[16:17], v[124:125] neg_lo:[0,1] neg_hi:[0,1]
	v_pk_mul_f32 v[124:125], v[16:17], s[76:77]
	v_pk_fma_f32 v[16:17], v[16:17], s[28:29], v[124:125] op_sel:[0,0,1] op_sel_hi:[1,0,0] neg_lo:[1,0,0] neg_hi:[1,0,0]
	v_pk_add_f32 v[124:125], v[18:19], v[126:127]
	v_pk_add_f32 v[18:19], v[18:19], v[126:127] neg_lo:[0,1] neg_hi:[0,1]
	v_pk_mul_f32 v[126:127], v[18:19], s[34:35]
	v_pk_fma_f32 v[18:19], v[18:19], s[8:9], v[126:127] op_sel:[0,0,1] op_sel_hi:[1,0,0] neg_lo:[1,0,0] neg_hi:[1,0,0]
	v_pk_add_f32 v[126:127], v[20:21], v[128:129]
	v_pk_add_f32 v[20:21], v[20:21], v[128:129] neg_lo:[0,1] neg_hi:[0,1]
	v_pk_mul_f32 v[128:129], v[20:21], s[12:13]
	v_pk_fma_f32 v[20:21], v[20:21], s[4:5], v[128:129] op_sel:[0,0,1] op_sel_hi:[1,0,0] neg_lo:[1,0,0] neg_hi:[1,0,0]
	s_waitcnt lgkmcnt(6)
	v_pk_add_f32 v[128:129], v[22:23], v[132:133]
	v_pk_add_f32 v[22:23], v[22:23], v[132:133] neg_lo:[0,1] neg_hi:[0,1]
	s_nop 0
	v_pk_mul_f32 v[132:133], v[22:23], s[10:11]
	v_pk_fma_f32 v[22:23], v[22:23], s[14:15], v[132:133] op_sel:[0,0,1] op_sel_hi:[1,0,0] neg_lo:[1,0,0] neg_hi:[1,0,0]
	s_waitcnt lgkmcnt(3)
	v_pk_add_f32 v[132:133], v[138:139], v[134:135]
	v_pk_add_f32 v[134:135], v[138:139], v[134:135] neg_lo:[0,1] neg_hi:[0,1]
	s_nop 0
	v_pk_mul_f32 v[138:139], v[134:135], s[20:21]
	v_pk_fma_f32 v[134:135], v[134:135], s[86:87], v[138:139] op_sel:[0,0,1] op_sel_hi:[1,0,0] neg_lo:[1,0,0] neg_hi:[1,0,0]
	s_waitcnt lgkmcnt(2)
	v_pk_add_f32 v[138:139], v[140:141], v[136:137]
	v_pk_add_f32 v[136:137], v[140:141], v[136:137] neg_lo:[0,1] neg_hi:[0,1]
	s_nop 0
	v_pk_mul_f32 v[140:141], v[136:137], s[18:19]
	v_pk_fma_f32 v[136:137], v[136:137], s[30:31], v[140:141] op_sel:[0,0,1] op_sel_hi:[1,0,0] neg_lo:[1,0,0] neg_hi:[1,0,0]
	s_waitcnt lgkmcnt(0)
	v_pk_add_f32 v[140:141], v[142:143], v[144:145]
	v_pk_add_f32 v[142:143], v[142:143], v[144:145] neg_lo:[0,1] neg_hi:[0,1]
	s_nop 0
	v_pk_mul_f32 v[144:145], v[142:143], s[16:17]
	v_pk_fma_f32 v[142:143], v[142:143], s[6:7], v[144:145] op_sel:[0,0,1] op_sel_hi:[1,0,0] neg_lo:[1,0,0] neg_hi:[1,0,0]
	v_pk_add_f32 v[144:145], v[158:159], v[120:121]
	v_pk_add_f32 v[120:121], v[158:159], v[120:121] neg_lo:[0,1] neg_hi:[0,1]
	v_pk_add_f32 v[158:159], v[130:131], v[122:123]
	v_pk_add_f32 v[122:123], v[130:131], v[122:123] neg_lo:[0,1] neg_hi:[0,1]
	v_pk_mul_f32 v[130:131], v[122:123], s[18:19]
	v_pk_fma_f32 v[122:123], v[122:123], s[30:31], v[130:131] op_sel:[0,0,1] op_sel_hi:[1,0,0]
	v_pk_add_f32 v[130:131], v[26:27], v[124:125]
	v_pk_add_f32 v[26:27], v[26:27], v[124:125] neg_lo:[0,1] neg_hi:[0,1]
	v_pk_mul_f32 v[124:125], v[26:27], s[10:11]
	v_pk_fma_f32 v[26:27], v[26:27], s[14:15], v[124:125] op_sel:[0,0,1] op_sel_hi:[1,0,0]
	v_pk_add_f32 v[124:125], v[28:29], v[126:127]
	v_pk_add_f32 v[28:29], v[28:29], v[126:127] neg_lo:[0,1] neg_hi:[0,1]
	v_pk_mul_f32 v[126:127], v[28:29], s[34:35]
	v_pk_fma_f32 v[28:29], v[28:29], s[8:9], v[126:127] op_sel:[0,0,1] op_sel_hi:[1,0,0]
	v_pk_add_f32 v[126:127], v[30:31], v[128:129]
	v_pk_add_f32 v[30:31], v[30:31], v[128:129] neg_lo:[0,1] neg_hi:[0,1]
	v_pk_add_f32 v[128:129], v[82:83], v[132:133]
	v_pk_add_f32 v[82:83], v[82:83], v[132:133] neg_lo:[0,1] neg_hi:[0,1]
	v_pk_mul_f32 v[132:133], v[82:83], s[34:35]
	v_pk_fma_f32 v[82:83], v[82:83], s[8:9], v[132:133] op_sel:[0,0,1] op_sel_hi:[1,0,0] neg_lo:[1,0,0] neg_hi:[1,0,0]
	v_pk_add_f32 v[132:133], v[84:85], v[138:139]
	v_pk_add_f32 v[84:85], v[84:85], v[138:139] neg_lo:[0,1] neg_hi:[0,1]
	v_pk_mul_f32 v[138:139], v[84:85], s[10:11]
	v_pk_fma_f32 v[84:85], v[84:85], s[14:15], v[138:139] op_sel:[0,0,1] op_sel_hi:[1,0,0] neg_lo:[1,0,0] neg_hi:[1,0,0]
	v_pk_add_f32 v[138:139], v[118:119], v[140:141]
	v_pk_add_f32 v[118:119], v[118:119], v[140:141] neg_lo:[0,1] neg_hi:[0,1]
	v_pk_mul_f32 v[140:141], v[118:119], s[18:19]
	v_pk_fma_f32 v[118:119], v[118:119], s[30:31], v[140:141] op_sel:[0,0,1] op_sel_hi:[1,0,0] neg_lo:[1,0,0] neg_hi:[1,0,0]
	v_pk_add_f32 v[140:141], v[24:25], v[14:15] op_sel:[0,1] op_sel_hi:[1,0] neg_hi:[0,1]
	v_pk_add_f32 v[14:15], v[24:25], v[14:15] op_sel:[0,1] op_sel_hi:[1,0] neg_lo:[0,1]
	v_pk_add_f32 v[24:25], v[0:1], v[16:17]
	v_pk_add_f32 v[0:1], v[0:1], v[16:17] neg_lo:[0,1] neg_hi:[0,1]
	v_pk_mul_f32 v[16:17], v[0:1], s[18:19]
	v_pk_fma_f32 v[0:1], v[0:1], s[30:31], v[16:17] op_sel:[0,0,1] op_sel_hi:[1,0,0]
	v_pk_add_f32 v[16:17], v[2:3], v[18:19]
	v_pk_add_f32 v[2:3], v[2:3], v[18:19] neg_lo:[0,1] neg_hi:[0,1]
	v_pk_mul_f32 v[18:19], v[2:3], s[10:11]
	v_pk_fma_f32 v[2:3], v[2:3], s[14:15], v[18:19] op_sel:[0,0,1] op_sel_hi:[1,0,0]
	v_pk_add_f32 v[18:19], v[4:5], v[20:21]
	v_pk_add_f32 v[4:5], v[4:5], v[20:21] neg_lo:[0,1] neg_hi:[0,1]
	v_pk_mul_f32 v[20:21], v[4:5], s[34:35]
	v_pk_fma_f32 v[4:5], v[4:5], s[8:9], v[20:21] op_sel:[0,0,1] op_sel_hi:[1,0,0]
	v_pk_add_f32 v[20:21], v[6:7], v[22:23]
	v_pk_add_f32 v[6:7], v[6:7], v[22:23] neg_lo:[0,1] neg_hi:[0,1]
	v_pk_add_f32 v[22:23], v[8:9], v[134:135]
	v_pk_add_f32 v[8:9], v[8:9], v[134:135] neg_lo:[0,1] neg_hi:[0,1]
	v_pk_mul_f32 v[134:135], v[8:9], s[34:35]
	v_pk_fma_f32 v[8:9], v[8:9], s[8:9], v[134:135] op_sel:[0,0,1] op_sel_hi:[1,0,0] neg_lo:[1,0,0] neg_hi:[1,0,0]
	v_pk_add_f32 v[134:135], v[10:11], v[136:137]
	v_pk_add_f32 v[10:11], v[10:11], v[136:137] neg_lo:[0,1] neg_hi:[0,1]
	v_pk_mul_f32 v[136:137], v[10:11], s[10:11]
	v_pk_fma_f32 v[10:11], v[10:11], s[14:15], v[136:137] op_sel:[0,0,1] op_sel_hi:[1,0,0] neg_lo:[1,0,0] neg_hi:[1,0,0]
	v_pk_add_f32 v[136:137], v[12:13], v[142:143]
	v_pk_add_f32 v[12:13], v[12:13], v[142:143] neg_lo:[0,1] neg_hi:[0,1]
	v_pk_mul_f32 v[142:143], v[12:13], s[18:19]
	v_pk_fma_f32 v[12:13], v[12:13], s[30:31], v[142:143] op_sel:[0,0,1] op_sel_hi:[1,0,0] neg_lo:[1,0,0] neg_hi:[1,0,0]
	v_pk_add_f32 v[142:143], v[144:145], v[126:127]
	v_pk_add_f32 v[126:127], v[144:145], v[126:127] neg_lo:[0,1] neg_hi:[0,1]
	v_pk_add_f32 v[144:145], v[158:159], v[128:129]
	v_pk_add_f32 v[128:129], v[158:159], v[128:129] neg_lo:[0,1] neg_hi:[0,1]
	v_pk_mul_f32 v[158:159], v[128:129], s[10:11]
	v_pk_fma_f32 v[128:129], v[128:129], s[14:15], v[158:159] op_sel:[0,0,1] op_sel_hi:[1,0,0]
	v_pk_add_f32 v[158:159], v[130:131], v[132:133]
	v_pk_add_f32 v[130:131], v[130:131], v[132:133] neg_lo:[0,1] neg_hi:[0,1]
	v_pk_add_f32 v[132:133], v[124:125], v[138:139]
	v_pk_add_f32 v[124:125], v[124:125], v[138:139] neg_lo:[0,1] neg_hi:[0,1]
	v_pk_mul_f32 v[138:139], v[124:125], s[10:11]
	v_pk_fma_f32 v[124:125], v[124:125], s[14:15], v[138:139] op_sel:[0,0,1] op_sel_hi:[1,0,0] neg_lo:[1,0,0] neg_hi:[1,0,0]
	v_pk_add_f32 v[138:139], v[120:121], v[30:31] op_sel:[0,1] op_sel_hi:[1,0] neg_hi:[0,1]
	v_pk_add_f32 v[30:31], v[120:121], v[30:31] op_sel:[0,1] op_sel_hi:[1,0] neg_lo:[0,1]
	v_pk_add_f32 v[120:121], v[122:123], v[82:83]
	v_pk_add_f32 v[82:83], v[122:123], v[82:83] neg_lo:[0,1] neg_hi:[0,1]
	v_pk_add_f32 v[160:161], v[128:129], v[124:125]
	v_pk_mul_f32 v[122:123], v[82:83], s[10:11]
	v_pk_add_f32 v[124:125], v[128:129], v[124:125] neg_lo:[0,1] neg_hi:[0,1]
	v_pk_fma_f32 v[82:83], v[82:83], s[14:15], v[122:123] op_sel:[0,0,1] op_sel_hi:[1,0,0]
	v_pk_add_f32 v[122:123], v[26:27], v[84:85]
	v_pk_add_f32 v[26:27], v[26:27], v[84:85] neg_lo:[0,1] neg_hi:[0,1]
	v_pk_add_f32 v[84:85], v[28:29], v[118:119]
	v_pk_add_f32 v[28:29], v[28:29], v[118:119] neg_lo:[0,1] neg_hi:[0,1]
	v_pk_mul_f32 v[118:119], v[28:29], s[10:11]
	v_pk_add_f32 v[166:167], v[120:121], v[84:85]
	v_pk_fma_f32 v[28:29], v[28:29], s[14:15], v[118:119] op_sel:[0,0,1] op_sel_hi:[1,0,0] neg_lo:[1,0,0] neg_hi:[1,0,0]
	v_pk_add_f32 v[118:119], v[140:141], v[20:21]
	v_pk_add_f32 v[20:21], v[140:141], v[20:21] neg_lo:[0,1] neg_hi:[0,1]
	v_pk_add_f32 v[140:141], v[24:25], v[22:23]
	v_pk_add_f32 v[22:23], v[24:25], v[22:23] neg_lo:[0,1] neg_hi:[0,1]
	v_pk_add_f32 v[84:85], v[120:121], v[84:85] neg_lo:[0,1] neg_hi:[0,1]
	v_pk_mul_f32 v[24:25], v[22:23], s[10:11]
	v_pk_add_f32 v[168:169], v[30:31], v[26:27] op_sel:[0,1] op_sel_hi:[1,0] neg_hi:[0,1]
	v_pk_fma_f32 v[22:23], v[22:23], s[14:15], v[24:25] op_sel:[0,0,1] op_sel_hi:[1,0,0]
	v_pk_add_f32 v[24:25], v[16:17], v[134:135]
	v_pk_add_f32 v[16:17], v[16:17], v[134:135] neg_lo:[0,1] neg_hi:[0,1]
	v_pk_add_f32 v[134:135], v[18:19], v[136:137]
	v_pk_add_f32 v[18:19], v[18:19], v[136:137] neg_lo:[0,1] neg_hi:[0,1]
	v_pk_mul_f32 v[136:137], v[18:19], s[10:11]
	v_pk_add_f32 v[26:27], v[30:31], v[26:27] op_sel:[0,1] op_sel_hi:[1,0] neg_lo:[0,1]
	v_pk_fma_f32 v[18:19], v[18:19], s[14:15], v[136:137] op_sel:[0,0,1] op_sel_hi:[1,0,0] neg_lo:[1,0,0] neg_hi:[1,0,0]
	v_pk_add_f32 v[136:137], v[14:15], v[6:7] op_sel:[0,1] op_sel_hi:[1,0] neg_hi:[0,1]
	v_pk_add_f32 v[6:7], v[14:15], v[6:7] op_sel:[0,1] op_sel_hi:[1,0] neg_lo:[0,1]
	v_pk_add_f32 v[14:15], v[0:1], v[8:9]
	v_pk_add_f32 v[0:1], v[0:1], v[8:9] neg_lo:[0,1] neg_hi:[0,1]
	v_pk_add_f32 v[30:31], v[82:83], v[28:29]
	v_pk_mul_f32 v[8:9], v[0:1], s[10:11]
	v_pk_add_f32 v[28:29], v[82:83], v[28:29] neg_lo:[0,1] neg_hi:[0,1]
	v_pk_fma_f32 v[0:1], v[0:1], s[14:15], v[8:9] op_sel:[0,0,1] op_sel_hi:[1,0,0]
	v_pk_add_f32 v[8:9], v[2:3], v[10:11]
	v_pk_add_f32 v[2:3], v[2:3], v[10:11] neg_lo:[0,1] neg_hi:[0,1]
	v_pk_add_f32 v[10:11], v[4:5], v[12:13]
	v_pk_add_f32 v[4:5], v[4:5], v[12:13] neg_lo:[0,1] neg_hi:[0,1]
	v_pk_mul_f32 v[12:13], v[4:5], s[10:11]
	v_pk_add_f32 v[170:171], v[118:119], v[24:25]
	v_pk_fma_f32 v[4:5], v[4:5], s[14:15], v[12:13] op_sel:[0,0,1] op_sel_hi:[1,0,0] neg_lo:[1,0,0] neg_hi:[1,0,0]
	v_pk_add_f32 v[12:13], v[142:143], v[158:159]
	v_pk_add_f32 v[142:143], v[142:143], v[158:159] neg_lo:[0,1] neg_hi:[0,1]
	v_pk_add_f32 v[158:159], v[144:145], v[132:133]
	v_pk_add_f32 v[132:133], v[144:145], v[132:133] neg_lo:[0,1] neg_hi:[0,1]
	v_pk_add_f32 v[182:183], v[118:119], v[24:25] neg_lo:[0,1] neg_hi:[0,1]
	v_pk_add_f32 v[184:185], v[140:141], v[134:135]
	v_pk_add_f32 v[24:25], v[140:141], v[134:135] neg_lo:[0,1] neg_hi:[0,1]
	v_pk_add_f32 v[140:141], v[20:21], v[16:17] op_sel:[0,1] op_sel_hi:[1,0] neg_hi:[0,1]
	v_pk_add_f32 v[186:187], v[20:21], v[16:17] op_sel:[0,1] op_sel_hi:[1,0] neg_lo:[0,1]
	v_pk_add_f32 v[16:17], v[22:23], v[18:19] neg_lo:[0,1] neg_hi:[0,1]
	v_pk_add_f32 v[192:193], v[136:137], v[8:9]
	v_pk_add_f32 v[194:195], v[136:137], v[8:9] neg_lo:[0,1] neg_hi:[0,1]
	v_pk_add_f32 v[8:9], v[14:15], v[10:11] neg_lo:[0,1] neg_hi:[0,1]
	v_pk_add_f32 v[198:199], v[6:7], v[2:3] op_sel:[0,1] op_sel_hi:[1,0] neg_hi:[0,1]
	v_pk_add_f32 v[200:201], v[6:7], v[2:3] op_sel:[0,1] op_sel_hi:[1,0] neg_lo:[0,1]
	v_pk_add_f32 v[2:3], v[0:1], v[4:5]
	v_pk_add_f32 v[0:1], v[0:1], v[4:5] neg_lo:[0,1] neg_hi:[0,1]
	v_pk_add_f32 v[144:145], v[126:127], v[130:131] op_sel:[0,1] op_sel_hi:[1,0] neg_hi:[0,1]
	v_pk_add_f32 v[130:131], v[126:127], v[130:131] op_sel:[0,1] op_sel_hi:[1,0] neg_lo:[0,1]
	v_pk_mul_f32 v[162:163], v[124:125], s[22:23]
	v_pk_add_f32 v[164:165], v[138:139], v[122:123]
	v_pk_add_f32 v[138:139], v[138:139], v[122:123] neg_lo:[0,1] neg_hi:[0,1]
	v_pk_mul_f32 v[82:83], v[28:29], s[22:23]
	v_pk_mul_f32 v[134:135], v[24:25], s[22:23]
	v_pk_add_f32 v[188:189], v[22:23], v[18:19]
	v_pk_mul_f32 v[190:191], v[16:17], s[22:23]
	v_pk_add_f32 v[136:137], v[14:15], v[10:11]
	v_pk_mul_f32 v[196:197], v[8:9], s[22:23]
	v_pk_mul_f32 v[202:203], v[0:1], s[22:23]
	v_pk_add_f32 v[28:29], v[12:13], v[158:159]
	v_pk_add_f32 v[128:129], v[12:13], v[158:159] neg_lo:[0,1] neg_hi:[0,1]
	v_pk_add_f32 v[24:25], v[142:143], v[132:133] op_sel:[0,1] op_sel_hi:[1,0] neg_hi:[0,1]
	v_pk_add_f32 v[126:127], v[142:143], v[132:133] op_sel:[0,1] op_sel_hi:[1,0] neg_lo:[0,1]
	v_pk_add_f32 v[20:21], v[144:145], v[160:161]
	v_pk_add_f32 v[124:125], v[144:145], v[160:161] neg_lo:[0,1] neg_hi:[0,1]
	v_pk_add_f32 v[16:17], v[130:131], v[162:163] op_sel:[0,1] op_sel_hi:[1,0]
	v_pk_add_f32 v[122:123], v[130:131], v[162:163] op_sel:[0,1] op_sel_hi:[1,0] neg_lo:[0,1] neg_hi:[0,1]
	v_pk_add_f32 v[12:13], v[164:165], v[166:167]
	v_pk_add_f32 v[120:121], v[164:165], v[166:167] neg_lo:[0,1] neg_hi:[0,1]
	v_pk_add_f32 v[8:9], v[138:139], v[84:85] op_sel:[0,1] op_sel_hi:[1,0] neg_hi:[0,1]
	v_pk_add_f32 v[118:119], v[138:139], v[84:85] op_sel:[0,1] op_sel_hi:[1,0] neg_lo:[0,1]
	v_pk_add_f32 v[4:5], v[168:169], v[30:31]
	v_pk_add_f32 v[84:85], v[168:169], v[30:31] neg_lo:[0,1] neg_hi:[0,1]
	v_pk_add_f32 v[0:1], v[26:27], v[82:83] op_sel:[0,1] op_sel_hi:[1,0]
	v_pk_add_f32 v[82:83], v[26:27], v[82:83] op_sel:[0,1] op_sel_hi:[1,0] neg_lo:[0,1] neg_hi:[0,1]
	v_pk_add_f32 v[30:31], v[170:171], v[184:185]
	v_pk_add_f32 v[144:145], v[170:171], v[184:185] neg_lo:[0,1] neg_hi:[0,1]
	v_pk_add_f32 v[26:27], v[182:183], v[134:135] op_sel:[0,1] op_sel_hi:[1,0]
	v_pk_add_f32 v[142:143], v[182:183], v[134:135] op_sel:[0,1] op_sel_hi:[1,0] neg_lo:[0,1] neg_hi:[0,1]
	v_pk_add_f32 v[22:23], v[140:141], v[188:189]
	v_pk_add_f32 v[140:141], v[140:141], v[188:189] neg_lo:[0,1] neg_hi:[0,1]
	v_pk_add_f32 v[18:19], v[186:187], v[190:191] op_sel:[0,1] op_sel_hi:[1,0]
	v_pk_add_f32 v[138:139], v[186:187], v[190:191] op_sel:[0,1] op_sel_hi:[1,0] neg_lo:[0,1] neg_hi:[0,1]
	v_pk_add_f32 v[14:15], v[192:193], v[136:137]
	v_pk_add_f32 v[136:137], v[192:193], v[136:137] neg_lo:[0,1] neg_hi:[0,1]
	v_pk_add_f32 v[10:11], v[194:195], v[196:197] op_sel:[0,1] op_sel_hi:[1,0]
	v_pk_add_f32 v[134:135], v[194:195], v[196:197] op_sel:[0,1] op_sel_hi:[1,0] neg_lo:[0,1] neg_hi:[0,1]
	v_pk_add_f32 v[6:7], v[198:199], v[2:3]
	v_pk_add_f32 v[132:133], v[198:199], v[2:3] neg_lo:[0,1] neg_hi:[0,1]
	v_pk_add_f32 v[2:3], v[200:201], v[202:203] op_sel:[0,1] op_sel_hi:[1,0]
	v_pk_add_f32 v[130:131], v[200:201], v[202:203] op_sel:[0,1] op_sel_hi:[1,0] neg_lo:[0,1] neg_hi:[0,1]

.LBB0_484:
	s_or_b64 exec, exec, s[0:1]
	v_mov_b32_e32 v47, v32
	s_waitcnt lgkmcnt(0)
	s_barrier
	s_mov_b32 s11, s14
	v_and_b32_e32 v81, 31, v47
	v_cvt_f32_ubyte0_e32 v24, v81
	v_mul_f32_e32 v84, 0x3b000000, v24
	v_sin_f32_e32 v24, v84
	v_ashrrev_i32_e32 v0, 4, v47
	v_lshlrev_b32_e32 v0, 3, v0
	v_lshlrev_b32_e32 v1, 3, v47
	v_cos_f32_e32 v84, v84
	v_add3_u32 v25, 0, v0, v1
	ds_read_b64 v[0:1], v25
	ds_read_b64 v[2:3], v25 offset:4352
	ds_read_b64 v[4:5], v25 offset:8704
	ds_read_b64 v[6:7], v25 offset:13056
	ds_read_b64 v[8:9], v25 offset:17408
	ds_read_b64 v[10:11], v25 offset:21760
	ds_read_b64 v[12:13], v25 offset:26112
	ds_read_b64 v[14:15], v25 offset:30464
	ds_read_b64 v[16:17], v25 offset:34816
	ds_read_b64 v[18:19], v25 offset:39168
	ds_read_b64 v[20:21], v25 offset:43520
	ds_read_b64 v[22:23], v25 offset:47872
	v_xor_b32_e32 v85, 0x80000000, v24
	s_waitcnt lgkmcnt(10)
	v_pk_mul_f32 v[118:119], v[2:3], v[24:25] op_sel:[1,0] op_sel_hi:[0,0] neg_hi:[0,1]
	v_pk_fma_f32 v[2:3], v[2:3], v[84:85], v[118:119] op_sel_hi:[1,0,1]
	v_pk_mul_f32 v[118:119], v[24:25], v[84:85] op_sel:[0,1] op_sel_hi:[0,0] neg_hi:[1,0]
	v_pk_fma_f32 v[118:119], v[84:85], v[84:85], v[118:119] op_sel_hi:[0,1,1]
	ds_read_b64 v[26:27], v25 offset:52224
	ds_read_b64 v[28:29], v25 offset:56576
	ds_read_b64 v[30:31], v25 offset:60928
	ds_read_b64 v[82:83], v25 offset:65280
	s_waitcnt lgkmcnt(13)
	v_pk_mul_f32 v[120:121], v[4:5], v[118:119] op_sel:[1,1] op_sel_hi:[0,1] neg_lo:[0,1]
	v_pk_fma_f32 v[4:5], v[4:5], v[118:119], v[120:121] op_sel_hi:[1,0,1]
	v_pk_mul_f32 v[120:121], v[24:25], v[118:119] op_sel:[0,1] op_sel_hi:[0,0] neg_hi:[1,0]
	v_pk_fma_f32 v[118:119], v[84:85], v[118:119], v[120:121] op_sel_hi:[0,1,1]
	s_mov_b32 s35, s30
	s_waitcnt lgkmcnt(12)
	v_pk_mul_f32 v[120:121], v[6:7], v[118:119] op_sel:[1,1] op_sel_hi:[0,1] neg_lo:[0,1]
	v_pk_fma_f32 v[6:7], v[6:7], v[118:119], v[120:121] op_sel_hi:[1,0,1]
	v_pk_mul_f32 v[120:121], v[24:25], v[118:119] op_sel:[0,1] op_sel_hi:[0,0] neg_hi:[1,0]
	v_pk_fma_f32 v[118:119], v[84:85], v[118:119], v[120:121] op_sel_hi:[0,1,1]
	s_mov_b32 s0, s19
	s_waitcnt lgkmcnt(11)
	v_pk_mul_f32 v[120:121], v[8:9], v[118:119] op_sel:[1,1] op_sel_hi:[0,1] neg_lo:[0,1]
	v_pk_fma_f32 v[8:9], v[8:9], v[118:119], v[120:121] op_sel_hi:[1,0,1]
	v_pk_mul_f32 v[120:121], v[24:25], v[118:119] op_sel:[0,1] op_sel_hi:[0,0] neg_hi:[1,0]
	v_pk_fma_f32 v[118:119], v[84:85], v[118:119], v[120:121] op_sel_hi:[0,1,1]
	s_waitcnt lgkmcnt(0)
	v_pk_mul_f32 v[120:121], v[10:11], v[118:119] op_sel:[1,1] op_sel_hi:[0,1] neg_lo:[0,1]
	v_pk_fma_f32 v[10:11], v[10:11], v[118:119], v[120:121] op_sel_hi:[1,0,1]
	v_pk_mul_f32 v[120:121], v[24:25], v[118:119] op_sel:[0,1] op_sel_hi:[0,0] neg_hi:[1,0]
	v_pk_fma_f32 v[118:119], v[84:85], v[118:119], v[120:121] op_sel_hi:[0,1,1]
	s_barrier
	v_pk_mul_f32 v[120:121], v[12:13], v[118:119] op_sel:[1,1] op_sel_hi:[0,1] neg_lo:[0,1]
	v_pk_fma_f32 v[12:13], v[12:13], v[118:119], v[120:121] op_sel_hi:[1,0,1]
	v_pk_mul_f32 v[120:121], v[24:25], v[118:119] op_sel:[0,1] op_sel_hi:[0,0] neg_hi:[1,0]
	v_pk_fma_f32 v[118:119], v[84:85], v[118:119], v[120:121] op_sel_hi:[0,1,1]
	v_pk_mul_f32 v[120:121], v[14:15], v[118:119] op_sel:[1,1] op_sel_hi:[0,1] neg_lo:[0,1]
	v_pk_fma_f32 v[14:15], v[14:15], v[118:119], v[120:121] op_sel_hi:[1,0,1]
	v_pk_mul_f32 v[120:121], v[24:25], v[118:119] op_sel:[0,1] op_sel_hi:[0,0] neg_hi:[1,0]
	v_pk_fma_f32 v[118:119], v[84:85], v[118:119], v[120:121] op_sel_hi:[0,1,1]
	v_pk_mul_f32 v[120:121], v[16:17], v[118:119] op_sel:[1,1] op_sel_hi:[0,1] neg_lo:[0,1]
	v_pk_fma_f32 v[16:17], v[16:17], v[118:119], v[120:121] op_sel_hi:[1,0,1]
	v_pk_mul_f32 v[120:121], v[24:25], v[118:119] op_sel:[0,1] op_sel_hi:[0,0] neg_hi:[1,0]
	v_pk_fma_f32 v[118:119], v[84:85], v[118:119], v[120:121] op_sel_hi:[0,1,1]
	v_pk_mul_f32 v[120:121], v[18:19], v[118:119] op_sel:[1,1] op_sel_hi:[0,1] neg_lo:[0,1]
	v_pk_fma_f32 v[18:19], v[18:19], v[118:119], v[120:121] op_sel_hi:[1,0,1]
	v_pk_mul_f32 v[120:121], v[24:25], v[118:119] op_sel:[0,1] op_sel_hi:[0,0] neg_hi:[1,0]
	v_pk_fma_f32 v[118:119], v[84:85], v[118:119], v[120:121] op_sel_hi:[0,1,1]
	v_pk_mul_f32 v[120:121], v[20:21], v[118:119] op_sel:[1,1] op_sel_hi:[0,1] neg_lo:[0,1]
	v_pk_fma_f32 v[20:21], v[20:21], v[118:119], v[120:121] op_sel_hi:[1,0,1]
	v_pk_mul_f32 v[120:121], v[24:25], v[118:119] op_sel:[0,1] op_sel_hi:[0,0] neg_hi:[1,0]
	v_pk_fma_f32 v[118:119], v[84:85], v[118:119], v[120:121] op_sel_hi:[0,1,1]
	v_pk_mul_f32 v[120:121], v[22:23], v[118:119] op_sel:[1,1] op_sel_hi:[0,1] neg_lo:[0,1]
	v_pk_fma_f32 v[22:23], v[22:23], v[118:119], v[120:121] op_sel_hi:[1,0,1]
	v_pk_mul_f32 v[120:121], v[24:25], v[118:119] op_sel:[0,1] op_sel_hi:[0,0] neg_hi:[1,0]
	v_pk_fma_f32 v[118:119], v[84:85], v[118:119], v[120:121] op_sel_hi:[0,1,1]
	v_pk_mul_f32 v[120:121], v[26:27], v[118:119] op_sel:[1,1] op_sel_hi:[0,1] neg_lo:[0,1]
	v_pk_fma_f32 v[26:27], v[26:27], v[118:119], v[120:121] op_sel_hi:[1,0,1]
	v_pk_mul_f32 v[120:121], v[24:25], v[118:119] op_sel:[0,1] op_sel_hi:[0,0] neg_hi:[1,0]
	v_pk_fma_f32 v[118:119], v[84:85], v[118:119], v[120:121] op_sel_hi:[0,1,1]
	v_pk_mul_f32 v[120:121], v[28:29], v[118:119] op_sel:[1,1] op_sel_hi:[0,1] neg_lo:[0,1]
	v_pk_fma_f32 v[28:29], v[28:29], v[118:119], v[120:121] op_sel_hi:[1,0,1]
	v_pk_mul_f32 v[120:121], v[24:25], v[118:119] op_sel:[0,1] op_sel_hi:[0,0] neg_hi:[1,0]
	v_pk_fma_f32 v[118:119], v[84:85], v[118:119], v[120:121] op_sel_hi:[0,1,1]
	v_pk_mul_f32 v[24:25], v[24:25], v[118:119] op_sel:[0,1] op_sel_hi:[0,0] neg_hi:[1,0]
	v_pk_fma_f32 v[24:25], v[84:85], v[118:119], v[24:25] op_sel_hi:[0,1,1]
	v_pk_mul_f32 v[84:85], v[82:83], v[24:25] op_sel:[1,1] op_sel_hi:[0,1] neg_lo:[0,1]
	v_pk_fma_f32 v[24:25], v[82:83], v[24:25], v[84:85] op_sel_hi:[1,0,1]
	v_pk_add_f32 v[82:83], v[0:1], v[16:17]
	v_pk_add_f32 v[0:1], v[0:1], v[16:17] neg_lo:[0,1] neg_hi:[0,1]
	v_pk_add_f32 v[16:17], v[2:3], v[18:19]
	v_pk_add_f32 v[2:3], v[2:3], v[18:19] neg_lo:[0,1] neg_hi:[0,1]
	v_pk_mul_f32 v[120:121], v[30:31], v[118:119] op_sel:[1,1] op_sel_hi:[0,1] neg_lo:[0,1]
	v_pk_mul_f32 v[18:19], v[2:3], s[18:19]
	v_pk_fma_f32 v[30:31], v[30:31], v[118:119], v[120:121] op_sel_hi:[1,0,1]
	v_pk_fma_f32 v[2:3], v[2:3], s[30:31], v[18:19] op_sel:[0,0,1] op_sel_hi:[1,0,0]
	v_pk_add_f32 v[18:19], v[4:5], v[20:21]
	v_pk_add_f32 v[4:5], v[4:5], v[20:21] neg_lo:[0,1] neg_hi:[0,1]
	v_pk_mul_f32 v[20:21], v[4:5], s[10:11]
	v_pk_fma_f32 v[4:5], v[4:5], s[14:15], v[20:21] op_sel:[0,0,1] op_sel_hi:[1,0,0]
	v_pk_add_f32 v[20:21], v[6:7], v[22:23]
	v_pk_add_f32 v[6:7], v[6:7], v[22:23] neg_lo:[0,1] neg_hi:[0,1]
	v_pk_mul_f32 v[22:23], v[6:7], s[34:35]
	v_pk_fma_f32 v[6:7], v[6:7], s[0:1], v[22:23] op_sel:[0,0,1] op_sel_hi:[1,0,0]
	v_pk_add_f32 v[22:23], v[8:9], v[26:27]
	v_pk_add_f32 v[8:9], v[8:9], v[26:27] neg_lo:[0,1] neg_hi:[0,1]
	v_pk_add_f32 v[26:27], v[10:11], v[28:29]
	v_pk_add_f32 v[10:11], v[10:11], v[28:29] neg_lo:[0,1] neg_hi:[0,1]
	v_pk_mul_f32 v[28:29], v[10:11], s[34:35]
	v_pk_fma_f32 v[10:11], v[10:11], s[0:1], v[28:29] op_sel:[0,0,1] op_sel_hi:[1,0,0] neg_lo:[1,0,0] neg_hi:[1,0,0]
	v_pk_add_f32 v[28:29], v[12:13], v[30:31]
	v_pk_add_f32 v[12:13], v[12:13], v[30:31] neg_lo:[0,1] neg_hi:[0,1]
	v_pk_mul_f32 v[30:31], v[12:13], s[10:11]
	v_pk_fma_f32 v[12:13], v[12:13], s[14:15], v[30:31] op_sel:[0,0,1] op_sel_hi:[1,0,0] neg_lo:[1,0,0] neg_hi:[1,0,0]
	v_pk_add_f32 v[30:31], v[14:15], v[24:25]
	v_pk_add_f32 v[14:15], v[14:15], v[24:25] neg_lo:[0,1] neg_hi:[0,1]
	v_pk_mul_f32 v[24:25], v[14:15], s[18:19]
	v_pk_fma_f32 v[14:15], v[14:15], s[30:31], v[24:25] op_sel:[0,0,1] op_sel_hi:[1,0,0] neg_lo:[1,0,0] neg_hi:[1,0,0]
	v_pk_add_f32 v[24:25], v[82:83], v[22:23]
	v_pk_add_f32 v[22:23], v[82:83], v[22:23] neg_lo:[0,1] neg_hi:[0,1]
	v_pk_add_f32 v[82:83], v[16:17], v[26:27]
	v_pk_add_f32 v[16:17], v[16:17], v[26:27] neg_lo:[0,1] neg_hi:[0,1]
	v_pk_mul_f32 v[26:27], v[16:17], s[10:11]
	v_pk_fma_f32 v[16:17], v[16:17], s[14:15], v[26:27] op_sel:[0,0,1] op_sel_hi:[1,0,0]
	v_pk_add_f32 v[26:27], v[18:19], v[28:29]
	v_pk_add_f32 v[18:19], v[18:19], v[28:29] neg_lo:[0,1] neg_hi:[0,1]
	v_pk_add_f32 v[28:29], v[20:21], v[30:31]
	v_pk_add_f32 v[20:21], v[20:21], v[30:31] neg_lo:[0,1] neg_hi:[0,1]
	v_pk_mul_f32 v[30:31], v[20:21], s[10:11]
	v_pk_fma_f32 v[20:21], v[20:21], s[14:15], v[30:31] op_sel:[0,0,1] op_sel_hi:[1,0,0] neg_lo:[1,0,0] neg_hi:[1,0,0]
	v_pk_add_f32 v[30:31], v[0:1], v[8:9] op_sel:[0,1] op_sel_hi:[1,0] neg_hi:[0,1]
	v_pk_add_f32 v[0:1], v[0:1], v[8:9] op_sel:[0,1] op_sel_hi:[1,0] neg_lo:[0,1]
	v_pk_add_f32 v[8:9], v[2:3], v[10:11]
	v_pk_add_f32 v[2:3], v[2:3], v[10:11] neg_lo:[0,1] neg_hi:[0,1]
	v_pk_mul_f32 v[10:11], v[2:3], s[10:11]
	v_pk_fma_f32 v[2:3], v[2:3], s[14:15], v[10:11] op_sel:[0,0,1] op_sel_hi:[1,0,0]
	v_pk_add_f32 v[10:11], v[4:5], v[12:13]
	v_pk_add_f32 v[4:5], v[4:5], v[12:13] neg_lo:[0,1] neg_hi:[0,1]
	v_pk_add_f32 v[12:13], v[6:7], v[14:15]
	v_pk_add_f32 v[6:7], v[6:7], v[14:15] neg_lo:[0,1] neg_hi:[0,1]
	v_pk_mul_f32 v[14:15], v[6:7], s[10:11]
	v_pk_fma_f32 v[6:7], v[6:7], s[14:15], v[14:15] op_sel:[0,0,1] op_sel_hi:[1,0,0] neg_lo:[1,0,0] neg_hi:[1,0,0]
	v_pk_add_f32 v[14:15], v[24:25], v[26:27]
	v_pk_add_f32 v[24:25], v[24:25], v[26:27] neg_lo:[0,1] neg_hi:[0,1]
	v_pk_add_f32 v[26:27], v[82:83], v[28:29]
	v_pk_add_f32 v[28:29], v[82:83], v[28:29] neg_lo:[0,1] neg_hi:[0,1]
	v_pk_add_f32 v[82:83], v[22:23], v[18:19] op_sel:[0,1] op_sel_hi:[1,0] neg_hi:[0,1]
	v_pk_add_f32 v[18:19], v[22:23], v[18:19] op_sel:[0,1] op_sel_hi:[1,0] neg_lo:[0,1]
	v_pk_add_f32 v[22:23], v[16:17], v[20:21]
	v_pk_add_f32 v[16:17], v[16:17], v[20:21] neg_lo:[0,1] neg_hi:[0,1]
	v_pk_add_f32 v[20:21], v[30:31], v[10:11]
	v_pk_add_f32 v[10:11], v[30:31], v[10:11] neg_lo:[0,1] neg_hi:[0,1]
	v_pk_add_f32 v[30:31], v[8:9], v[12:13]
	v_pk_add_f32 v[8:9], v[8:9], v[12:13] neg_lo:[0,1] neg_hi:[0,1]
	v_pk_add_f32 v[12:13], v[0:1], v[4:5] op_sel:[0,1] op_sel_hi:[1,0] neg_hi:[0,1]
	v_pk_add_f32 v[0:1], v[0:1], v[4:5] op_sel:[0,1] op_sel_hi:[1,0] neg_lo:[0,1]
	v_pk_add_f32 v[4:5], v[2:3], v[6:7]
	v_pk_add_f32 v[2:3], v[2:3], v[6:7] neg_lo:[0,1] neg_hi:[0,1]
	v_pk_mul_f32 v[2:3], v[2:3], s[22:23]
	v_pk_add_f32 v[6:7], v[14:15], v[26:27]
	v_pk_add_f32 v[14:15], v[14:15], v[26:27] neg_lo:[0,1] neg_hi:[0,1]
	v_pk_add_f32 v[26:27], v[24:25], v[28:29] op_sel:[0,1] op_sel_hi:[1,0] neg_hi:[0,1]
	v_pk_add_f32 v[24:25], v[24:25], v[28:29] op_sel:[0,1] op_sel_hi:[1,0] neg_lo:[0,1]
	v_pk_add_f32 v[28:29], v[82:83], v[22:23]
	v_pk_add_f32 v[22:23], v[82:83], v[22:23] neg_lo:[0,1] neg_hi:[0,1]
	v_pk_add_f32 v[82:83], v[18:19], v[16:17] op_sel:[0,1] op_sel_hi:[1,0] neg_hi:[0,1]
	v_pk_add_f32 v[16:17], v[18:19], v[16:17] op_sel:[0,1] op_sel_hi:[1,0] neg_lo:[0,1]
	v_pk_add_f32 v[18:19], v[20:21], v[30:31]
	v_pk_add_f32 v[20:21], v[20:21], v[30:31] neg_lo:[0,1] neg_hi:[0,1]
	v_pk_add_f32 v[30:31], v[10:11], v[8:9] op_sel:[0,1] op_sel_hi:[1,0] neg_hi:[0,1]
	v_pk_add_f32 v[8:9], v[10:11], v[8:9] op_sel:[0,1] op_sel_hi:[1,0] neg_lo:[0,1]
	v_pk_add_f32 v[10:11], v[12:13], v[4:5]
	v_pk_add_f32 v[4:5], v[12:13], v[4:5] neg_lo:[0,1] neg_hi:[0,1]
	v_pk_add_f32 v[12:13], v[0:1], v[2:3] op_sel:[0,1] op_sel_hi:[1,0]
	v_pk_add_f32 v[0:1], v[0:1], v[2:3] op_sel:[0,1] op_sel_hi:[1,0] neg_lo:[0,1] neg_hi:[0,1]
	v_lshlrev_b32_e32 v2, 4, v47
	v_and_or_b32 v2, v2, s7, v81
	v_ashrrev_i32_e32 v3, 4, v2
	v_lshlrev_b32_e32 v3, 3, v3
	v_lshlrev_b32_e32 v2, 3, v2
	v_add3_u32 v2, 0, v3, v2
	v_add_u32_e32 v3, 0x800, v2
	v_mov_b32_e32 v47, v32
	ds_write2_b64 v2, v[6:7], v[18:19] offset1:34
	ds_write2_b64 v3, v[14:15], v[20:21] offset0:16 offset1:50
	ds_write2_b64 v2, v[26:27], v[30:31] offset0:136 offset1:170
	ds_write2_b64 v3, v[24:25], v[8:9] offset0:152 offset1:186
	ds_write2_b64 v2, v[28:29], v[10:11] offset0:68 offset1:102
	ds_write2_b64 v3, v[22:23], v[4:5] offset0:84 offset1:118
	ds_write2_b64 v2, v[82:83], v[12:13] offset0:204 offset1:238
	ds_write2_b64 v3, v[16:17], v[0:1] offset0:220 offset1:254
	s_waitcnt lgkmcnt(0)
	s_barrier
	s_nop 0
	v_and_b32_e32 v81, 0x1ff, v47
	v_cvt_f32_u32_e32 v24, v81
	v_ashrrev_i32_e32 v0, 4, v47
	v_lshlrev_b32_e32 v0, 3, v0
	v_lshlrev_b32_e32 v1, 3, v47
	v_mul_f32_e32 v84, 0x39000000, v24
	v_sin_f32_e32 v24, v84
	v_cos_f32_e32 v84, v84
	v_add3_u32 v25, 0, v0, v1
	ds_read_b64 v[0:1], v25
	ds_read_b64 v[2:3], v25 offset:4352
	ds_read_b64 v[4:5], v25 offset:8704
	ds_read_b64 v[6:7], v25 offset:13056
	ds_read_b64 v[8:9], v25 offset:17408
	ds_read_b64 v[10:11], v25 offset:21760
	ds_read_b64 v[12:13], v25 offset:26112
	ds_read_b64 v[14:15], v25 offset:30464
	v_xor_b32_e32 v85, 0x80000000, v24
	s_waitcnt lgkmcnt(6)
	v_pk_mul_f32 v[118:119], v[2:3], v[24:25] op_sel:[1,0] op_sel_hi:[0,0] neg_hi:[0,1]
	v_pk_fma_f32 v[2:3], v[2:3], v[84:85], v[118:119] op_sel_hi:[1,0,1]
	v_pk_mul_f32 v[118:119], v[24:25], v[84:85] op_sel:[0,1] op_sel_hi:[0,0] neg_hi:[1,0]
	v_pk_fma_f32 v[118:119], v[84:85], v[84:85], v[118:119] op_sel_hi:[0,1,1]
	ds_read_b64 v[16:17], v25 offset:34816
	ds_read_b64 v[18:19], v25 offset:39168
	ds_read_b64 v[20:21], v25 offset:43520
	ds_read_b64 v[22:23], v25 offset:47872
	s_waitcnt lgkmcnt(9)
	v_pk_mul_f32 v[120:121], v[4:5], v[118:119] op_sel:[1,1] op_sel_hi:[0,1] neg_lo:[0,1]
	v_pk_fma_f32 v[4:5], v[4:5], v[118:119], v[120:121] op_sel_hi:[1,0,1]
	v_pk_mul_f32 v[120:121], v[24:25], v[118:119] op_sel:[0,1] op_sel_hi:[0,0] neg_hi:[1,0]
	v_pk_fma_f32 v[118:119], v[84:85], v[118:119], v[120:121] op_sel_hi:[0,1,1]
	ds_read_b64 v[26:27], v25 offset:52224
	ds_read_b64 v[28:29], v25 offset:56576
	ds_read_b64 v[30:31], v25 offset:60928
	ds_read_b64 v[82:83], v25 offset:65280
	s_waitcnt lgkmcnt(12)
	v_pk_mul_f32 v[120:121], v[6:7], v[118:119] op_sel:[1,1] op_sel_hi:[0,1] neg_lo:[0,1]
	v_pk_fma_f32 v[6:7], v[6:7], v[118:119], v[120:121] op_sel_hi:[1,0,1]
	v_pk_mul_f32 v[120:121], v[24:25], v[118:119] op_sel:[0,1] op_sel_hi:[0,0] neg_hi:[1,0]
	v_pk_fma_f32 v[118:119], v[84:85], v[118:119], v[120:121] op_sel_hi:[0,1,1]
	s_waitcnt lgkmcnt(0)
	v_pk_mul_f32 v[120:121], v[8:9], v[118:119] op_sel:[1,1] op_sel_hi:[0,1] neg_lo:[0,1]
	v_pk_fma_f32 v[8:9], v[8:9], v[118:119], v[120:121] op_sel_hi:[1,0,1]
	v_pk_mul_f32 v[120:121], v[24:25], v[118:119] op_sel:[0,1] op_sel_hi:[0,0] neg_hi:[1,0]
	v_pk_fma_f32 v[118:119], v[84:85], v[118:119], v[120:121] op_sel_hi:[0,1,1]
	s_barrier
	v_pk_mul_f32 v[120:121], v[10:11], v[118:119] op_sel:[1,1] op_sel_hi:[0,1] neg_lo:[0,1]
	v_pk_fma_f32 v[10:11], v[10:11], v[118:119], v[120:121] op_sel_hi:[1,0,1]
	v_pk_mul_f32 v[120:121], v[24:25], v[118:119] op_sel:[0,1] op_sel_hi:[0,0] neg_hi:[1,0]
	v_pk_fma_f32 v[118:119], v[84:85], v[118:119], v[120:121] op_sel_hi:[0,1,1]
	v_pk_mul_f32 v[120:121], v[12:13], v[118:119] op_sel:[1,1] op_sel_hi:[0,1] neg_lo:[0,1]
	v_pk_fma_f32 v[12:13], v[12:13], v[118:119], v[120:121] op_sel_hi:[1,0,1]
	v_pk_mul_f32 v[120:121], v[24:25], v[118:119] op_sel:[0,1] op_sel_hi:[0,0] neg_hi:[1,0]
	v_pk_fma_f32 v[118:119], v[84:85], v[118:119], v[120:121] op_sel_hi:[0,1,1]
	v_pk_mul_f32 v[120:121], v[14:15], v[118:119] op_sel:[1,1] op_sel_hi:[0,1] neg_lo:[0,1]
	v_pk_fma_f32 v[14:15], v[14:15], v[118:119], v[120:121] op_sel_hi:[1,0,1]
	v_pk_mul_f32 v[120:121], v[24:25], v[118:119] op_sel:[0,1] op_sel_hi:[0,0] neg_hi:[1,0]
	v_pk_fma_f32 v[118:119], v[84:85], v[118:119], v[120:121] op_sel_hi:[0,1,1]
	v_pk_mul_f32 v[120:121], v[16:17], v[118:119] op_sel:[1,1] op_sel_hi:[0,1] neg_lo:[0,1]
	v_pk_fma_f32 v[16:17], v[16:17], v[118:119], v[120:121] op_sel_hi:[1,0,1]
	v_pk_mul_f32 v[120:121], v[24:25], v[118:119] op_sel:[0,1] op_sel_hi:[0,0] neg_hi:[1,0]
	v_pk_fma_f32 v[118:119], v[84:85], v[118:119], v[120:121] op_sel_hi:[0,1,1]
	v_pk_mul_f32 v[120:121], v[18:19], v[118:119] op_sel:[1,1] op_sel_hi:[0,1] neg_lo:[0,1]
	v_pk_fma_f32 v[18:19], v[18:19], v[118:119], v[120:121] op_sel_hi:[1,0,1]
	v_pk_mul_f32 v[120:121], v[24:25], v[118:119] op_sel:[0,1] op_sel_hi:[0,0] neg_hi:[1,0]
	v_pk_fma_f32 v[118:119], v[84:85], v[118:119], v[120:121] op_sel_hi:[0,1,1]
	v_pk_mul_f32 v[120:121], v[20:21], v[118:119] op_sel:[1,1] op_sel_hi:[0,1] neg_lo:[0,1]
	v_pk_fma_f32 v[20:21], v[20:21], v[118:119], v[120:121] op_sel_hi:[1,0,1]
	v_pk_mul_f32 v[120:121], v[24:25], v[118:119] op_sel:[0,1] op_sel_hi:[0,0] neg_hi:[1,0]
	v_pk_fma_f32 v[118:119], v[84:85], v[118:119], v[120:121] op_sel_hi:[0,1,1]
	v_pk_mul_f32 v[120:121], v[22:23], v[118:119] op_sel:[1,1] op_sel_hi:[0,1] neg_lo:[0,1]
	v_pk_fma_f32 v[22:23], v[22:23], v[118:119], v[120:121] op_sel_hi:[1,0,1]
	v_pk_mul_f32 v[120:121], v[24:25], v[118:119] op_sel:[0,1] op_sel_hi:[0,0] neg_hi:[1,0]
	v_pk_fma_f32 v[118:119], v[84:85], v[118:119], v[120:121] op_sel_hi:[0,1,1]
	v_pk_mul_f32 v[120:121], v[26:27], v[118:119] op_sel:[1,1] op_sel_hi:[0,1] neg_lo:[0,1]
	v_pk_fma_f32 v[26:27], v[26:27], v[118:119], v[120:121] op_sel_hi:[1,0,1]
	v_pk_mul_f32 v[120:121], v[24:25], v[118:119] op_sel:[0,1] op_sel_hi:[0,0] neg_hi:[1,0]
	v_pk_fma_f32 v[118:119], v[84:85], v[118:119], v[120:121] op_sel_hi:[0,1,1]
	v_pk_mul_f32 v[120:121], v[28:29], v[118:119] op_sel:[1,1] op_sel_hi:[0,1] neg_lo:[0,1]
	v_pk_fma_f32 v[28:29], v[28:29], v[118:119], v[120:121] op_sel_hi:[1,0,1]
	v_pk_mul_f32 v[120:121], v[24:25], v[118:119] op_sel:[0,1] op_sel_hi:[0,0] neg_hi:[1,0]
	v_pk_fma_f32 v[118:119], v[84:85], v[118:119], v[120:121] op_sel_hi:[0,1,1]
	v_pk_mul_f32 v[24:25], v[24:25], v[118:119] op_sel:[0,1] op_sel_hi:[0,0] neg_hi:[1,0]
	v_pk_fma_f32 v[24:25], v[84:85], v[118:119], v[24:25] op_sel_hi:[0,1,1]
	v_pk_mul_f32 v[84:85], v[82:83], v[24:25] op_sel:[1,1] op_sel_hi:[0,1] neg_lo:[0,1]
	v_pk_fma_f32 v[24:25], v[82:83], v[24:25], v[84:85] op_sel_hi:[1,0,1]
	v_pk_add_f32 v[82:83], v[0:1], v[16:17]
	v_pk_add_f32 v[0:1], v[0:1], v[16:17] neg_lo:[0,1] neg_hi:[0,1]
	v_pk_add_f32 v[16:17], v[2:3], v[18:19]
	v_pk_add_f32 v[2:3], v[2:3], v[18:19] neg_lo:[0,1] neg_hi:[0,1]
	v_pk_mul_f32 v[120:121], v[30:31], v[118:119] op_sel:[1,1] op_sel_hi:[0,1] neg_lo:[0,1]
	v_pk_mul_f32 v[18:19], v[2:3], s[18:19]
	v_pk_fma_f32 v[30:31], v[30:31], v[118:119], v[120:121] op_sel_hi:[1,0,1]
	v_pk_fma_f32 v[2:3], v[2:3], s[30:31], v[18:19] op_sel:[0,0,1] op_sel_hi:[1,0,0]
	v_pk_add_f32 v[18:19], v[4:5], v[20:21]
	v_pk_add_f32 v[4:5], v[4:5], v[20:21] neg_lo:[0,1] neg_hi:[0,1]
	v_pk_mul_f32 v[20:21], v[4:5], s[10:11]
	v_pk_fma_f32 v[4:5], v[4:5], s[14:15], v[20:21] op_sel:[0,0,1] op_sel_hi:[1,0,0]
	v_pk_add_f32 v[20:21], v[6:7], v[22:23]
	v_pk_add_f32 v[6:7], v[6:7], v[22:23] neg_lo:[0,1] neg_hi:[0,1]
	v_pk_mul_f32 v[22:23], v[6:7], s[34:35]
	v_pk_fma_f32 v[6:7], v[6:7], s[0:1], v[22:23] op_sel:[0,0,1] op_sel_hi:[1,0,0]
	v_pk_add_f32 v[22:23], v[8:9], v[26:27]
	v_pk_add_f32 v[8:9], v[8:9], v[26:27] neg_lo:[0,1] neg_hi:[0,1]
	v_pk_add_f32 v[26:27], v[10:11], v[28:29]
	v_pk_add_f32 v[10:11], v[10:11], v[28:29] neg_lo:[0,1] neg_hi:[0,1]
	v_pk_mul_f32 v[28:29], v[10:11], s[34:35]
	v_pk_fma_f32 v[10:11], v[10:11], s[0:1], v[28:29] op_sel:[0,0,1] op_sel_hi:[1,0,0] neg_lo:[1,0,0] neg_hi:[1,0,0]
	v_pk_add_f32 v[28:29], v[12:13], v[30:31]
	v_pk_add_f32 v[12:13], v[12:13], v[30:31] neg_lo:[0,1] neg_hi:[0,1]
	s_mov_b32 s0, 0
	v_pk_mul_f32 v[30:31], v[12:13], s[10:11]
	s_nop 0
	v_pk_fma_f32 v[12:13], v[12:13], s[14:15], v[30:31] op_sel:[0,0,1] op_sel_hi:[1,0,0] neg_lo:[1,0,0] neg_hi:[1,0,0]
	v_pk_add_f32 v[30:31], v[14:15], v[24:25]
	v_pk_add_f32 v[14:15], v[14:15], v[24:25] neg_lo:[0,1] neg_hi:[0,1]
	v_pk_mul_f32 v[24:25], v[14:15], s[18:19]
	v_pk_fma_f32 v[14:15], v[14:15], s[30:31], v[24:25] op_sel:[0,0,1] op_sel_hi:[1,0,0] neg_lo:[1,0,0] neg_hi:[1,0,0]
	v_pk_add_f32 v[24:25], v[82:83], v[22:23]
	v_pk_add_f32 v[22:23], v[82:83], v[22:23] neg_lo:[0,1] neg_hi:[0,1]
	v_pk_add_f32 v[82:83], v[16:17], v[26:27]
	v_pk_add_f32 v[16:17], v[16:17], v[26:27] neg_lo:[0,1] neg_hi:[0,1]
	v_pk_mul_f32 v[26:27], v[16:17], s[10:11]
	v_pk_fma_f32 v[16:17], v[16:17], s[14:15], v[26:27] op_sel:[0,0,1] op_sel_hi:[1,0,0]
	v_pk_add_f32 v[26:27], v[18:19], v[28:29]
	v_pk_add_f32 v[18:19], v[18:19], v[28:29] neg_lo:[0,1] neg_hi:[0,1]
	v_pk_add_f32 v[28:29], v[20:21], v[30:31]
	v_pk_add_f32 v[20:21], v[20:21], v[30:31] neg_lo:[0,1] neg_hi:[0,1]
	v_pk_mul_f32 v[30:31], v[20:21], s[10:11]
	v_pk_fma_f32 v[20:21], v[20:21], s[14:15], v[30:31] op_sel:[0,0,1] op_sel_hi:[1,0,0] neg_lo:[1,0,0] neg_hi:[1,0,0]
	v_pk_add_f32 v[30:31], v[0:1], v[8:9] op_sel:[0,1] op_sel_hi:[1,0] neg_hi:[0,1]
	v_pk_add_f32 v[0:1], v[0:1], v[8:9] op_sel:[0,1] op_sel_hi:[1,0] neg_lo:[0,1]
	v_pk_add_f32 v[8:9], v[2:3], v[10:11]
	v_pk_add_f32 v[2:3], v[2:3], v[10:11] neg_lo:[0,1] neg_hi:[0,1]
	v_pk_mul_f32 v[10:11], v[2:3], s[10:11]
	v_pk_fma_f32 v[2:3], v[2:3], s[14:15], v[10:11] op_sel:[0,0,1] op_sel_hi:[1,0,0]
	v_pk_add_f32 v[10:11], v[4:5], v[12:13]
	v_pk_add_f32 v[4:5], v[4:5], v[12:13] neg_lo:[0,1] neg_hi:[0,1]
	v_pk_add_f32 v[12:13], v[6:7], v[14:15]
	v_pk_add_f32 v[6:7], v[6:7], v[14:15] neg_lo:[0,1] neg_hi:[0,1]
	v_pk_mul_f32 v[14:15], v[6:7], s[10:11]
	v_pk_fma_f32 v[6:7], v[6:7], s[14:15], v[14:15] op_sel:[0,0,1] op_sel_hi:[1,0,0] neg_lo:[1,0,0] neg_hi:[1,0,0]
	v_pk_add_f32 v[14:15], v[24:25], v[26:27]
	v_pk_add_f32 v[24:25], v[24:25], v[26:27] neg_lo:[0,1] neg_hi:[0,1]
	v_pk_add_f32 v[26:27], v[82:83], v[28:29]
	v_pk_add_f32 v[28:29], v[82:83], v[28:29] neg_lo:[0,1] neg_hi:[0,1]
	v_pk_add_f32 v[82:83], v[22:23], v[18:19] op_sel:[0,1] op_sel_hi:[1,0] neg_hi:[0,1]
	v_pk_add_f32 v[18:19], v[22:23], v[18:19] op_sel:[0,1] op_sel_hi:[1,0] neg_lo:[0,1]
	v_pk_add_f32 v[22:23], v[16:17], v[20:21]
	v_pk_add_f32 v[16:17], v[16:17], v[20:21] neg_lo:[0,1] neg_hi:[0,1]
	v_pk_add_f32 v[20:21], v[30:31], v[10:11]
	v_pk_add_f32 v[10:11], v[30:31], v[10:11] neg_lo:[0,1] neg_hi:[0,1]
	v_pk_add_f32 v[30:31], v[8:9], v[12:13]
	v_pk_add_f32 v[8:9], v[8:9], v[12:13] neg_lo:[0,1] neg_hi:[0,1]
	v_pk_add_f32 v[12:13], v[0:1], v[4:5] op_sel:[0,1] op_sel_hi:[1,0] neg_hi:[0,1]
	v_pk_add_f32 v[0:1], v[0:1], v[4:5] op_sel:[0,1] op_sel_hi:[1,0] neg_lo:[0,1]
	v_pk_add_f32 v[4:5], v[2:3], v[6:7]
	v_pk_add_f32 v[2:3], v[2:3], v[6:7] neg_lo:[0,1] neg_hi:[0,1]
	v_pk_mul_f32 v[2:3], v[2:3], s[22:23]
	v_pk_add_f32 v[6:7], v[14:15], v[26:27]
	v_pk_add_f32 v[14:15], v[14:15], v[26:27] neg_lo:[0,1] neg_hi:[0,1]
	v_pk_add_f32 v[26:27], v[24:25], v[28:29] op_sel:[0,1] op_sel_hi:[1,0] neg_hi:[0,1]
	v_pk_add_f32 v[24:25], v[24:25], v[28:29] op_sel:[0,1] op_sel_hi:[1,0] neg_lo:[0,1]
	v_pk_add_f32 v[28:29], v[82:83], v[22:23]
	v_pk_add_f32 v[22:23], v[82:83], v[22:23] neg_lo:[0,1] neg_hi:[0,1]
	v_pk_add_f32 v[82:83], v[18:19], v[16:17] op_sel:[0,1] op_sel_hi:[1,0] neg_hi:[0,1]
	v_pk_add_f32 v[16:17], v[18:19], v[16:17] op_sel:[0,1] op_sel_hi:[1,0] neg_lo:[0,1]
	v_pk_add_f32 v[18:19], v[20:21], v[30:31]
	v_pk_add_f32 v[20:21], v[20:21], v[30:31] neg_lo:[0,1] neg_hi:[0,1]
	v_pk_add_f32 v[30:31], v[10:11], v[8:9] op_sel:[0,1] op_sel_hi:[1,0] neg_hi:[0,1]
	v_pk_add_f32 v[8:9], v[10:11], v[8:9] op_sel:[0,1] op_sel_hi:[1,0] neg_lo:[0,1]
	v_pk_add_f32 v[10:11], v[12:13], v[4:5]
	v_pk_add_f32 v[4:5], v[12:13], v[4:5] neg_lo:[0,1] neg_hi:[0,1]
	v_pk_add_f32 v[12:13], v[0:1], v[2:3] op_sel:[0,1] op_sel_hi:[1,0]
	v_pk_add_f32 v[0:1], v[0:1], v[2:3] op_sel:[0,1] op_sel_hi:[1,0] neg_lo:[0,1] neg_hi:[0,1]
	v_lshlrev_b32_e32 v2, 4, v47
	v_and_or_b32 v2, v2, s15, v81
	v_ashrrev_i32_e32 v3, 4, v2
	v_lshlrev_b32_e32 v3, 3, v3
	v_lshlrev_b32_e32 v2, 3, v2
	v_add3_u32 v2, 0, v3, v2
	ds_write_b64 v2, v[6:7]
	ds_write_b64 v2, v[14:15] offset:34816
	ds_write_b64 v2, v[26:27] offset:17408
	ds_write_b64 v2, v[24:25] offset:52224
	ds_write_b64 v2, v[28:29] offset:8704
	ds_write_b64 v2, v[22:23] offset:43520
	ds_write_b64 v2, v[82:83] offset:26112
	ds_write_b64 v2, v[16:17] offset:60928
	ds_write_b64 v2, v[18:19] offset:4352
	ds_write_b64 v2, v[20:21] offset:39168
	ds_write_b64 v2, v[30:31] offset:21760
	ds_write_b64 v2, v[8:9] offset:56576
	ds_write_b64 v2, v[10:11] offset:13056
	ds_write_b64 v2, v[4:5] offset:47872
	ds_write_b64 v2, v[12:13] offset:30464
	ds_write_b64 v2, v[0:1] offset:65280
	v_mov_b32_e32 v0, v154
	v_mov_b32_e32 v1, v156
	v_mov_b32_e32 v2, v155
	s_waitcnt lgkmcnt(0)
	s_barrier
.LBB0_485:
	v_or_b32_e32 v3, s0, v32
	v_cmp_ne_u32_e32 vcc, 0, v3
	v_add_u32_e32 v9, 0, v2
	v_add_u32_e32 v4, 0x11000, v9
	v_cndmask_b32_e32 v3, 0, v0, vcc
	v_lshl_add_u32 v3, v3, 3, 0
	v_add_u32_e32 v3, 0x11000, v3
	ds_read_b64 v[4:5], v4
	ds_read_b64 v[6:7], v3
	s_add_i32 s0, s0, 2
	v_add_u32_e32 v2, 0x2200, v2
	v_add_u32_e32 v0, 0xfffffbc0, v0
	s_cmp_lg_u32 s0, 16
	s_waitcnt lgkmcnt(0)
	v_add_f32_e32 v3, v5, v7
	v_mul_f32_e32 v8, 0.5, v3
	v_sub_f32_e32 v3, v4, v6
	ds_read_b64 v[6:7], v9
	v_mul_f32_e32 v4, -0.5, v3
	v_add_u32_e32 v3, 0x12100, v9
	s_waitcnt lgkmcnt(0)
	v_pk_mul_f32 v[4:5], v[6:7], v[4:5] op_sel:[1,0] op_sel_hi:[0,0]
	v_pk_fma_f32 v[10:11], v[6:7], v[8:9], v[4:5] neg_lo:[0,0,1] neg_hi:[0,0,1]
	v_pk_fma_f32 v[4:5], v[6:7], v[8:9], v[4:5] op_sel_hi:[1,0,1]
	s_nop 0
	v_mov_b32_e32 v11, v5
	v_pk_mul_f32 v[4:5], v[10:11], s[24:25]
	ds_write_b64 v9, v[4:5]
	ds_read_b64 v[4:5], v3
	v_add_u32_e32 v3, 0, v1
	v_add_u32_e32 v3, 0x1ff00, v3
	ds_read_b64 v[6:7], v3
	v_add_u32_e32 v1, 0xffffde00, v1
	s_waitcnt lgkmcnt(0)
	v_add_f32_e32 v3, v5, v7
	v_mul_f32_e32 v8, 0.5, v3
	v_sub_f32_e32 v3, v4, v6
	ds_read_b64 v[6:7], v9 offset:4352
	v_mul_f32_e32 v4, -0.5, v3
	s_waitcnt lgkmcnt(0)
	v_pk_mul_f32 v[4:5], v[6:7], v[4:5] op_sel:[1,0] op_sel_hi:[0,0]
	v_pk_fma_f32 v[10:11], v[6:7], v[8:9], v[4:5] neg_lo:[0,0,1] neg_hi:[0,0,1]
	v_pk_fma_f32 v[4:5], v[6:7], v[8:9], v[4:5] op_sel_hi:[1,0,1]
	s_nop 0
	v_mov_b32_e32 v11, v5
	v_pk_mul_f32 v[4:5], v[10:11], s[24:25]
	ds_write_b64 v9, v[4:5] offset:4352
	s_cbranch_scc1 .LBB0_485
	s_waitcnt lgkmcnt(0)
	s_barrier
	s_and_saveexec_b64 s[0:1], s[40:41]
	s_cbranch_execz .LBB0_488
	ds_read_b64 v[0:1], v37 offset:2176
	ds_read_b64 v[2:3], v37 offset:4352
	ds_read_b64 v[4:5], v37 offset:6528
	ds_read_b64 v[6:7], v37 offset:8704
	ds_read_b64 v[8:9], v37 offset:10880
	ds_read_b64 v[10:11], v37 offset:13056
	ds_read_b64 v[12:13], v37 offset:15232
	ds_read_b64 v[14:15], v37 offset:17408
	ds_read_b64 v[16:17], v37 offset:19584
	ds_read_b64 v[18:19], v37 offset:21760
	ds_read_b64 v[20:21], v37 offset:23936
	ds_read_b64 v[22:23], v37 offset:26112
	ds_read_b64 v[24:25], v37 offset:34816
	ds_read_b64 v[26:27], v37 offset:36992
	ds_read_b64 v[28:29], v37 offset:39168
	ds_read_b64 v[30:31], v37 offset:41344
	ds_read_b64 v[82:83], v37 offset:43520
	ds_read_b64 v[84:85], v37 offset:45696
	ds_read_b64 v[118:119], v37 offset:47872
	ds_read_b64 v[120:121], v37 offset:50048
	ds_read_b64 v[122:123], v37 offset:52224
	ds_read_b64 v[124:125], v37 offset:54400
	ds_read_b64 v[126:127], v37 offset:56576
	ds_read_b64 v[128:129], v37 offset:58752
	ds_read_b64 v[130:131], v37
	ds_read_b64 v[132:133], v37 offset:60928
	ds_read_b64 v[134:135], v37 offset:63104
	ds_read_b64 v[136:137], v37 offset:65280
	s_mov_b32 s11, s14
	s_waitcnt lgkmcnt(3)
	v_pk_add_f32 v[158:159], v[130:131], v[24:25]
	v_pk_add_f32 v[24:25], v[130:131], v[24:25] neg_lo:[0,1] neg_hi:[0,1]
	v_pk_add_f32 v[130:131], v[0:1], v[26:27]
	v_pk_add_f32 v[0:1], v[0:1], v[26:27] neg_lo:[0,1] neg_hi:[0,1]
	s_mov_b32 s13, s86
	v_pk_mul_f32 v[26:27], v[0:1], s[16:17]
	s_mov_b32 s4, s21
	v_pk_fma_f32 v[0:1], v[0:1], s[6:7], v[26:27] op_sel:[0,0,1] op_sel_hi:[1,0,0]
	v_pk_add_f32 v[26:27], v[2:3], v[28:29]
	v_pk_add_f32 v[2:3], v[2:3], v[28:29] neg_lo:[0,1] neg_hi:[0,1]
	s_mov_b32 s35, s30
	v_pk_mul_f32 v[28:29], v[2:3], s[18:19]
	s_mov_b32 s8, s19
	v_pk_fma_f32 v[2:3], v[2:3], s[30:31], v[28:29] op_sel:[0,0,1] op_sel_hi:[1,0,0]
	v_pk_add_f32 v[28:29], v[4:5], v[30:31]
	v_pk_add_f32 v[4:5], v[4:5], v[30:31] neg_lo:[0,1] neg_hi:[0,1]
	s_mov_b32 s77, s6
	v_pk_mul_f32 v[30:31], v[4:5], s[20:21]
	s_mov_b32 s28, s17
	v_pk_fma_f32 v[4:5], v[4:5], s[86:87], v[30:31] op_sel:[0,0,1] op_sel_hi:[1,0,0]
	v_pk_add_f32 v[30:31], v[6:7], v[82:83]
	v_pk_add_f32 v[6:7], v[6:7], v[82:83] neg_lo:[0,1] neg_hi:[0,1]
	v_add_u32_e32 v47, 0x10780, v37
	v_pk_mul_f32 v[82:83], v[6:7], s[10:11]
	ds_read_b64 v[138:139], v37 offset:28288
	ds_read_b64 v[140:141], v37 offset:30464
	ds_read_b64 v[142:143], v37 offset:32640
	ds_read_b64 v[144:145], v47
	v_pk_fma_f32 v[6:7], v[6:7], s[14:15], v[82:83] op_sel:[0,0,1] op_sel_hi:[1,0,0]
	v_pk_add_f32 v[82:83], v[8:9], v[84:85]
	v_pk_add_f32 v[8:9], v[8:9], v[84:85] neg_lo:[0,1] neg_hi:[0,1]
	v_pk_mul_f32 v[84:85], v[8:9], s[12:13]
	v_pk_fma_f32 v[8:9], v[8:9], s[4:5], v[84:85] op_sel:[0,0,1] op_sel_hi:[1,0,0]
	v_pk_add_f32 v[84:85], v[10:11], v[118:119]
	v_pk_add_f32 v[10:11], v[10:11], v[118:119] neg_lo:[0,1] neg_hi:[0,1]
	v_pk_mul_f32 v[118:119], v[10:11], s[34:35]
	v_pk_fma_f32 v[10:11], v[10:11], s[8:9], v[118:119] op_sel:[0,0,1] op_sel_hi:[1,0,0]
	v_pk_add_f32 v[118:119], v[12:13], v[120:121]
	v_pk_add_f32 v[12:13], v[12:13], v[120:121] neg_lo:[0,1] neg_hi:[0,1]
	v_pk_mul_f32 v[120:121], v[12:13], s[76:77]
	v_pk_fma_f32 v[12:13], v[12:13], s[28:29], v[120:121] op_sel:[0,0,1] op_sel_hi:[1,0,0]
	v_pk_add_f32 v[120:121], v[14:15], v[122:123]
	v_pk_add_f32 v[14:15], v[14:15], v[122:123] neg_lo:[0,1] neg_hi:[0,1]
	v_pk_add_f32 v[122:123], v[16:17], v[124:125]
	v_pk_add_f32 v[16:17], v[16:17], v[124:125] neg_lo:[0,1] neg_hi:[0,1]
	v_pk_mul_f32 v[124:125], v[16:17], s[76:77]
	v_pk_fma_f32 v[16:17], v[16:17], s[28:29], v[124:125] op_sel:[0,0,1] op_sel_hi:[1,0,0] neg_lo:[1,0,0] neg_hi:[1,0,0]
	v_pk_add_f32 v[124:125], v[18:19], v[126:127]
	v_pk_add_f32 v[18:19], v[18:19], v[126:127] neg_lo:[0,1] neg_hi:[0,1]
	v_pk_mul_f32 v[126:127], v[18:19], s[34:35]
	v_pk_fma_f32 v[18:19], v[18:19], s[8:9], v[126:127] op_sel:[0,0,1] op_sel_hi:[1,0,0] neg_lo:[1,0,0] neg_hi:[1,0,0]
	v_pk_add_f32 v[126:127], v[20:21], v[128:129]
	v_pk_add_f32 v[20:21], v[20:21], v[128:129] neg_lo:[0,1] neg_hi:[0,1]
	v_pk_mul_f32 v[128:129], v[20:21], s[12:13]
	v_pk_fma_f32 v[20:21], v[20:21], s[4:5], v[128:129] op_sel:[0,0,1] op_sel_hi:[1,0,0] neg_lo:[1,0,0] neg_hi:[1,0,0]
	s_waitcnt lgkmcnt(6)
	v_pk_add_f32 v[128:129], v[22:23], v[132:133]
	v_pk_add_f32 v[22:23], v[22:23], v[132:133] neg_lo:[0,1] neg_hi:[0,1]
	s_nop 0
	v_pk_mul_f32 v[132:133], v[22:23], s[10:11]
	v_pk_fma_f32 v[22:23], v[22:23], s[14:15], v[132:133] op_sel:[0,0,1] op_sel_hi:[1,0,0] neg_lo:[1,0,0] neg_hi:[1,0,0]
	s_waitcnt lgkmcnt(3)
	v_pk_add_f32 v[132:133], v[138:139], v[134:135]
	v_pk_add_f32 v[134:135], v[138:139], v[134:135] neg_lo:[0,1] neg_hi:[0,1]
	s_nop 0
	v_pk_mul_f32 v[138:139], v[134:135], s[20:21]
	v_pk_fma_f32 v[134:135], v[134:135], s[86:87], v[138:139] op_sel:[0,0,1] op_sel_hi:[1,0,0] neg_lo:[1,0,0] neg_hi:[1,0,0]
	s_waitcnt lgkmcnt(2)
	v_pk_add_f32 v[138:139], v[140:141], v[136:137]
	v_pk_add_f32 v[136:137], v[140:141], v[136:137] neg_lo:[0,1] neg_hi:[0,1]
	s_nop 0
	v_pk_mul_f32 v[140:141], v[136:137], s[18:19]
	v_pk_fma_f32 v[136:137], v[136:137], s[30:31], v[140:141] op_sel:[0,0,1] op_sel_hi:[1,0,0] neg_lo:[1,0,0] neg_hi:[1,0,0]
	s_waitcnt lgkmcnt(0)
	v_pk_add_f32 v[140:141], v[142:143], v[144:145]
	v_pk_add_f32 v[142:143], v[142:143], v[144:145] neg_lo:[0,1] neg_hi:[0,1]
	s_nop 0
	v_pk_mul_f32 v[144:145], v[142:143], s[16:17]
	v_pk_fma_f32 v[142:143], v[142:143], s[6:7], v[144:145] op_sel:[0,0,1] op_sel_hi:[1,0,0] neg_lo:[1,0,0] neg_hi:[1,0,0]
	v_pk_add_f32 v[144:145], v[158:159], v[120:121]
	v_pk_add_f32 v[120:121], v[158:159], v[120:121] neg_lo:[0,1] neg_hi:[0,1]
	v_pk_add_f32 v[158:159], v[130:131], v[122:123]
	v_pk_add_f32 v[122:123], v[130:131], v[122:123] neg_lo:[0,1] neg_hi:[0,1]
	v_pk_mul_f32 v[130:131], v[122:123], s[18:19]
	v_pk_fma_f32 v[122:123], v[122:123], s[30:31], v[130:131] op_sel:[0,0,1] op_sel_hi:[1,0,0]
	v_pk_add_f32 v[130:131], v[26:27], v[124:125]
	v_pk_add_f32 v[26:27], v[26:27], v[124:125] neg_lo:[0,1] neg_hi:[0,1]
	v_pk_mul_f32 v[124:125], v[26:27], s[10:11]
	v_pk_fma_f32 v[26:27], v[26:27], s[14:15], v[124:125] op_sel:[0,0,1] op_sel_hi:[1,0,0]
	v_pk_add_f32 v[124:125], v[28:29], v[126:127]
	v_pk_add_f32 v[28:29], v[28:29], v[126:127] neg_lo:[0,1] neg_hi:[0,1]
	v_pk_mul_f32 v[126:127], v[28:29], s[34:35]
	v_pk_fma_f32 v[28:29], v[28:29], s[8:9], v[126:127] op_sel:[0,0,1] op_sel_hi:[1,0,0]
	v_pk_add_f32 v[126:127], v[30:31], v[128:129]
	v_pk_add_f32 v[30:31], v[30:31], v[128:129] neg_lo:[0,1] neg_hi:[0,1]
	v_pk_add_f32 v[128:129], v[82:83], v[132:133]
	v_pk_add_f32 v[82:83], v[82:83], v[132:133] neg_lo:[0,1] neg_hi:[0,1]
	v_pk_mul_f32 v[132:133], v[82:83], s[34:35]
	v_pk_fma_f32 v[82:83], v[82:83], s[8:9], v[132:133] op_sel:[0,0,1] op_sel_hi:[1,0,0] neg_lo:[1,0,0] neg_hi:[1,0,0]
	v_pk_add_f32 v[132:133], v[84:85], v[138:139]
	v_pk_add_f32 v[84:85], v[84:85], v[138:139] neg_lo:[0,1] neg_hi:[0,1]
	v_pk_mul_f32 v[138:139], v[84:85], s[10:11]
	v_pk_fma_f32 v[84:85], v[84:85], s[14:15], v[138:139] op_sel:[0,0,1] op_sel_hi:[1,0,0] neg_lo:[1,0,0] neg_hi:[1,0,0]
	v_pk_add_f32 v[138:139], v[118:119], v[140:141]
	v_pk_add_f32 v[118:119], v[118:119], v[140:141] neg_lo:[0,1] neg_hi:[0,1]
	v_pk_mul_f32 v[140:141], v[118:119], s[18:19]
	v_pk_fma_f32 v[118:119], v[118:119], s[30:31], v[140:141] op_sel:[0,0,1] op_sel_hi:[1,0,0] neg_lo:[1,0,0] neg_hi:[1,0,0]
	v_pk_add_f32 v[140:141], v[24:25], v[14:15] op_sel:[0,1] op_sel_hi:[1,0] neg_hi:[0,1]
	v_pk_add_f32 v[14:15], v[24:25], v[14:15] op_sel:[0,1] op_sel_hi:[1,0] neg_lo:[0,1]
	v_pk_add_f32 v[24:25], v[0:1], v[16:17]
	v_pk_add_f32 v[0:1], v[0:1], v[16:17] neg_lo:[0,1] neg_hi:[0,1]
	v_pk_mul_f32 v[16:17], v[0:1], s[18:19]
	v_pk_fma_f32 v[0:1], v[0:1], s[30:31], v[16:17] op_sel:[0,0,1] op_sel_hi:[1,0,0]
	v_pk_add_f32 v[16:17], v[2:3], v[18:19]
	v_pk_add_f32 v[2:3], v[2:3], v[18:19] neg_lo:[0,1] neg_hi:[0,1]
	v_pk_mul_f32 v[18:19], v[2:3], s[10:11]
	v_pk_fma_f32 v[2:3], v[2:3], s[14:15], v[18:19] op_sel:[0,0,1] op_sel_hi:[1,0,0]
	v_pk_add_f32 v[18:19], v[4:5], v[20:21]
	v_pk_add_f32 v[4:5], v[4:5], v[20:21] neg_lo:[0,1] neg_hi:[0,1]
	v_pk_mul_f32 v[20:21], v[4:5], s[34:35]
	v_pk_fma_f32 v[4:5], v[4:5], s[8:9], v[20:21] op_sel:[0,0,1] op_sel_hi:[1,0,0]
	v_pk_add_f32 v[20:21], v[6:7], v[22:23]
	v_pk_add_f32 v[6:7], v[6:7], v[22:23] neg_lo:[0,1] neg_hi:[0,1]
	v_pk_add_f32 v[22:23], v[8:9], v[134:135]
	v_pk_add_f32 v[8:9], v[8:9], v[134:135] neg_lo:[0,1] neg_hi:[0,1]
	v_pk_mul_f32 v[134:135], v[8:9], s[34:35]
	v_pk_fma_f32 v[8:9], v[8:9], s[8:9], v[134:135] op_sel:[0,0,1] op_sel_hi:[1,0,0] neg_lo:[1,0,0] neg_hi:[1,0,0]
	v_pk_add_f32 v[134:135], v[10:11], v[136:137]
	v_pk_add_f32 v[10:11], v[10:11], v[136:137] neg_lo:[0,1] neg_hi:[0,1]
	v_pk_mul_f32 v[136:137], v[10:11], s[10:11]
	v_pk_fma_f32 v[10:11], v[10:11], s[14:15], v[136:137] op_sel:[0,0,1] op_sel_hi:[1,0,0] neg_lo:[1,0,0] neg_hi:[1,0,0]
	v_pk_add_f32 v[136:137], v[12:13], v[142:143]
	v_pk_add_f32 v[12:13], v[12:13], v[142:143] neg_lo:[0,1] neg_hi:[0,1]
	v_pk_mul_f32 v[142:143], v[12:13], s[18:19]
	v_pk_fma_f32 v[12:13], v[12:13], s[30:31], v[142:143] op_sel:[0,0,1] op_sel_hi:[1,0,0] neg_lo:[1,0,0] neg_hi:[1,0,0]
	v_pk_add_f32 v[142:143], v[144:145], v[126:127]
	v_pk_add_f32 v[126:127], v[144:145], v[126:127] neg_lo:[0,1] neg_hi:[0,1]
	v_pk_add_f32 v[144:145], v[158:159], v[128:129]
	v_pk_add_f32 v[128:129], v[158:159], v[128:129] neg_lo:[0,1] neg_hi:[0,1]
	v_pk_mul_f32 v[158:159], v[128:129], s[10:11]
	v_pk_fma_f32 v[128:129], v[128:129], s[14:15], v[158:159] op_sel:[0,0,1] op_sel_hi:[1,0,0]
	v_pk_add_f32 v[158:159], v[130:131], v[132:133]
	v_pk_add_f32 v[130:131], v[130:131], v[132:133] neg_lo:[0,1] neg_hi:[0,1]
	v_pk_add_f32 v[132:133], v[124:125], v[138:139]
	v_pk_add_f32 v[124:125], v[124:125], v[138:139] neg_lo:[0,1] neg_hi:[0,1]
	v_pk_mul_f32 v[138:139], v[124:125], s[10:11]
	v_pk_fma_f32 v[124:125], v[124:125], s[14:15], v[138:139] op_sel:[0,0,1] op_sel_hi:[1,0,0] neg_lo:[1,0,0] neg_hi:[1,0,0]
	v_pk_add_f32 v[138:139], v[120:121], v[30:31] op_sel:[0,1] op_sel_hi:[1,0] neg_hi:[0,1]
	v_pk_add_f32 v[30:31], v[120:121], v[30:31] op_sel:[0,1] op_sel_hi:[1,0] neg_lo:[0,1]
	v_pk_add_f32 v[120:121], v[122:123], v[82:83]
	v_pk_add_f32 v[82:83], v[122:123], v[82:83] neg_lo:[0,1] neg_hi:[0,1]
	v_pk_add_f32 v[160:161], v[128:129], v[124:125]
	v_pk_mul_f32 v[122:123], v[82:83], s[10:11]
	v_pk_add_f32 v[124:125], v[128:129], v[124:125] neg_lo:[0,1] neg_hi:[0,1]
	v_pk_fma_f32 v[82:83], v[82:83], s[14:15], v[122:123] op_sel:[0,0,1] op_sel_hi:[1,0,0]
	v_pk_add_f32 v[122:123], v[26:27], v[84:85]
	v_pk_add_f32 v[26:27], v[26:27], v[84:85] neg_lo:[0,1] neg_hi:[0,1]
	v_pk_add_f32 v[84:85], v[28:29], v[118:119]
	v_pk_add_f32 v[28:29], v[28:29], v[118:119] neg_lo:[0,1] neg_hi:[0,1]
	v_pk_mul_f32 v[118:119], v[28:29], s[10:11]
	v_pk_add_f32 v[166:167], v[120:121], v[84:85]
	v_pk_fma_f32 v[28:29], v[28:29], s[14:15], v[118:119] op_sel:[0,0,1] op_sel_hi:[1,0,0] neg_lo:[1,0,0] neg_hi:[1,0,0]
	v_pk_add_f32 v[118:119], v[140:141], v[20:21]
	v_pk_add_f32 v[20:21], v[140:141], v[20:21] neg_lo:[0,1] neg_hi:[0,1]
	v_pk_add_f32 v[140:141], v[24:25], v[22:23]
	v_pk_add_f32 v[22:23], v[24:25], v[22:23] neg_lo:[0,1] neg_hi:[0,1]
	v_pk_add_f32 v[84:85], v[120:121], v[84:85] neg_lo:[0,1] neg_hi:[0,1]
	v_pk_mul_f32 v[24:25], v[22:23], s[10:11]
	v_pk_add_f32 v[168:169], v[30:31], v[26:27] op_sel:[0,1] op_sel_hi:[1,0] neg_hi:[0,1]
	v_pk_fma_f32 v[22:23], v[22:23], s[14:15], v[24:25] op_sel:[0,0,1] op_sel_hi:[1,0,0]
	v_pk_add_f32 v[24:25], v[16:17], v[134:135]
	v_pk_add_f32 v[16:17], v[16:17], v[134:135] neg_lo:[0,1] neg_hi:[0,1]
	v_pk_add_f32 v[134:135], v[18:19], v[136:137]
	v_pk_add_f32 v[18:19], v[18:19], v[136:137] neg_lo:[0,1] neg_hi:[0,1]
	v_pk_mul_f32 v[136:137], v[18:19], s[10:11]
	v_pk_add_f32 v[26:27], v[30:31], v[26:27] op_sel:[0,1] op_sel_hi:[1,0] neg_lo:[0,1]
	v_pk_fma_f32 v[18:19], v[18:19], s[14:15], v[136:137] op_sel:[0,0,1] op_sel_hi:[1,0,0] neg_lo:[1,0,0] neg_hi:[1,0,0]
	v_pk_add_f32 v[136:137], v[14:15], v[6:7] op_sel:[0,1] op_sel_hi:[1,0] neg_hi:[0,1]
	v_pk_add_f32 v[6:7], v[14:15], v[6:7] op_sel:[0,1] op_sel_hi:[1,0] neg_lo:[0,1]
	v_pk_add_f32 v[14:15], v[0:1], v[8:9]
	v_pk_add_f32 v[0:1], v[0:1], v[8:9] neg_lo:[0,1] neg_hi:[0,1]
	v_pk_add_f32 v[30:31], v[82:83], v[28:29]
	v_pk_mul_f32 v[8:9], v[0:1], s[10:11]
	v_pk_add_f32 v[28:29], v[82:83], v[28:29] neg_lo:[0,1] neg_hi:[0,1]
	v_pk_fma_f32 v[0:1], v[0:1], s[14:15], v[8:9] op_sel:[0,0,1] op_sel_hi:[1,0,0]
	v_pk_add_f32 v[8:9], v[2:3], v[10:11]
	v_pk_add_f32 v[2:3], v[2:3], v[10:11] neg_lo:[0,1] neg_hi:[0,1]
	v_pk_add_f32 v[10:11], v[4:5], v[12:13]
	v_pk_add_f32 v[4:5], v[4:5], v[12:13] neg_lo:[0,1] neg_hi:[0,1]
	v_pk_mul_f32 v[12:13], v[4:5], s[10:11]
	v_pk_add_f32 v[170:171], v[118:119], v[24:25]
	v_pk_fma_f32 v[4:5], v[4:5], s[14:15], v[12:13] op_sel:[0,0,1] op_sel_hi:[1,0,0] neg_lo:[1,0,0] neg_hi:[1,0,0]
	v_pk_add_f32 v[12:13], v[142:143], v[158:159]
	v_pk_add_f32 v[142:143], v[142:143], v[158:159] neg_lo:[0,1] neg_hi:[0,1]
	v_pk_add_f32 v[158:159], v[144:145], v[132:133]
	v_pk_add_f32 v[132:133], v[144:145], v[132:133] neg_lo:[0,1] neg_hi:[0,1]
	v_pk_add_f32 v[182:183], v[118:119], v[24:25] neg_lo:[0,1] neg_hi:[0,1]
	v_pk_add_f32 v[184:185], v[140:141], v[134:135]
	v_pk_add_f32 v[24:25], v[140:141], v[134:135] neg_lo:[0,1] neg_hi:[0,1]
	v_pk_add_f32 v[140:141], v[20:21], v[16:17] op_sel:[0,1] op_sel_hi:[1,0] neg_hi:[0,1]
	v_pk_add_f32 v[186:187], v[20:21], v[16:17] op_sel:[0,1] op_sel_hi:[1,0] neg_lo:[0,1]
	v_pk_add_f32 v[16:17], v[22:23], v[18:19] neg_lo:[0,1] neg_hi:[0,1]
	v_pk_add_f32 v[192:193], v[136:137], v[8:9]
	v_pk_add_f32 v[194:195], v[136:137], v[8:9] neg_lo:[0,1] neg_hi:[0,1]
	v_pk_add_f32 v[8:9], v[14:15], v[10:11] neg_lo:[0,1] neg_hi:[0,1]
	v_pk_add_f32 v[198:199], v[6:7], v[2:3] op_sel:[0,1] op_sel_hi:[1,0] neg_hi:[0,1]
	v_pk_add_f32 v[200:201], v[6:7], v[2:3] op_sel:[0,1] op_sel_hi:[1,0] neg_lo:[0,1]
	v_pk_add_f32 v[2:3], v[0:1], v[4:5]
	v_pk_add_f32 v[0:1], v[0:1], v[4:5] neg_lo:[0,1] neg_hi:[0,1]
	v_pk_add_f32 v[144:145], v[126:127], v[130:131] op_sel:[0,1] op_sel_hi:[1,0] neg_hi:[0,1]
	v_pk_add_f32 v[130:131], v[126:127], v[130:131] op_sel:[0,1] op_sel_hi:[1,0] neg_lo:[0,1]
	v_pk_mul_f32 v[162:163], v[124:125], s[22:23]
	v_pk_add_f32 v[164:165], v[138:139], v[122:123]
	v_pk_add_f32 v[138:139], v[138:139], v[122:123] neg_lo:[0,1] neg_hi:[0,1]
	v_pk_mul_f32 v[82:83], v[28:29], s[22:23]
	v_pk_mul_f32 v[134:135], v[24:25], s[22:23]
	v_pk_add_f32 v[188:189], v[22:23], v[18:19]
	v_pk_mul_f32 v[190:191], v[16:17], s[22:23]
	v_pk_add_f32 v[136:137], v[14:15], v[10:11]
	v_pk_mul_f32 v[196:197], v[8:9], s[22:23]
	v_pk_mul_f32 v[202:203], v[0:1], s[22:23]
	v_pk_add_f32 v[28:29], v[12:13], v[158:159]
	v_pk_add_f32 v[128:129], v[12:13], v[158:159] neg_lo:[0,1] neg_hi:[0,1]
	v_pk_add_f32 v[24:25], v[142:143], v[132:133] op_sel:[0,1] op_sel_hi:[1,0] neg_hi:[0,1]
	v_pk_add_f32 v[126:127], v[142:143], v[132:133] op_sel:[0,1] op_sel_hi:[1,0] neg_lo:[0,1]
	v_pk_add_f32 v[20:21], v[144:145], v[160:161]
	v_pk_add_f32 v[124:125], v[144:145], v[160:161] neg_lo:[0,1] neg_hi:[0,1]
	v_pk_add_f32 v[16:17], v[130:131], v[162:163] op_sel:[0,1] op_sel_hi:[1,0]
	v_pk_add_f32 v[122:123], v[130:131], v[162:163] op_sel:[0,1] op_sel_hi:[1,0] neg_lo:[0,1] neg_hi:[0,1]
	v_pk_add_f32 v[12:13], v[164:165], v[166:167]
	v_pk_add_f32 v[120:121], v[164:165], v[166:167] neg_lo:[0,1] neg_hi:[0,1]
	v_pk_add_f32 v[8:9], v[138:139], v[84:85] op_sel:[0,1] op_sel_hi:[1,0] neg_hi:[0,1]
	v_pk_add_f32 v[118:119], v[138:139], v[84:85] op_sel:[0,1] op_sel_hi:[1,0] neg_lo:[0,1]
	v_pk_add_f32 v[4:5], v[168:169], v[30:31]
	v_pk_add_f32 v[84:85], v[168:169], v[30:31] neg_lo:[0,1] neg_hi:[0,1]
	v_pk_add_f32 v[0:1], v[26:27], v[82:83] op_sel:[0,1] op_sel_hi:[1,0]
	v_pk_add_f32 v[82:83], v[26:27], v[82:83] op_sel:[0,1] op_sel_hi:[1,0] neg_lo:[0,1] neg_hi:[0,1]
	v_pk_add_f32 v[30:31], v[170:171], v[184:185]
	v_pk_add_f32 v[144:145], v[170:171], v[184:185] neg_lo:[0,1] neg_hi:[0,1]
	v_pk_add_f32 v[26:27], v[182:183], v[134:135] op_sel:[0,1] op_sel_hi:[1,0]
	v_pk_add_f32 v[142:143], v[182:183], v[134:135] op_sel:[0,1] op_sel_hi:[1,0] neg_lo:[0,1] neg_hi:[0,1]
	v_pk_add_f32 v[22:23], v[140:141], v[188:189]
	v_pk_add_f32 v[140:141], v[140:141], v[188:189] neg_lo:[0,1] neg_hi:[0,1]
	v_pk_add_f32 v[18:19], v[186:187], v[190:191] op_sel:[0,1] op_sel_hi:[1,0]
	v_pk_add_f32 v[138:139], v[186:187], v[190:191] op_sel:[0,1] op_sel_hi:[1,0] neg_lo:[0,1] neg_hi:[0,1]
	v_pk_add_f32 v[14:15], v[192:193], v[136:137]
	v_pk_add_f32 v[136:137], v[192:193], v[136:137] neg_lo:[0,1] neg_hi:[0,1]
	v_pk_add_f32 v[10:11], v[194:195], v[196:197] op_sel:[0,1] op_sel_hi:[1,0]
	v_pk_add_f32 v[134:135], v[194:195], v[196:197] op_sel:[0,1] op_sel_hi:[1,0] neg_lo:[0,1] neg_hi:[0,1]
	v_pk_add_f32 v[6:7], v[198:199], v[2:3]
	v_pk_add_f32 v[132:133], v[198:199], v[2:3] neg_lo:[0,1] neg_hi:[0,1]
	v_pk_add_f32 v[2:3], v[200:201], v[202:203] op_sel:[0,1] op_sel_hi:[1,0]
	v_pk_add_f32 v[130:131], v[200:201], v[202:203] op_sel:[0,1] op_sel_hi:[1,0] neg_lo:[0,1] neg_hi:[0,1]

.LBB0_490:
	s_or_b64 exec, exec, s[0:1]
	v_mov_b32_e32 v37, v32
	s_waitcnt lgkmcnt(0)
	s_barrier
	s_mov_b32 s11, s14
	v_and_b32_e32 v47, 31, v37
	v_cvt_f32_ubyte0_e32 v24, v47
	v_mul_f32_e32 v81, 0x3b000000, v24
	v_sin_f32_e32 v24, v81
	v_ashrrev_i32_e32 v0, 4, v37
	v_lshlrev_b32_e32 v0, 3, v0
	v_lshlrev_b32_e32 v1, 3, v37
	v_cos_f32_e32 v84, v81
	v_add3_u32 v25, 0, v0, v1
	ds_read_b64 v[0:1], v25
	ds_read_b64 v[2:3], v25 offset:4352
	ds_read_b64 v[4:5], v25 offset:8704
	ds_read_b64 v[6:7], v25 offset:13056
	ds_read_b64 v[8:9], v25 offset:17408
	ds_read_b64 v[10:11], v25 offset:21760
	ds_read_b64 v[12:13], v25 offset:26112
	ds_read_b64 v[14:15], v25 offset:30464
	ds_read_b64 v[16:17], v25 offset:34816
	ds_read_b64 v[18:19], v25 offset:39168
	ds_read_b64 v[20:21], v25 offset:43520
	ds_read_b64 v[22:23], v25 offset:47872
	v_xor_b32_e32 v85, 0x80000000, v24
	s_waitcnt lgkmcnt(10)
	v_pk_mul_f32 v[118:119], v[2:3], v[24:25] op_sel:[1,0] op_sel_hi:[0,0] neg_hi:[0,1]
	v_pk_fma_f32 v[2:3], v[2:3], v[84:85], v[118:119] op_sel_hi:[1,0,1]
	v_pk_mul_f32 v[118:119], v[24:25], v[84:85] op_sel:[0,1] op_sel_hi:[0,0] neg_hi:[1,0]
	v_pk_fma_f32 v[118:119], v[84:85], v[84:85], v[118:119] op_sel_hi:[0,1,1]
	ds_read_b64 v[26:27], v25 offset:52224
	ds_read_b64 v[28:29], v25 offset:56576
	ds_read_b64 v[30:31], v25 offset:60928
	ds_read_b64 v[82:83], v25 offset:65280
	s_waitcnt lgkmcnt(13)
	v_pk_mul_f32 v[120:121], v[4:5], v[118:119] op_sel:[1,1] op_sel_hi:[0,1] neg_lo:[0,1]
	v_pk_fma_f32 v[4:5], v[4:5], v[118:119], v[120:121] op_sel_hi:[1,0,1]
	v_pk_mul_f32 v[120:121], v[24:25], v[118:119] op_sel:[0,1] op_sel_hi:[0,0] neg_hi:[1,0]
	v_pk_fma_f32 v[118:119], v[84:85], v[118:119], v[120:121] op_sel_hi:[0,1,1]
	s_mov_b32 s35, s30
	s_waitcnt lgkmcnt(12)
	v_pk_mul_f32 v[120:121], v[6:7], v[118:119] op_sel:[1,1] op_sel_hi:[0,1] neg_lo:[0,1]
	v_pk_fma_f32 v[6:7], v[6:7], v[118:119], v[120:121] op_sel_hi:[1,0,1]
	v_pk_mul_f32 v[120:121], v[24:25], v[118:119] op_sel:[0,1] op_sel_hi:[0,0] neg_hi:[1,0]
	v_pk_fma_f32 v[118:119], v[84:85], v[118:119], v[120:121] op_sel_hi:[0,1,1]
	s_mov_b32 s0, s19
	s_waitcnt lgkmcnt(11)
	v_pk_mul_f32 v[120:121], v[8:9], v[118:119] op_sel:[1,1] op_sel_hi:[0,1] neg_lo:[0,1]
	v_pk_fma_f32 v[8:9], v[8:9], v[118:119], v[120:121] op_sel_hi:[1,0,1]
	v_pk_mul_f32 v[120:121], v[24:25], v[118:119] op_sel:[0,1] op_sel_hi:[0,0] neg_hi:[1,0]
	v_pk_fma_f32 v[118:119], v[84:85], v[118:119], v[120:121] op_sel_hi:[0,1,1]
	s_waitcnt lgkmcnt(0)
	v_pk_mul_f32 v[120:121], v[10:11], v[118:119] op_sel:[1,1] op_sel_hi:[0,1] neg_lo:[0,1]
	v_pk_fma_f32 v[10:11], v[10:11], v[118:119], v[120:121] op_sel_hi:[1,0,1]
	v_pk_mul_f32 v[120:121], v[24:25], v[118:119] op_sel:[0,1] op_sel_hi:[0,0] neg_hi:[1,0]
	v_pk_fma_f32 v[118:119], v[84:85], v[118:119], v[120:121] op_sel_hi:[0,1,1]
	s_barrier
	v_pk_mul_f32 v[120:121], v[12:13], v[118:119] op_sel:[1,1] op_sel_hi:[0,1] neg_lo:[0,1]
	v_pk_fma_f32 v[12:13], v[12:13], v[118:119], v[120:121] op_sel_hi:[1,0,1]
	v_pk_mul_f32 v[120:121], v[24:25], v[118:119] op_sel:[0,1] op_sel_hi:[0,0] neg_hi:[1,0]
	v_pk_fma_f32 v[118:119], v[84:85], v[118:119], v[120:121] op_sel_hi:[0,1,1]
	v_pk_mul_f32 v[120:121], v[14:15], v[118:119] op_sel:[1,1] op_sel_hi:[0,1] neg_lo:[0,1]
	v_pk_fma_f32 v[14:15], v[14:15], v[118:119], v[120:121] op_sel_hi:[1,0,1]
	v_pk_mul_f32 v[120:121], v[24:25], v[118:119] op_sel:[0,1] op_sel_hi:[0,0] neg_hi:[1,0]
	v_pk_fma_f32 v[118:119], v[84:85], v[118:119], v[120:121] op_sel_hi:[0,1,1]
	v_pk_mul_f32 v[120:121], v[16:17], v[118:119] op_sel:[1,1] op_sel_hi:[0,1] neg_lo:[0,1]
	v_pk_fma_f32 v[16:17], v[16:17], v[118:119], v[120:121] op_sel_hi:[1,0,1]
	v_pk_mul_f32 v[120:121], v[24:25], v[118:119] op_sel:[0,1] op_sel_hi:[0,0] neg_hi:[1,0]
	v_pk_fma_f32 v[118:119], v[84:85], v[118:119], v[120:121] op_sel_hi:[0,1,1]
	v_pk_mul_f32 v[120:121], v[18:19], v[118:119] op_sel:[1,1] op_sel_hi:[0,1] neg_lo:[0,1]
	v_pk_fma_f32 v[18:19], v[18:19], v[118:119], v[120:121] op_sel_hi:[1,0,1]
	v_pk_mul_f32 v[120:121], v[24:25], v[118:119] op_sel:[0,1] op_sel_hi:[0,0] neg_hi:[1,0]
	v_pk_fma_f32 v[118:119], v[84:85], v[118:119], v[120:121] op_sel_hi:[0,1,1]
	v_pk_mul_f32 v[120:121], v[20:21], v[118:119] op_sel:[1,1] op_sel_hi:[0,1] neg_lo:[0,1]
	v_pk_fma_f32 v[20:21], v[20:21], v[118:119], v[120:121] op_sel_hi:[1,0,1]
	v_pk_mul_f32 v[120:121], v[24:25], v[118:119] op_sel:[0,1] op_sel_hi:[0,0] neg_hi:[1,0]
	v_pk_fma_f32 v[118:119], v[84:85], v[118:119], v[120:121] op_sel_hi:[0,1,1]
	v_pk_mul_f32 v[120:121], v[22:23], v[118:119] op_sel:[1,1] op_sel_hi:[0,1] neg_lo:[0,1]
	v_pk_fma_f32 v[22:23], v[22:23], v[118:119], v[120:121] op_sel_hi:[1,0,1]
	v_pk_mul_f32 v[120:121], v[24:25], v[118:119] op_sel:[0,1] op_sel_hi:[0,0] neg_hi:[1,0]
	v_pk_fma_f32 v[118:119], v[84:85], v[118:119], v[120:121] op_sel_hi:[0,1,1]
	v_pk_mul_f32 v[120:121], v[26:27], v[118:119] op_sel:[1,1] op_sel_hi:[0,1] neg_lo:[0,1]
	v_pk_fma_f32 v[26:27], v[26:27], v[118:119], v[120:121] op_sel_hi:[1,0,1]
	v_pk_mul_f32 v[120:121], v[24:25], v[118:119] op_sel:[0,1] op_sel_hi:[0,0] neg_hi:[1,0]
	v_pk_fma_f32 v[118:119], v[84:85], v[118:119], v[120:121] op_sel_hi:[0,1,1]
	v_pk_mul_f32 v[120:121], v[28:29], v[118:119] op_sel:[1,1] op_sel_hi:[0,1] neg_lo:[0,1]
	v_pk_fma_f32 v[28:29], v[28:29], v[118:119], v[120:121] op_sel_hi:[1,0,1]
	v_pk_mul_f32 v[120:121], v[24:25], v[118:119] op_sel:[0,1] op_sel_hi:[0,0] neg_hi:[1,0]
	v_pk_fma_f32 v[118:119], v[84:85], v[118:119], v[120:121] op_sel_hi:[0,1,1]
	v_pk_mul_f32 v[24:25], v[24:25], v[118:119] op_sel:[0,1] op_sel_hi:[0,0] neg_hi:[1,0]
	v_pk_fma_f32 v[24:25], v[84:85], v[118:119], v[24:25] op_sel_hi:[0,1,1]
	v_pk_mul_f32 v[84:85], v[82:83], v[24:25] op_sel:[1,1] op_sel_hi:[0,1] neg_lo:[0,1]
	v_pk_fma_f32 v[24:25], v[82:83], v[24:25], v[84:85] op_sel_hi:[1,0,1]
	v_pk_add_f32 v[82:83], v[0:1], v[16:17]
	v_pk_add_f32 v[0:1], v[0:1], v[16:17] neg_lo:[0,1] neg_hi:[0,1]
	v_pk_add_f32 v[16:17], v[2:3], v[18:19]
	v_pk_add_f32 v[2:3], v[2:3], v[18:19] neg_lo:[0,1] neg_hi:[0,1]
	v_pk_mul_f32 v[120:121], v[30:31], v[118:119] op_sel:[1,1] op_sel_hi:[0,1] neg_lo:[0,1]
	v_pk_mul_f32 v[18:19], v[2:3], s[18:19]
	v_pk_fma_f32 v[30:31], v[30:31], v[118:119], v[120:121] op_sel_hi:[1,0,1]
	v_pk_fma_f32 v[2:3], v[2:3], s[30:31], v[18:19] op_sel:[0,0,1] op_sel_hi:[1,0,0]
	v_pk_add_f32 v[18:19], v[4:5], v[20:21]
	v_pk_add_f32 v[4:5], v[4:5], v[20:21] neg_lo:[0,1] neg_hi:[0,1]
	v_pk_mul_f32 v[20:21], v[4:5], s[10:11]
	v_pk_fma_f32 v[4:5], v[4:5], s[14:15], v[20:21] op_sel:[0,0,1] op_sel_hi:[1,0,0]
	v_pk_add_f32 v[20:21], v[6:7], v[22:23]
	v_pk_add_f32 v[6:7], v[6:7], v[22:23] neg_lo:[0,1] neg_hi:[0,1]
	v_pk_mul_f32 v[22:23], v[6:7], s[34:35]
	v_pk_fma_f32 v[6:7], v[6:7], s[0:1], v[22:23] op_sel:[0,0,1] op_sel_hi:[1,0,0]
	v_pk_add_f32 v[22:23], v[8:9], v[26:27]
	v_pk_add_f32 v[8:9], v[8:9], v[26:27] neg_lo:[0,1] neg_hi:[0,1]
	v_pk_add_f32 v[26:27], v[10:11], v[28:29]
	v_pk_add_f32 v[10:11], v[10:11], v[28:29] neg_lo:[0,1] neg_hi:[0,1]
	v_pk_mul_f32 v[28:29], v[10:11], s[34:35]
	v_pk_fma_f32 v[10:11], v[10:11], s[0:1], v[28:29] op_sel:[0,0,1] op_sel_hi:[1,0,0] neg_lo:[1,0,0] neg_hi:[1,0,0]
	v_pk_add_f32 v[28:29], v[12:13], v[30:31]
	v_pk_add_f32 v[12:13], v[12:13], v[30:31] neg_lo:[0,1] neg_hi:[0,1]
	v_pk_mul_f32 v[30:31], v[12:13], s[10:11]
	v_pk_fma_f32 v[12:13], v[12:13], s[14:15], v[30:31] op_sel:[0,0,1] op_sel_hi:[1,0,0] neg_lo:[1,0,0] neg_hi:[1,0,0]
	v_pk_add_f32 v[30:31], v[14:15], v[24:25]
	v_pk_add_f32 v[14:15], v[14:15], v[24:25] neg_lo:[0,1] neg_hi:[0,1]
	v_pk_mul_f32 v[24:25], v[14:15], s[18:19]
	v_pk_fma_f32 v[14:15], v[14:15], s[30:31], v[24:25] op_sel:[0,0,1] op_sel_hi:[1,0,0] neg_lo:[1,0,0] neg_hi:[1,0,0]
	v_pk_add_f32 v[24:25], v[82:83], v[22:23]
	v_pk_add_f32 v[22:23], v[82:83], v[22:23] neg_lo:[0,1] neg_hi:[0,1]
	v_pk_add_f32 v[82:83], v[16:17], v[26:27]
	v_pk_add_f32 v[16:17], v[16:17], v[26:27] neg_lo:[0,1] neg_hi:[0,1]
	v_pk_mul_f32 v[26:27], v[16:17], s[10:11]
	v_pk_fma_f32 v[16:17], v[16:17], s[14:15], v[26:27] op_sel:[0,0,1] op_sel_hi:[1,0,0]
	v_pk_add_f32 v[26:27], v[18:19], v[28:29]
	v_pk_add_f32 v[18:19], v[18:19], v[28:29] neg_lo:[0,1] neg_hi:[0,1]
	v_pk_add_f32 v[28:29], v[20:21], v[30:31]
	v_pk_add_f32 v[20:21], v[20:21], v[30:31] neg_lo:[0,1] neg_hi:[0,1]
	v_pk_mul_f32 v[30:31], v[20:21], s[10:11]
	v_pk_fma_f32 v[20:21], v[20:21], s[14:15], v[30:31] op_sel:[0,0,1] op_sel_hi:[1,0,0] neg_lo:[1,0,0] neg_hi:[1,0,0]
	v_pk_add_f32 v[30:31], v[0:1], v[8:9] op_sel:[0,1] op_sel_hi:[1,0] neg_hi:[0,1]
	v_pk_add_f32 v[0:1], v[0:1], v[8:9] op_sel:[0,1] op_sel_hi:[1,0] neg_lo:[0,1]
	v_pk_add_f32 v[8:9], v[2:3], v[10:11]
	v_pk_add_f32 v[2:3], v[2:3], v[10:11] neg_lo:[0,1] neg_hi:[0,1]
	v_pk_mul_f32 v[10:11], v[2:3], s[10:11]
	v_pk_fma_f32 v[2:3], v[2:3], s[14:15], v[10:11] op_sel:[0,0,1] op_sel_hi:[1,0,0]
	v_pk_add_f32 v[10:11], v[4:5], v[12:13]
	v_pk_add_f32 v[4:5], v[4:5], v[12:13] neg_lo:[0,1] neg_hi:[0,1]
	v_pk_add_f32 v[12:13], v[6:7], v[14:15]
	v_pk_add_f32 v[6:7], v[6:7], v[14:15] neg_lo:[0,1] neg_hi:[0,1]
	v_pk_mul_f32 v[14:15], v[6:7], s[10:11]
	v_pk_fma_f32 v[6:7], v[6:7], s[14:15], v[14:15] op_sel:[0,0,1] op_sel_hi:[1,0,0] neg_lo:[1,0,0] neg_hi:[1,0,0]
	v_pk_add_f32 v[14:15], v[24:25], v[26:27]
	v_pk_add_f32 v[24:25], v[24:25], v[26:27] neg_lo:[0,1] neg_hi:[0,1]
	v_pk_add_f32 v[26:27], v[82:83], v[28:29]
	v_pk_add_f32 v[28:29], v[82:83], v[28:29] neg_lo:[0,1] neg_hi:[0,1]
	v_pk_add_f32 v[82:83], v[22:23], v[18:19] op_sel:[0,1] op_sel_hi:[1,0] neg_hi:[0,1]
	v_pk_add_f32 v[18:19], v[22:23], v[18:19] op_sel:[0,1] op_sel_hi:[1,0] neg_lo:[0,1]
	v_pk_add_f32 v[22:23], v[16:17], v[20:21]
	v_pk_add_f32 v[16:17], v[16:17], v[20:21] neg_lo:[0,1] neg_hi:[0,1]
	v_pk_add_f32 v[20:21], v[30:31], v[10:11]
	v_pk_add_f32 v[10:11], v[30:31], v[10:11] neg_lo:[0,1] neg_hi:[0,1]
	v_pk_add_f32 v[30:31], v[8:9], v[12:13]
	v_pk_add_f32 v[8:9], v[8:9], v[12:13] neg_lo:[0,1] neg_hi:[0,1]
	v_pk_add_f32 v[12:13], v[0:1], v[4:5] op_sel:[0,1] op_sel_hi:[1,0] neg_hi:[0,1]
	v_pk_add_f32 v[0:1], v[0:1], v[4:5] op_sel:[0,1] op_sel_hi:[1,0] neg_lo:[0,1]
	v_pk_add_f32 v[4:5], v[2:3], v[6:7]
	v_pk_add_f32 v[2:3], v[2:3], v[6:7] neg_lo:[0,1] neg_hi:[0,1]
	v_pk_mul_f32 v[2:3], v[2:3], s[22:23]
	v_pk_add_f32 v[6:7], v[14:15], v[26:27]
	v_pk_add_f32 v[14:15], v[14:15], v[26:27] neg_lo:[0,1] neg_hi:[0,1]
	v_pk_add_f32 v[26:27], v[24:25], v[28:29] op_sel:[0,1] op_sel_hi:[1,0] neg_hi:[0,1]
	v_pk_add_f32 v[24:25], v[24:25], v[28:29] op_sel:[0,1] op_sel_hi:[1,0] neg_lo:[0,1]
	v_pk_add_f32 v[28:29], v[82:83], v[22:23]
	v_pk_add_f32 v[22:23], v[82:83], v[22:23] neg_lo:[0,1] neg_hi:[0,1]
	v_pk_add_f32 v[82:83], v[18:19], v[16:17] op_sel:[0,1] op_sel_hi:[1,0] neg_hi:[0,1]
	v_pk_add_f32 v[16:17], v[18:19], v[16:17] op_sel:[0,1] op_sel_hi:[1,0] neg_lo:[0,1]
	v_pk_add_f32 v[18:19], v[20:21], v[30:31]
	v_pk_add_f32 v[20:21], v[20:21], v[30:31] neg_lo:[0,1] neg_hi:[0,1]
	v_pk_add_f32 v[30:31], v[10:11], v[8:9] op_sel:[0,1] op_sel_hi:[1,0] neg_hi:[0,1]
	v_pk_add_f32 v[8:9], v[10:11], v[8:9] op_sel:[0,1] op_sel_hi:[1,0] neg_lo:[0,1]
	v_pk_add_f32 v[10:11], v[12:13], v[4:5]
	v_pk_add_f32 v[4:5], v[12:13], v[4:5] neg_lo:[0,1] neg_hi:[0,1]
	v_pk_add_f32 v[12:13], v[0:1], v[2:3] op_sel:[0,1] op_sel_hi:[1,0]
	v_pk_add_f32 v[0:1], v[0:1], v[2:3] op_sel:[0,1] op_sel_hi:[1,0] neg_lo:[0,1] neg_hi:[0,1]
	v_lshlrev_b32_e32 v2, 4, v37
	v_and_or_b32 v2, v2, s7, v47
	v_ashrrev_i32_e32 v3, 4, v2
	v_lshlrev_b32_e32 v3, 3, v3
	v_lshlrev_b32_e32 v2, 3, v2
	v_add3_u32 v2, 0, v3, v2
	v_add_u32_e32 v3, 0x800, v2
	v_mov_b32_e32 v37, v32
	ds_write2_b64 v2, v[6:7], v[18:19] offset1:34
	ds_write2_b64 v3, v[14:15], v[20:21] offset0:16 offset1:50
	ds_write2_b64 v2, v[26:27], v[30:31] offset0:136 offset1:170
	ds_write2_b64 v3, v[24:25], v[8:9] offset0:152 offset1:186
	ds_write2_b64 v2, v[28:29], v[10:11] offset0:68 offset1:102
	ds_write2_b64 v3, v[22:23], v[4:5] offset0:84 offset1:118
	ds_write2_b64 v2, v[82:83], v[12:13] offset0:204 offset1:238
	ds_write2_b64 v3, v[16:17], v[0:1] offset0:220 offset1:254
	s_waitcnt lgkmcnt(0)
	s_barrier
	s_nop 0
	v_and_b32_e32 v47, 0x1ff, v37
	v_cvt_f32_u32_e32 v24, v47
	v_ashrrev_i32_e32 v0, 4, v37
	v_lshlrev_b32_e32 v0, 3, v0
	v_lshlrev_b32_e32 v1, 3, v37
	v_mul_f32_e32 v81, 0x39000000, v24
	v_sin_f32_e32 v24, v81
	v_cos_f32_e32 v84, v81
	v_add3_u32 v25, 0, v0, v1
	ds_read_b64 v[0:1], v25
	ds_read_b64 v[2:3], v25 offset:4352
	ds_read_b64 v[4:5], v25 offset:8704
	ds_read_b64 v[6:7], v25 offset:13056
	ds_read_b64 v[8:9], v25 offset:17408
	ds_read_b64 v[10:11], v25 offset:21760
	ds_read_b64 v[12:13], v25 offset:26112
	ds_read_b64 v[14:15], v25 offset:30464
	v_xor_b32_e32 v85, 0x80000000, v24
	s_waitcnt lgkmcnt(6)
	v_pk_mul_f32 v[118:119], v[2:3], v[24:25] op_sel:[1,0] op_sel_hi:[0,0] neg_hi:[0,1]
	v_pk_fma_f32 v[2:3], v[2:3], v[84:85], v[118:119] op_sel_hi:[1,0,1]
	v_pk_mul_f32 v[118:119], v[24:25], v[84:85] op_sel:[0,1] op_sel_hi:[0,0] neg_hi:[1,0]
	v_pk_fma_f32 v[118:119], v[84:85], v[84:85], v[118:119] op_sel_hi:[0,1,1]
	ds_read_b64 v[16:17], v25 offset:34816
	ds_read_b64 v[18:19], v25 offset:39168
	ds_read_b64 v[20:21], v25 offset:43520
	ds_read_b64 v[22:23], v25 offset:47872
	s_waitcnt lgkmcnt(9)
	v_pk_mul_f32 v[120:121], v[4:5], v[118:119] op_sel:[1,1] op_sel_hi:[0,1] neg_lo:[0,1]
	v_pk_fma_f32 v[4:5], v[4:5], v[118:119], v[120:121] op_sel_hi:[1,0,1]
	v_pk_mul_f32 v[120:121], v[24:25], v[118:119] op_sel:[0,1] op_sel_hi:[0,0] neg_hi:[1,0]
	v_pk_fma_f32 v[118:119], v[84:85], v[118:119], v[120:121] op_sel_hi:[0,1,1]
	ds_read_b64 v[26:27], v25 offset:52224
	ds_read_b64 v[28:29], v25 offset:56576
	ds_read_b64 v[30:31], v25 offset:60928
	ds_read_b64 v[82:83], v25 offset:65280
	s_waitcnt lgkmcnt(12)
	v_pk_mul_f32 v[120:121], v[6:7], v[118:119] op_sel:[1,1] op_sel_hi:[0,1] neg_lo:[0,1]
	v_pk_fma_f32 v[6:7], v[6:7], v[118:119], v[120:121] op_sel_hi:[1,0,1]
	v_pk_mul_f32 v[120:121], v[24:25], v[118:119] op_sel:[0,1] op_sel_hi:[0,0] neg_hi:[1,0]
	v_pk_fma_f32 v[118:119], v[84:85], v[118:119], v[120:121] op_sel_hi:[0,1,1]
	s_waitcnt lgkmcnt(0)
	v_pk_mul_f32 v[120:121], v[8:9], v[118:119] op_sel:[1,1] op_sel_hi:[0,1] neg_lo:[0,1]
	v_pk_fma_f32 v[8:9], v[8:9], v[118:119], v[120:121] op_sel_hi:[1,0,1]
	v_pk_mul_f32 v[120:121], v[24:25], v[118:119] op_sel:[0,1] op_sel_hi:[0,0] neg_hi:[1,0]
	v_pk_fma_f32 v[118:119], v[84:85], v[118:119], v[120:121] op_sel_hi:[0,1,1]
	s_barrier
	v_pk_mul_f32 v[120:121], v[10:11], v[118:119] op_sel:[1,1] op_sel_hi:[0,1] neg_lo:[0,1]
	v_pk_fma_f32 v[10:11], v[10:11], v[118:119], v[120:121] op_sel_hi:[1,0,1]
	v_pk_mul_f32 v[120:121], v[24:25], v[118:119] op_sel:[0,1] op_sel_hi:[0,0] neg_hi:[1,0]
	v_pk_fma_f32 v[118:119], v[84:85], v[118:119], v[120:121] op_sel_hi:[0,1,1]
	v_pk_mul_f32 v[120:121], v[12:13], v[118:119] op_sel:[1,1] op_sel_hi:[0,1] neg_lo:[0,1]
	v_pk_fma_f32 v[12:13], v[12:13], v[118:119], v[120:121] op_sel_hi:[1,0,1]
	v_pk_mul_f32 v[120:121], v[24:25], v[118:119] op_sel:[0,1] op_sel_hi:[0,0] neg_hi:[1,0]
	v_pk_fma_f32 v[118:119], v[84:85], v[118:119], v[120:121] op_sel_hi:[0,1,1]
	v_pk_mul_f32 v[120:121], v[14:15], v[118:119] op_sel:[1,1] op_sel_hi:[0,1] neg_lo:[0,1]
	v_pk_fma_f32 v[14:15], v[14:15], v[118:119], v[120:121] op_sel_hi:[1,0,1]
	v_pk_mul_f32 v[120:121], v[24:25], v[118:119] op_sel:[0,1] op_sel_hi:[0,0] neg_hi:[1,0]
	v_pk_fma_f32 v[118:119], v[84:85], v[118:119], v[120:121] op_sel_hi:[0,1,1]
	v_pk_mul_f32 v[120:121], v[16:17], v[118:119] op_sel:[1,1] op_sel_hi:[0,1] neg_lo:[0,1]
	v_pk_fma_f32 v[16:17], v[16:17], v[118:119], v[120:121] op_sel_hi:[1,0,1]
	v_pk_mul_f32 v[120:121], v[24:25], v[118:119] op_sel:[0,1] op_sel_hi:[0,0] neg_hi:[1,0]
	v_pk_fma_f32 v[118:119], v[84:85], v[118:119], v[120:121] op_sel_hi:[0,1,1]
	v_pk_mul_f32 v[120:121], v[18:19], v[118:119] op_sel:[1,1] op_sel_hi:[0,1] neg_lo:[0,1]
	v_pk_fma_f32 v[18:19], v[18:19], v[118:119], v[120:121] op_sel_hi:[1,0,1]
	v_pk_mul_f32 v[120:121], v[24:25], v[118:119] op_sel:[0,1] op_sel_hi:[0,0] neg_hi:[1,0]
	v_pk_fma_f32 v[118:119], v[84:85], v[118:119], v[120:121] op_sel_hi:[0,1,1]
	v_pk_mul_f32 v[120:121], v[20:21], v[118:119] op_sel:[1,1] op_sel_hi:[0,1] neg_lo:[0,1]
	v_pk_fma_f32 v[20:21], v[20:21], v[118:119], v[120:121] op_sel_hi:[1,0,1]
	v_pk_mul_f32 v[120:121], v[24:25], v[118:119] op_sel:[0,1] op_sel_hi:[0,0] neg_hi:[1,0]
	v_pk_fma_f32 v[118:119], v[84:85], v[118:119], v[120:121] op_sel_hi:[0,1,1]
	v_pk_mul_f32 v[120:121], v[22:23], v[118:119] op_sel:[1,1] op_sel_hi:[0,1] neg_lo:[0,1]
	v_pk_fma_f32 v[22:23], v[22:23], v[118:119], v[120:121] op_sel_hi:[1,0,1]
	v_pk_mul_f32 v[120:121], v[24:25], v[118:119] op_sel:[0,1] op_sel_hi:[0,0] neg_hi:[1,0]
	v_pk_fma_f32 v[118:119], v[84:85], v[118:119], v[120:121] op_sel_hi:[0,1,1]
	v_pk_mul_f32 v[120:121], v[26:27], v[118:119] op_sel:[1,1] op_sel_hi:[0,1] neg_lo:[0,1]
	v_pk_fma_f32 v[26:27], v[26:27], v[118:119], v[120:121] op_sel_hi:[1,0,1]
	v_pk_mul_f32 v[120:121], v[24:25], v[118:119] op_sel:[0,1] op_sel_hi:[0,0] neg_hi:[1,0]
	v_pk_fma_f32 v[118:119], v[84:85], v[118:119], v[120:121] op_sel_hi:[0,1,1]
	v_pk_mul_f32 v[120:121], v[28:29], v[118:119] op_sel:[1,1] op_sel_hi:[0,1] neg_lo:[0,1]
	v_pk_fma_f32 v[28:29], v[28:29], v[118:119], v[120:121] op_sel_hi:[1,0,1]
	v_pk_mul_f32 v[120:121], v[24:25], v[118:119] op_sel:[0,1] op_sel_hi:[0,0] neg_hi:[1,0]
	v_pk_fma_f32 v[118:119], v[84:85], v[118:119], v[120:121] op_sel_hi:[0,1,1]
	v_pk_mul_f32 v[24:25], v[24:25], v[118:119] op_sel:[0,1] op_sel_hi:[0,0] neg_hi:[1,0]
	v_pk_fma_f32 v[24:25], v[84:85], v[118:119], v[24:25] op_sel_hi:[0,1,1]
	v_pk_mul_f32 v[84:85], v[82:83], v[24:25] op_sel:[1,1] op_sel_hi:[0,1] neg_lo:[0,1]
	v_pk_fma_f32 v[24:25], v[82:83], v[24:25], v[84:85] op_sel_hi:[1,0,1]
	v_pk_add_f32 v[82:83], v[0:1], v[16:17]
	v_pk_add_f32 v[0:1], v[0:1], v[16:17] neg_lo:[0,1] neg_hi:[0,1]
	v_pk_add_f32 v[16:17], v[2:3], v[18:19]
	v_pk_add_f32 v[2:3], v[2:3], v[18:19] neg_lo:[0,1] neg_hi:[0,1]
	v_pk_mul_f32 v[120:121], v[30:31], v[118:119] op_sel:[1,1] op_sel_hi:[0,1] neg_lo:[0,1]
	v_pk_mul_f32 v[18:19], v[2:3], s[18:19]
	v_pk_fma_f32 v[30:31], v[30:31], v[118:119], v[120:121] op_sel_hi:[1,0,1]
	v_pk_fma_f32 v[2:3], v[2:3], s[30:31], v[18:19] op_sel:[0,0,1] op_sel_hi:[1,0,0]
	v_pk_add_f32 v[18:19], v[4:5], v[20:21]
	v_pk_add_f32 v[4:5], v[4:5], v[20:21] neg_lo:[0,1] neg_hi:[0,1]
	v_pk_mul_f32 v[20:21], v[4:5], s[10:11]
	v_pk_fma_f32 v[4:5], v[4:5], s[14:15], v[20:21] op_sel:[0,0,1] op_sel_hi:[1,0,0]
	v_pk_add_f32 v[20:21], v[6:7], v[22:23]
	v_pk_add_f32 v[6:7], v[6:7], v[22:23] neg_lo:[0,1] neg_hi:[0,1]
	v_pk_mul_f32 v[22:23], v[6:7], s[34:35]
	v_pk_fma_f32 v[6:7], v[6:7], s[0:1], v[22:23] op_sel:[0,0,1] op_sel_hi:[1,0,0]
	v_pk_add_f32 v[22:23], v[8:9], v[26:27]
	v_pk_add_f32 v[8:9], v[8:9], v[26:27] neg_lo:[0,1] neg_hi:[0,1]
	v_pk_add_f32 v[26:27], v[10:11], v[28:29]
	v_pk_add_f32 v[10:11], v[10:11], v[28:29] neg_lo:[0,1] neg_hi:[0,1]
	v_pk_mul_f32 v[28:29], v[10:11], s[34:35]
	v_pk_fma_f32 v[10:11], v[10:11], s[0:1], v[28:29] op_sel:[0,0,1] op_sel_hi:[1,0,0] neg_lo:[1,0,0] neg_hi:[1,0,0]
	v_pk_add_f32 v[28:29], v[12:13], v[30:31]
	v_pk_add_f32 v[12:13], v[12:13], v[30:31] neg_lo:[0,1] neg_hi:[0,1]
	v_pk_mul_f32 v[30:31], v[12:13], s[10:11]
	v_pk_fma_f32 v[12:13], v[12:13], s[14:15], v[30:31] op_sel:[0,0,1] op_sel_hi:[1,0,0] neg_lo:[1,0,0] neg_hi:[1,0,0]
	v_pk_add_f32 v[30:31], v[14:15], v[24:25]
	v_pk_add_f32 v[14:15], v[14:15], v[24:25] neg_lo:[0,1] neg_hi:[0,1]
	v_pk_mul_f32 v[24:25], v[14:15], s[18:19]
	v_pk_fma_f32 v[14:15], v[14:15], s[30:31], v[24:25] op_sel:[0,0,1] op_sel_hi:[1,0,0] neg_lo:[1,0,0] neg_hi:[1,0,0]
	v_pk_add_f32 v[24:25], v[82:83], v[22:23]
	v_pk_add_f32 v[22:23], v[82:83], v[22:23] neg_lo:[0,1] neg_hi:[0,1]
	v_pk_add_f32 v[82:83], v[16:17], v[26:27]
	v_pk_add_f32 v[16:17], v[16:17], v[26:27] neg_lo:[0,1] neg_hi:[0,1]
	v_pk_mul_f32 v[26:27], v[16:17], s[10:11]
	v_pk_fma_f32 v[16:17], v[16:17], s[14:15], v[26:27] op_sel:[0,0,1] op_sel_hi:[1,0,0]
	v_pk_add_f32 v[26:27], v[18:19], v[28:29]
	v_pk_add_f32 v[18:19], v[18:19], v[28:29] neg_lo:[0,1] neg_hi:[0,1]
	v_pk_add_f32 v[28:29], v[20:21], v[30:31]
	v_pk_add_f32 v[20:21], v[20:21], v[30:31] neg_lo:[0,1] neg_hi:[0,1]
	v_pk_mul_f32 v[30:31], v[20:21], s[10:11]
	v_pk_fma_f32 v[20:21], v[20:21], s[14:15], v[30:31] op_sel:[0,0,1] op_sel_hi:[1,0,0] neg_lo:[1,0,0] neg_hi:[1,0,0]
	v_pk_add_f32 v[30:31], v[0:1], v[8:9] op_sel:[0,1] op_sel_hi:[1,0] neg_hi:[0,1]
	v_pk_add_f32 v[0:1], v[0:1], v[8:9] op_sel:[0,1] op_sel_hi:[1,0] neg_lo:[0,1]
	v_pk_add_f32 v[8:9], v[2:3], v[10:11]
	v_pk_add_f32 v[2:3], v[2:3], v[10:11] neg_lo:[0,1] neg_hi:[0,1]
	v_pk_mul_f32 v[10:11], v[2:3], s[10:11]
	v_pk_fma_f32 v[2:3], v[2:3], s[14:15], v[10:11] op_sel:[0,0,1] op_sel_hi:[1,0,0]
	v_pk_add_f32 v[10:11], v[4:5], v[12:13]
	v_pk_add_f32 v[4:5], v[4:5], v[12:13] neg_lo:[0,1] neg_hi:[0,1]
	v_pk_add_f32 v[12:13], v[6:7], v[14:15]
	v_pk_add_f32 v[6:7], v[6:7], v[14:15] neg_lo:[0,1] neg_hi:[0,1]
	v_pk_mul_f32 v[14:15], v[6:7], s[10:11]
	v_pk_fma_f32 v[6:7], v[6:7], s[14:15], v[14:15] op_sel:[0,0,1] op_sel_hi:[1,0,0] neg_lo:[1,0,0] neg_hi:[1,0,0]
	v_pk_add_f32 v[14:15], v[24:25], v[26:27]
	v_pk_add_f32 v[24:25], v[24:25], v[26:27] neg_lo:[0,1] neg_hi:[0,1]
	v_pk_add_f32 v[26:27], v[82:83], v[28:29]
	v_pk_add_f32 v[28:29], v[82:83], v[28:29] neg_lo:[0,1] neg_hi:[0,1]
	v_pk_add_f32 v[82:83], v[22:23], v[18:19] op_sel:[0,1] op_sel_hi:[1,0] neg_hi:[0,1]
	v_pk_add_f32 v[18:19], v[22:23], v[18:19] op_sel:[0,1] op_sel_hi:[1,0] neg_lo:[0,1]
	v_pk_add_f32 v[22:23], v[16:17], v[20:21]
	v_pk_add_f32 v[16:17], v[16:17], v[20:21] neg_lo:[0,1] neg_hi:[0,1]
	v_pk_add_f32 v[20:21], v[30:31], v[10:11]
	v_pk_add_f32 v[10:11], v[30:31], v[10:11] neg_lo:[0,1] neg_hi:[0,1]
	v_pk_add_f32 v[30:31], v[8:9], v[12:13]
	v_pk_add_f32 v[8:9], v[8:9], v[12:13] neg_lo:[0,1] neg_hi:[0,1]
	v_pk_add_f32 v[12:13], v[0:1], v[4:5] op_sel:[0,1] op_sel_hi:[1,0] neg_hi:[0,1]
	v_pk_add_f32 v[0:1], v[0:1], v[4:5] op_sel:[0,1] op_sel_hi:[1,0] neg_lo:[0,1]
	v_pk_add_f32 v[4:5], v[2:3], v[6:7]
	v_pk_add_f32 v[2:3], v[2:3], v[6:7] neg_lo:[0,1] neg_hi:[0,1]
	v_pk_mul_f32 v[2:3], v[2:3], s[22:23]
	v_pk_add_f32 v[6:7], v[14:15], v[26:27]
	v_pk_add_f32 v[14:15], v[14:15], v[26:27] neg_lo:[0,1] neg_hi:[0,1]
	v_pk_add_f32 v[26:27], v[24:25], v[28:29] op_sel:[0,1] op_sel_hi:[1,0] neg_hi:[0,1]
	v_pk_add_f32 v[24:25], v[24:25], v[28:29] op_sel:[0,1] op_sel_hi:[1,0] neg_lo:[0,1]
	v_pk_add_f32 v[28:29], v[82:83], v[22:23]
	v_pk_add_f32 v[22:23], v[82:83], v[22:23] neg_lo:[0,1] neg_hi:[0,1]
	v_pk_add_f32 v[82:83], v[18:19], v[16:17] op_sel:[0,1] op_sel_hi:[1,0] neg_hi:[0,1]
	v_pk_add_f32 v[16:17], v[18:19], v[16:17] op_sel:[0,1] op_sel_hi:[1,0] neg_lo:[0,1]
	v_pk_add_f32 v[18:19], v[20:21], v[30:31]
	v_pk_add_f32 v[20:21], v[20:21], v[30:31] neg_lo:[0,1] neg_hi:[0,1]
	v_pk_add_f32 v[30:31], v[10:11], v[8:9] op_sel:[0,1] op_sel_hi:[1,0] neg_hi:[0,1]
	v_pk_add_f32 v[8:9], v[10:11], v[8:9] op_sel:[0,1] op_sel_hi:[1,0] neg_lo:[0,1]
	v_pk_add_f32 v[10:11], v[12:13], v[4:5]
	v_pk_add_f32 v[4:5], v[12:13], v[4:5] neg_lo:[0,1] neg_hi:[0,1]
	v_pk_add_f32 v[12:13], v[0:1], v[2:3] op_sel:[0,1] op_sel_hi:[1,0]
	v_pk_add_f32 v[0:1], v[0:1], v[2:3] op_sel:[0,1] op_sel_hi:[1,0] neg_lo:[0,1] neg_hi:[0,1]
	v_lshlrev_b32_e32 v2, 4, v37
	v_and_or_b32 v2, v2, s15, v47
	v_ashrrev_i32_e32 v3, 4, v2
	v_lshlrev_b32_e32 v3, 3, v3
	v_lshlrev_b32_e32 v2, 3, v2
	v_add3_u32 v2, 0, v3, v2
	ds_write_b64 v2, v[6:7]
	ds_write_b64 v2, v[14:15] offset:34816
	ds_write_b64 v2, v[26:27] offset:17408
	ds_write_b64 v2, v[24:25] offset:52224
	ds_write_b64 v2, v[28:29] offset:8704
	ds_write_b64 v2, v[22:23] offset:43520
	ds_write_b64 v2, v[82:83] offset:26112
	ds_write_b64 v2, v[16:17] offset:60928
	ds_write_b64 v2, v[18:19] offset:4352
	ds_write_b64 v2, v[20:21] offset:39168
	ds_write_b64 v2, v[30:31] offset:21760
	ds_write_b64 v2, v[8:9] offset:56576
	ds_write_b64 v2, v[10:11] offset:13056
	ds_write_b64 v2, v[4:5] offset:47872
	ds_write_b64 v2, v[12:13] offset:30464
	ds_write_b64 v2, v[0:1] offset:65280
	s_waitcnt lgkmcnt(0)
	s_barrier
	s_and_saveexec_b64 s[0:1], s[42:43]
	s_cbranch_execz .LBB0_500
	v_lshl_add_u64 v[2:3], v[78:79], 0, v[172:173]
	s_mov_b64 s[4:5], 0x80000
	v_lshl_add_u64 v[0:1], v[2:3], 0, s[4:5]
	v_add_co_u32_e32 v2, vcc, 0x80000, v2
	v_cmp_ne_u32_e64 s[42:43], 0, v39
	s_nop 0
	v_addc_co_u32_e32 v3, vcc, 0, v3, vcc
	global_load_dwordx4 v[12:15], v[2:3], off
	global_load_dwordx4 v[8:11], v[0:1], off offset:16
	v_mov_b32_e32 v19, 0
	v_mov_b32_e32 v21, 0
	s_and_saveexec_b64 s[4:5], s[42:43]
	s_cbranch_execz .LBB0_493
	global_load_ushort v2, v[0:1], off offset:-2
	s_waitcnt vmcnt(0)
	v_lshlrev_b32_e32 v21, 16, v2

.LBB0_596:
	s_or_b64 exec, exec, s[4:5]
	s_waitcnt vmcnt(0)
	ds_write_b64 v35, v[0:1] offset:65280
	s_waitcnt lgkmcnt(0)
	s_barrier
	s_and_saveexec_b64 s[0:1], s[40:41]
	s_xor_b64 s[0:1], exec, s[0:1]
	s_cbranch_execz .LBB0_598
	v_add3_u32 v33, s26, v41, v157
	ds_read_b64 v[0:1], v33 offset:2176
	ds_read_b64 v[2:3], v33 offset:4352
	ds_read_b64 v[4:5], v33 offset:6528
	ds_read_b64 v[6:7], v33 offset:8704
	ds_read_b64 v[8:9], v33 offset:10880
	ds_read_b64 v[10:11], v33 offset:13056
	ds_read_b64 v[12:13], v33 offset:15232
	ds_read_b64 v[14:15], v33 offset:17408
	ds_read_b64 v[16:17], v33 offset:19584
	ds_read_b64 v[18:19], v33 offset:21760
	ds_read_b64 v[20:21], v33 offset:23936
	ds_read_b64 v[22:23], v33 offset:26112
	ds_read_b64 v[24:25], v33 offset:34816
	ds_read_b64 v[26:27], v33 offset:36992
	ds_read_b64 v[28:29], v33 offset:39168
	ds_read_b64 v[30:31], v33 offset:41344
	ds_read_b64 v[48:49], v33 offset:43520
	ds_read_b64 v[50:51], v33 offset:45696
	ds_read_b64 v[52:53], v33 offset:47872
	ds_read_b64 v[54:55], v33 offset:50048
	ds_read_b64 v[56:57], v33 offset:52224
	ds_read_b64 v[58:59], v33 offset:54400
	ds_read_b64 v[60:61], v33 offset:56576
	ds_read_b64 v[62:63], v33 offset:58752
	ds_read_b64 v[64:65], v33
	ds_read_b64 v[66:67], v33 offset:60928
	ds_read_b64 v[68:69], v33 offset:63104
	ds_read_b64 v[70:71], v33 offset:65280
	s_mov_b32 s11, s14
	s_waitcnt lgkmcnt(3)
	v_pk_add_f32 v[80:81], v[64:65], v[24:25]
	v_pk_add_f32 v[24:25], v[64:65], v[24:25] neg_lo:[0,1] neg_hi:[0,1]
	v_pk_add_f32 v[64:65], v[0:1], v[26:27]
	v_pk_add_f32 v[0:1], v[0:1], v[26:27] neg_lo:[0,1] neg_hi:[0,1]
	s_mov_b32 s13, s86
	v_pk_mul_f32 v[26:27], v[0:1], s[16:17]
	s_mov_b32 s4, s21
	v_pk_fma_f32 v[0:1], v[0:1], s[6:7], v[26:27] op_sel:[0,0,1] op_sel_hi:[1,0,0]
	v_pk_add_f32 v[26:27], v[2:3], v[28:29]
	v_pk_add_f32 v[2:3], v[2:3], v[28:29] neg_lo:[0,1] neg_hi:[0,1]
	s_mov_b32 s35, s30
	v_pk_mul_f32 v[28:29], v[2:3], s[18:19]
	s_mov_b32 s8, s19
	v_pk_fma_f32 v[2:3], v[2:3], s[30:31], v[28:29] op_sel:[0,0,1] op_sel_hi:[1,0,0]
	v_pk_add_f32 v[28:29], v[4:5], v[30:31]
	v_pk_add_f32 v[4:5], v[4:5], v[30:31] neg_lo:[0,1] neg_hi:[0,1]
	s_mov_b32 s77, s6
	v_pk_mul_f32 v[30:31], v[4:5], s[20:21]
	s_mov_b32 s28, s17
	v_pk_fma_f32 v[4:5], v[4:5], s[86:87], v[30:31] op_sel:[0,0,1] op_sel_hi:[1,0,0]
	v_pk_add_f32 v[30:31], v[6:7], v[48:49]
	v_pk_add_f32 v[6:7], v[6:7], v[48:49] neg_lo:[0,1] neg_hi:[0,1]
	v_add_u32_e32 v35, 0x10780, v33
	v_pk_mul_f32 v[48:49], v[6:7], s[10:11]
	ds_read_b64 v[72:73], v33 offset:28288
	ds_read_b64 v[74:75], v33 offset:30464
	ds_read_b64 v[76:77], v33 offset:32640
	ds_read_b64 v[78:79], v35
	v_pk_fma_f32 v[6:7], v[6:7], s[14:15], v[48:49] op_sel:[0,0,1] op_sel_hi:[1,0,0]
	v_pk_add_f32 v[48:49], v[8:9], v[50:51]
	v_pk_add_f32 v[8:9], v[8:9], v[50:51] neg_lo:[0,1] neg_hi:[0,1]
	v_pk_mul_f32 v[50:51], v[8:9], s[12:13]
	v_pk_fma_f32 v[8:9], v[8:9], s[4:5], v[50:51] op_sel:[0,0,1] op_sel_hi:[1,0,0]
	v_pk_add_f32 v[50:51], v[10:11], v[52:53]
	v_pk_add_f32 v[10:11], v[10:11], v[52:53] neg_lo:[0,1] neg_hi:[0,1]
	v_pk_mul_f32 v[52:53], v[10:11], s[34:35]
	v_pk_fma_f32 v[10:11], v[10:11], s[8:9], v[52:53] op_sel:[0,0,1] op_sel_hi:[1,0,0]
	v_pk_add_f32 v[52:53], v[12:13], v[54:55]
	v_pk_add_f32 v[12:13], v[12:13], v[54:55] neg_lo:[0,1] neg_hi:[0,1]
	v_pk_mul_f32 v[54:55], v[12:13], s[76:77]
	v_pk_fma_f32 v[12:13], v[12:13], s[28:29], v[54:55] op_sel:[0,0,1] op_sel_hi:[1,0,0]
	v_pk_add_f32 v[54:55], v[14:15], v[56:57]
	v_pk_add_f32 v[14:15], v[14:15], v[56:57] neg_lo:[0,1] neg_hi:[0,1]
	v_pk_add_f32 v[56:57], v[16:17], v[58:59]
	v_pk_add_f32 v[16:17], v[16:17], v[58:59] neg_lo:[0,1] neg_hi:[0,1]
	v_pk_mul_f32 v[58:59], v[16:17], s[76:77]
	v_pk_fma_f32 v[16:17], v[16:17], s[28:29], v[58:59] op_sel:[0,0,1] op_sel_hi:[1,0,0] neg_lo:[1,0,0] neg_hi:[1,0,0]
	v_pk_add_f32 v[58:59], v[18:19], v[60:61]
	v_pk_add_f32 v[18:19], v[18:19], v[60:61] neg_lo:[0,1] neg_hi:[0,1]
	v_pk_mul_f32 v[60:61], v[18:19], s[34:35]
	v_pk_fma_f32 v[18:19], v[18:19], s[8:9], v[60:61] op_sel:[0,0,1] op_sel_hi:[1,0,0] neg_lo:[1,0,0] neg_hi:[1,0,0]
	v_pk_add_f32 v[60:61], v[20:21], v[62:63]
	v_pk_add_f32 v[20:21], v[20:21], v[62:63] neg_lo:[0,1] neg_hi:[0,1]
	v_pk_mul_f32 v[62:63], v[20:21], s[12:13]
	v_pk_fma_f32 v[20:21], v[20:21], s[4:5], v[62:63] op_sel:[0,0,1] op_sel_hi:[1,0,0] neg_lo:[1,0,0] neg_hi:[1,0,0]
	s_waitcnt lgkmcnt(6)
	v_pk_add_f32 v[62:63], v[22:23], v[66:67]
	v_pk_add_f32 v[22:23], v[22:23], v[66:67] neg_lo:[0,1] neg_hi:[0,1]
	s_nop 0
	v_pk_mul_f32 v[66:67], v[22:23], s[10:11]
	v_pk_fma_f32 v[22:23], v[22:23], s[14:15], v[66:67] op_sel:[0,0,1] op_sel_hi:[1,0,0] neg_lo:[1,0,0] neg_hi:[1,0,0]
	s_waitcnt lgkmcnt(3)
	v_pk_add_f32 v[66:67], v[72:73], v[68:69]
	v_pk_add_f32 v[68:69], v[72:73], v[68:69] neg_lo:[0,1] neg_hi:[0,1]
	s_nop 0
	v_pk_mul_f32 v[72:73], v[68:69], s[20:21]
	v_pk_fma_f32 v[68:69], v[68:69], s[86:87], v[72:73] op_sel:[0,0,1] op_sel_hi:[1,0,0] neg_lo:[1,0,0] neg_hi:[1,0,0]
	s_waitcnt lgkmcnt(2)
	v_pk_add_f32 v[72:73], v[74:75], v[70:71]
	v_pk_add_f32 v[70:71], v[74:75], v[70:71] neg_lo:[0,1] neg_hi:[0,1]
	s_nop 0
	v_pk_mul_f32 v[74:75], v[70:71], s[18:19]
	v_pk_fma_f32 v[70:71], v[70:71], s[30:31], v[74:75] op_sel:[0,0,1] op_sel_hi:[1,0,0] neg_lo:[1,0,0] neg_hi:[1,0,0]
	s_waitcnt lgkmcnt(0)
	v_pk_add_f32 v[74:75], v[76:77], v[78:79]
	v_pk_add_f32 v[76:77], v[76:77], v[78:79] neg_lo:[0,1] neg_hi:[0,1]
	s_nop 0
	v_pk_mul_f32 v[78:79], v[76:77], s[16:17]
	v_pk_fma_f32 v[76:77], v[76:77], s[6:7], v[78:79] op_sel:[0,0,1] op_sel_hi:[1,0,0] neg_lo:[1,0,0] neg_hi:[1,0,0]
	v_pk_add_f32 v[78:79], v[80:81], v[54:55]
	v_pk_add_f32 v[54:55], v[80:81], v[54:55] neg_lo:[0,1] neg_hi:[0,1]
	v_pk_add_f32 v[80:81], v[64:65], v[56:57]
	v_pk_add_f32 v[56:57], v[64:65], v[56:57] neg_lo:[0,1] neg_hi:[0,1]
	v_pk_mul_f32 v[64:65], v[56:57], s[18:19]
	v_pk_fma_f32 v[56:57], v[56:57], s[30:31], v[64:65] op_sel:[0,0,1] op_sel_hi:[1,0,0]
	v_pk_add_f32 v[64:65], v[26:27], v[58:59]
	v_pk_add_f32 v[26:27], v[26:27], v[58:59] neg_lo:[0,1] neg_hi:[0,1]
	v_pk_mul_f32 v[58:59], v[26:27], s[10:11]
	v_pk_fma_f32 v[26:27], v[26:27], s[14:15], v[58:59] op_sel:[0,0,1] op_sel_hi:[1,0,0]
	v_pk_add_f32 v[58:59], v[28:29], v[60:61]
	v_pk_add_f32 v[28:29], v[28:29], v[60:61] neg_lo:[0,1] neg_hi:[0,1]
	v_pk_mul_f32 v[60:61], v[28:29], s[34:35]
	v_pk_fma_f32 v[28:29], v[28:29], s[8:9], v[60:61] op_sel:[0,0,1] op_sel_hi:[1,0,0]
	v_pk_add_f32 v[60:61], v[30:31], v[62:63]
	v_pk_add_f32 v[30:31], v[30:31], v[62:63] neg_lo:[0,1] neg_hi:[0,1]
	v_pk_add_f32 v[62:63], v[48:49], v[66:67]
	v_pk_add_f32 v[48:49], v[48:49], v[66:67] neg_lo:[0,1] neg_hi:[0,1]
	v_pk_mul_f32 v[66:67], v[48:49], s[34:35]
	v_pk_fma_f32 v[48:49], v[48:49], s[8:9], v[66:67] op_sel:[0,0,1] op_sel_hi:[1,0,0] neg_lo:[1,0,0] neg_hi:[1,0,0]
	v_pk_add_f32 v[66:67], v[50:51], v[72:73]
	v_pk_add_f32 v[50:51], v[50:51], v[72:73] neg_lo:[0,1] neg_hi:[0,1]
	v_pk_mul_f32 v[72:73], v[50:51], s[10:11]
	v_pk_fma_f32 v[50:51], v[50:51], s[14:15], v[72:73] op_sel:[0,0,1] op_sel_hi:[1,0,0] neg_lo:[1,0,0] neg_hi:[1,0,0]
	v_pk_add_f32 v[72:73], v[52:53], v[74:75]
	v_pk_add_f32 v[52:53], v[52:53], v[74:75] neg_lo:[0,1] neg_hi:[0,1]
	v_pk_mul_f32 v[74:75], v[52:53], s[18:19]
	v_pk_fma_f32 v[52:53], v[52:53], s[30:31], v[74:75] op_sel:[0,0,1] op_sel_hi:[1,0,0] neg_lo:[1,0,0] neg_hi:[1,0,0]
	v_pk_add_f32 v[74:75], v[24:25], v[14:15] op_sel:[0,1] op_sel_hi:[1,0] neg_hi:[0,1]
	v_pk_add_f32 v[14:15], v[24:25], v[14:15] op_sel:[0,1] op_sel_hi:[1,0] neg_lo:[0,1]
	v_pk_add_f32 v[24:25], v[0:1], v[16:17]
	v_pk_add_f32 v[0:1], v[0:1], v[16:17] neg_lo:[0,1] neg_hi:[0,1]
	v_pk_mul_f32 v[16:17], v[0:1], s[18:19]
	v_pk_fma_f32 v[0:1], v[0:1], s[30:31], v[16:17] op_sel:[0,0,1] op_sel_hi:[1,0,0]
	v_pk_add_f32 v[16:17], v[2:3], v[18:19]
	v_pk_add_f32 v[2:3], v[2:3], v[18:19] neg_lo:[0,1] neg_hi:[0,1]
	v_pk_mul_f32 v[18:19], v[2:3], s[10:11]
	v_pk_fma_f32 v[2:3], v[2:3], s[14:15], v[18:19] op_sel:[0,0,1] op_sel_hi:[1,0,0]
	v_pk_add_f32 v[18:19], v[4:5], v[20:21]
	v_pk_add_f32 v[4:5], v[4:5], v[20:21] neg_lo:[0,1] neg_hi:[0,1]
	v_pk_mul_f32 v[20:21], v[4:5], s[34:35]
	v_pk_fma_f32 v[4:5], v[4:5], s[8:9], v[20:21] op_sel:[0,0,1] op_sel_hi:[1,0,0]
	v_pk_add_f32 v[20:21], v[6:7], v[22:23]
	v_pk_add_f32 v[6:7], v[6:7], v[22:23] neg_lo:[0,1] neg_hi:[0,1]
	v_pk_add_f32 v[22:23], v[8:9], v[68:69]
	v_pk_add_f32 v[8:9], v[8:9], v[68:69] neg_lo:[0,1] neg_hi:[0,1]
	v_pk_mul_f32 v[68:69], v[8:9], s[34:35]
	v_pk_fma_f32 v[8:9], v[8:9], s[8:9], v[68:69] op_sel:[0,0,1] op_sel_hi:[1,0,0] neg_lo:[1,0,0] neg_hi:[1,0,0]
	v_pk_add_f32 v[68:69], v[10:11], v[70:71]
	v_pk_add_f32 v[10:11], v[10:11], v[70:71] neg_lo:[0,1] neg_hi:[0,1]
	v_pk_mul_f32 v[70:71], v[10:11], s[10:11]
	v_pk_fma_f32 v[10:11], v[10:11], s[14:15], v[70:71] op_sel:[0,0,1] op_sel_hi:[1,0,0] neg_lo:[1,0,0] neg_hi:[1,0,0]
	v_pk_add_f32 v[70:71], v[12:13], v[76:77]
	v_pk_add_f32 v[12:13], v[12:13], v[76:77] neg_lo:[0,1] neg_hi:[0,1]
	v_pk_mul_f32 v[76:77], v[12:13], s[18:19]
	v_pk_fma_f32 v[12:13], v[12:13], s[30:31], v[76:77] op_sel:[0,0,1] op_sel_hi:[1,0,0] neg_lo:[1,0,0] neg_hi:[1,0,0]
	v_pk_add_f32 v[76:77], v[78:79], v[60:61]
	v_pk_add_f32 v[60:61], v[78:79], v[60:61] neg_lo:[0,1] neg_hi:[0,1]
	v_pk_add_f32 v[78:79], v[80:81], v[62:63]
	v_pk_add_f32 v[62:63], v[80:81], v[62:63] neg_lo:[0,1] neg_hi:[0,1]
	v_pk_mul_f32 v[80:81], v[62:63], s[10:11]
	v_pk_fma_f32 v[62:63], v[62:63], s[14:15], v[80:81] op_sel:[0,0,1] op_sel_hi:[1,0,0]
	v_pk_add_f32 v[80:81], v[64:65], v[66:67]
	v_pk_add_f32 v[64:65], v[64:65], v[66:67] neg_lo:[0,1] neg_hi:[0,1]
	v_pk_add_f32 v[66:67], v[58:59], v[72:73]
	v_pk_add_f32 v[58:59], v[58:59], v[72:73] neg_lo:[0,1] neg_hi:[0,1]
	v_pk_mul_f32 v[72:73], v[58:59], s[10:11]
	v_pk_fma_f32 v[58:59], v[58:59], s[14:15], v[72:73] op_sel:[0,0,1] op_sel_hi:[1,0,0] neg_lo:[1,0,0] neg_hi:[1,0,0]
	v_pk_add_f32 v[72:73], v[54:55], v[30:31] op_sel:[0,1] op_sel_hi:[1,0] neg_hi:[0,1]
	v_pk_add_f32 v[30:31], v[54:55], v[30:31] op_sel:[0,1] op_sel_hi:[1,0] neg_lo:[0,1]
	v_pk_add_f32 v[54:55], v[56:57], v[48:49]
	v_pk_add_f32 v[48:49], v[56:57], v[48:49] neg_lo:[0,1] neg_hi:[0,1]
	v_pk_add_f32 v[82:83], v[62:63], v[58:59]
	v_pk_mul_f32 v[56:57], v[48:49], s[10:11]
	v_pk_add_f32 v[58:59], v[62:63], v[58:59] neg_lo:[0,1] neg_hi:[0,1]
	v_pk_fma_f32 v[48:49], v[48:49], s[14:15], v[56:57] op_sel:[0,0,1] op_sel_hi:[1,0,0]
	v_pk_add_f32 v[56:57], v[26:27], v[50:51]
	v_pk_add_f32 v[26:27], v[26:27], v[50:51] neg_lo:[0,1] neg_hi:[0,1]
	v_pk_add_f32 v[50:51], v[28:29], v[52:53]
	v_pk_add_f32 v[28:29], v[28:29], v[52:53] neg_lo:[0,1] neg_hi:[0,1]
	v_pk_mul_f32 v[52:53], v[28:29], s[10:11]
	v_pk_add_f32 v[88:89], v[54:55], v[50:51]
	v_pk_fma_f32 v[28:29], v[28:29], s[14:15], v[52:53] op_sel:[0,0,1] op_sel_hi:[1,0,0] neg_lo:[1,0,0] neg_hi:[1,0,0]
	v_pk_add_f32 v[52:53], v[74:75], v[20:21]
	v_pk_add_f32 v[20:21], v[74:75], v[20:21] neg_lo:[0,1] neg_hi:[0,1]
	v_pk_add_f32 v[74:75], v[24:25], v[22:23]
	v_pk_add_f32 v[22:23], v[24:25], v[22:23] neg_lo:[0,1] neg_hi:[0,1]
	v_pk_add_f32 v[50:51], v[54:55], v[50:51] neg_lo:[0,1] neg_hi:[0,1]
	v_pk_mul_f32 v[24:25], v[22:23], s[10:11]
	v_pk_add_f32 v[90:91], v[30:31], v[26:27] op_sel:[0,1] op_sel_hi:[1,0] neg_hi:[0,1]
	v_pk_fma_f32 v[22:23], v[22:23], s[14:15], v[24:25] op_sel:[0,0,1] op_sel_hi:[1,0,0]
	v_pk_add_f32 v[24:25], v[16:17], v[68:69]
	v_pk_add_f32 v[16:17], v[16:17], v[68:69] neg_lo:[0,1] neg_hi:[0,1]
	v_pk_add_f32 v[68:69], v[18:19], v[70:71]
	v_pk_add_f32 v[18:19], v[18:19], v[70:71] neg_lo:[0,1] neg_hi:[0,1]
	v_pk_mul_f32 v[70:71], v[18:19], s[10:11]
	v_pk_add_f32 v[26:27], v[30:31], v[26:27] op_sel:[0,1] op_sel_hi:[1,0] neg_lo:[0,1]
	v_pk_fma_f32 v[18:19], v[18:19], s[14:15], v[70:71] op_sel:[0,0,1] op_sel_hi:[1,0,0] neg_lo:[1,0,0] neg_hi:[1,0,0]
	v_pk_add_f32 v[70:71], v[14:15], v[6:7] op_sel:[0,1] op_sel_hi:[1,0] neg_hi:[0,1]
	v_pk_add_f32 v[6:7], v[14:15], v[6:7] op_sel:[0,1] op_sel_hi:[1,0] neg_lo:[0,1]
	v_pk_add_f32 v[14:15], v[0:1], v[8:9]
	v_pk_add_f32 v[0:1], v[0:1], v[8:9] neg_lo:[0,1] neg_hi:[0,1]
	v_pk_add_f32 v[30:31], v[48:49], v[28:29]
	v_pk_mul_f32 v[8:9], v[0:1], s[10:11]
	v_pk_add_f32 v[28:29], v[48:49], v[28:29] neg_lo:[0,1] neg_hi:[0,1]
	v_pk_fma_f32 v[0:1], v[0:1], s[14:15], v[8:9] op_sel:[0,0,1] op_sel_hi:[1,0,0]
	v_pk_add_f32 v[8:9], v[2:3], v[10:11]
	v_pk_add_f32 v[2:3], v[2:3], v[10:11] neg_lo:[0,1] neg_hi:[0,1]
	v_pk_add_f32 v[10:11], v[4:5], v[12:13]
	v_pk_add_f32 v[4:5], v[4:5], v[12:13] neg_lo:[0,1] neg_hi:[0,1]
	v_pk_mul_f32 v[12:13], v[4:5], s[10:11]
	v_pk_add_f32 v[92:93], v[52:53], v[24:25]
	v_pk_fma_f32 v[4:5], v[4:5], s[14:15], v[12:13] op_sel:[0,0,1] op_sel_hi:[1,0,0] neg_lo:[1,0,0] neg_hi:[1,0,0]
	v_pk_add_f32 v[12:13], v[76:77], v[80:81]
	v_pk_add_f32 v[76:77], v[76:77], v[80:81] neg_lo:[0,1] neg_hi:[0,1]
	v_pk_add_f32 v[80:81], v[78:79], v[66:67]
	v_pk_add_f32 v[66:67], v[78:79], v[66:67] neg_lo:[0,1] neg_hi:[0,1]
	v_pk_add_f32 v[94:95], v[52:53], v[24:25] neg_lo:[0,1] neg_hi:[0,1]
	v_pk_add_f32 v[96:97], v[74:75], v[68:69]
	v_pk_add_f32 v[24:25], v[74:75], v[68:69] neg_lo:[0,1] neg_hi:[0,1]
	v_pk_add_f32 v[74:75], v[20:21], v[16:17] op_sel:[0,1] op_sel_hi:[1,0] neg_hi:[0,1]
	v_pk_add_f32 v[98:99], v[20:21], v[16:17] op_sel:[0,1] op_sel_hi:[1,0] neg_lo:[0,1]
	v_pk_add_f32 v[16:17], v[22:23], v[18:19] neg_lo:[0,1] neg_hi:[0,1]
	v_pk_add_f32 v[104:105], v[70:71], v[8:9]
	v_pk_add_f32 v[106:107], v[70:71], v[8:9] neg_lo:[0,1] neg_hi:[0,1]
	v_pk_add_f32 v[8:9], v[14:15], v[10:11] neg_lo:[0,1] neg_hi:[0,1]
	v_pk_add_f32 v[110:111], v[6:7], v[2:3] op_sel:[0,1] op_sel_hi:[1,0] neg_hi:[0,1]
	v_pk_add_f32 v[112:113], v[6:7], v[2:3] op_sel:[0,1] op_sel_hi:[1,0] neg_lo:[0,1]
	v_pk_add_f32 v[2:3], v[0:1], v[4:5]
	v_pk_add_f32 v[0:1], v[0:1], v[4:5] neg_lo:[0,1] neg_hi:[0,1]
	v_pk_add_f32 v[78:79], v[60:61], v[64:65] op_sel:[0,1] op_sel_hi:[1,0] neg_hi:[0,1]
	v_pk_add_f32 v[64:65], v[60:61], v[64:65] op_sel:[0,1] op_sel_hi:[1,0] neg_lo:[0,1]
	v_pk_mul_f32 v[84:85], v[58:59], s[22:23]
	v_pk_add_f32 v[86:87], v[72:73], v[56:57]
	v_pk_add_f32 v[72:73], v[72:73], v[56:57] neg_lo:[0,1] neg_hi:[0,1]
	v_pk_mul_f32 v[48:49], v[28:29], s[22:23]
	v_pk_mul_f32 v[68:69], v[24:25], s[22:23]
	v_pk_add_f32 v[100:101], v[22:23], v[18:19]
	v_pk_mul_f32 v[102:103], v[16:17], s[22:23]
	v_pk_add_f32 v[70:71], v[14:15], v[10:11]
	v_pk_mul_f32 v[108:109], v[8:9], s[22:23]
	v_pk_mul_f32 v[114:115], v[0:1], s[22:23]
	v_pk_add_f32 v[28:29], v[12:13], v[80:81]
	v_pk_add_f32 v[62:63], v[12:13], v[80:81] neg_lo:[0,1] neg_hi:[0,1]
	v_pk_add_f32 v[24:25], v[76:77], v[66:67] op_sel:[0,1] op_sel_hi:[1,0] neg_hi:[0,1]
	v_pk_add_f32 v[60:61], v[76:77], v[66:67] op_sel:[0,1] op_sel_hi:[1,0] neg_lo:[0,1]
	v_pk_add_f32 v[20:21], v[78:79], v[82:83]
	v_pk_add_f32 v[58:59], v[78:79], v[82:83] neg_lo:[0,1] neg_hi:[0,1]
	v_pk_add_f32 v[16:17], v[64:65], v[84:85] op_sel:[0,1] op_sel_hi:[1,0]
	v_pk_add_f32 v[56:57], v[64:65], v[84:85] op_sel:[0,1] op_sel_hi:[1,0] neg_lo:[0,1] neg_hi:[0,1]
	v_pk_add_f32 v[12:13], v[86:87], v[88:89]
	v_pk_add_f32 v[54:55], v[86:87], v[88:89] neg_lo:[0,1] neg_hi:[0,1]
	v_pk_add_f32 v[8:9], v[72:73], v[50:51] op_sel:[0,1] op_sel_hi:[1,0] neg_hi:[0,1]
	v_pk_add_f32 v[52:53], v[72:73], v[50:51] op_sel:[0,1] op_sel_hi:[1,0] neg_lo:[0,1]
	v_pk_add_f32 v[4:5], v[90:91], v[30:31]
	v_pk_add_f32 v[50:51], v[90:91], v[30:31] neg_lo:[0,1] neg_hi:[0,1]
	v_pk_add_f32 v[0:1], v[26:27], v[48:49] op_sel:[0,1] op_sel_hi:[1,0]
	v_pk_add_f32 v[48:49], v[26:27], v[48:49] op_sel:[0,1] op_sel_hi:[1,0] neg_lo:[0,1] neg_hi:[0,1]
	v_pk_add_f32 v[30:31], v[92:93], v[96:97]
	v_pk_add_f32 v[78:79], v[92:93], v[96:97] neg_lo:[0,1] neg_hi:[0,1]
	v_pk_add_f32 v[26:27], v[94:95], v[68:69] op_sel:[0,1] op_sel_hi:[1,0]
	v_pk_add_f32 v[76:77], v[94:95], v[68:69] op_sel:[0,1] op_sel_hi:[1,0] neg_lo:[0,1] neg_hi:[0,1]
	v_pk_add_f32 v[22:23], v[74:75], v[100:101]
	v_pk_add_f32 v[74:75], v[74:75], v[100:101] neg_lo:[0,1] neg_hi:[0,1]
	v_pk_add_f32 v[18:19], v[98:99], v[102:103] op_sel:[0,1] op_sel_hi:[1,0]
	v_pk_add_f32 v[72:73], v[98:99], v[102:103] op_sel:[0,1] op_sel_hi:[1,0] neg_lo:[0,1] neg_hi:[0,1]
	v_pk_add_f32 v[14:15], v[104:105], v[70:71]
	v_pk_add_f32 v[70:71], v[104:105], v[70:71] neg_lo:[0,1] neg_hi:[0,1]
	v_pk_add_f32 v[10:11], v[106:107], v[108:109] op_sel:[0,1] op_sel_hi:[1,0]
	v_pk_add_f32 v[68:69], v[106:107], v[108:109] op_sel:[0,1] op_sel_hi:[1,0] neg_lo:[0,1] neg_hi:[0,1]
	v_pk_add_f32 v[6:7], v[110:111], v[2:3]
	v_pk_add_f32 v[66:67], v[110:111], v[2:3] neg_lo:[0,1] neg_hi:[0,1]
	v_pk_add_f32 v[2:3], v[112:113], v[114:115] op_sel:[0,1] op_sel_hi:[1,0]
	v_pk_add_f32 v[64:65], v[112:113], v[114:115] op_sel:[0,1] op_sel_hi:[1,0] neg_lo:[0,1] neg_hi:[0,1]

.LBB0_600:
	s_or_b64 exec, exec, s[0:1]
	v_mov_b32_e32 v33, v32
	s_waitcnt lgkmcnt(0)
	s_barrier
	s_mov_b32 s11, s14
	v_and_b32_e32 v35, 31, v33
	v_cvt_f32_ubyte0_e32 v24, v35
	v_mul_f32_e32 v37, 0x3b000000, v24
	v_sin_f32_e32 v24, v37
	v_ashrrev_i32_e32 v0, 4, v33
	v_lshlrev_b32_e32 v0, 3, v0
	v_lshlrev_b32_e32 v1, 3, v33
	v_cos_f32_e32 v50, v37
	v_add3_u32 v25, s26, v0, v1
	ds_read_b64 v[0:1], v25
	ds_read_b64 v[2:3], v25 offset:4352
	ds_read_b64 v[4:5], v25 offset:8704
	ds_read_b64 v[6:7], v25 offset:13056
	ds_read_b64 v[8:9], v25 offset:17408
	ds_read_b64 v[10:11], v25 offset:21760
	ds_read_b64 v[12:13], v25 offset:26112
	ds_read_b64 v[14:15], v25 offset:30464
	ds_read_b64 v[16:17], v25 offset:34816
	ds_read_b64 v[18:19], v25 offset:39168
	ds_read_b64 v[20:21], v25 offset:43520
	ds_read_b64 v[22:23], v25 offset:47872
	v_xor_b32_e32 v51, 0x80000000, v24
	s_waitcnt lgkmcnt(10)
	v_pk_mul_f32 v[52:53], v[2:3], v[24:25] op_sel:[1,0] op_sel_hi:[0,0] neg_hi:[0,1]
	v_pk_fma_f32 v[2:3], v[2:3], v[50:51], v[52:53] op_sel_hi:[1,0,1]
	v_pk_mul_f32 v[52:53], v[24:25], v[50:51] op_sel:[0,1] op_sel_hi:[0,0] neg_hi:[1,0]
	v_pk_fma_f32 v[52:53], v[50:51], v[50:51], v[52:53] op_sel_hi:[0,1,1]
	ds_read_b64 v[26:27], v25 offset:52224
	ds_read_b64 v[28:29], v25 offset:56576
	ds_read_b64 v[30:31], v25 offset:60928
	ds_read_b64 v[48:49], v25 offset:65280
	s_waitcnt lgkmcnt(13)
	v_pk_mul_f32 v[54:55], v[4:5], v[52:53] op_sel:[1,1] op_sel_hi:[0,1] neg_lo:[0,1]
	v_pk_fma_f32 v[4:5], v[4:5], v[52:53], v[54:55] op_sel_hi:[1,0,1]
	v_pk_mul_f32 v[54:55], v[24:25], v[52:53] op_sel:[0,1] op_sel_hi:[0,0] neg_hi:[1,0]
	v_pk_fma_f32 v[52:53], v[50:51], v[52:53], v[54:55] op_sel_hi:[0,1,1]
	s_mov_b32 s35, s30
	s_waitcnt lgkmcnt(12)
	v_pk_mul_f32 v[54:55], v[6:7], v[52:53] op_sel:[1,1] op_sel_hi:[0,1] neg_lo:[0,1]
	v_pk_fma_f32 v[6:7], v[6:7], v[52:53], v[54:55] op_sel_hi:[1,0,1]
	v_pk_mul_f32 v[54:55], v[24:25], v[52:53] op_sel:[0,1] op_sel_hi:[0,0] neg_hi:[1,0]
	v_pk_fma_f32 v[52:53], v[50:51], v[52:53], v[54:55] op_sel_hi:[0,1,1]
	s_mov_b32 s0, s19
	s_waitcnt lgkmcnt(11)
	v_pk_mul_f32 v[54:55], v[8:9], v[52:53] op_sel:[1,1] op_sel_hi:[0,1] neg_lo:[0,1]
	v_pk_fma_f32 v[8:9], v[8:9], v[52:53], v[54:55] op_sel_hi:[1,0,1]
	v_pk_mul_f32 v[54:55], v[24:25], v[52:53] op_sel:[0,1] op_sel_hi:[0,0] neg_hi:[1,0]
	v_pk_fma_f32 v[52:53], v[50:51], v[52:53], v[54:55] op_sel_hi:[0,1,1]
	s_waitcnt lgkmcnt(0)
	v_pk_mul_f32 v[54:55], v[10:11], v[52:53] op_sel:[1,1] op_sel_hi:[0,1] neg_lo:[0,1]
	v_pk_fma_f32 v[10:11], v[10:11], v[52:53], v[54:55] op_sel_hi:[1,0,1]
	v_pk_mul_f32 v[54:55], v[24:25], v[52:53] op_sel:[0,1] op_sel_hi:[0,0] neg_hi:[1,0]
	v_pk_fma_f32 v[52:53], v[50:51], v[52:53], v[54:55] op_sel_hi:[0,1,1]
	s_barrier
	v_pk_mul_f32 v[54:55], v[12:13], v[52:53] op_sel:[1,1] op_sel_hi:[0,1] neg_lo:[0,1]
	v_pk_fma_f32 v[12:13], v[12:13], v[52:53], v[54:55] op_sel_hi:[1,0,1]
	v_pk_mul_f32 v[54:55], v[24:25], v[52:53] op_sel:[0,1] op_sel_hi:[0,0] neg_hi:[1,0]
	v_pk_fma_f32 v[52:53], v[50:51], v[52:53], v[54:55] op_sel_hi:[0,1,1]
	v_pk_mul_f32 v[54:55], v[14:15], v[52:53] op_sel:[1,1] op_sel_hi:[0,1] neg_lo:[0,1]
	v_pk_fma_f32 v[14:15], v[14:15], v[52:53], v[54:55] op_sel_hi:[1,0,1]
	v_pk_mul_f32 v[54:55], v[24:25], v[52:53] op_sel:[0,1] op_sel_hi:[0,0] neg_hi:[1,0]
	v_pk_fma_f32 v[52:53], v[50:51], v[52:53], v[54:55] op_sel_hi:[0,1,1]
	s_add_u32 s46, s60, 0x99b2000
	v_pk_mul_f32 v[54:55], v[16:17], v[52:53] op_sel:[1,1] op_sel_hi:[0,1] neg_lo:[0,1]
	v_pk_fma_f32 v[16:17], v[16:17], v[52:53], v[54:55] op_sel_hi:[1,0,1]
	v_pk_mul_f32 v[54:55], v[24:25], v[52:53] op_sel:[0,1] op_sel_hi:[0,0] neg_hi:[1,0]
	v_pk_fma_f32 v[52:53], v[50:51], v[52:53], v[54:55] op_sel_hi:[0,1,1]
	s_addc_u32 s47, s61, 0
	v_pk_mul_f32 v[54:55], v[18:19], v[52:53] op_sel:[1,1] op_sel_hi:[0,1] neg_lo:[0,1]
	v_pk_fma_f32 v[18:19], v[18:19], v[52:53], v[54:55] op_sel_hi:[1,0,1]
	v_pk_mul_f32 v[54:55], v[24:25], v[52:53] op_sel:[0,1] op_sel_hi:[0,0] neg_hi:[1,0]
	v_pk_fma_f32 v[52:53], v[50:51], v[52:53], v[54:55] op_sel_hi:[0,1,1]
	s_mov_b32 s4, 0
	v_pk_mul_f32 v[54:55], v[20:21], v[52:53] op_sel:[1,1] op_sel_hi:[0,1] neg_lo:[0,1]
	v_pk_fma_f32 v[20:21], v[20:21], v[52:53], v[54:55] op_sel_hi:[1,0,1]
	v_pk_mul_f32 v[54:55], v[24:25], v[52:53] op_sel:[0,1] op_sel_hi:[0,0] neg_hi:[1,0]
	v_pk_fma_f32 v[52:53], v[50:51], v[52:53], v[54:55] op_sel_hi:[0,1,1]
	v_cmp_lt_i32_e64 s[42:43], 0, v32
	v_pk_mul_f32 v[54:55], v[22:23], v[52:53] op_sel:[1,1] op_sel_hi:[0,1] neg_lo:[0,1]
	v_pk_fma_f32 v[22:23], v[22:23], v[52:53], v[54:55] op_sel_hi:[1,0,1]
	v_pk_mul_f32 v[54:55], v[24:25], v[52:53] op_sel:[0,1] op_sel_hi:[0,0] neg_hi:[1,0]
	v_pk_fma_f32 v[52:53], v[50:51], v[52:53], v[54:55] op_sel_hi:[0,1,1]
	v_mov_b32_e32 v47, v46
	v_pk_mul_f32 v[54:55], v[26:27], v[52:53] op_sel:[1,1] op_sel_hi:[0,1] neg_lo:[0,1]
	v_pk_fma_f32 v[26:27], v[26:27], v[52:53], v[54:55] op_sel_hi:[1,0,1]
	v_pk_mul_f32 v[54:55], v[24:25], v[52:53] op_sel:[0,1] op_sel_hi:[0,0] neg_hi:[1,0]
	v_pk_fma_f32 v[52:53], v[50:51], v[52:53], v[54:55] op_sel_hi:[0,1,1]
	v_mov_b32_e32 v39, v38
	v_pk_mul_f32 v[54:55], v[28:29], v[52:53] op_sel:[1,1] op_sel_hi:[0,1] neg_lo:[0,1]
	v_pk_fma_f32 v[28:29], v[28:29], v[52:53], v[54:55] op_sel_hi:[1,0,1]
	v_pk_mul_f32 v[54:55], v[24:25], v[52:53] op_sel:[0,1] op_sel_hi:[0,0] neg_hi:[1,0]
	v_pk_fma_f32 v[52:53], v[50:51], v[52:53], v[54:55] op_sel_hi:[0,1,1]
	v_pk_mul_f32 v[24:25], v[24:25], v[52:53] op_sel:[0,1] op_sel_hi:[0,0] neg_hi:[1,0]
	v_pk_fma_f32 v[24:25], v[50:51], v[52:53], v[24:25] op_sel_hi:[0,1,1]
	v_pk_mul_f32 v[50:51], v[48:49], v[24:25] op_sel:[1,1] op_sel_hi:[0,1] neg_lo:[0,1]
	v_pk_fma_f32 v[24:25], v[48:49], v[24:25], v[50:51] op_sel_hi:[1,0,1]
	v_pk_add_f32 v[48:49], v[0:1], v[16:17]
	v_pk_add_f32 v[0:1], v[0:1], v[16:17] neg_lo:[0,1] neg_hi:[0,1]
	v_pk_add_f32 v[16:17], v[2:3], v[18:19]
	v_pk_add_f32 v[2:3], v[2:3], v[18:19] neg_lo:[0,1] neg_hi:[0,1]
	v_pk_mul_f32 v[54:55], v[30:31], v[52:53] op_sel:[1,1] op_sel_hi:[0,1] neg_lo:[0,1]
	v_pk_mul_f32 v[18:19], v[2:3], s[18:19]
	v_pk_fma_f32 v[30:31], v[30:31], v[52:53], v[54:55] op_sel_hi:[1,0,1]
	v_pk_fma_f32 v[2:3], v[2:3], s[30:31], v[18:19] op_sel:[0,0,1] op_sel_hi:[1,0,0]
	v_pk_add_f32 v[18:19], v[4:5], v[20:21]
	v_pk_add_f32 v[4:5], v[4:5], v[20:21] neg_lo:[0,1] neg_hi:[0,1]
	v_add_u32_e32 v122, v157, v41
	v_pk_mul_f32 v[20:21], v[4:5], s[10:11]
	v_pk_fma_f32 v[4:5], v[4:5], s[14:15], v[20:21] op_sel:[0,0,1] op_sel_hi:[1,0,0]
	v_pk_add_f32 v[20:21], v[6:7], v[22:23]
	v_pk_add_f32 v[6:7], v[6:7], v[22:23] neg_lo:[0,1] neg_hi:[0,1]
	v_pk_mul_f32 v[22:23], v[6:7], s[34:35]
	v_pk_fma_f32 v[6:7], v[6:7], s[0:1], v[22:23] op_sel:[0,0,1] op_sel_hi:[1,0,0]
	v_pk_add_f32 v[22:23], v[8:9], v[26:27]
	v_pk_add_f32 v[8:9], v[8:9], v[26:27] neg_lo:[0,1] neg_hi:[0,1]
	v_pk_add_f32 v[26:27], v[10:11], v[28:29]
	v_pk_add_f32 v[10:11], v[10:11], v[28:29] neg_lo:[0,1] neg_hi:[0,1]
	v_pk_mul_f32 v[28:29], v[10:11], s[34:35]
	v_pk_fma_f32 v[10:11], v[10:11], s[0:1], v[28:29] op_sel:[0,0,1] op_sel_hi:[1,0,0] neg_lo:[1,0,0] neg_hi:[1,0,0]
	v_pk_add_f32 v[28:29], v[12:13], v[30:31]
	v_pk_add_f32 v[12:13], v[12:13], v[30:31] neg_lo:[0,1] neg_hi:[0,1]
	v_pk_mul_f32 v[30:31], v[12:13], s[10:11]
	v_pk_fma_f32 v[12:13], v[12:13], s[14:15], v[30:31] op_sel:[0,0,1] op_sel_hi:[1,0,0] neg_lo:[1,0,0] neg_hi:[1,0,0]
	v_pk_add_f32 v[30:31], v[14:15], v[24:25]
	v_pk_add_f32 v[14:15], v[14:15], v[24:25] neg_lo:[0,1] neg_hi:[0,1]
	v_pk_mul_f32 v[24:25], v[14:15], s[18:19]
	v_pk_fma_f32 v[14:15], v[14:15], s[30:31], v[24:25] op_sel:[0,0,1] op_sel_hi:[1,0,0] neg_lo:[1,0,0] neg_hi:[1,0,0]
	v_pk_add_f32 v[24:25], v[48:49], v[22:23]
	v_pk_add_f32 v[22:23], v[48:49], v[22:23] neg_lo:[0,1] neg_hi:[0,1]
	v_pk_add_f32 v[48:49], v[16:17], v[26:27]
	v_pk_add_f32 v[16:17], v[16:17], v[26:27] neg_lo:[0,1] neg_hi:[0,1]
	v_pk_mul_f32 v[26:27], v[16:17], s[10:11]
	v_pk_fma_f32 v[16:17], v[16:17], s[14:15], v[26:27] op_sel:[0,0,1] op_sel_hi:[1,0,0]
	v_pk_add_f32 v[26:27], v[18:19], v[28:29]
	v_pk_add_f32 v[18:19], v[18:19], v[28:29] neg_lo:[0,1] neg_hi:[0,1]
	v_pk_add_f32 v[28:29], v[20:21], v[30:31]
	v_pk_add_f32 v[20:21], v[20:21], v[30:31] neg_lo:[0,1] neg_hi:[0,1]
	v_pk_mul_f32 v[30:31], v[20:21], s[10:11]
	v_pk_fma_f32 v[20:21], v[20:21], s[14:15], v[30:31] op_sel:[0,0,1] op_sel_hi:[1,0,0] neg_lo:[1,0,0] neg_hi:[1,0,0]
	v_pk_add_f32 v[30:31], v[0:1], v[8:9] op_sel:[0,1] op_sel_hi:[1,0] neg_hi:[0,1]
	v_pk_add_f32 v[0:1], v[0:1], v[8:9] op_sel:[0,1] op_sel_hi:[1,0] neg_lo:[0,1]
	v_pk_add_f32 v[8:9], v[2:3], v[10:11]
	v_pk_add_f32 v[2:3], v[2:3], v[10:11] neg_lo:[0,1] neg_hi:[0,1]
	v_pk_mul_f32 v[10:11], v[2:3], s[10:11]
	v_pk_fma_f32 v[2:3], v[2:3], s[14:15], v[10:11] op_sel:[0,0,1] op_sel_hi:[1,0,0]
	v_pk_add_f32 v[10:11], v[4:5], v[12:13]
	v_pk_add_f32 v[4:5], v[4:5], v[12:13] neg_lo:[0,1] neg_hi:[0,1]
	v_pk_add_f32 v[12:13], v[6:7], v[14:15]
	v_pk_add_f32 v[6:7], v[6:7], v[14:15] neg_lo:[0,1] neg_hi:[0,1]
	v_pk_mul_f32 v[14:15], v[6:7], s[10:11]
	v_pk_fma_f32 v[6:7], v[6:7], s[14:15], v[14:15] op_sel:[0,0,1] op_sel_hi:[1,0,0] neg_lo:[1,0,0] neg_hi:[1,0,0]
	v_pk_add_f32 v[14:15], v[24:25], v[26:27]
	v_pk_add_f32 v[24:25], v[24:25], v[26:27] neg_lo:[0,1] neg_hi:[0,1]
	v_pk_add_f32 v[26:27], v[48:49], v[28:29]
	v_pk_add_f32 v[28:29], v[48:49], v[28:29] neg_lo:[0,1] neg_hi:[0,1]
	v_pk_add_f32 v[48:49], v[22:23], v[18:19] op_sel:[0,1] op_sel_hi:[1,0] neg_hi:[0,1]
	v_pk_add_f32 v[18:19], v[22:23], v[18:19] op_sel:[0,1] op_sel_hi:[1,0] neg_lo:[0,1]
	v_pk_add_f32 v[22:23], v[16:17], v[20:21]
	v_pk_add_f32 v[16:17], v[16:17], v[20:21] neg_lo:[0,1] neg_hi:[0,1]
	v_pk_add_f32 v[20:21], v[30:31], v[10:11]
	v_pk_add_f32 v[10:11], v[30:31], v[10:11] neg_lo:[0,1] neg_hi:[0,1]
	v_pk_add_f32 v[30:31], v[8:9], v[12:13]
	v_pk_add_f32 v[8:9], v[8:9], v[12:13] neg_lo:[0,1] neg_hi:[0,1]
	v_pk_add_f32 v[12:13], v[0:1], v[4:5] op_sel:[0,1] op_sel_hi:[1,0] neg_hi:[0,1]
	v_pk_add_f32 v[0:1], v[0:1], v[4:5] op_sel:[0,1] op_sel_hi:[1,0] neg_lo:[0,1]
	v_pk_add_f32 v[4:5], v[2:3], v[6:7]
	v_pk_add_f32 v[2:3], v[2:3], v[6:7] neg_lo:[0,1] neg_hi:[0,1]
	v_pk_mul_f32 v[2:3], v[2:3], s[22:23]
	v_pk_add_f32 v[6:7], v[14:15], v[26:27]
	v_pk_add_f32 v[14:15], v[14:15], v[26:27] neg_lo:[0,1] neg_hi:[0,1]
	v_pk_add_f32 v[26:27], v[24:25], v[28:29] op_sel:[0,1] op_sel_hi:[1,0] neg_hi:[0,1]
	v_pk_add_f32 v[24:25], v[24:25], v[28:29] op_sel:[0,1] op_sel_hi:[1,0] neg_lo:[0,1]
	v_pk_add_f32 v[28:29], v[48:49], v[22:23]
	v_pk_add_f32 v[22:23], v[48:49], v[22:23] neg_lo:[0,1] neg_hi:[0,1]
	v_pk_add_f32 v[48:49], v[18:19], v[16:17] op_sel:[0,1] op_sel_hi:[1,0] neg_hi:[0,1]
	v_pk_add_f32 v[16:17], v[18:19], v[16:17] op_sel:[0,1] op_sel_hi:[1,0] neg_lo:[0,1]
	v_pk_add_f32 v[18:19], v[20:21], v[30:31]
	v_pk_add_f32 v[20:21], v[20:21], v[30:31] neg_lo:[0,1] neg_hi:[0,1]
	v_pk_add_f32 v[30:31], v[10:11], v[8:9] op_sel:[0,1] op_sel_hi:[1,0] neg_hi:[0,1]
	v_pk_add_f32 v[8:9], v[10:11], v[8:9] op_sel:[0,1] op_sel_hi:[1,0] neg_lo:[0,1]
	v_pk_add_f32 v[10:11], v[12:13], v[4:5]
	v_pk_add_f32 v[4:5], v[12:13], v[4:5] neg_lo:[0,1] neg_hi:[0,1]
	v_pk_add_f32 v[12:13], v[0:1], v[2:3] op_sel:[0,1] op_sel_hi:[1,0]
	v_pk_add_f32 v[0:1], v[0:1], v[2:3] op_sel:[0,1] op_sel_hi:[1,0] neg_lo:[0,1] neg_hi:[0,1]
	v_lshlrev_b32_e32 v2, 4, v33
	v_and_or_b32 v2, v2, s7, v35
	v_ashrrev_i32_e32 v3, 4, v2
	v_lshlrev_b32_e32 v3, 3, v3
	v_lshlrev_b32_e32 v2, 3, v2
	v_add3_u32 v2, s26, v3, v2
	v_add_u32_e32 v3, 0x800, v2
	v_mov_b32_e32 v33, v32
	ds_write2_b64 v2, v[6:7], v[18:19] offset1:34
	ds_write2_b64 v3, v[14:15], v[20:21] offset0:16 offset1:50
	ds_write2_b64 v2, v[26:27], v[30:31] offset0:136 offset1:170
	ds_write2_b64 v3, v[24:25], v[8:9] offset0:152 offset1:186
	ds_write2_b64 v2, v[28:29], v[10:11] offset0:68 offset1:102
	ds_write2_b64 v3, v[22:23], v[4:5] offset0:84 offset1:118
	ds_write2_b64 v2, v[48:49], v[12:13] offset0:204 offset1:238
	ds_write2_b64 v3, v[16:17], v[0:1] offset0:220 offset1:254
	s_waitcnt lgkmcnt(0)
	s_barrier
	s_nop 0
	v_and_b32_e32 v35, 0x1ff, v33
	v_cvt_f32_u32_e32 v24, v35
	v_ashrrev_i32_e32 v0, 4, v33
	v_lshlrev_b32_e32 v0, 3, v0
	v_lshlrev_b32_e32 v1, 3, v33
	v_mul_f32_e32 v37, 0x39000000, v24
	v_sin_f32_e32 v24, v37
	v_cos_f32_e32 v50, v37
	v_add3_u32 v25, s26, v0, v1
	ds_read_b64 v[0:1], v25
	ds_read_b64 v[2:3], v25 offset:4352
	ds_read_b64 v[4:5], v25 offset:8704
	ds_read_b64 v[6:7], v25 offset:13056
	ds_read_b64 v[8:9], v25 offset:17408
	ds_read_b64 v[10:11], v25 offset:21760
	ds_read_b64 v[12:13], v25 offset:26112
	ds_read_b64 v[14:15], v25 offset:30464
	v_xor_b32_e32 v51, 0x80000000, v24
	s_waitcnt lgkmcnt(6)
	v_pk_mul_f32 v[52:53], v[2:3], v[24:25] op_sel:[1,0] op_sel_hi:[0,0] neg_hi:[0,1]
	v_pk_fma_f32 v[2:3], v[2:3], v[50:51], v[52:53] op_sel_hi:[1,0,1]
	v_pk_mul_f32 v[52:53], v[24:25], v[50:51] op_sel:[0,1] op_sel_hi:[0,0] neg_hi:[1,0]
	v_pk_fma_f32 v[52:53], v[50:51], v[50:51], v[52:53] op_sel_hi:[0,1,1]
	ds_read_b64 v[16:17], v25 offset:34816
	ds_read_b64 v[18:19], v25 offset:39168
	ds_read_b64 v[20:21], v25 offset:43520
	ds_read_b64 v[22:23], v25 offset:47872
	s_waitcnt lgkmcnt(9)
	v_pk_mul_f32 v[54:55], v[4:5], v[52:53] op_sel:[1,1] op_sel_hi:[0,1] neg_lo:[0,1]
	v_pk_fma_f32 v[4:5], v[4:5], v[52:53], v[54:55] op_sel_hi:[1,0,1]
	v_pk_mul_f32 v[54:55], v[24:25], v[52:53] op_sel:[0,1] op_sel_hi:[0,0] neg_hi:[1,0]
	v_pk_fma_f32 v[52:53], v[50:51], v[52:53], v[54:55] op_sel_hi:[0,1,1]
	ds_read_b64 v[26:27], v25 offset:52224
	ds_read_b64 v[28:29], v25 offset:56576
	ds_read_b64 v[30:31], v25 offset:60928
	ds_read_b64 v[48:49], v25 offset:65280
	s_waitcnt lgkmcnt(12)
	v_pk_mul_f32 v[54:55], v[6:7], v[52:53] op_sel:[1,1] op_sel_hi:[0,1] neg_lo:[0,1]
	v_pk_fma_f32 v[6:7], v[6:7], v[52:53], v[54:55] op_sel_hi:[1,0,1]
	v_pk_mul_f32 v[54:55], v[24:25], v[52:53] op_sel:[0,1] op_sel_hi:[0,0] neg_hi:[1,0]
	v_pk_fma_f32 v[52:53], v[50:51], v[52:53], v[54:55] op_sel_hi:[0,1,1]
	s_waitcnt lgkmcnt(0)
	v_pk_mul_f32 v[54:55], v[8:9], v[52:53] op_sel:[1,1] op_sel_hi:[0,1] neg_lo:[0,1]
	v_pk_fma_f32 v[8:9], v[8:9], v[52:53], v[54:55] op_sel_hi:[1,0,1]
	v_pk_mul_f32 v[54:55], v[24:25], v[52:53] op_sel:[0,1] op_sel_hi:[0,0] neg_hi:[1,0]
	v_pk_fma_f32 v[52:53], v[50:51], v[52:53], v[54:55] op_sel_hi:[0,1,1]
	s_barrier
	v_pk_mul_f32 v[54:55], v[10:11], v[52:53] op_sel:[1,1] op_sel_hi:[0,1] neg_lo:[0,1]
	v_pk_fma_f32 v[10:11], v[10:11], v[52:53], v[54:55] op_sel_hi:[1,0,1]
	v_pk_mul_f32 v[54:55], v[24:25], v[52:53] op_sel:[0,1] op_sel_hi:[0,0] neg_hi:[1,0]
	v_pk_fma_f32 v[52:53], v[50:51], v[52:53], v[54:55] op_sel_hi:[0,1,1]
	v_pk_mul_f32 v[54:55], v[12:13], v[52:53] op_sel:[1,1] op_sel_hi:[0,1] neg_lo:[0,1]
	v_pk_fma_f32 v[12:13], v[12:13], v[52:53], v[54:55] op_sel_hi:[1,0,1]
	v_pk_mul_f32 v[54:55], v[24:25], v[52:53] op_sel:[0,1] op_sel_hi:[0,0] neg_hi:[1,0]
	v_pk_fma_f32 v[52:53], v[50:51], v[52:53], v[54:55] op_sel_hi:[0,1,1]
	v_mov_b32_e32 v37, v36
	v_pk_mul_f32 v[54:55], v[14:15], v[52:53] op_sel:[1,1] op_sel_hi:[0,1] neg_lo:[0,1]
	v_pk_fma_f32 v[14:15], v[14:15], v[52:53], v[54:55] op_sel_hi:[1,0,1]
	v_pk_mul_f32 v[54:55], v[24:25], v[52:53] op_sel:[0,1] op_sel_hi:[0,0] neg_hi:[1,0]
	v_pk_fma_f32 v[52:53], v[50:51], v[52:53], v[54:55] op_sel_hi:[0,1,1]
	v_pk_mul_f32 v[54:55], v[16:17], v[52:53] op_sel:[1,1] op_sel_hi:[0,1] neg_lo:[0,1]
	v_pk_fma_f32 v[16:17], v[16:17], v[52:53], v[54:55] op_sel_hi:[1,0,1]
	v_pk_mul_f32 v[54:55], v[24:25], v[52:53] op_sel:[0,1] op_sel_hi:[0,0] neg_hi:[1,0]
	v_pk_fma_f32 v[52:53], v[50:51], v[52:53], v[54:55] op_sel_hi:[0,1,1]
	v_pk_mul_f32 v[54:55], v[18:19], v[52:53] op_sel:[1,1] op_sel_hi:[0,1] neg_lo:[0,1]
	v_pk_fma_f32 v[18:19], v[18:19], v[52:53], v[54:55] op_sel_hi:[1,0,1]
	v_pk_mul_f32 v[54:55], v[24:25], v[52:53] op_sel:[0,1] op_sel_hi:[0,0] neg_hi:[1,0]
	v_pk_fma_f32 v[52:53], v[50:51], v[52:53], v[54:55] op_sel_hi:[0,1,1]
	v_pk_mul_f32 v[54:55], v[20:21], v[52:53] op_sel:[1,1] op_sel_hi:[0,1] neg_lo:[0,1]
	v_pk_fma_f32 v[20:21], v[20:21], v[52:53], v[54:55] op_sel_hi:[1,0,1]
	v_pk_mul_f32 v[54:55], v[24:25], v[52:53] op_sel:[0,1] op_sel_hi:[0,0] neg_hi:[1,0]
	v_pk_fma_f32 v[52:53], v[50:51], v[52:53], v[54:55] op_sel_hi:[0,1,1]
	v_pk_mul_f32 v[54:55], v[22:23], v[52:53] op_sel:[1,1] op_sel_hi:[0,1] neg_lo:[0,1]
	v_pk_fma_f32 v[22:23], v[22:23], v[52:53], v[54:55] op_sel_hi:[1,0,1]
	v_pk_mul_f32 v[54:55], v[24:25], v[52:53] op_sel:[0,1] op_sel_hi:[0,0] neg_hi:[1,0]
	v_pk_fma_f32 v[52:53], v[50:51], v[52:53], v[54:55] op_sel_hi:[0,1,1]
	v_pk_mul_f32 v[54:55], v[26:27], v[52:53] op_sel:[1,1] op_sel_hi:[0,1] neg_lo:[0,1]
	v_pk_fma_f32 v[26:27], v[26:27], v[52:53], v[54:55] op_sel_hi:[1,0,1]
	v_pk_mul_f32 v[54:55], v[24:25], v[52:53] op_sel:[0,1] op_sel_hi:[0,0] neg_hi:[1,0]
	v_pk_fma_f32 v[52:53], v[50:51], v[52:53], v[54:55] op_sel_hi:[0,1,1]
	v_pk_mul_f32 v[54:55], v[28:29], v[52:53] op_sel:[1,1] op_sel_hi:[0,1] neg_lo:[0,1]
	v_pk_fma_f32 v[28:29], v[28:29], v[52:53], v[54:55] op_sel_hi:[1,0,1]
	v_pk_mul_f32 v[54:55], v[24:25], v[52:53] op_sel:[0,1] op_sel_hi:[0,0] neg_hi:[1,0]
	v_pk_fma_f32 v[52:53], v[50:51], v[52:53], v[54:55] op_sel_hi:[0,1,1]
	v_pk_mul_f32 v[24:25], v[24:25], v[52:53] op_sel:[0,1] op_sel_hi:[0,0] neg_hi:[1,0]
	v_pk_fma_f32 v[24:25], v[50:51], v[52:53], v[24:25] op_sel_hi:[0,1,1]
	v_pk_mul_f32 v[50:51], v[48:49], v[24:25] op_sel:[1,1] op_sel_hi:[0,1] neg_lo:[0,1]
	v_pk_fma_f32 v[24:25], v[48:49], v[24:25], v[50:51] op_sel_hi:[1,0,1]
	v_pk_add_f32 v[48:49], v[0:1], v[16:17]
	v_pk_add_f32 v[0:1], v[0:1], v[16:17] neg_lo:[0,1] neg_hi:[0,1]
	v_pk_add_f32 v[16:17], v[2:3], v[18:19]
	v_pk_add_f32 v[2:3], v[2:3], v[18:19] neg_lo:[0,1] neg_hi:[0,1]
	v_pk_mul_f32 v[54:55], v[30:31], v[52:53] op_sel:[1,1] op_sel_hi:[0,1] neg_lo:[0,1]
	v_pk_mul_f32 v[18:19], v[2:3], s[18:19]
	v_pk_fma_f32 v[30:31], v[30:31], v[52:53], v[54:55] op_sel_hi:[1,0,1]
	v_pk_fma_f32 v[2:3], v[2:3], s[30:31], v[18:19] op_sel:[0,0,1] op_sel_hi:[1,0,0]
	v_pk_add_f32 v[18:19], v[4:5], v[20:21]
	v_pk_add_f32 v[4:5], v[4:5], v[20:21] neg_lo:[0,1] neg_hi:[0,1]
	v_mov_b32_e32 v50, v45
	v_pk_mul_f32 v[20:21], v[4:5], s[10:11]
	v_mov_b32_e32 v51, v44
	v_pk_fma_f32 v[4:5], v[4:5], s[14:15], v[20:21] op_sel:[0,0,1] op_sel_hi:[1,0,0]
	v_pk_add_f32 v[20:21], v[6:7], v[22:23]
	v_pk_add_f32 v[6:7], v[6:7], v[22:23] neg_lo:[0,1] neg_hi:[0,1]
	v_mov_b32_e32 v52, v43
	v_pk_mul_f32 v[22:23], v[6:7], s[34:35]
	v_mov_b32_e32 v53, v42
	v_pk_fma_f32 v[6:7], v[6:7], s[0:1], v[22:23] op_sel:[0,0,1] op_sel_hi:[1,0,0]
	v_pk_add_f32 v[22:23], v[8:9], v[26:27]
	v_pk_add_f32 v[8:9], v[8:9], v[26:27] neg_lo:[0,1] neg_hi:[0,1]
	v_pk_add_f32 v[26:27], v[10:11], v[28:29]
	v_pk_add_f32 v[10:11], v[10:11], v[28:29] neg_lo:[0,1] neg_hi:[0,1]
	v_pk_mul_f32 v[28:29], v[10:11], s[34:35]
	v_mov_b32_e32 v54, v40
	v_pk_fma_f32 v[10:11], v[10:11], s[0:1], v[28:29] op_sel:[0,0,1] op_sel_hi:[1,0,0] neg_lo:[1,0,0] neg_hi:[1,0,0]
	v_pk_add_f32 v[28:29], v[12:13], v[30:31]
	v_pk_add_f32 v[12:13], v[12:13], v[30:31] neg_lo:[0,1] neg_hi:[0,1]
	s_movk_i32 s0, 0xff
	v_pk_mul_f32 v[30:31], v[12:13], s[10:11]
	v_cmp_ne_u32_e64 s[44:45], s0, v32
	v_pk_fma_f32 v[12:13], v[12:13], s[14:15], v[30:31] op_sel:[0,0,1] op_sel_hi:[1,0,0] neg_lo:[1,0,0] neg_hi:[1,0,0]
	v_pk_add_f32 v[30:31], v[14:15], v[24:25]
	v_pk_add_f32 v[14:15], v[14:15], v[24:25] neg_lo:[0,1] neg_hi:[0,1]
	v_mov_b32_e32 v55, v40
	v_pk_mul_f32 v[24:25], v[14:15], s[18:19]
	s_mov_b64 s[0:1], -1
	v_pk_fma_f32 v[14:15], v[14:15], s[30:31], v[24:25] op_sel:[0,0,1] op_sel_hi:[1,0,0] neg_lo:[1,0,0] neg_hi:[1,0,0]
	v_pk_add_f32 v[24:25], v[48:49], v[22:23]
	v_pk_add_f32 v[22:23], v[48:49], v[22:23] neg_lo:[0,1] neg_hi:[0,1]
	v_pk_add_f32 v[48:49], v[16:17], v[26:27]
	v_pk_add_f32 v[16:17], v[16:17], v[26:27] neg_lo:[0,1] neg_hi:[0,1]
	v_pk_mul_f32 v[26:27], v[16:17], s[10:11]
	v_pk_fma_f32 v[16:17], v[16:17], s[14:15], v[26:27] op_sel:[0,0,1] op_sel_hi:[1,0,0]
	v_pk_add_f32 v[26:27], v[18:19], v[28:29]
	v_pk_add_f32 v[18:19], v[18:19], v[28:29] neg_lo:[0,1] neg_hi:[0,1]
	v_pk_add_f32 v[28:29], v[20:21], v[30:31]
	v_pk_add_f32 v[20:21], v[20:21], v[30:31] neg_lo:[0,1] neg_hi:[0,1]
	v_pk_mul_f32 v[30:31], v[20:21], s[10:11]
	v_pk_fma_f32 v[20:21], v[20:21], s[14:15], v[30:31] op_sel:[0,0,1] op_sel_hi:[1,0,0] neg_lo:[1,0,0] neg_hi:[1,0,0]
	v_pk_add_f32 v[30:31], v[0:1], v[8:9] op_sel:[0,1] op_sel_hi:[1,0] neg_hi:[0,1]
	v_pk_add_f32 v[0:1], v[0:1], v[8:9] op_sel:[0,1] op_sel_hi:[1,0] neg_lo:[0,1]
	v_pk_add_f32 v[8:9], v[2:3], v[10:11]
	v_pk_add_f32 v[2:3], v[2:3], v[10:11] neg_lo:[0,1] neg_hi:[0,1]
	v_pk_mul_f32 v[10:11], v[2:3], s[10:11]
	v_pk_fma_f32 v[2:3], v[2:3], s[14:15], v[10:11] op_sel:[0,0,1] op_sel_hi:[1,0,0]
	v_pk_add_f32 v[10:11], v[4:5], v[12:13]
	v_pk_add_f32 v[4:5], v[4:5], v[12:13] neg_lo:[0,1] neg_hi:[0,1]
	v_pk_add_f32 v[12:13], v[6:7], v[14:15]
	v_pk_add_f32 v[6:7], v[6:7], v[14:15] neg_lo:[0,1] neg_hi:[0,1]
	v_pk_mul_f32 v[14:15], v[6:7], s[10:11]
	v_pk_fma_f32 v[6:7], v[6:7], s[14:15], v[14:15] op_sel:[0,0,1] op_sel_hi:[1,0,0] neg_lo:[1,0,0] neg_hi:[1,0,0]
	v_pk_add_f32 v[14:15], v[24:25], v[26:27]
	v_pk_add_f32 v[24:25], v[24:25], v[26:27] neg_lo:[0,1] neg_hi:[0,1]
	v_pk_add_f32 v[26:27], v[48:49], v[28:29]
	v_pk_add_f32 v[28:29], v[48:49], v[28:29] neg_lo:[0,1] neg_hi:[0,1]
	v_pk_add_f32 v[48:49], v[22:23], v[18:19] op_sel:[0,1] op_sel_hi:[1,0] neg_hi:[0,1]
	v_pk_add_f32 v[18:19], v[22:23], v[18:19] op_sel:[0,1] op_sel_hi:[1,0] neg_lo:[0,1]
	v_pk_add_f32 v[22:23], v[16:17], v[20:21]
	v_pk_add_f32 v[16:17], v[16:17], v[20:21] neg_lo:[0,1] neg_hi:[0,1]
	v_pk_add_f32 v[20:21], v[30:31], v[10:11]
	v_pk_add_f32 v[10:11], v[30:31], v[10:11] neg_lo:[0,1] neg_hi:[0,1]
	v_pk_add_f32 v[30:31], v[8:9], v[12:13]
	v_pk_add_f32 v[8:9], v[8:9], v[12:13] neg_lo:[0,1] neg_hi:[0,1]
	v_pk_add_f32 v[12:13], v[0:1], v[4:5] op_sel:[0,1] op_sel_hi:[1,0] neg_hi:[0,1]
	v_pk_add_f32 v[0:1], v[0:1], v[4:5] op_sel:[0,1] op_sel_hi:[1,0] neg_lo:[0,1]
	v_pk_add_f32 v[4:5], v[2:3], v[6:7]
	v_pk_add_f32 v[2:3], v[2:3], v[6:7] neg_lo:[0,1] neg_hi:[0,1]
	v_pk_mul_f32 v[2:3], v[2:3], s[22:23]
	v_pk_add_f32 v[6:7], v[14:15], v[26:27]
	v_pk_add_f32 v[14:15], v[14:15], v[26:27] neg_lo:[0,1] neg_hi:[0,1]
	v_pk_add_f32 v[26:27], v[24:25], v[28:29] op_sel:[0,1] op_sel_hi:[1,0] neg_hi:[0,1]
	v_pk_add_f32 v[24:25], v[24:25], v[28:29] op_sel:[0,1] op_sel_hi:[1,0] neg_lo:[0,1]
	v_pk_add_f32 v[28:29], v[48:49], v[22:23]
	v_pk_add_f32 v[22:23], v[48:49], v[22:23] neg_lo:[0,1] neg_hi:[0,1]
	v_pk_add_f32 v[48:49], v[18:19], v[16:17] op_sel:[0,1] op_sel_hi:[1,0] neg_hi:[0,1]
	v_pk_add_f32 v[16:17], v[18:19], v[16:17] op_sel:[0,1] op_sel_hi:[1,0] neg_lo:[0,1]
	v_pk_add_f32 v[18:19], v[20:21], v[30:31]
	v_pk_add_f32 v[20:21], v[20:21], v[30:31] neg_lo:[0,1] neg_hi:[0,1]
	v_pk_add_f32 v[30:31], v[10:11], v[8:9] op_sel:[0,1] op_sel_hi:[1,0] neg_hi:[0,1]
	v_pk_add_f32 v[8:9], v[10:11], v[8:9] op_sel:[0,1] op_sel_hi:[1,0] neg_lo:[0,1]
	v_pk_add_f32 v[10:11], v[12:13], v[4:5]
	v_pk_add_f32 v[4:5], v[12:13], v[4:5] neg_lo:[0,1] neg_hi:[0,1]
	v_pk_add_f32 v[12:13], v[0:1], v[2:3] op_sel:[0,1] op_sel_hi:[1,0]
	v_pk_add_f32 v[0:1], v[0:1], v[2:3] op_sel:[0,1] op_sel_hi:[1,0] neg_lo:[0,1] neg_hi:[0,1]
	v_lshlrev_b32_e32 v2, 4, v33
	v_and_or_b32 v2, v2, s15, v35
	v_ashrrev_i32_e32 v3, 4, v2
	v_lshlrev_b32_e32 v3, 3, v3
	v_lshlrev_b32_e32 v2, 3, v2
	v_add3_u32 v2, s26, v3, v2
	ds_write_b64 v2, v[6:7]
	ds_write_b64 v2, v[14:15] offset:34816
	ds_write_b64 v2, v[26:27] offset:17408
	ds_write_b64 v2, v[24:25] offset:52224
	ds_write_b64 v2, v[28:29] offset:8704
	ds_write_b64 v2, v[22:23] offset:43520
	ds_write_b64 v2, v[48:49] offset:26112
	ds_write_b64 v2, v[16:17] offset:60928
	ds_write_b64 v2, v[18:19] offset:4352
	ds_write_b64 v2, v[20:21] offset:39168
	ds_write_b64 v2, v[30:31] offset:21760
	ds_write_b64 v2, v[8:9] offset:56576
	ds_write_b64 v2, v[10:11] offset:13056
	ds_write_b64 v2, v[4:5] offset:47872
	ds_write_b64 v2, v[12:13] offset:30464
	ds_write_b64 v2, v[0:1] offset:65280
	v_lshlrev_b32_e32 v48, 4, v32
	v_ashrrev_i32_e32 v49, 31, v48
	v_mov_b32_e32 v172, v48
	v_add_u32_e32 v33, 0x10780, v153
	v_mov_b32_e32 v35, v34
	s_waitcnt lgkmcnt(0)
	s_barrier
	s_branch .LBB0_603

.LBB0_613:
	s_or_b64 exec, exec, s[28:29]
	s_xor_b64 s[0:1], s[0:1], -1
	v_cndmask_b32_e64 v76, 0, v24, s[40:41]
	v_cndmask_b32_e64 v77, 0, v58, s[40:41]
	v_cndmask_b32_e64 v70, 0, v25, s[40:41]
	v_cndmask_b32_e64 v71, 0, v59, s[40:41]
	v_cndmask_b32_e64 v90, 0, v22, s[40:41]
	v_cndmask_b32_e64 v91, 0, v30, s[40:41]
	v_cndmask_b32_e64 v82, 0, v23, s[40:41]
	v_cndmask_b32_e64 v83, 0, v31, s[40:41]
	v_cndmask_b32_e64 v74, 0, v20, s[40:41]
	v_cndmask_b32_e64 v75, 0, v28, s[40:41]
	v_cndmask_b32_e64 v66, 0, v21, s[40:41]
	v_cndmask_b32_e64 v67, 0, v29, s[40:41]
	v_cndmask_b32_e64 v88, 0, v16, s[40:41]
	v_cndmask_b32_e64 v89, 0, v26, s[40:41]
	v_cndmask_b32_e64 v80, 0, v17, s[40:41]
	v_cndmask_b32_e64 v81, 0, v27, s[40:41]
	v_cndmask_b32_e64 v72, 0, v14, s[40:41]
	v_cndmask_b32_e64 v73, 0, v6, s[40:41]
	v_cndmask_b32_e64 v64, 0, v15, s[40:41]
	v_cndmask_b32_e64 v65, 0, v7, s[40:41]
	v_cndmask_b32_e64 v84, 0, v12, s[40:41]
	v_cndmask_b32_e64 v85, 0, v4, s[40:41]
	v_cndmask_b32_e64 v78, 0, v13, s[40:41]
	v_cndmask_b32_e64 v79, 0, v5, s[40:41]
	v_cndmask_b32_e64 v68, 0, v10, s[40:41]
	v_cndmask_b32_e64 v69, 0, v2, s[40:41]
	v_cndmask_b32_e64 v62, 0, v11, s[40:41]
	v_cndmask_b32_e64 v63, 0, v3, s[40:41]
	v_cndmask_b32_e64 v60, 0, v8, s[40:41]
	v_cndmask_b32_e64 v61, 0, v0, s[40:41]
	v_cndmask_b32_e64 v58, 0, v9, s[40:41]
	v_cndmask_b32_e64 v59, 0, v1, s[40:41]
	ds_write2_b64 v152, v[76:77], v[70:71] offset1:1
	ds_write2_b64 v152, v[90:91], v[82:83] offset0:2 offset1:3
	ds_write2_b64 v152, v[74:75], v[66:67] offset0:4 offset1:5
	ds_write2_b64 v152, v[88:89], v[80:81] offset0:6 offset1:7
	ds_write2_b64 v152, v[72:73], v[64:65] offset0:8 offset1:9
	ds_write2_b64 v152, v[84:85], v[78:79] offset0:10 offset1:11
	ds_write2_b64 v152, v[68:69], v[62:63] offset0:12 offset1:13
	ds_write2_b64 v152, v[60:61], v[58:59] offset0:14 offset1:15
	s_waitcnt lgkmcnt(0)
	s_barrier
	s_and_saveexec_b64 s[28:29], s[40:41]
	s_cbranch_execz .LBB0_615
	ds_read_b64 v[0:1], v153
	ds_read_b64 v[2:3], v153 offset:2176
	ds_read_b64 v[4:5], v153 offset:4352
	ds_read_b64 v[6:7], v153 offset:6528
	ds_read_b64 v[8:9], v153 offset:8704
	ds_read_b64 v[10:11], v153 offset:10880
	ds_read_b64 v[12:13], v153 offset:13056
	ds_read_b64 v[14:15], v153 offset:15232
	ds_read_b64 v[16:17], v153 offset:17408
	ds_read_b64 v[18:19], v153 offset:19584
	ds_read_b64 v[20:21], v153 offset:21760
	ds_read_b64 v[22:23], v153 offset:23936
	ds_read_b64 v[24:25], v153 offset:26112
	ds_read_b64 v[26:27], v153 offset:28288
	ds_read_b64 v[28:29], v153 offset:30464
	ds_read_b64 v[30:31], v153 offset:32640
	ds_read_b64 v[86:87], v153 offset:34816
	ds_read_b64 v[92:93], v153 offset:41344
	ds_read_b64 v[94:95], v153 offset:43520
	ds_read_b64 v[96:97], v153 offset:45696
	ds_read_b64 v[98:99], v153 offset:47872
	ds_read_b64 v[100:101], v153 offset:50048
	ds_read_b64 v[102:103], v153 offset:52224
	ds_read_b64 v[104:105], v153 offset:54400
	ds_read_b64 v[106:107], v153 offset:56576
	ds_read_b64 v[108:109], v153 offset:58752
	ds_read_b64 v[110:111], v153 offset:60928
	ds_read_b64 v[112:113], v153 offset:63104
	ds_read_b64 v[114:115], v153 offset:65280
	ds_read_b64 v[116:117], v153 offset:36992
	ds_read_b64 v[118:119], v153 offset:39168
	ds_read_b64 v[120:121], v33
	s_waitcnt lgkmcnt(14)
	v_pk_add_f32 v[124:125], v[0:1], v[86:87]
	v_pk_add_f32 v[0:1], v[0:1], v[86:87] neg_lo:[0,1] neg_hi:[0,1]
	s_waitcnt lgkmcnt(2)
	v_pk_add_f32 v[86:87], v[2:3], v[116:117]
	v_pk_add_f32 v[2:3], v[2:3], v[116:117] neg_lo:[0,1] neg_hi:[0,1]
	s_mov_b32 s11, s14
	v_pk_mul_f32 v[116:117], v[2:3], s[16:17]
	s_mov_b32 s13, s86
	v_pk_fma_f32 v[2:3], v[2:3], s[6:7], v[116:117] op_sel:[0,0,1] op_sel_hi:[1,0,0]
	s_waitcnt lgkmcnt(1)
	v_pk_add_f32 v[116:117], v[4:5], v[118:119]
	v_pk_add_f32 v[4:5], v[4:5], v[118:119] neg_lo:[0,1] neg_hi:[0,1]
	s_mov_b32 s4, s21
	v_pk_mul_f32 v[118:119], v[4:5], s[18:19]
	s_mov_b32 s35, s30
	v_pk_fma_f32 v[4:5], v[4:5], s[30:31], v[118:119] op_sel:[0,0,1] op_sel_hi:[1,0,0]
	v_pk_add_f32 v[118:119], v[6:7], v[92:93]
	v_pk_add_f32 v[6:7], v[6:7], v[92:93] neg_lo:[0,1] neg_hi:[0,1]
	s_mov_b32 s8, s19
	v_pk_mul_f32 v[92:93], v[6:7], s[20:21]
	s_mov_b32 s77, s6
	v_pk_fma_f32 v[6:7], v[6:7], s[86:87], v[92:93] op_sel:[0,0,1] op_sel_hi:[1,0,0]
	v_pk_add_f32 v[92:93], v[8:9], v[94:95]
	v_pk_add_f32 v[8:9], v[8:9], v[94:95] neg_lo:[0,1] neg_hi:[0,1]
	s_mov_b32 s26, s17
	v_pk_mul_f32 v[94:95], v[8:9], s[10:11]
	s_nop 0
	v_pk_fma_f32 v[8:9], v[8:9], s[14:15], v[94:95] op_sel:[0,0,1] op_sel_hi:[1,0,0]
	v_pk_add_f32 v[94:95], v[10:11], v[96:97]
	v_pk_add_f32 v[10:11], v[10:11], v[96:97] neg_lo:[0,1] neg_hi:[0,1]
	v_pk_mul_f32 v[96:97], v[10:11], s[12:13]
	v_pk_fma_f32 v[10:11], v[10:11], s[4:5], v[96:97] op_sel:[0,0,1] op_sel_hi:[1,0,0]
	v_pk_add_f32 v[96:97], v[12:13], v[98:99]
	v_pk_add_f32 v[12:13], v[12:13], v[98:99] neg_lo:[0,1] neg_hi:[0,1]
	v_pk_mul_f32 v[98:99], v[12:13], s[34:35]
	v_pk_fma_f32 v[12:13], v[12:13], s[8:9], v[98:99] op_sel:[0,0,1] op_sel_hi:[1,0,0]
	v_pk_add_f32 v[98:99], v[14:15], v[100:101]
	v_pk_add_f32 v[14:15], v[14:15], v[100:101] neg_lo:[0,1] neg_hi:[0,1]
	v_pk_mul_f32 v[100:101], v[14:15], s[76:77]
	v_pk_fma_f32 v[14:15], v[14:15], s[26:27], v[100:101] op_sel:[0,0,1] op_sel_hi:[1,0,0]
	v_pk_add_f32 v[100:101], v[16:17], v[102:103]
	v_pk_add_f32 v[16:17], v[16:17], v[102:103] neg_lo:[0,1] neg_hi:[0,1]
	v_pk_add_f32 v[102:103], v[18:19], v[104:105]
	v_pk_add_f32 v[18:19], v[18:19], v[104:105] neg_lo:[0,1] neg_hi:[0,1]
	v_pk_mul_f32 v[104:105], v[18:19], s[76:77]
	v_pk_fma_f32 v[18:19], v[18:19], s[26:27], v[104:105] op_sel:[0,0,1] op_sel_hi:[1,0,0] neg_lo:[1,0,0] neg_hi:[1,0,0]
	v_pk_add_f32 v[104:105], v[20:21], v[106:107]
	v_pk_add_f32 v[20:21], v[20:21], v[106:107] neg_lo:[0,1] neg_hi:[0,1]
	v_pk_mul_f32 v[106:107], v[20:21], s[34:35]
	v_pk_fma_f32 v[20:21], v[20:21], s[8:9], v[106:107] op_sel:[0,0,1] op_sel_hi:[1,0,0] neg_lo:[1,0,0] neg_hi:[1,0,0]
	v_pk_add_f32 v[106:107], v[22:23], v[108:109]
	v_pk_add_f32 v[22:23], v[22:23], v[108:109] neg_lo:[0,1] neg_hi:[0,1]
	v_pk_mul_f32 v[108:109], v[22:23], s[12:13]
	v_pk_fma_f32 v[22:23], v[22:23], s[4:5], v[108:109] op_sel:[0,0,1] op_sel_hi:[1,0,0] neg_lo:[1,0,0] neg_hi:[1,0,0]
	v_pk_add_f32 v[108:109], v[24:25], v[110:111]
	v_pk_add_f32 v[24:25], v[24:25], v[110:111] neg_lo:[0,1] neg_hi:[0,1]
	v_pk_mul_f32 v[110:111], v[24:25], s[10:11]
	v_pk_fma_f32 v[24:25], v[24:25], s[14:15], v[110:111] op_sel:[0,0,1] op_sel_hi:[1,0,0] neg_lo:[1,0,0] neg_hi:[1,0,0]
	v_pk_add_f32 v[110:111], v[26:27], v[112:113]
	v_pk_add_f32 v[26:27], v[26:27], v[112:113] neg_lo:[0,1] neg_hi:[0,1]
	v_pk_mul_f32 v[112:113], v[26:27], s[20:21]
	v_pk_fma_f32 v[26:27], v[26:27], s[86:87], v[112:113] op_sel:[0,0,1] op_sel_hi:[1,0,0] neg_lo:[1,0,0] neg_hi:[1,0,0]
	v_pk_add_f32 v[112:113], v[28:29], v[114:115]
	v_pk_add_f32 v[28:29], v[28:29], v[114:115] neg_lo:[0,1] neg_hi:[0,1]
	v_pk_mul_f32 v[114:115], v[28:29], s[18:19]
	v_pk_fma_f32 v[28:29], v[28:29], s[30:31], v[114:115] op_sel:[0,0,1] op_sel_hi:[1,0,0] neg_lo:[1,0,0] neg_hi:[1,0,0]
	s_waitcnt lgkmcnt(0)
	v_pk_add_f32 v[114:115], v[30:31], v[120:121]
	v_pk_add_f32 v[30:31], v[30:31], v[120:121] neg_lo:[0,1] neg_hi:[0,1]
	s_nop 0
	v_pk_mul_f32 v[120:121], v[30:31], s[16:17]
	v_pk_fma_f32 v[30:31], v[30:31], s[6:7], v[120:121] op_sel:[0,0,1] op_sel_hi:[1,0,0] neg_lo:[1,0,0] neg_hi:[1,0,0]
	v_pk_add_f32 v[120:121], v[124:125], v[100:101]
	v_pk_add_f32 v[100:101], v[124:125], v[100:101] neg_lo:[0,1] neg_hi:[0,1]
	v_pk_add_f32 v[124:125], v[86:87], v[102:103]
	v_pk_add_f32 v[86:87], v[86:87], v[102:103] neg_lo:[0,1] neg_hi:[0,1]
	v_pk_mul_f32 v[102:103], v[86:87], s[18:19]
	v_pk_fma_f32 v[86:87], v[86:87], s[30:31], v[102:103] op_sel:[0,0,1] op_sel_hi:[1,0,0]
	v_pk_add_f32 v[102:103], v[116:117], v[104:105]
	v_pk_add_f32 v[104:105], v[116:117], v[104:105] neg_lo:[0,1] neg_hi:[0,1]
	v_pk_mul_f32 v[116:117], v[104:105], s[10:11]
	v_pk_fma_f32 v[104:105], v[104:105], s[14:15], v[116:117] op_sel:[0,0,1] op_sel_hi:[1,0,0]
	v_pk_add_f32 v[116:117], v[118:119], v[106:107]
	v_pk_add_f32 v[106:107], v[118:119], v[106:107] neg_lo:[0,1] neg_hi:[0,1]
	v_pk_mul_f32 v[118:119], v[106:107], s[34:35]
	v_pk_fma_f32 v[106:107], v[106:107], s[8:9], v[118:119] op_sel:[0,0,1] op_sel_hi:[1,0,0]
	v_pk_add_f32 v[118:119], v[92:93], v[108:109]
	v_pk_add_f32 v[92:93], v[92:93], v[108:109] neg_lo:[0,1] neg_hi:[0,1]
	v_pk_add_f32 v[108:109], v[94:95], v[110:111]
	v_pk_add_f32 v[94:95], v[94:95], v[110:111] neg_lo:[0,1] neg_hi:[0,1]
	v_pk_mul_f32 v[110:111], v[94:95], s[34:35]
	v_pk_fma_f32 v[94:95], v[94:95], s[8:9], v[110:111] op_sel:[0,0,1] op_sel_hi:[1,0,0] neg_lo:[1,0,0] neg_hi:[1,0,0]
	v_pk_add_f32 v[110:111], v[96:97], v[112:113]
	v_pk_add_f32 v[96:97], v[96:97], v[112:113] neg_lo:[0,1] neg_hi:[0,1]
	v_pk_mul_f32 v[112:113], v[96:97], s[10:11]
	v_pk_fma_f32 v[96:97], v[96:97], s[14:15], v[112:113] op_sel:[0,0,1] op_sel_hi:[1,0,0] neg_lo:[1,0,0] neg_hi:[1,0,0]
	v_pk_add_f32 v[112:113], v[98:99], v[114:115]
	v_pk_add_f32 v[98:99], v[98:99], v[114:115] neg_lo:[0,1] neg_hi:[0,1]
	v_pk_mul_f32 v[114:115], v[98:99], s[18:19]
	v_pk_fma_f32 v[98:99], v[98:99], s[30:31], v[114:115] op_sel:[0,0,1] op_sel_hi:[1,0,0] neg_lo:[1,0,0] neg_hi:[1,0,0]
	v_pk_add_f32 v[114:115], v[0:1], v[16:17] op_sel:[0,1] op_sel_hi:[1,0] neg_hi:[0,1]
	v_pk_add_f32 v[0:1], v[0:1], v[16:17] op_sel:[0,1] op_sel_hi:[1,0] neg_lo:[0,1]
	v_pk_add_f32 v[16:17], v[2:3], v[18:19]
	v_pk_add_f32 v[2:3], v[2:3], v[18:19] neg_lo:[0,1] neg_hi:[0,1]
	v_pk_mul_f32 v[18:19], v[2:3], s[18:19]
	v_pk_fma_f32 v[2:3], v[2:3], s[30:31], v[18:19] op_sel:[0,0,1] op_sel_hi:[1,0,0]
	v_pk_add_f32 v[18:19], v[4:5], v[20:21]
	v_pk_add_f32 v[4:5], v[4:5], v[20:21] neg_lo:[0,1] neg_hi:[0,1]
	v_pk_mul_f32 v[20:21], v[4:5], s[10:11]
	v_pk_fma_f32 v[4:5], v[4:5], s[14:15], v[20:21] op_sel:[0,0,1] op_sel_hi:[1,0,0]
	v_pk_add_f32 v[20:21], v[6:7], v[22:23]
	v_pk_add_f32 v[6:7], v[6:7], v[22:23] neg_lo:[0,1] neg_hi:[0,1]
	v_pk_mul_f32 v[22:23], v[6:7], s[34:35]
	v_pk_fma_f32 v[6:7], v[6:7], s[8:9], v[22:23] op_sel:[0,0,1] op_sel_hi:[1,0,0]
	v_pk_add_f32 v[22:23], v[8:9], v[24:25]
	v_pk_add_f32 v[8:9], v[8:9], v[24:25] neg_lo:[0,1] neg_hi:[0,1]
	v_pk_add_f32 v[24:25], v[10:11], v[26:27]
	v_pk_add_f32 v[10:11], v[10:11], v[26:27] neg_lo:[0,1] neg_hi:[0,1]
	v_pk_mul_f32 v[26:27], v[10:11], s[34:35]
	v_pk_fma_f32 v[10:11], v[10:11], s[8:9], v[26:27] op_sel:[0,0,1] op_sel_hi:[1,0,0] neg_lo:[1,0,0] neg_hi:[1,0,0]
	v_pk_add_f32 v[26:27], v[12:13], v[28:29]
	v_pk_add_f32 v[12:13], v[12:13], v[28:29] neg_lo:[0,1] neg_hi:[0,1]
	v_pk_mul_f32 v[28:29], v[12:13], s[10:11]
	v_pk_fma_f32 v[12:13], v[12:13], s[14:15], v[28:29] op_sel:[0,0,1] op_sel_hi:[1,0,0] neg_lo:[1,0,0] neg_hi:[1,0,0]
	v_pk_add_f32 v[28:29], v[14:15], v[30:31]
	v_pk_add_f32 v[14:15], v[14:15], v[30:31] neg_lo:[0,1] neg_hi:[0,1]
	v_pk_mul_f32 v[30:31], v[14:15], s[18:19]
	v_pk_fma_f32 v[14:15], v[14:15], s[30:31], v[30:31] op_sel:[0,0,1] op_sel_hi:[1,0,0] neg_lo:[1,0,0] neg_hi:[1,0,0]
	v_pk_add_f32 v[30:31], v[120:121], v[118:119]
	v_pk_add_f32 v[118:119], v[120:121], v[118:119] neg_lo:[0,1] neg_hi:[0,1]
	v_pk_add_f32 v[120:121], v[124:125], v[108:109]
	v_pk_add_f32 v[108:109], v[124:125], v[108:109] neg_lo:[0,1] neg_hi:[0,1]
	v_pk_mul_f32 v[124:125], v[108:109], s[10:11]
	v_pk_fma_f32 v[108:109], v[108:109], s[14:15], v[124:125] op_sel:[0,0,1] op_sel_hi:[1,0,0]
	v_pk_add_f32 v[124:125], v[102:103], v[110:111]
	v_pk_add_f32 v[102:103], v[102:103], v[110:111] neg_lo:[0,1] neg_hi:[0,1]
	v_pk_add_f32 v[110:111], v[116:117], v[112:113]
	v_pk_add_f32 v[112:113], v[116:117], v[112:113] neg_lo:[0,1] neg_hi:[0,1]
	v_pk_mul_f32 v[116:117], v[112:113], s[10:11]
	v_pk_fma_f32 v[112:113], v[112:113], s[14:15], v[116:117] op_sel:[0,0,1] op_sel_hi:[1,0,0] neg_lo:[1,0,0] neg_hi:[1,0,0]
	v_pk_add_f32 v[116:117], v[100:101], v[92:93] op_sel:[0,1] op_sel_hi:[1,0] neg_hi:[0,1]
	v_pk_add_f32 v[92:93], v[100:101], v[92:93] op_sel:[0,1] op_sel_hi:[1,0] neg_lo:[0,1]
	v_pk_add_f32 v[100:101], v[86:87], v[94:95]
	v_pk_add_f32 v[86:87], v[86:87], v[94:95] neg_lo:[0,1] neg_hi:[0,1]
	v_pk_add_f32 v[126:127], v[108:109], v[112:113]
	v_pk_mul_f32 v[94:95], v[86:87], s[10:11]
	v_pk_fma_f32 v[86:87], v[86:87], s[14:15], v[94:95] op_sel:[0,0,1] op_sel_hi:[1,0,0]
	v_pk_add_f32 v[94:95], v[104:105], v[96:97]
	v_pk_add_f32 v[96:97], v[104:105], v[96:97] neg_lo:[0,1] neg_hi:[0,1]
	v_pk_add_f32 v[104:105], v[106:107], v[98:99]
	v_pk_add_f32 v[98:99], v[106:107], v[98:99] neg_lo:[0,1] neg_hi:[0,1]
	v_pk_mul_f32 v[106:107], v[98:99], s[10:11]
	v_pk_add_f32 v[130:131], v[92:93], v[96:97] op_sel:[0,1] op_sel_hi:[1,0] neg_hi:[0,1]
	v_pk_fma_f32 v[98:99], v[98:99], s[14:15], v[106:107] op_sel:[0,0,1] op_sel_hi:[1,0,0] neg_lo:[1,0,0] neg_hi:[1,0,0]
	v_pk_add_f32 v[106:107], v[114:115], v[22:23]
	v_pk_add_f32 v[22:23], v[114:115], v[22:23] neg_lo:[0,1] neg_hi:[0,1]
	v_pk_add_f32 v[114:115], v[16:17], v[24:25]
	v_pk_add_f32 v[16:17], v[16:17], v[24:25] neg_lo:[0,1] neg_hi:[0,1]
	v_pk_add_f32 v[132:133], v[92:93], v[96:97] op_sel:[0,1] op_sel_hi:[1,0] neg_lo:[0,1]
	v_pk_mul_f32 v[24:25], v[16:17], s[10:11]
	v_pk_add_f32 v[92:93], v[86:87], v[98:99]
	v_pk_fma_f32 v[16:17], v[16:17], s[14:15], v[24:25] op_sel:[0,0,1] op_sel_hi:[1,0,0]
	v_pk_add_f32 v[24:25], v[18:19], v[26:27]
	v_pk_add_f32 v[18:19], v[18:19], v[26:27] neg_lo:[0,1] neg_hi:[0,1]
	v_pk_add_f32 v[26:27], v[20:21], v[28:29]
	v_pk_add_f32 v[20:21], v[20:21], v[28:29] neg_lo:[0,1] neg_hi:[0,1]
	v_pk_mul_f32 v[28:29], v[20:21], s[10:11]
	v_pk_add_f32 v[86:87], v[86:87], v[98:99] neg_lo:[0,1] neg_hi:[0,1]
	v_pk_fma_f32 v[20:21], v[20:21], s[14:15], v[28:29] op_sel:[0,0,1] op_sel_hi:[1,0,0] neg_lo:[1,0,0] neg_hi:[1,0,0]
	v_pk_add_f32 v[28:29], v[0:1], v[8:9] op_sel:[0,1] op_sel_hi:[1,0] neg_hi:[0,1]
	v_pk_add_f32 v[0:1], v[0:1], v[8:9] op_sel:[0,1] op_sel_hi:[1,0] neg_lo:[0,1]
	v_pk_add_f32 v[8:9], v[2:3], v[10:11]
	v_pk_add_f32 v[2:3], v[2:3], v[10:11] neg_lo:[0,1] neg_hi:[0,1]
	v_pk_add_f32 v[134:135], v[106:107], v[24:25]
	v_pk_mul_f32 v[10:11], v[2:3], s[10:11]
	v_pk_add_f32 v[106:107], v[106:107], v[24:25] neg_lo:[0,1] neg_hi:[0,1]
	v_pk_fma_f32 v[2:3], v[2:3], s[14:15], v[10:11] op_sel:[0,0,1] op_sel_hi:[1,0,0]
	v_pk_add_f32 v[10:11], v[4:5], v[12:13]
	v_pk_add_f32 v[4:5], v[4:5], v[12:13] neg_lo:[0,1] neg_hi:[0,1]
	v_pk_add_f32 v[12:13], v[6:7], v[14:15]
	v_pk_add_f32 v[6:7], v[6:7], v[14:15] neg_lo:[0,1] neg_hi:[0,1]
	v_pk_mul_f32 v[14:15], v[6:7], s[10:11]
	v_pk_add_f32 v[24:25], v[114:115], v[26:27] neg_lo:[0,1] neg_hi:[0,1]
	v_pk_fma_f32 v[6:7], v[6:7], s[14:15], v[14:15] op_sel:[0,0,1] op_sel_hi:[1,0,0] neg_lo:[1,0,0] neg_hi:[1,0,0]
	v_pk_add_f32 v[14:15], v[30:31], v[124:125]
	v_pk_add_f32 v[30:31], v[30:31], v[124:125] neg_lo:[0,1] neg_hi:[0,1]
	v_pk_add_f32 v[124:125], v[120:121], v[110:111]
	v_pk_add_f32 v[110:111], v[120:121], v[110:111] neg_lo:[0,1] neg_hi:[0,1]
	v_pk_add_f32 v[120:121], v[118:119], v[102:103] op_sel:[0,1] op_sel_hi:[1,0] neg_hi:[0,1]
	v_pk_add_f32 v[118:119], v[118:119], v[102:103] op_sel:[0,1] op_sel_hi:[1,0] neg_lo:[0,1]
	v_pk_add_f32 v[102:103], v[108:109], v[112:113] neg_lo:[0,1] neg_hi:[0,1]
	v_pk_add_f32 v[112:113], v[116:117], v[94:95]
	v_pk_add_f32 v[94:95], v[116:117], v[94:95] neg_lo:[0,1] neg_hi:[0,1]
	v_pk_add_f32 v[116:117], v[100:101], v[104:105]
	v_pk_add_f32 v[100:101], v[100:101], v[104:105] neg_lo:[0,1] neg_hi:[0,1]
	v_pk_add_f32 v[138:139], v[22:23], v[18:19] op_sel:[0,1] op_sel_hi:[1,0] neg_hi:[0,1]
	v_pk_add_f32 v[140:141], v[22:23], v[18:19] op_sel:[0,1] op_sel_hi:[1,0] neg_lo:[0,1]
	v_pk_add_f32 v[18:19], v[16:17], v[20:21]
	v_pk_add_f32 v[16:17], v[16:17], v[20:21] neg_lo:[0,1] neg_hi:[0,1]
	v_pk_add_f32 v[144:145], v[28:29], v[10:11]
	v_pk_add_f32 v[158:159], v[28:29], v[10:11] neg_lo:[0,1] neg_hi:[0,1]
	v_pk_add_f32 v[10:11], v[8:9], v[12:13]
	v_pk_add_f32 v[8:9], v[8:9], v[12:13] neg_lo:[0,1] neg_hi:[0,1]
	v_pk_add_f32 v[162:163], v[0:1], v[4:5] op_sel:[0,1] op_sel_hi:[1,0] neg_hi:[0,1]
	v_pk_add_f32 v[164:165], v[0:1], v[4:5] op_sel:[0,1] op_sel_hi:[1,0] neg_lo:[0,1]
	v_pk_add_f32 v[0:1], v[2:3], v[6:7] neg_lo:[0,1] neg_hi:[0,1]
	v_pk_mul_f32 v[108:109], v[102:103], s[22:23]
	v_pk_mul_f32 v[128:129], v[100:101], s[22:23]
	v_pk_add_f32 v[136:137], v[114:115], v[26:27]
	v_pk_mul_f32 v[114:115], v[24:25], s[22:23]
	v_pk_mul_f32 v[142:143], v[16:17], s[22:23]
	v_pk_mul_f32 v[160:161], v[8:9], s[22:23]
	v_pk_add_f32 v[166:167], v[2:3], v[6:7]
	v_pk_mul_f32 v[168:169], v[0:1], s[22:23]
	v_pk_add_f32 v[28:29], v[14:15], v[124:125]
	v_pk_add_f32 v[104:105], v[14:15], v[124:125] neg_lo:[0,1] neg_hi:[0,1]
	v_pk_add_f32 v[24:25], v[30:31], v[110:111] op_sel:[0,1] op_sel_hi:[1,0] neg_hi:[0,1]
	v_pk_add_f32 v[102:103], v[30:31], v[110:111] op_sel:[0,1] op_sel_hi:[1,0] neg_lo:[0,1]
	v_pk_add_f32 v[20:21], v[120:121], v[126:127]
	v_pk_add_f32 v[100:101], v[120:121], v[126:127] neg_lo:[0,1] neg_hi:[0,1]
	v_pk_add_f32 v[16:17], v[118:119], v[108:109] op_sel:[0,1] op_sel_hi:[1,0]
	v_pk_add_f32 v[98:99], v[118:119], v[108:109] op_sel:[0,1] op_sel_hi:[1,0] neg_lo:[0,1] neg_hi:[0,1]
	v_pk_add_f32 v[12:13], v[112:113], v[116:117]
	v_pk_add_f32 v[96:97], v[112:113], v[116:117] neg_lo:[0,1] neg_hi:[0,1]
	v_pk_add_f32 v[8:9], v[94:95], v[128:129] op_sel:[0,1] op_sel_hi:[1,0]
	v_pk_add_f32 v[94:95], v[94:95], v[128:129] op_sel:[0,1] op_sel_hi:[1,0] neg_lo:[0,1] neg_hi:[0,1]
	v_pk_add_f32 v[4:5], v[130:131], v[92:93]
	v_pk_add_f32 v[92:93], v[130:131], v[92:93] neg_lo:[0,1] neg_hi:[0,1]
	v_pk_add_f32 v[0:1], v[132:133], v[86:87] op_sel:[0,1] op_sel_hi:[1,0] neg_hi:[0,1]
	v_pk_add_f32 v[86:87], v[132:133], v[86:87] op_sel:[0,1] op_sel_hi:[1,0] neg_lo:[0,1]
	v_pk_add_f32 v[30:31], v[134:135], v[136:137]
	v_pk_add_f32 v[120:121], v[134:135], v[136:137] neg_lo:[0,1] neg_hi:[0,1]
	v_pk_add_f32 v[26:27], v[106:107], v[114:115] op_sel:[0,1] op_sel_hi:[1,0]
	v_pk_add_f32 v[118:119], v[106:107], v[114:115] op_sel:[0,1] op_sel_hi:[1,0] neg_lo:[0,1] neg_hi:[0,1]
	v_pk_add_f32 v[22:23], v[138:139], v[18:19]
	v_pk_add_f32 v[116:117], v[138:139], v[18:19] neg_lo:[0,1] neg_hi:[0,1]
	v_pk_add_f32 v[18:19], v[140:141], v[142:143] op_sel:[0,1] op_sel_hi:[1,0]
	v_pk_add_f32 v[114:115], v[140:141], v[142:143] op_sel:[0,1] op_sel_hi:[1,0] neg_lo:[0,1] neg_hi:[0,1]
	v_pk_add_f32 v[14:15], v[144:145], v[10:11]
	v_pk_add_f32 v[112:113], v[144:145], v[10:11] neg_lo:[0,1] neg_hi:[0,1]
	v_pk_add_f32 v[10:11], v[158:159], v[160:161] op_sel:[0,1] op_sel_hi:[1,0]
	v_pk_add_f32 v[110:111], v[158:159], v[160:161] op_sel:[0,1] op_sel_hi:[1,0] neg_lo:[0,1] neg_hi:[0,1]
	v_pk_add_f32 v[6:7], v[162:163], v[166:167]
	v_pk_add_f32 v[108:109], v[162:163], v[166:167] neg_lo:[0,1] neg_hi:[0,1]
	v_pk_add_f32 v[2:3], v[164:165], v[168:169] op_sel:[0,1] op_sel_hi:[1,0]
	v_pk_add_f32 v[106:107], v[164:165], v[168:169] op_sel:[0,1] op_sel_hi:[1,0] neg_lo:[0,1] neg_hi:[0,1]

.LBB0_617:
	s_or_b64 exec, exec, s[4:5]
	v_mov_b32_e32 v41, v32
	s_waitcnt lgkmcnt(0)
	s_barrier
	s_mov_b32 s11, s14
	v_and_b32_e32 v98, 31, v41
	v_cvt_f32_ubyte0_e32 v24, v98
	v_mul_f32_e32 v92, 0x3b000000, v24
	v_sin_f32_e32 v24, v92
	v_ashrrev_i32_e32 v0, 4, v41
	v_lshlrev_b32_e32 v0, 3, v0
	v_lshlrev_b32_e32 v1, 3, v41
	v_cos_f32_e32 v92, v92
	v_add3_u32 v25, 0, v0, v1
	ds_read_b64 v[0:1], v25
	ds_read_b64 v[2:3], v25 offset:4352
	ds_read_b64 v[4:5], v25 offset:8704
	ds_read_b64 v[6:7], v25 offset:13056
	ds_read_b64 v[8:9], v25 offset:17408
	ds_read_b64 v[10:11], v25 offset:21760
	ds_read_b64 v[12:13], v25 offset:26112
	ds_read_b64 v[14:15], v25 offset:30464
	ds_read_b64 v[16:17], v25 offset:34816
	ds_read_b64 v[18:19], v25 offset:39168
	ds_read_b64 v[20:21], v25 offset:43520
	ds_read_b64 v[22:23], v25 offset:47872
	v_xor_b32_e32 v93, 0x80000000, v24
	s_waitcnt lgkmcnt(10)
	v_pk_mul_f32 v[94:95], v[2:3], v[24:25] op_sel:[1,0] op_sel_hi:[0,0] neg_hi:[0,1]
	v_pk_fma_f32 v[2:3], v[2:3], v[92:93], v[94:95] op_sel_hi:[1,0,1]
	v_pk_mul_f32 v[94:95], v[24:25], v[92:93] op_sel:[0,1] op_sel_hi:[0,0] neg_hi:[1,0]
	v_pk_fma_f32 v[94:95], v[92:93], v[92:93], v[94:95] op_sel_hi:[0,1,1]
	ds_read_b64 v[26:27], v25 offset:52224
	ds_read_b64 v[28:29], v25 offset:56576
	ds_read_b64 v[30:31], v25 offset:60928
	ds_read_b64 v[86:87], v25 offset:65280
	s_waitcnt lgkmcnt(13)
	v_pk_mul_f32 v[96:97], v[4:5], v[94:95] op_sel:[1,1] op_sel_hi:[0,1] neg_lo:[0,1]
	v_pk_fma_f32 v[4:5], v[4:5], v[94:95], v[96:97] op_sel_hi:[1,0,1]
	v_pk_mul_f32 v[96:97], v[24:25], v[94:95] op_sel:[0,1] op_sel_hi:[0,0] neg_hi:[1,0]
	v_pk_fma_f32 v[94:95], v[92:93], v[94:95], v[96:97] op_sel_hi:[0,1,1]
	s_mov_b32 s35, s30
	s_waitcnt lgkmcnt(12)
	v_pk_mul_f32 v[96:97], v[6:7], v[94:95] op_sel:[1,1] op_sel_hi:[0,1] neg_lo:[0,1]
	v_pk_fma_f32 v[6:7], v[6:7], v[94:95], v[96:97] op_sel_hi:[1,0,1]
	v_pk_mul_f32 v[96:97], v[24:25], v[94:95] op_sel:[0,1] op_sel_hi:[0,0] neg_hi:[1,0]
	v_pk_fma_f32 v[94:95], v[92:93], v[94:95], v[96:97] op_sel_hi:[0,1,1]
	s_mov_b32 s26, s19
	s_waitcnt lgkmcnt(11)
	v_pk_mul_f32 v[96:97], v[8:9], v[94:95] op_sel:[1,1] op_sel_hi:[0,1] neg_lo:[0,1]
	v_pk_fma_f32 v[8:9], v[8:9], v[94:95], v[96:97] op_sel_hi:[1,0,1]
	v_pk_mul_f32 v[96:97], v[24:25], v[94:95] op_sel:[0,1] op_sel_hi:[0,0] neg_hi:[1,0]
	v_pk_fma_f32 v[94:95], v[92:93], v[94:95], v[96:97] op_sel_hi:[0,1,1]
	s_waitcnt lgkmcnt(0)
	v_pk_mul_f32 v[96:97], v[10:11], v[94:95] op_sel:[1,1] op_sel_hi:[0,1] neg_lo:[0,1]
	v_pk_fma_f32 v[10:11], v[10:11], v[94:95], v[96:97] op_sel_hi:[1,0,1]
	v_pk_mul_f32 v[96:97], v[24:25], v[94:95] op_sel:[0,1] op_sel_hi:[0,0] neg_hi:[1,0]
	v_pk_fma_f32 v[94:95], v[92:93], v[94:95], v[96:97] op_sel_hi:[0,1,1]
	s_barrier
	v_pk_mul_f32 v[96:97], v[12:13], v[94:95] op_sel:[1,1] op_sel_hi:[0,1] neg_lo:[0,1]
	v_pk_fma_f32 v[12:13], v[12:13], v[94:95], v[96:97] op_sel_hi:[1,0,1]
	v_pk_mul_f32 v[96:97], v[24:25], v[94:95] op_sel:[0,1] op_sel_hi:[0,0] neg_hi:[1,0]
	v_pk_fma_f32 v[94:95], v[92:93], v[94:95], v[96:97] op_sel_hi:[0,1,1]
	v_pk_mul_f32 v[96:97], v[14:15], v[94:95] op_sel:[1,1] op_sel_hi:[0,1] neg_lo:[0,1]
	v_pk_fma_f32 v[14:15], v[14:15], v[94:95], v[96:97] op_sel_hi:[1,0,1]
	v_pk_mul_f32 v[96:97], v[24:25], v[94:95] op_sel:[0,1] op_sel_hi:[0,0] neg_hi:[1,0]
	v_pk_fma_f32 v[94:95], v[92:93], v[94:95], v[96:97] op_sel_hi:[0,1,1]
	s_mov_b32 s4, 0
	v_pk_mul_f32 v[96:97], v[16:17], v[94:95] op_sel:[1,1] op_sel_hi:[0,1] neg_lo:[0,1]
	v_pk_fma_f32 v[16:17], v[16:17], v[94:95], v[96:97] op_sel_hi:[1,0,1]
	v_pk_mul_f32 v[96:97], v[24:25], v[94:95] op_sel:[0,1] op_sel_hi:[0,0] neg_hi:[1,0]
	v_pk_fma_f32 v[94:95], v[92:93], v[94:95], v[96:97] op_sel_hi:[0,1,1]
	v_pk_mul_f32 v[96:97], v[18:19], v[94:95] op_sel:[1,1] op_sel_hi:[0,1] neg_lo:[0,1]
	v_pk_fma_f32 v[18:19], v[18:19], v[94:95], v[96:97] op_sel_hi:[1,0,1]
	v_pk_mul_f32 v[96:97], v[24:25], v[94:95] op_sel:[0,1] op_sel_hi:[0,0] neg_hi:[1,0]
	v_pk_fma_f32 v[94:95], v[92:93], v[94:95], v[96:97] op_sel_hi:[0,1,1]
	v_pk_mul_f32 v[96:97], v[20:21], v[94:95] op_sel:[1,1] op_sel_hi:[0,1] neg_lo:[0,1]
	v_pk_fma_f32 v[20:21], v[20:21], v[94:95], v[96:97] op_sel_hi:[1,0,1]
	v_pk_mul_f32 v[96:97], v[24:25], v[94:95] op_sel:[0,1] op_sel_hi:[0,0] neg_hi:[1,0]
	v_pk_fma_f32 v[94:95], v[92:93], v[94:95], v[96:97] op_sel_hi:[0,1,1]
	v_pk_mul_f32 v[96:97], v[22:23], v[94:95] op_sel:[1,1] op_sel_hi:[0,1] neg_lo:[0,1]
	v_pk_fma_f32 v[22:23], v[22:23], v[94:95], v[96:97] op_sel_hi:[1,0,1]
	v_pk_mul_f32 v[96:97], v[24:25], v[94:95] op_sel:[0,1] op_sel_hi:[0,0] neg_hi:[1,0]
	v_pk_fma_f32 v[94:95], v[92:93], v[94:95], v[96:97] op_sel_hi:[0,1,1]
	v_pk_mul_f32 v[96:97], v[26:27], v[94:95] op_sel:[1,1] op_sel_hi:[0,1] neg_lo:[0,1]
	v_pk_fma_f32 v[26:27], v[26:27], v[94:95], v[96:97] op_sel_hi:[1,0,1]
	v_pk_mul_f32 v[96:97], v[24:25], v[94:95] op_sel:[0,1] op_sel_hi:[0,0] neg_hi:[1,0]
	v_pk_fma_f32 v[94:95], v[92:93], v[94:95], v[96:97] op_sel_hi:[0,1,1]
	v_pk_mul_f32 v[96:97], v[28:29], v[94:95] op_sel:[1,1] op_sel_hi:[0,1] neg_lo:[0,1]
	v_pk_fma_f32 v[28:29], v[28:29], v[94:95], v[96:97] op_sel_hi:[1,0,1]
	v_pk_mul_f32 v[96:97], v[24:25], v[94:95] op_sel:[0,1] op_sel_hi:[0,0] neg_hi:[1,0]
	v_pk_fma_f32 v[94:95], v[92:93], v[94:95], v[96:97] op_sel_hi:[0,1,1]
	v_pk_mul_f32 v[24:25], v[24:25], v[94:95] op_sel:[0,1] op_sel_hi:[0,0] neg_hi:[1,0]
	v_pk_fma_f32 v[24:25], v[92:93], v[94:95], v[24:25] op_sel_hi:[0,1,1]
	v_pk_mul_f32 v[92:93], v[86:87], v[24:25] op_sel:[1,1] op_sel_hi:[0,1] neg_lo:[0,1]
	v_pk_fma_f32 v[24:25], v[86:87], v[24:25], v[92:93] op_sel_hi:[1,0,1]
	v_pk_add_f32 v[86:87], v[0:1], v[16:17]
	v_pk_add_f32 v[0:1], v[0:1], v[16:17] neg_lo:[0,1] neg_hi:[0,1]
	v_pk_add_f32 v[16:17], v[2:3], v[18:19]
	v_pk_add_f32 v[2:3], v[2:3], v[18:19] neg_lo:[0,1] neg_hi:[0,1]
	v_pk_mul_f32 v[96:97], v[30:31], v[94:95] op_sel:[1,1] op_sel_hi:[0,1] neg_lo:[0,1]
	v_pk_mul_f32 v[18:19], v[2:3], s[18:19]
	v_pk_fma_f32 v[30:31], v[30:31], v[94:95], v[96:97] op_sel_hi:[1,0,1]
	v_pk_fma_f32 v[2:3], v[2:3], s[30:31], v[18:19] op_sel:[0,0,1] op_sel_hi:[1,0,0]
	v_pk_add_f32 v[18:19], v[4:5], v[20:21]
	v_pk_add_f32 v[4:5], v[4:5], v[20:21] neg_lo:[0,1] neg_hi:[0,1]
	v_pk_mul_f32 v[20:21], v[4:5], s[10:11]
	v_pk_fma_f32 v[4:5], v[4:5], s[14:15], v[20:21] op_sel:[0,0,1] op_sel_hi:[1,0,0]
	v_pk_add_f32 v[20:21], v[6:7], v[22:23]
	v_pk_add_f32 v[6:7], v[6:7], v[22:23] neg_lo:[0,1] neg_hi:[0,1]
	v_pk_mul_f32 v[22:23], v[6:7], s[34:35]
	v_pk_fma_f32 v[6:7], v[6:7], s[26:27], v[22:23] op_sel:[0,0,1] op_sel_hi:[1,0,0]
	v_pk_add_f32 v[22:23], v[8:9], v[26:27]
	v_pk_add_f32 v[8:9], v[8:9], v[26:27] neg_lo:[0,1] neg_hi:[0,1]
	v_pk_add_f32 v[26:27], v[10:11], v[28:29]
	v_pk_add_f32 v[10:11], v[10:11], v[28:29] neg_lo:[0,1] neg_hi:[0,1]
	v_pk_mul_f32 v[28:29], v[10:11], s[34:35]
	v_pk_fma_f32 v[10:11], v[10:11], s[26:27], v[28:29] op_sel:[0,0,1] op_sel_hi:[1,0,0] neg_lo:[1,0,0] neg_hi:[1,0,0]
	v_pk_add_f32 v[28:29], v[12:13], v[30:31]
	v_pk_add_f32 v[12:13], v[12:13], v[30:31] neg_lo:[0,1] neg_hi:[0,1]
	v_pk_mul_f32 v[30:31], v[12:13], s[10:11]
	v_pk_fma_f32 v[12:13], v[12:13], s[14:15], v[30:31] op_sel:[0,0,1] op_sel_hi:[1,0,0] neg_lo:[1,0,0] neg_hi:[1,0,0]
	v_pk_add_f32 v[30:31], v[14:15], v[24:25]
	v_pk_add_f32 v[14:15], v[14:15], v[24:25] neg_lo:[0,1] neg_hi:[0,1]
	v_pk_mul_f32 v[24:25], v[14:15], s[18:19]
	v_pk_fma_f32 v[14:15], v[14:15], s[30:31], v[24:25] op_sel:[0,0,1] op_sel_hi:[1,0,0] neg_lo:[1,0,0] neg_hi:[1,0,0]
	v_pk_add_f32 v[24:25], v[86:87], v[22:23]
	v_pk_add_f32 v[22:23], v[86:87], v[22:23] neg_lo:[0,1] neg_hi:[0,1]
	v_pk_add_f32 v[86:87], v[16:17], v[26:27]
	v_pk_add_f32 v[16:17], v[16:17], v[26:27] neg_lo:[0,1] neg_hi:[0,1]
	v_pk_mul_f32 v[26:27], v[16:17], s[10:11]
	v_pk_fma_f32 v[16:17], v[16:17], s[14:15], v[26:27] op_sel:[0,0,1] op_sel_hi:[1,0,0]
	v_pk_add_f32 v[26:27], v[18:19], v[28:29]
	v_pk_add_f32 v[18:19], v[18:19], v[28:29] neg_lo:[0,1] neg_hi:[0,1]
	v_pk_add_f32 v[28:29], v[20:21], v[30:31]
	v_pk_add_f32 v[20:21], v[20:21], v[30:31] neg_lo:[0,1] neg_hi:[0,1]
	v_pk_mul_f32 v[30:31], v[20:21], s[10:11]
	v_pk_fma_f32 v[20:21], v[20:21], s[14:15], v[30:31] op_sel:[0,0,1] op_sel_hi:[1,0,0] neg_lo:[1,0,0] neg_hi:[1,0,0]
	v_pk_add_f32 v[30:31], v[0:1], v[8:9] op_sel:[0,1] op_sel_hi:[1,0] neg_hi:[0,1]
	v_pk_add_f32 v[0:1], v[0:1], v[8:9] op_sel:[0,1] op_sel_hi:[1,0] neg_lo:[0,1]
	v_pk_add_f32 v[8:9], v[2:3], v[10:11]
	v_pk_add_f32 v[2:3], v[2:3], v[10:11] neg_lo:[0,1] neg_hi:[0,1]
	v_pk_mul_f32 v[10:11], v[2:3], s[10:11]
	v_pk_fma_f32 v[2:3], v[2:3], s[14:15], v[10:11] op_sel:[0,0,1] op_sel_hi:[1,0,0]
	v_pk_add_f32 v[10:11], v[4:5], v[12:13]
	v_pk_add_f32 v[4:5], v[4:5], v[12:13] neg_lo:[0,1] neg_hi:[0,1]
	v_pk_add_f32 v[12:13], v[6:7], v[14:15]
	v_pk_add_f32 v[6:7], v[6:7], v[14:15] neg_lo:[0,1] neg_hi:[0,1]
	v_pk_mul_f32 v[14:15], v[6:7], s[10:11]
	v_pk_fma_f32 v[6:7], v[6:7], s[14:15], v[14:15] op_sel:[0,0,1] op_sel_hi:[1,0,0] neg_lo:[1,0,0] neg_hi:[1,0,0]
	v_pk_add_f32 v[14:15], v[24:25], v[26:27]
	v_pk_add_f32 v[24:25], v[24:25], v[26:27] neg_lo:[0,1] neg_hi:[0,1]
	v_pk_add_f32 v[26:27], v[86:87], v[28:29]
	v_pk_add_f32 v[28:29], v[86:87], v[28:29] neg_lo:[0,1] neg_hi:[0,1]
	v_pk_add_f32 v[86:87], v[22:23], v[18:19] op_sel:[0,1] op_sel_hi:[1,0] neg_hi:[0,1]
	v_pk_add_f32 v[18:19], v[22:23], v[18:19] op_sel:[0,1] op_sel_hi:[1,0] neg_lo:[0,1]
	v_pk_add_f32 v[22:23], v[16:17], v[20:21]
	v_pk_add_f32 v[16:17], v[16:17], v[20:21] neg_lo:[0,1] neg_hi:[0,1]
	v_pk_add_f32 v[20:21], v[30:31], v[10:11]
	v_pk_add_f32 v[10:11], v[30:31], v[10:11] neg_lo:[0,1] neg_hi:[0,1]
	v_pk_add_f32 v[30:31], v[8:9], v[12:13]
	v_pk_add_f32 v[8:9], v[8:9], v[12:13] neg_lo:[0,1] neg_hi:[0,1]
	v_pk_add_f32 v[12:13], v[0:1], v[4:5] op_sel:[0,1] op_sel_hi:[1,0] neg_hi:[0,1]
	v_pk_add_f32 v[0:1], v[0:1], v[4:5] op_sel:[0,1] op_sel_hi:[1,0] neg_lo:[0,1]
	v_pk_add_f32 v[4:5], v[2:3], v[6:7]
	v_pk_add_f32 v[2:3], v[2:3], v[6:7] neg_lo:[0,1] neg_hi:[0,1]
	v_pk_mul_f32 v[2:3], v[2:3], s[22:23]
	v_pk_add_f32 v[6:7], v[14:15], v[26:27]
	v_pk_add_f32 v[14:15], v[14:15], v[26:27] neg_lo:[0,1] neg_hi:[0,1]
	v_pk_add_f32 v[26:27], v[24:25], v[28:29] op_sel:[0,1] op_sel_hi:[1,0] neg_hi:[0,1]
	v_pk_add_f32 v[24:25], v[24:25], v[28:29] op_sel:[0,1] op_sel_hi:[1,0] neg_lo:[0,1]
	v_pk_add_f32 v[28:29], v[86:87], v[22:23]
	v_pk_add_f32 v[22:23], v[86:87], v[22:23] neg_lo:[0,1] neg_hi:[0,1]
	v_pk_add_f32 v[86:87], v[18:19], v[16:17] op_sel:[0,1] op_sel_hi:[1,0] neg_hi:[0,1]
	v_pk_add_f32 v[16:17], v[18:19], v[16:17] op_sel:[0,1] op_sel_hi:[1,0] neg_lo:[0,1]
	v_pk_add_f32 v[18:19], v[20:21], v[30:31]
	v_pk_add_f32 v[20:21], v[20:21], v[30:31] neg_lo:[0,1] neg_hi:[0,1]
	v_pk_add_f32 v[30:31], v[10:11], v[8:9] op_sel:[0,1] op_sel_hi:[1,0] neg_hi:[0,1]
	v_pk_add_f32 v[8:9], v[10:11], v[8:9] op_sel:[0,1] op_sel_hi:[1,0] neg_lo:[0,1]
	v_pk_add_f32 v[10:11], v[12:13], v[4:5]
	v_pk_add_f32 v[4:5], v[12:13], v[4:5] neg_lo:[0,1] neg_hi:[0,1]
	v_pk_add_f32 v[12:13], v[0:1], v[2:3] op_sel:[0,1] op_sel_hi:[1,0]
	v_pk_add_f32 v[0:1], v[0:1], v[2:3] op_sel:[0,1] op_sel_hi:[1,0] neg_lo:[0,1] neg_hi:[0,1]
	v_lshlrev_b32_e32 v2, 4, v41
	v_and_or_b32 v2, v2, s7, v98
	v_ashrrev_i32_e32 v3, 4, v2
	v_lshlrev_b32_e32 v3, 3, v3
	v_lshlrev_b32_e32 v2, 3, v2
	v_add3_u32 v2, 0, v3, v2
	v_add_u32_e32 v3, 0x800, v2
	v_mov_b32_e32 v41, v32
	ds_write2_b64 v2, v[6:7], v[18:19] offset1:34
	ds_write2_b64 v3, v[14:15], v[20:21] offset0:16 offset1:50
	ds_write2_b64 v2, v[26:27], v[30:31] offset0:136 offset1:170
	ds_write2_b64 v3, v[24:25], v[8:9] offset0:152 offset1:186
	ds_write2_b64 v2, v[28:29], v[10:11] offset0:68 offset1:102
	ds_write2_b64 v3, v[22:23], v[4:5] offset0:84 offset1:118
	ds_write2_b64 v2, v[86:87], v[12:13] offset0:204 offset1:238
	ds_write2_b64 v3, v[16:17], v[0:1] offset0:220 offset1:254
	s_waitcnt lgkmcnt(0)
	s_barrier
	s_nop 0
	v_and_b32_e32 v98, 0x1ff, v41
	v_cvt_f32_u32_e32 v24, v98
	v_ashrrev_i32_e32 v0, 4, v41
	v_lshlrev_b32_e32 v0, 3, v0
	v_lshlrev_b32_e32 v1, 3, v41
	v_mul_f32_e32 v92, 0x39000000, v24
	v_sin_f32_e32 v24, v92
	v_cos_f32_e32 v92, v92
	v_add3_u32 v25, 0, v0, v1
	ds_read_b64 v[0:1], v25
	ds_read_b64 v[2:3], v25 offset:4352
	ds_read_b64 v[4:5], v25 offset:8704
	ds_read_b64 v[6:7], v25 offset:13056
	ds_read_b64 v[8:9], v25 offset:17408
	ds_read_b64 v[10:11], v25 offset:21760
	ds_read_b64 v[12:13], v25 offset:26112
	ds_read_b64 v[14:15], v25 offset:30464
	v_xor_b32_e32 v93, 0x80000000, v24
	s_waitcnt lgkmcnt(6)
	v_pk_mul_f32 v[94:95], v[2:3], v[24:25] op_sel:[1,0] op_sel_hi:[0,0] neg_hi:[0,1]
	v_pk_fma_f32 v[2:3], v[2:3], v[92:93], v[94:95] op_sel_hi:[1,0,1]
	v_pk_mul_f32 v[94:95], v[24:25], v[92:93] op_sel:[0,1] op_sel_hi:[0,0] neg_hi:[1,0]
	v_pk_fma_f32 v[94:95], v[92:93], v[92:93], v[94:95] op_sel_hi:[0,1,1]
	ds_read_b64 v[16:17], v25 offset:34816
	ds_read_b64 v[18:19], v25 offset:39168
	ds_read_b64 v[20:21], v25 offset:43520
	ds_read_b64 v[22:23], v25 offset:47872
	s_waitcnt lgkmcnt(9)
	v_pk_mul_f32 v[96:97], v[4:5], v[94:95] op_sel:[1,1] op_sel_hi:[0,1] neg_lo:[0,1]
	v_pk_fma_f32 v[4:5], v[4:5], v[94:95], v[96:97] op_sel_hi:[1,0,1]
	v_pk_mul_f32 v[96:97], v[24:25], v[94:95] op_sel:[0,1] op_sel_hi:[0,0] neg_hi:[1,0]
	v_pk_fma_f32 v[94:95], v[92:93], v[94:95], v[96:97] op_sel_hi:[0,1,1]
	ds_read_b64 v[26:27], v25 offset:52224
	ds_read_b64 v[28:29], v25 offset:56576
	ds_read_b64 v[30:31], v25 offset:60928
	ds_read_b64 v[86:87], v25 offset:65280
	s_waitcnt lgkmcnt(12)
	v_pk_mul_f32 v[96:97], v[6:7], v[94:95] op_sel:[1,1] op_sel_hi:[0,1] neg_lo:[0,1]
	v_pk_fma_f32 v[6:7], v[6:7], v[94:95], v[96:97] op_sel_hi:[1,0,1]
	v_pk_mul_f32 v[96:97], v[24:25], v[94:95] op_sel:[0,1] op_sel_hi:[0,0] neg_hi:[1,0]
	v_pk_fma_f32 v[94:95], v[92:93], v[94:95], v[96:97] op_sel_hi:[0,1,1]
	s_waitcnt lgkmcnt(0)
	v_pk_mul_f32 v[96:97], v[8:9], v[94:95] op_sel:[1,1] op_sel_hi:[0,1] neg_lo:[0,1]
	v_pk_fma_f32 v[8:9], v[8:9], v[94:95], v[96:97] op_sel_hi:[1,0,1]
	v_pk_mul_f32 v[96:97], v[24:25], v[94:95] op_sel:[0,1] op_sel_hi:[0,0] neg_hi:[1,0]
	v_pk_fma_f32 v[94:95], v[92:93], v[94:95], v[96:97] op_sel_hi:[0,1,1]
	s_barrier
	v_pk_mul_f32 v[96:97], v[10:11], v[94:95] op_sel:[1,1] op_sel_hi:[0,1] neg_lo:[0,1]
	v_pk_fma_f32 v[10:11], v[10:11], v[94:95], v[96:97] op_sel_hi:[1,0,1]
	v_pk_mul_f32 v[96:97], v[24:25], v[94:95] op_sel:[0,1] op_sel_hi:[0,0] neg_hi:[1,0]
	v_pk_fma_f32 v[94:95], v[92:93], v[94:95], v[96:97] op_sel_hi:[0,1,1]
	v_pk_mul_f32 v[96:97], v[12:13], v[94:95] op_sel:[1,1] op_sel_hi:[0,1] neg_lo:[0,1]
	v_pk_fma_f32 v[12:13], v[12:13], v[94:95], v[96:97] op_sel_hi:[1,0,1]
	v_pk_mul_f32 v[96:97], v[24:25], v[94:95] op_sel:[0,1] op_sel_hi:[0,0] neg_hi:[1,0]
	v_pk_fma_f32 v[94:95], v[92:93], v[94:95], v[96:97] op_sel_hi:[0,1,1]
	v_pk_mul_f32 v[96:97], v[14:15], v[94:95] op_sel:[1,1] op_sel_hi:[0,1] neg_lo:[0,1]
	v_pk_fma_f32 v[14:15], v[14:15], v[94:95], v[96:97] op_sel_hi:[1,0,1]
	v_pk_mul_f32 v[96:97], v[24:25], v[94:95] op_sel:[0,1] op_sel_hi:[0,0] neg_hi:[1,0]
	v_pk_fma_f32 v[94:95], v[92:93], v[94:95], v[96:97] op_sel_hi:[0,1,1]
	v_pk_mul_f32 v[96:97], v[16:17], v[94:95] op_sel:[1,1] op_sel_hi:[0,1] neg_lo:[0,1]
	v_pk_fma_f32 v[16:17], v[16:17], v[94:95], v[96:97] op_sel_hi:[1,0,1]
	v_pk_mul_f32 v[96:97], v[24:25], v[94:95] op_sel:[0,1] op_sel_hi:[0,0] neg_hi:[1,0]
	v_pk_fma_f32 v[94:95], v[92:93], v[94:95], v[96:97] op_sel_hi:[0,1,1]
	v_pk_mul_f32 v[96:97], v[18:19], v[94:95] op_sel:[1,1] op_sel_hi:[0,1] neg_lo:[0,1]
	v_pk_fma_f32 v[18:19], v[18:19], v[94:95], v[96:97] op_sel_hi:[1,0,1]
	v_pk_mul_f32 v[96:97], v[24:25], v[94:95] op_sel:[0,1] op_sel_hi:[0,0] neg_hi:[1,0]
	v_pk_fma_f32 v[94:95], v[92:93], v[94:95], v[96:97] op_sel_hi:[0,1,1]
	v_pk_mul_f32 v[96:97], v[20:21], v[94:95] op_sel:[1,1] op_sel_hi:[0,1] neg_lo:[0,1]
	v_pk_fma_f32 v[20:21], v[20:21], v[94:95], v[96:97] op_sel_hi:[1,0,1]
	v_pk_mul_f32 v[96:97], v[24:25], v[94:95] op_sel:[0,1] op_sel_hi:[0,0] neg_hi:[1,0]
	v_pk_fma_f32 v[94:95], v[92:93], v[94:95], v[96:97] op_sel_hi:[0,1,1]
	v_pk_mul_f32 v[96:97], v[22:23], v[94:95] op_sel:[1,1] op_sel_hi:[0,1] neg_lo:[0,1]
	v_pk_fma_f32 v[22:23], v[22:23], v[94:95], v[96:97] op_sel_hi:[1,0,1]
	v_pk_mul_f32 v[96:97], v[24:25], v[94:95] op_sel:[0,1] op_sel_hi:[0,0] neg_hi:[1,0]
	v_pk_fma_f32 v[94:95], v[92:93], v[94:95], v[96:97] op_sel_hi:[0,1,1]
	v_pk_mul_f32 v[96:97], v[26:27], v[94:95] op_sel:[1,1] op_sel_hi:[0,1] neg_lo:[0,1]
	v_pk_fma_f32 v[26:27], v[26:27], v[94:95], v[96:97] op_sel_hi:[1,0,1]
	v_pk_mul_f32 v[96:97], v[24:25], v[94:95] op_sel:[0,1] op_sel_hi:[0,0] neg_hi:[1,0]
	v_pk_fma_f32 v[94:95], v[92:93], v[94:95], v[96:97] op_sel_hi:[0,1,1]
	v_pk_mul_f32 v[96:97], v[28:29], v[94:95] op_sel:[1,1] op_sel_hi:[0,1] neg_lo:[0,1]
	v_pk_fma_f32 v[28:29], v[28:29], v[94:95], v[96:97] op_sel_hi:[1,0,1]
	v_pk_mul_f32 v[96:97], v[24:25], v[94:95] op_sel:[0,1] op_sel_hi:[0,0] neg_hi:[1,0]
	v_pk_fma_f32 v[94:95], v[92:93], v[94:95], v[96:97] op_sel_hi:[0,1,1]
	v_pk_mul_f32 v[24:25], v[24:25], v[94:95] op_sel:[0,1] op_sel_hi:[0,0] neg_hi:[1,0]
	v_pk_fma_f32 v[24:25], v[92:93], v[94:95], v[24:25] op_sel_hi:[0,1,1]
	v_pk_mul_f32 v[92:93], v[86:87], v[24:25] op_sel:[1,1] op_sel_hi:[0,1] neg_lo:[0,1]
	v_pk_fma_f32 v[24:25], v[86:87], v[24:25], v[92:93] op_sel_hi:[1,0,1]
	v_pk_add_f32 v[86:87], v[0:1], v[16:17]
	v_pk_add_f32 v[0:1], v[0:1], v[16:17] neg_lo:[0,1] neg_hi:[0,1]
	v_pk_add_f32 v[16:17], v[2:3], v[18:19]
	v_pk_add_f32 v[2:3], v[2:3], v[18:19] neg_lo:[0,1] neg_hi:[0,1]
	v_pk_mul_f32 v[96:97], v[30:31], v[94:95] op_sel:[1,1] op_sel_hi:[0,1] neg_lo:[0,1]
	v_pk_mul_f32 v[18:19], v[2:3], s[18:19]
	v_pk_fma_f32 v[30:31], v[30:31], v[94:95], v[96:97] op_sel_hi:[1,0,1]
	v_pk_fma_f32 v[2:3], v[2:3], s[30:31], v[18:19] op_sel:[0,0,1] op_sel_hi:[1,0,0]
	v_pk_add_f32 v[18:19], v[4:5], v[20:21]
	v_pk_add_f32 v[4:5], v[4:5], v[20:21] neg_lo:[0,1] neg_hi:[0,1]
	v_pk_mul_f32 v[20:21], v[4:5], s[10:11]
	v_pk_fma_f32 v[4:5], v[4:5], s[14:15], v[20:21] op_sel:[0,0,1] op_sel_hi:[1,0,0]
	v_pk_add_f32 v[20:21], v[6:7], v[22:23]
	v_pk_add_f32 v[6:7], v[6:7], v[22:23] neg_lo:[0,1] neg_hi:[0,1]
	v_pk_mul_f32 v[22:23], v[6:7], s[34:35]
	v_pk_fma_f32 v[6:7], v[6:7], s[26:27], v[22:23] op_sel:[0,0,1] op_sel_hi:[1,0,0]
	v_pk_add_f32 v[22:23], v[8:9], v[26:27]
	v_pk_add_f32 v[8:9], v[8:9], v[26:27] neg_lo:[0,1] neg_hi:[0,1]
	v_pk_add_f32 v[26:27], v[10:11], v[28:29]
	v_pk_add_f32 v[10:11], v[10:11], v[28:29] neg_lo:[0,1] neg_hi:[0,1]
	v_pk_mul_f32 v[28:29], v[10:11], s[34:35]
	v_pk_fma_f32 v[10:11], v[10:11], s[26:27], v[28:29] op_sel:[0,0,1] op_sel_hi:[1,0,0] neg_lo:[1,0,0] neg_hi:[1,0,0]
	v_pk_add_f32 v[28:29], v[12:13], v[30:31]
	v_pk_add_f32 v[12:13], v[12:13], v[30:31] neg_lo:[0,1] neg_hi:[0,1]
	v_pk_mul_f32 v[30:31], v[12:13], s[10:11]
	v_pk_fma_f32 v[12:13], v[12:13], s[14:15], v[30:31] op_sel:[0,0,1] op_sel_hi:[1,0,0] neg_lo:[1,0,0] neg_hi:[1,0,0]
	v_pk_add_f32 v[30:31], v[14:15], v[24:25]
	v_pk_add_f32 v[14:15], v[14:15], v[24:25] neg_lo:[0,1] neg_hi:[0,1]
	v_pk_mul_f32 v[24:25], v[14:15], s[18:19]
	v_pk_fma_f32 v[14:15], v[14:15], s[30:31], v[24:25] op_sel:[0,0,1] op_sel_hi:[1,0,0] neg_lo:[1,0,0] neg_hi:[1,0,0]
	v_pk_add_f32 v[24:25], v[86:87], v[22:23]
	v_pk_add_f32 v[22:23], v[86:87], v[22:23] neg_lo:[0,1] neg_hi:[0,1]
	v_pk_add_f32 v[86:87], v[16:17], v[26:27]
	v_pk_add_f32 v[16:17], v[16:17], v[26:27] neg_lo:[0,1] neg_hi:[0,1]
	v_pk_mul_f32 v[26:27], v[16:17], s[10:11]
	v_pk_fma_f32 v[16:17], v[16:17], s[14:15], v[26:27] op_sel:[0,0,1] op_sel_hi:[1,0,0]
	v_pk_add_f32 v[26:27], v[18:19], v[28:29]
	v_pk_add_f32 v[18:19], v[18:19], v[28:29] neg_lo:[0,1] neg_hi:[0,1]
	v_pk_add_f32 v[28:29], v[20:21], v[30:31]
	v_pk_add_f32 v[20:21], v[20:21], v[30:31] neg_lo:[0,1] neg_hi:[0,1]
	v_pk_mul_f32 v[30:31], v[20:21], s[10:11]
	v_pk_fma_f32 v[20:21], v[20:21], s[14:15], v[30:31] op_sel:[0,0,1] op_sel_hi:[1,0,0] neg_lo:[1,0,0] neg_hi:[1,0,0]
	v_pk_add_f32 v[30:31], v[0:1], v[8:9] op_sel:[0,1] op_sel_hi:[1,0] neg_hi:[0,1]
	v_pk_add_f32 v[0:1], v[0:1], v[8:9] op_sel:[0,1] op_sel_hi:[1,0] neg_lo:[0,1]
	v_pk_add_f32 v[8:9], v[2:3], v[10:11]
	v_pk_add_f32 v[2:3], v[2:3], v[10:11] neg_lo:[0,1] neg_hi:[0,1]
	v_pk_mul_f32 v[10:11], v[2:3], s[10:11]
	v_pk_fma_f32 v[2:3], v[2:3], s[14:15], v[10:11] op_sel:[0,0,1] op_sel_hi:[1,0,0]
	v_pk_add_f32 v[10:11], v[4:5], v[12:13]
	v_pk_add_f32 v[4:5], v[4:5], v[12:13] neg_lo:[0,1] neg_hi:[0,1]
	v_pk_add_f32 v[12:13], v[6:7], v[14:15]
	v_pk_add_f32 v[6:7], v[6:7], v[14:15] neg_lo:[0,1] neg_hi:[0,1]
	v_pk_mul_f32 v[14:15], v[6:7], s[10:11]
	v_pk_fma_f32 v[6:7], v[6:7], s[14:15], v[14:15] op_sel:[0,0,1] op_sel_hi:[1,0,0] neg_lo:[1,0,0] neg_hi:[1,0,0]
	v_pk_add_f32 v[14:15], v[24:25], v[26:27]
	v_pk_add_f32 v[24:25], v[24:25], v[26:27] neg_lo:[0,1] neg_hi:[0,1]
	v_pk_add_f32 v[26:27], v[86:87], v[28:29]
	v_pk_add_f32 v[28:29], v[86:87], v[28:29] neg_lo:[0,1] neg_hi:[0,1]
	v_pk_add_f32 v[86:87], v[22:23], v[18:19] op_sel:[0,1] op_sel_hi:[1,0] neg_hi:[0,1]
	v_pk_add_f32 v[18:19], v[22:23], v[18:19] op_sel:[0,1] op_sel_hi:[1,0] neg_lo:[0,1]
	v_pk_add_f32 v[22:23], v[16:17], v[20:21]
	v_pk_add_f32 v[16:17], v[16:17], v[20:21] neg_lo:[0,1] neg_hi:[0,1]
	v_pk_add_f32 v[20:21], v[30:31], v[10:11]
	v_pk_add_f32 v[10:11], v[30:31], v[10:11] neg_lo:[0,1] neg_hi:[0,1]
	v_pk_add_f32 v[30:31], v[8:9], v[12:13]
	v_pk_add_f32 v[8:9], v[8:9], v[12:13] neg_lo:[0,1] neg_hi:[0,1]
	v_pk_add_f32 v[12:13], v[0:1], v[4:5] op_sel:[0,1] op_sel_hi:[1,0] neg_hi:[0,1]
	v_pk_add_f32 v[0:1], v[0:1], v[4:5] op_sel:[0,1] op_sel_hi:[1,0] neg_lo:[0,1]
	v_pk_add_f32 v[4:5], v[2:3], v[6:7]
	v_pk_add_f32 v[2:3], v[2:3], v[6:7] neg_lo:[0,1] neg_hi:[0,1]
	v_pk_mul_f32 v[2:3], v[2:3], s[22:23]
	v_pk_add_f32 v[6:7], v[14:15], v[26:27]
	v_pk_add_f32 v[14:15], v[14:15], v[26:27] neg_lo:[0,1] neg_hi:[0,1]
	v_pk_add_f32 v[26:27], v[24:25], v[28:29] op_sel:[0,1] op_sel_hi:[1,0] neg_hi:[0,1]
	v_pk_add_f32 v[24:25], v[24:25], v[28:29] op_sel:[0,1] op_sel_hi:[1,0] neg_lo:[0,1]
	v_pk_add_f32 v[28:29], v[86:87], v[22:23]
	v_pk_add_f32 v[22:23], v[86:87], v[22:23] neg_lo:[0,1] neg_hi:[0,1]
	v_pk_add_f32 v[86:87], v[18:19], v[16:17] op_sel:[0,1] op_sel_hi:[1,0] neg_hi:[0,1]
	v_pk_add_f32 v[16:17], v[18:19], v[16:17] op_sel:[0,1] op_sel_hi:[1,0] neg_lo:[0,1]
	v_pk_add_f32 v[18:19], v[20:21], v[30:31]
	v_pk_add_f32 v[20:21], v[20:21], v[30:31] neg_lo:[0,1] neg_hi:[0,1]
	v_pk_add_f32 v[30:31], v[10:11], v[8:9] op_sel:[0,1] op_sel_hi:[1,0] neg_hi:[0,1]
	v_pk_add_f32 v[8:9], v[10:11], v[8:9] op_sel:[0,1] op_sel_hi:[1,0] neg_lo:[0,1]
	v_pk_add_f32 v[10:11], v[12:13], v[4:5]
	v_pk_add_f32 v[4:5], v[12:13], v[4:5] neg_lo:[0,1] neg_hi:[0,1]
	v_pk_add_f32 v[12:13], v[0:1], v[2:3] op_sel:[0,1] op_sel_hi:[1,0]
	v_pk_add_f32 v[0:1], v[0:1], v[2:3] op_sel:[0,1] op_sel_hi:[1,0] neg_lo:[0,1] neg_hi:[0,1]
	v_lshlrev_b32_e32 v2, 4, v41
	v_and_or_b32 v2, v2, s15, v98
	v_ashrrev_i32_e32 v3, 4, v2
	v_lshlrev_b32_e32 v3, 3, v3
	v_lshlrev_b32_e32 v2, 3, v2
	v_add3_u32 v2, 0, v3, v2
	ds_write_b64 v2, v[6:7]
	ds_write_b64 v2, v[14:15] offset:34816
	ds_write_b64 v2, v[26:27] offset:17408
	ds_write_b64 v2, v[24:25] offset:52224
	ds_write_b64 v2, v[28:29] offset:8704
	ds_write_b64 v2, v[22:23] offset:43520
	ds_write_b64 v2, v[86:87] offset:26112
	ds_write_b64 v2, v[16:17] offset:60928
	ds_write_b64 v2, v[18:19] offset:4352
	ds_write_b64 v2, v[20:21] offset:39168
	ds_write_b64 v2, v[30:31] offset:21760
	ds_write_b64 v2, v[8:9] offset:56576
	ds_write_b64 v2, v[10:11] offset:13056
	ds_write_b64 v2, v[4:5] offset:47872
	ds_write_b64 v2, v[12:13] offset:30464
	ds_write_b64 v2, v[0:1] offset:65280
	v_mov_b32_e32 v0, v154
	v_mov_b32_e32 v1, v156
	v_mov_b32_e32 v2, v155
	v_mov_b32_e32 v3, v122
	s_waitcnt lgkmcnt(0)
	s_barrier
.LBB0_618:
	v_or_b32_e32 v4, s4, v32
	v_cmp_ne_u32_e32 vcc, 0, v4
	v_add_u32_e32 v13, 0, v2
	v_add_u32_e32 v4, 0x11000, v13
	v_cndmask_b32_e32 v6, 0, v0, vcc
	v_lshl_add_u32 v6, v6, 3, 0
	v_add_u32_e32 v6, 0x11000, v6
	ds_read_b64 v[4:5], v4
	ds_read_b64 v[6:7], v6
	v_add_u32_e32 v12, 0, v3
	ds_read_b64 v[8:9], v12
	s_add_i32 s4, s4, 2
	v_add_u32_e32 v3, 0x2200, v3
	s_waitcnt lgkmcnt(1)
	v_sub_f32_e32 v5, v5, v7
	v_add_f32_e32 v4, v4, v6
	v_mul_f32_e32 v6, 0.5, v5
	v_mul_f32_e32 v4, 0.5, v4
	s_waitcnt lgkmcnt(0)
	v_pk_mul_f32 v[6:7], v[8:9], v[6:7] op_sel:[1,0] op_sel_hi:[0,0]
	v_pk_fma_f32 v[10:11], v[8:9], v[4:5], v[6:7] neg_lo:[0,0,1] neg_hi:[0,0,1]
	v_pk_fma_f32 v[4:5], v[8:9], v[4:5], v[6:7] op_sel_hi:[1,0,1]
	v_add_u32_e32 v6, 0, v1
	v_mov_b32_e32 v11, v5
	v_pk_mul_f32 v[4:5], v[10:11], s[24:25]
	ds_write_b64 v12, v[4:5]
	v_add_u32_e32 v4, 0x12100, v13
	v_add_u32_e32 v6, 0x1ff00, v6
	ds_read_b64 v[4:5], v4
	ds_read_b64 v[6:7], v6
	ds_read_b64 v[8:9], v12 offset:4352
	v_add_u32_e32 v2, 0x2200, v2
	v_add_u32_e32 v1, 0xffffde00, v1
	v_add_u32_e32 v0, 0xfffffbc0, v0
	s_waitcnt lgkmcnt(1)
	v_sub_f32_e32 v5, v5, v7
	v_add_f32_e32 v4, v4, v6
	v_mul_f32_e32 v6, 0.5, v5
	v_mul_f32_e32 v4, 0.5, v4
	s_waitcnt lgkmcnt(0)
	v_pk_mul_f32 v[6:7], v[8:9], v[6:7] op_sel:[1,0] op_sel_hi:[0,0]
	v_pk_fma_f32 v[10:11], v[8:9], v[4:5], v[6:7] neg_lo:[0,0,1] neg_hi:[0,0,1]
	v_pk_fma_f32 v[4:5], v[8:9], v[4:5], v[6:7] op_sel_hi:[1,0,1]
	s_cmp_lg_u32 s4, 16
	v_mov_b32_e32 v11, v5
	v_pk_mul_f32 v[4:5], v[10:11], s[24:25]
	ds_write_b64 v12, v[4:5] offset:4352
	s_cbranch_scc1 .LBB0_618
	s_waitcnt lgkmcnt(0)
	s_barrier
	s_and_saveexec_b64 s[28:29], s[40:41]
	s_cbranch_execz .LBB0_621
	ds_read_b64 v[0:1], v153
	ds_read_b64 v[2:3], v153 offset:2176
	ds_read_b64 v[4:5], v153 offset:4352
	ds_read_b64 v[6:7], v153 offset:6528
	ds_read_b64 v[8:9], v153 offset:8704
	ds_read_b64 v[10:11], v153 offset:10880
	ds_read_b64 v[12:13], v153 offset:13056
	ds_read_b64 v[14:15], v153 offset:15232
	ds_read_b64 v[16:17], v153 offset:17408
	ds_read_b64 v[18:19], v153 offset:19584
	ds_read_b64 v[20:21], v153 offset:21760
	ds_read_b64 v[22:23], v153 offset:23936
	ds_read_b64 v[24:25], v153 offset:26112
	ds_read_b64 v[26:27], v153 offset:28288
	ds_read_b64 v[28:29], v153 offset:30464
	ds_read_b64 v[30:31], v153 offset:32640
	ds_read_b64 v[86:87], v153 offset:34816
	ds_read_b64 v[92:93], v153 offset:41344
	ds_read_b64 v[94:95], v153 offset:43520
	ds_read_b64 v[96:97], v153 offset:45696
	ds_read_b64 v[98:99], v153 offset:47872
	ds_read_b64 v[100:101], v153 offset:50048
	ds_read_b64 v[102:103], v153 offset:52224
	ds_read_b64 v[104:105], v153 offset:54400
	ds_read_b64 v[106:107], v153 offset:56576
	ds_read_b64 v[108:109], v153 offset:58752
	ds_read_b64 v[110:111], v153 offset:60928
	ds_read_b64 v[112:113], v153 offset:63104
	ds_read_b64 v[114:115], v153 offset:65280
	ds_read_b64 v[116:117], v153 offset:36992
	ds_read_b64 v[118:119], v153 offset:39168
	ds_read_b64 v[120:121], v33
	s_waitcnt lgkmcnt(14)
	v_pk_add_f32 v[124:125], v[0:1], v[86:87]
	v_pk_add_f32 v[0:1], v[0:1], v[86:87] neg_lo:[0,1] neg_hi:[0,1]
	s_waitcnt lgkmcnt(2)
	v_pk_add_f32 v[86:87], v[2:3], v[116:117]
	v_pk_add_f32 v[2:3], v[2:3], v[116:117] neg_lo:[0,1] neg_hi:[0,1]
	s_mov_b32 s11, s14
	v_pk_mul_f32 v[116:117], v[2:3], s[16:17]
	s_mov_b32 s13, s86
	v_pk_fma_f32 v[2:3], v[2:3], s[6:7], v[116:117] op_sel:[0,0,1] op_sel_hi:[1,0,0]
	s_waitcnt lgkmcnt(1)
	v_pk_add_f32 v[116:117], v[4:5], v[118:119]
	v_pk_add_f32 v[4:5], v[4:5], v[118:119] neg_lo:[0,1] neg_hi:[0,1]
	s_mov_b32 s4, s21
	v_pk_mul_f32 v[118:119], v[4:5], s[18:19]
	s_mov_b32 s35, s30
	v_pk_fma_f32 v[4:5], v[4:5], s[30:31], v[118:119] op_sel:[0,0,1] op_sel_hi:[1,0,0]
	v_pk_add_f32 v[118:119], v[6:7], v[92:93]
	v_pk_add_f32 v[6:7], v[6:7], v[92:93] neg_lo:[0,1] neg_hi:[0,1]
	s_mov_b32 s8, s19
	v_pk_mul_f32 v[92:93], v[6:7], s[20:21]
	s_mov_b32 s77, s6
	v_pk_fma_f32 v[6:7], v[6:7], s[86:87], v[92:93] op_sel:[0,0,1] op_sel_hi:[1,0,0]
	v_pk_add_f32 v[92:93], v[8:9], v[94:95]
	v_pk_add_f32 v[8:9], v[8:9], v[94:95] neg_lo:[0,1] neg_hi:[0,1]
	s_mov_b32 s26, s17
	v_pk_mul_f32 v[94:95], v[8:9], s[10:11]
	s_nop 0
	v_pk_fma_f32 v[8:9], v[8:9], s[14:15], v[94:95] op_sel:[0,0,1] op_sel_hi:[1,0,0]
	v_pk_add_f32 v[94:95], v[10:11], v[96:97]
	v_pk_add_f32 v[10:11], v[10:11], v[96:97] neg_lo:[0,1] neg_hi:[0,1]
	v_pk_mul_f32 v[96:97], v[10:11], s[12:13]
	v_pk_fma_f32 v[10:11], v[10:11], s[4:5], v[96:97] op_sel:[0,0,1] op_sel_hi:[1,0,0]
	v_pk_add_f32 v[96:97], v[12:13], v[98:99]
	v_pk_add_f32 v[12:13], v[12:13], v[98:99] neg_lo:[0,1] neg_hi:[0,1]
	v_pk_mul_f32 v[98:99], v[12:13], s[34:35]
	v_pk_fma_f32 v[12:13], v[12:13], s[8:9], v[98:99] op_sel:[0,0,1] op_sel_hi:[1,0,0]
	v_pk_add_f32 v[98:99], v[14:15], v[100:101]
	v_pk_add_f32 v[14:15], v[14:15], v[100:101] neg_lo:[0,1] neg_hi:[0,1]
	v_pk_mul_f32 v[100:101], v[14:15], s[76:77]
	v_pk_fma_f32 v[14:15], v[14:15], s[26:27], v[100:101] op_sel:[0,0,1] op_sel_hi:[1,0,0]
	v_pk_add_f32 v[100:101], v[16:17], v[102:103]
	v_pk_add_f32 v[16:17], v[16:17], v[102:103] neg_lo:[0,1] neg_hi:[0,1]
	v_pk_add_f32 v[102:103], v[18:19], v[104:105]
	v_pk_add_f32 v[18:19], v[18:19], v[104:105] neg_lo:[0,1] neg_hi:[0,1]
	v_pk_mul_f32 v[104:105], v[18:19], s[76:77]
	v_pk_fma_f32 v[18:19], v[18:19], s[26:27], v[104:105] op_sel:[0,0,1] op_sel_hi:[1,0,0] neg_lo:[1,0,0] neg_hi:[1,0,0]
	v_pk_add_f32 v[104:105], v[20:21], v[106:107]
	v_pk_add_f32 v[20:21], v[20:21], v[106:107] neg_lo:[0,1] neg_hi:[0,1]
	v_pk_mul_f32 v[106:107], v[20:21], s[34:35]
	v_pk_fma_f32 v[20:21], v[20:21], s[8:9], v[106:107] op_sel:[0,0,1] op_sel_hi:[1,0,0] neg_lo:[1,0,0] neg_hi:[1,0,0]
	v_pk_add_f32 v[106:107], v[22:23], v[108:109]
	v_pk_add_f32 v[22:23], v[22:23], v[108:109] neg_lo:[0,1] neg_hi:[0,1]
	v_pk_mul_f32 v[108:109], v[22:23], s[12:13]
	v_pk_fma_f32 v[22:23], v[22:23], s[4:5], v[108:109] op_sel:[0,0,1] op_sel_hi:[1,0,0] neg_lo:[1,0,0] neg_hi:[1,0,0]
	v_pk_add_f32 v[108:109], v[24:25], v[110:111]
	v_pk_add_f32 v[24:25], v[24:25], v[110:111] neg_lo:[0,1] neg_hi:[0,1]
	v_pk_mul_f32 v[110:111], v[24:25], s[10:11]
	v_pk_fma_f32 v[24:25], v[24:25], s[14:15], v[110:111] op_sel:[0,0,1] op_sel_hi:[1,0,0] neg_lo:[1,0,0] neg_hi:[1,0,0]
	v_pk_add_f32 v[110:111], v[26:27], v[112:113]
	v_pk_add_f32 v[26:27], v[26:27], v[112:113] neg_lo:[0,1] neg_hi:[0,1]
	v_pk_mul_f32 v[112:113], v[26:27], s[20:21]
	v_pk_fma_f32 v[26:27], v[26:27], s[86:87], v[112:113] op_sel:[0,0,1] op_sel_hi:[1,0,0] neg_lo:[1,0,0] neg_hi:[1,0,0]
	v_pk_add_f32 v[112:113], v[28:29], v[114:115]
	v_pk_add_f32 v[28:29], v[28:29], v[114:115] neg_lo:[0,1] neg_hi:[0,1]
	v_pk_mul_f32 v[114:115], v[28:29], s[18:19]
	v_pk_fma_f32 v[28:29], v[28:29], s[30:31], v[114:115] op_sel:[0,0,1] op_sel_hi:[1,0,0] neg_lo:[1,0,0] neg_hi:[1,0,0]
	s_waitcnt lgkmcnt(0)
	v_pk_add_f32 v[114:115], v[30:31], v[120:121]
	v_pk_add_f32 v[30:31], v[30:31], v[120:121] neg_lo:[0,1] neg_hi:[0,1]
	s_nop 0
	v_pk_mul_f32 v[120:121], v[30:31], s[16:17]
	v_pk_fma_f32 v[30:31], v[30:31], s[6:7], v[120:121] op_sel:[0,0,1] op_sel_hi:[1,0,0] neg_lo:[1,0,0] neg_hi:[1,0,0]
	v_pk_add_f32 v[120:121], v[124:125], v[100:101]
	v_pk_add_f32 v[100:101], v[124:125], v[100:101] neg_lo:[0,1] neg_hi:[0,1]
	v_pk_add_f32 v[124:125], v[86:87], v[102:103]
	v_pk_add_f32 v[86:87], v[86:87], v[102:103] neg_lo:[0,1] neg_hi:[0,1]
	v_pk_mul_f32 v[102:103], v[86:87], s[18:19]
	v_pk_fma_f32 v[86:87], v[86:87], s[30:31], v[102:103] op_sel:[0,0,1] op_sel_hi:[1,0,0]
	v_pk_add_f32 v[102:103], v[116:117], v[104:105]
	v_pk_add_f32 v[104:105], v[116:117], v[104:105] neg_lo:[0,1] neg_hi:[0,1]
	v_pk_mul_f32 v[116:117], v[104:105], s[10:11]
	v_pk_fma_f32 v[104:105], v[104:105], s[14:15], v[116:117] op_sel:[0,0,1] op_sel_hi:[1,0,0]
	v_pk_add_f32 v[116:117], v[118:119], v[106:107]
	v_pk_add_f32 v[106:107], v[118:119], v[106:107] neg_lo:[0,1] neg_hi:[0,1]
	v_pk_mul_f32 v[118:119], v[106:107], s[34:35]
	v_pk_fma_f32 v[106:107], v[106:107], s[8:9], v[118:119] op_sel:[0,0,1] op_sel_hi:[1,0,0]
	v_pk_add_f32 v[118:119], v[92:93], v[108:109]
	v_pk_add_f32 v[92:93], v[92:93], v[108:109] neg_lo:[0,1] neg_hi:[0,1]
	v_pk_add_f32 v[108:109], v[94:95], v[110:111]
	v_pk_add_f32 v[94:95], v[94:95], v[110:111] neg_lo:[0,1] neg_hi:[0,1]
	v_pk_mul_f32 v[110:111], v[94:95], s[34:35]
	v_pk_fma_f32 v[94:95], v[94:95], s[8:9], v[110:111] op_sel:[0,0,1] op_sel_hi:[1,0,0] neg_lo:[1,0,0] neg_hi:[1,0,0]
	v_pk_add_f32 v[110:111], v[96:97], v[112:113]
	v_pk_add_f32 v[96:97], v[96:97], v[112:113] neg_lo:[0,1] neg_hi:[0,1]
	v_pk_mul_f32 v[112:113], v[96:97], s[10:11]
	v_pk_fma_f32 v[96:97], v[96:97], s[14:15], v[112:113] op_sel:[0,0,1] op_sel_hi:[1,0,0] neg_lo:[1,0,0] neg_hi:[1,0,0]
	v_pk_add_f32 v[112:113], v[98:99], v[114:115]
	v_pk_add_f32 v[98:99], v[98:99], v[114:115] neg_lo:[0,1] neg_hi:[0,1]
	v_pk_mul_f32 v[114:115], v[98:99], s[18:19]
	v_pk_fma_f32 v[98:99], v[98:99], s[30:31], v[114:115] op_sel:[0,0,1] op_sel_hi:[1,0,0] neg_lo:[1,0,0] neg_hi:[1,0,0]
	v_pk_add_f32 v[114:115], v[0:1], v[16:17] op_sel:[0,1] op_sel_hi:[1,0] neg_hi:[0,1]
	v_pk_add_f32 v[0:1], v[0:1], v[16:17] op_sel:[0,1] op_sel_hi:[1,0] neg_lo:[0,1]
	v_pk_add_f32 v[16:17], v[2:3], v[18:19]
	v_pk_add_f32 v[2:3], v[2:3], v[18:19] neg_lo:[0,1] neg_hi:[0,1]
	v_pk_mul_f32 v[18:19], v[2:3], s[18:19]
	v_pk_fma_f32 v[2:3], v[2:3], s[30:31], v[18:19] op_sel:[0,0,1] op_sel_hi:[1,0,0]
	v_pk_add_f32 v[18:19], v[4:5], v[20:21]
	v_pk_add_f32 v[4:5], v[4:5], v[20:21] neg_lo:[0,1] neg_hi:[0,1]
	v_pk_mul_f32 v[20:21], v[4:5], s[10:11]
	v_pk_fma_f32 v[4:5], v[4:5], s[14:15], v[20:21] op_sel:[0,0,1] op_sel_hi:[1,0,0]
	v_pk_add_f32 v[20:21], v[6:7], v[22:23]
	v_pk_add_f32 v[6:7], v[6:7], v[22:23] neg_lo:[0,1] neg_hi:[0,1]
	v_pk_mul_f32 v[22:23], v[6:7], s[34:35]
	v_pk_fma_f32 v[6:7], v[6:7], s[8:9], v[22:23] op_sel:[0,0,1] op_sel_hi:[1,0,0]
	v_pk_add_f32 v[22:23], v[8:9], v[24:25]
	v_pk_add_f32 v[8:9], v[8:9], v[24:25] neg_lo:[0,1] neg_hi:[0,1]
	v_pk_add_f32 v[24:25], v[10:11], v[26:27]
	v_pk_add_f32 v[10:11], v[10:11], v[26:27] neg_lo:[0,1] neg_hi:[0,1]
	v_pk_mul_f32 v[26:27], v[10:11], s[34:35]
	v_pk_fma_f32 v[10:11], v[10:11], s[8:9], v[26:27] op_sel:[0,0,1] op_sel_hi:[1,0,0] neg_lo:[1,0,0] neg_hi:[1,0,0]
	v_pk_add_f32 v[26:27], v[12:13], v[28:29]
	v_pk_add_f32 v[12:13], v[12:13], v[28:29] neg_lo:[0,1] neg_hi:[0,1]
	v_pk_mul_f32 v[28:29], v[12:13], s[10:11]
	v_pk_fma_f32 v[12:13], v[12:13], s[14:15], v[28:29] op_sel:[0,0,1] op_sel_hi:[1,0,0] neg_lo:[1,0,0] neg_hi:[1,0,0]
	v_pk_add_f32 v[28:29], v[14:15], v[30:31]
	v_pk_add_f32 v[14:15], v[14:15], v[30:31] neg_lo:[0,1] neg_hi:[0,1]
	v_pk_mul_f32 v[30:31], v[14:15], s[18:19]
	v_pk_fma_f32 v[14:15], v[14:15], s[30:31], v[30:31] op_sel:[0,0,1] op_sel_hi:[1,0,0] neg_lo:[1,0,0] neg_hi:[1,0,0]
	v_pk_add_f32 v[30:31], v[120:121], v[118:119]
	v_pk_add_f32 v[118:119], v[120:121], v[118:119] neg_lo:[0,1] neg_hi:[0,1]
	v_pk_add_f32 v[120:121], v[124:125], v[108:109]
	v_pk_add_f32 v[108:109], v[124:125], v[108:109] neg_lo:[0,1] neg_hi:[0,1]
	v_pk_mul_f32 v[124:125], v[108:109], s[10:11]
	v_pk_fma_f32 v[108:109], v[108:109], s[14:15], v[124:125] op_sel:[0,0,1] op_sel_hi:[1,0,0]
	v_pk_add_f32 v[124:125], v[102:103], v[110:111]
	v_pk_add_f32 v[102:103], v[102:103], v[110:111] neg_lo:[0,1] neg_hi:[0,1]
	v_pk_add_f32 v[110:111], v[116:117], v[112:113]
	v_pk_add_f32 v[112:113], v[116:117], v[112:113] neg_lo:[0,1] neg_hi:[0,1]
	v_pk_mul_f32 v[116:117], v[112:113], s[10:11]
	v_pk_fma_f32 v[112:113], v[112:113], s[14:15], v[116:117] op_sel:[0,0,1] op_sel_hi:[1,0,0] neg_lo:[1,0,0] neg_hi:[1,0,0]
	v_pk_add_f32 v[116:117], v[100:101], v[92:93] op_sel:[0,1] op_sel_hi:[1,0] neg_hi:[0,1]
	v_pk_add_f32 v[92:93], v[100:101], v[92:93] op_sel:[0,1] op_sel_hi:[1,0] neg_lo:[0,1]
	v_pk_add_f32 v[100:101], v[86:87], v[94:95]
	v_pk_add_f32 v[86:87], v[86:87], v[94:95] neg_lo:[0,1] neg_hi:[0,1]
	v_pk_add_f32 v[126:127], v[108:109], v[112:113]
	v_pk_mul_f32 v[94:95], v[86:87], s[10:11]
	v_pk_fma_f32 v[86:87], v[86:87], s[14:15], v[94:95] op_sel:[0,0,1] op_sel_hi:[1,0,0]
	v_pk_add_f32 v[94:95], v[104:105], v[96:97]
	v_pk_add_f32 v[96:97], v[104:105], v[96:97] neg_lo:[0,1] neg_hi:[0,1]
	v_pk_add_f32 v[104:105], v[106:107], v[98:99]
	v_pk_add_f32 v[98:99], v[106:107], v[98:99] neg_lo:[0,1] neg_hi:[0,1]
	v_pk_mul_f32 v[106:107], v[98:99], s[10:11]
	v_pk_add_f32 v[130:131], v[92:93], v[96:97] op_sel:[0,1] op_sel_hi:[1,0] neg_hi:[0,1]
	v_pk_fma_f32 v[98:99], v[98:99], s[14:15], v[106:107] op_sel:[0,0,1] op_sel_hi:[1,0,0] neg_lo:[1,0,0] neg_hi:[1,0,0]
	v_pk_add_f32 v[106:107], v[114:115], v[22:23]
	v_pk_add_f32 v[22:23], v[114:115], v[22:23] neg_lo:[0,1] neg_hi:[0,1]
	v_pk_add_f32 v[114:115], v[16:17], v[24:25]
	v_pk_add_f32 v[16:17], v[16:17], v[24:25] neg_lo:[0,1] neg_hi:[0,1]
	v_pk_add_f32 v[132:133], v[92:93], v[96:97] op_sel:[0,1] op_sel_hi:[1,0] neg_lo:[0,1]
	v_pk_mul_f32 v[24:25], v[16:17], s[10:11]
	v_pk_add_f32 v[92:93], v[86:87], v[98:99]
	v_pk_fma_f32 v[16:17], v[16:17], s[14:15], v[24:25] op_sel:[0,0,1] op_sel_hi:[1,0,0]
	v_pk_add_f32 v[24:25], v[18:19], v[26:27]
	v_pk_add_f32 v[18:19], v[18:19], v[26:27] neg_lo:[0,1] neg_hi:[0,1]
	v_pk_add_f32 v[26:27], v[20:21], v[28:29]
	v_pk_add_f32 v[20:21], v[20:21], v[28:29] neg_lo:[0,1] neg_hi:[0,1]
	v_pk_mul_f32 v[28:29], v[20:21], s[10:11]
	v_pk_add_f32 v[86:87], v[86:87], v[98:99] neg_lo:[0,1] neg_hi:[0,1]
	v_pk_fma_f32 v[20:21], v[20:21], s[14:15], v[28:29] op_sel:[0,0,1] op_sel_hi:[1,0,0] neg_lo:[1,0,0] neg_hi:[1,0,0]
	v_pk_add_f32 v[28:29], v[0:1], v[8:9] op_sel:[0,1] op_sel_hi:[1,0] neg_hi:[0,1]
	v_pk_add_f32 v[0:1], v[0:1], v[8:9] op_sel:[0,1] op_sel_hi:[1,0] neg_lo:[0,1]
	v_pk_add_f32 v[8:9], v[2:3], v[10:11]
	v_pk_add_f32 v[2:3], v[2:3], v[10:11] neg_lo:[0,1] neg_hi:[0,1]
	v_pk_add_f32 v[134:135], v[106:107], v[24:25]
	v_pk_mul_f32 v[10:11], v[2:3], s[10:11]
	v_pk_add_f32 v[106:107], v[106:107], v[24:25] neg_lo:[0,1] neg_hi:[0,1]
	v_pk_fma_f32 v[2:3], v[2:3], s[14:15], v[10:11] op_sel:[0,0,1] op_sel_hi:[1,0,0]
	v_pk_add_f32 v[10:11], v[4:5], v[12:13]
	v_pk_add_f32 v[4:5], v[4:5], v[12:13] neg_lo:[0,1] neg_hi:[0,1]
	v_pk_add_f32 v[12:13], v[6:7], v[14:15]
	v_pk_add_f32 v[6:7], v[6:7], v[14:15] neg_lo:[0,1] neg_hi:[0,1]
	v_pk_mul_f32 v[14:15], v[6:7], s[10:11]
	v_pk_add_f32 v[24:25], v[114:115], v[26:27] neg_lo:[0,1] neg_hi:[0,1]
	v_pk_fma_f32 v[6:7], v[6:7], s[14:15], v[14:15] op_sel:[0,0,1] op_sel_hi:[1,0,0] neg_lo:[1,0,0] neg_hi:[1,0,0]
	v_pk_add_f32 v[14:15], v[30:31], v[124:125]
	v_pk_add_f32 v[30:31], v[30:31], v[124:125] neg_lo:[0,1] neg_hi:[0,1]
	v_pk_add_f32 v[124:125], v[120:121], v[110:111]
	v_pk_add_f32 v[110:111], v[120:121], v[110:111] neg_lo:[0,1] neg_hi:[0,1]
	v_pk_add_f32 v[120:121], v[118:119], v[102:103] op_sel:[0,1] op_sel_hi:[1,0] neg_hi:[0,1]
	v_pk_add_f32 v[118:119], v[118:119], v[102:103] op_sel:[0,1] op_sel_hi:[1,0] neg_lo:[0,1]
	v_pk_add_f32 v[102:103], v[108:109], v[112:113] neg_lo:[0,1] neg_hi:[0,1]
	v_pk_add_f32 v[112:113], v[116:117], v[94:95]
	v_pk_add_f32 v[94:95], v[116:117], v[94:95] neg_lo:[0,1] neg_hi:[0,1]
	v_pk_add_f32 v[116:117], v[100:101], v[104:105]
	v_pk_add_f32 v[100:101], v[100:101], v[104:105] neg_lo:[0,1] neg_hi:[0,1]
	v_pk_add_f32 v[138:139], v[22:23], v[18:19] op_sel:[0,1] op_sel_hi:[1,0] neg_hi:[0,1]
	v_pk_add_f32 v[140:141], v[22:23], v[18:19] op_sel:[0,1] op_sel_hi:[1,0] neg_lo:[0,1]
	v_pk_add_f32 v[18:19], v[16:17], v[20:21]
	v_pk_add_f32 v[16:17], v[16:17], v[20:21] neg_lo:[0,1] neg_hi:[0,1]
	v_pk_add_f32 v[144:145], v[28:29], v[10:11]
	v_pk_add_f32 v[158:159], v[28:29], v[10:11] neg_lo:[0,1] neg_hi:[0,1]
	v_pk_add_f32 v[10:11], v[8:9], v[12:13]
	v_pk_add_f32 v[8:9], v[8:9], v[12:13] neg_lo:[0,1] neg_hi:[0,1]
	v_pk_add_f32 v[162:163], v[0:1], v[4:5] op_sel:[0,1] op_sel_hi:[1,0] neg_hi:[0,1]
	v_pk_add_f32 v[164:165], v[0:1], v[4:5] op_sel:[0,1] op_sel_hi:[1,0] neg_lo:[0,1]
	v_pk_add_f32 v[0:1], v[2:3], v[6:7] neg_lo:[0,1] neg_hi:[0,1]
	v_pk_mul_f32 v[108:109], v[102:103], s[22:23]
	v_pk_mul_f32 v[128:129], v[100:101], s[22:23]
	v_pk_add_f32 v[136:137], v[114:115], v[26:27]
	v_pk_mul_f32 v[114:115], v[24:25], s[22:23]
	v_pk_mul_f32 v[142:143], v[16:17], s[22:23]
	v_pk_mul_f32 v[160:161], v[8:9], s[22:23]
	v_pk_add_f32 v[166:167], v[2:3], v[6:7]
	v_pk_mul_f32 v[168:169], v[0:1], s[22:23]
	v_pk_add_f32 v[28:29], v[14:15], v[124:125]
	v_pk_add_f32 v[104:105], v[14:15], v[124:125] neg_lo:[0,1] neg_hi:[0,1]
	v_pk_add_f32 v[24:25], v[30:31], v[110:111] op_sel:[0,1] op_sel_hi:[1,0] neg_hi:[0,1]
	v_pk_add_f32 v[102:103], v[30:31], v[110:111] op_sel:[0,1] op_sel_hi:[1,0] neg_lo:[0,1]
	v_pk_add_f32 v[20:21], v[120:121], v[126:127]
	v_pk_add_f32 v[100:101], v[120:121], v[126:127] neg_lo:[0,1] neg_hi:[0,1]
	v_pk_add_f32 v[16:17], v[118:119], v[108:109] op_sel:[0,1] op_sel_hi:[1,0]
	v_pk_add_f32 v[98:99], v[118:119], v[108:109] op_sel:[0,1] op_sel_hi:[1,0] neg_lo:[0,1] neg_hi:[0,1]
	v_pk_add_f32 v[12:13], v[112:113], v[116:117]
	v_pk_add_f32 v[96:97], v[112:113], v[116:117] neg_lo:[0,1] neg_hi:[0,1]
	v_pk_add_f32 v[8:9], v[94:95], v[128:129] op_sel:[0,1] op_sel_hi:[1,0]
	v_pk_add_f32 v[94:95], v[94:95], v[128:129] op_sel:[0,1] op_sel_hi:[1,0] neg_lo:[0,1] neg_hi:[0,1]
	v_pk_add_f32 v[4:5], v[130:131], v[92:93]
	v_pk_add_f32 v[92:93], v[130:131], v[92:93] neg_lo:[0,1] neg_hi:[0,1]
	v_pk_add_f32 v[0:1], v[132:133], v[86:87] op_sel:[0,1] op_sel_hi:[1,0] neg_hi:[0,1]
	v_pk_add_f32 v[86:87], v[132:133], v[86:87] op_sel:[0,1] op_sel_hi:[1,0] neg_lo:[0,1]
	v_pk_add_f32 v[30:31], v[134:135], v[136:137]
	v_pk_add_f32 v[120:121], v[134:135], v[136:137] neg_lo:[0,1] neg_hi:[0,1]
	v_pk_add_f32 v[26:27], v[106:107], v[114:115] op_sel:[0,1] op_sel_hi:[1,0]
	v_pk_add_f32 v[118:119], v[106:107], v[114:115] op_sel:[0,1] op_sel_hi:[1,0] neg_lo:[0,1] neg_hi:[0,1]
	v_pk_add_f32 v[22:23], v[138:139], v[18:19]
	v_pk_add_f32 v[116:117], v[138:139], v[18:19] neg_lo:[0,1] neg_hi:[0,1]
	v_pk_add_f32 v[18:19], v[140:141], v[142:143] op_sel:[0,1] op_sel_hi:[1,0]
	v_pk_add_f32 v[114:115], v[140:141], v[142:143] op_sel:[0,1] op_sel_hi:[1,0] neg_lo:[0,1] neg_hi:[0,1]
	v_pk_add_f32 v[14:15], v[144:145], v[10:11]
	v_pk_add_f32 v[112:113], v[144:145], v[10:11] neg_lo:[0,1] neg_hi:[0,1]
	v_pk_add_f32 v[10:11], v[158:159], v[160:161] op_sel:[0,1] op_sel_hi:[1,0]
	v_pk_add_f32 v[110:111], v[158:159], v[160:161] op_sel:[0,1] op_sel_hi:[1,0] neg_lo:[0,1] neg_hi:[0,1]
	v_pk_add_f32 v[6:7], v[162:163], v[166:167]
	v_pk_add_f32 v[108:109], v[162:163], v[166:167] neg_lo:[0,1] neg_hi:[0,1]
	v_pk_add_f32 v[2:3], v[164:165], v[168:169] op_sel:[0,1] op_sel_hi:[1,0]
	v_pk_add_f32 v[106:107], v[164:165], v[168:169] op_sel:[0,1] op_sel_hi:[1,0] neg_lo:[0,1] neg_hi:[0,1]

.LBB0_623:
	s_or_b64 exec, exec, s[4:5]
	v_mov_b32_e32 v41, v32
	s_waitcnt lgkmcnt(0)
	s_barrier
	s_mov_b32 s11, s14
	v_and_b32_e32 v98, 31, v41
	v_cvt_f32_ubyte0_e32 v24, v98
	v_mul_f32_e32 v92, 0x3b000000, v24
	v_sin_f32_e32 v24, v92
	v_ashrrev_i32_e32 v0, 4, v41
	v_lshlrev_b32_e32 v0, 3, v0
	v_lshlrev_b32_e32 v1, 3, v41
	v_cos_f32_e32 v92, v92
	v_add3_u32 v25, 0, v0, v1
	ds_read_b64 v[0:1], v25
	ds_read_b64 v[2:3], v25 offset:4352
	ds_read_b64 v[4:5], v25 offset:8704
	ds_read_b64 v[6:7], v25 offset:13056
	ds_read_b64 v[8:9], v25 offset:17408
	ds_read_b64 v[10:11], v25 offset:21760
	ds_read_b64 v[12:13], v25 offset:26112
	ds_read_b64 v[14:15], v25 offset:30464
	ds_read_b64 v[16:17], v25 offset:34816
	ds_read_b64 v[18:19], v25 offset:39168
	ds_read_b64 v[20:21], v25 offset:43520
	ds_read_b64 v[22:23], v25 offset:47872
	v_xor_b32_e32 v93, 0x80000000, v24
	s_waitcnt lgkmcnt(10)
	v_pk_mul_f32 v[94:95], v[2:3], v[24:25] op_sel:[1,0] op_sel_hi:[0,0] neg_hi:[0,1]
	v_pk_fma_f32 v[2:3], v[2:3], v[92:93], v[94:95] op_sel_hi:[1,0,1]
	v_pk_mul_f32 v[94:95], v[24:25], v[92:93] op_sel:[0,1] op_sel_hi:[0,0] neg_hi:[1,0]
	v_pk_fma_f32 v[94:95], v[92:93], v[92:93], v[94:95] op_sel_hi:[0,1,1]
	ds_read_b64 v[26:27], v25 offset:52224
	ds_read_b64 v[28:29], v25 offset:56576
	ds_read_b64 v[30:31], v25 offset:60928
	ds_read_b64 v[86:87], v25 offset:65280
	s_waitcnt lgkmcnt(13)
	v_pk_mul_f32 v[96:97], v[4:5], v[94:95] op_sel:[1,1] op_sel_hi:[0,1] neg_lo:[0,1]
	v_pk_fma_f32 v[4:5], v[4:5], v[94:95], v[96:97] op_sel_hi:[1,0,1]
	v_pk_mul_f32 v[96:97], v[24:25], v[94:95] op_sel:[0,1] op_sel_hi:[0,0] neg_hi:[1,0]
	v_pk_fma_f32 v[94:95], v[92:93], v[94:95], v[96:97] op_sel_hi:[0,1,1]
	s_mov_b32 s35, s30
	s_waitcnt lgkmcnt(12)
	v_pk_mul_f32 v[96:97], v[6:7], v[94:95] op_sel:[1,1] op_sel_hi:[0,1] neg_lo:[0,1]
	v_pk_fma_f32 v[6:7], v[6:7], v[94:95], v[96:97] op_sel_hi:[1,0,1]
	v_pk_mul_f32 v[96:97], v[24:25], v[94:95] op_sel:[0,1] op_sel_hi:[0,0] neg_hi:[1,0]
	v_pk_fma_f32 v[94:95], v[92:93], v[94:95], v[96:97] op_sel_hi:[0,1,1]
	s_mov_b32 s26, s19
	s_waitcnt lgkmcnt(11)
	v_pk_mul_f32 v[96:97], v[8:9], v[94:95] op_sel:[1,1] op_sel_hi:[0,1] neg_lo:[0,1]
	v_pk_fma_f32 v[8:9], v[8:9], v[94:95], v[96:97] op_sel_hi:[1,0,1]
	v_pk_mul_f32 v[96:97], v[24:25], v[94:95] op_sel:[0,1] op_sel_hi:[0,0] neg_hi:[1,0]
	v_pk_fma_f32 v[94:95], v[92:93], v[94:95], v[96:97] op_sel_hi:[0,1,1]
	s_waitcnt lgkmcnt(0)
	v_pk_mul_f32 v[96:97], v[10:11], v[94:95] op_sel:[1,1] op_sel_hi:[0,1] neg_lo:[0,1]
	v_pk_fma_f32 v[10:11], v[10:11], v[94:95], v[96:97] op_sel_hi:[1,0,1]
	v_pk_mul_f32 v[96:97], v[24:25], v[94:95] op_sel:[0,1] op_sel_hi:[0,0] neg_hi:[1,0]
	v_pk_fma_f32 v[94:95], v[92:93], v[94:95], v[96:97] op_sel_hi:[0,1,1]
	s_barrier
	v_pk_mul_f32 v[96:97], v[12:13], v[94:95] op_sel:[1,1] op_sel_hi:[0,1] neg_lo:[0,1]
	v_pk_fma_f32 v[12:13], v[12:13], v[94:95], v[96:97] op_sel_hi:[1,0,1]
	v_pk_mul_f32 v[96:97], v[24:25], v[94:95] op_sel:[0,1] op_sel_hi:[0,0] neg_hi:[1,0]
	v_pk_fma_f32 v[94:95], v[92:93], v[94:95], v[96:97] op_sel_hi:[0,1,1]
	v_pk_mul_f32 v[96:97], v[14:15], v[94:95] op_sel:[1,1] op_sel_hi:[0,1] neg_lo:[0,1]
	v_pk_fma_f32 v[14:15], v[14:15], v[94:95], v[96:97] op_sel_hi:[1,0,1]
	v_pk_mul_f32 v[96:97], v[24:25], v[94:95] op_sel:[0,1] op_sel_hi:[0,0] neg_hi:[1,0]
	v_pk_fma_f32 v[94:95], v[92:93], v[94:95], v[96:97] op_sel_hi:[0,1,1]
	v_pk_mul_f32 v[96:97], v[16:17], v[94:95] op_sel:[1,1] op_sel_hi:[0,1] neg_lo:[0,1]
	v_pk_fma_f32 v[16:17], v[16:17], v[94:95], v[96:97] op_sel_hi:[1,0,1]
	v_pk_mul_f32 v[96:97], v[24:25], v[94:95] op_sel:[0,1] op_sel_hi:[0,0] neg_hi:[1,0]
	v_pk_fma_f32 v[94:95], v[92:93], v[94:95], v[96:97] op_sel_hi:[0,1,1]
	v_pk_mul_f32 v[96:97], v[18:19], v[94:95] op_sel:[1,1] op_sel_hi:[0,1] neg_lo:[0,1]
	v_pk_fma_f32 v[18:19], v[18:19], v[94:95], v[96:97] op_sel_hi:[1,0,1]
	v_pk_mul_f32 v[96:97], v[24:25], v[94:95] op_sel:[0,1] op_sel_hi:[0,0] neg_hi:[1,0]
	v_pk_fma_f32 v[94:95], v[92:93], v[94:95], v[96:97] op_sel_hi:[0,1,1]
	v_pk_mul_f32 v[96:97], v[20:21], v[94:95] op_sel:[1,1] op_sel_hi:[0,1] neg_lo:[0,1]
	v_pk_fma_f32 v[20:21], v[20:21], v[94:95], v[96:97] op_sel_hi:[1,0,1]
	v_pk_mul_f32 v[96:97], v[24:25], v[94:95] op_sel:[0,1] op_sel_hi:[0,0] neg_hi:[1,0]
	v_pk_fma_f32 v[94:95], v[92:93], v[94:95], v[96:97] op_sel_hi:[0,1,1]
	v_pk_mul_f32 v[96:97], v[22:23], v[94:95] op_sel:[1,1] op_sel_hi:[0,1] neg_lo:[0,1]
	v_pk_fma_f32 v[22:23], v[22:23], v[94:95], v[96:97] op_sel_hi:[1,0,1]
	v_pk_mul_f32 v[96:97], v[24:25], v[94:95] op_sel:[0,1] op_sel_hi:[0,0] neg_hi:[1,0]
	v_pk_fma_f32 v[94:95], v[92:93], v[94:95], v[96:97] op_sel_hi:[0,1,1]
	v_pk_mul_f32 v[96:97], v[26:27], v[94:95] op_sel:[1,1] op_sel_hi:[0,1] neg_lo:[0,1]
	v_pk_fma_f32 v[26:27], v[26:27], v[94:95], v[96:97] op_sel_hi:[1,0,1]
	v_pk_mul_f32 v[96:97], v[24:25], v[94:95] op_sel:[0,1] op_sel_hi:[0,0] neg_hi:[1,0]
	v_pk_fma_f32 v[94:95], v[92:93], v[94:95], v[96:97] op_sel_hi:[0,1,1]
	v_pk_mul_f32 v[96:97], v[28:29], v[94:95] op_sel:[1,1] op_sel_hi:[0,1] neg_lo:[0,1]
	v_pk_fma_f32 v[28:29], v[28:29], v[94:95], v[96:97] op_sel_hi:[1,0,1]
	v_pk_mul_f32 v[96:97], v[24:25], v[94:95] op_sel:[0,1] op_sel_hi:[0,0] neg_hi:[1,0]
	v_pk_fma_f32 v[94:95], v[92:93], v[94:95], v[96:97] op_sel_hi:[0,1,1]
	v_pk_mul_f32 v[24:25], v[24:25], v[94:95] op_sel:[0,1] op_sel_hi:[0,0] neg_hi:[1,0]
	v_pk_fma_f32 v[24:25], v[92:93], v[94:95], v[24:25] op_sel_hi:[0,1,1]
	v_pk_mul_f32 v[92:93], v[86:87], v[24:25] op_sel:[1,1] op_sel_hi:[0,1] neg_lo:[0,1]
	v_pk_fma_f32 v[24:25], v[86:87], v[24:25], v[92:93] op_sel_hi:[1,0,1]
	v_pk_add_f32 v[86:87], v[0:1], v[16:17]
	v_pk_add_f32 v[0:1], v[0:1], v[16:17] neg_lo:[0,1] neg_hi:[0,1]
	v_pk_add_f32 v[16:17], v[2:3], v[18:19]
	v_pk_add_f32 v[2:3], v[2:3], v[18:19] neg_lo:[0,1] neg_hi:[0,1]
	v_pk_mul_f32 v[96:97], v[30:31], v[94:95] op_sel:[1,1] op_sel_hi:[0,1] neg_lo:[0,1]
	v_pk_mul_f32 v[18:19], v[2:3], s[18:19]
	v_pk_fma_f32 v[30:31], v[30:31], v[94:95], v[96:97] op_sel_hi:[1,0,1]
	v_pk_fma_f32 v[2:3], v[2:3], s[30:31], v[18:19] op_sel:[0,0,1] op_sel_hi:[1,0,0]
	v_pk_add_f32 v[18:19], v[4:5], v[20:21]
	v_pk_add_f32 v[4:5], v[4:5], v[20:21] neg_lo:[0,1] neg_hi:[0,1]
	v_pk_mul_f32 v[20:21], v[4:5], s[10:11]
	v_pk_fma_f32 v[4:5], v[4:5], s[14:15], v[20:21] op_sel:[0,0,1] op_sel_hi:[1,0,0]
	v_pk_add_f32 v[20:21], v[6:7], v[22:23]
	v_pk_add_f32 v[6:7], v[6:7], v[22:23] neg_lo:[0,1] neg_hi:[0,1]
	v_pk_mul_f32 v[22:23], v[6:7], s[34:35]
	v_pk_fma_f32 v[6:7], v[6:7], s[26:27], v[22:23] op_sel:[0,0,1] op_sel_hi:[1,0,0]
	v_pk_add_f32 v[22:23], v[8:9], v[26:27]
	v_pk_add_f32 v[8:9], v[8:9], v[26:27] neg_lo:[0,1] neg_hi:[0,1]
	v_pk_add_f32 v[26:27], v[10:11], v[28:29]
	v_pk_add_f32 v[10:11], v[10:11], v[28:29] neg_lo:[0,1] neg_hi:[0,1]
	v_pk_mul_f32 v[28:29], v[10:11], s[34:35]
	v_pk_fma_f32 v[10:11], v[10:11], s[26:27], v[28:29] op_sel:[0,0,1] op_sel_hi:[1,0,0] neg_lo:[1,0,0] neg_hi:[1,0,0]
	v_pk_add_f32 v[28:29], v[12:13], v[30:31]
	v_pk_add_f32 v[12:13], v[12:13], v[30:31] neg_lo:[0,1] neg_hi:[0,1]
	v_pk_mul_f32 v[30:31], v[12:13], s[10:11]
	v_pk_fma_f32 v[12:13], v[12:13], s[14:15], v[30:31] op_sel:[0,0,1] op_sel_hi:[1,0,0] neg_lo:[1,0,0] neg_hi:[1,0,0]
	v_pk_add_f32 v[30:31], v[14:15], v[24:25]
	v_pk_add_f32 v[14:15], v[14:15], v[24:25] neg_lo:[0,1] neg_hi:[0,1]
	v_pk_mul_f32 v[24:25], v[14:15], s[18:19]
	v_pk_fma_f32 v[14:15], v[14:15], s[30:31], v[24:25] op_sel:[0,0,1] op_sel_hi:[1,0,0] neg_lo:[1,0,0] neg_hi:[1,0,0]
	v_pk_add_f32 v[24:25], v[86:87], v[22:23]
	v_pk_add_f32 v[22:23], v[86:87], v[22:23] neg_lo:[0,1] neg_hi:[0,1]
	v_pk_add_f32 v[86:87], v[16:17], v[26:27]
	v_pk_add_f32 v[16:17], v[16:17], v[26:27] neg_lo:[0,1] neg_hi:[0,1]
	v_pk_mul_f32 v[26:27], v[16:17], s[10:11]
	v_pk_fma_f32 v[16:17], v[16:17], s[14:15], v[26:27] op_sel:[0,0,1] op_sel_hi:[1,0,0]
	v_pk_add_f32 v[26:27], v[18:19], v[28:29]
	v_pk_add_f32 v[18:19], v[18:19], v[28:29] neg_lo:[0,1] neg_hi:[0,1]
	v_pk_add_f32 v[28:29], v[20:21], v[30:31]
	v_pk_add_f32 v[20:21], v[20:21], v[30:31] neg_lo:[0,1] neg_hi:[0,1]
	v_pk_mul_f32 v[30:31], v[20:21], s[10:11]
	v_pk_fma_f32 v[20:21], v[20:21], s[14:15], v[30:31] op_sel:[0,0,1] op_sel_hi:[1,0,0] neg_lo:[1,0,0] neg_hi:[1,0,0]
	v_pk_add_f32 v[30:31], v[0:1], v[8:9] op_sel:[0,1] op_sel_hi:[1,0] neg_hi:[0,1]
	v_pk_add_f32 v[0:1], v[0:1], v[8:9] op_sel:[0,1] op_sel_hi:[1,0] neg_lo:[0,1]
	v_pk_add_f32 v[8:9], v[2:3], v[10:11]
	v_pk_add_f32 v[2:3], v[2:3], v[10:11] neg_lo:[0,1] neg_hi:[0,1]
	v_pk_mul_f32 v[10:11], v[2:3], s[10:11]
	v_pk_fma_f32 v[2:3], v[2:3], s[14:15], v[10:11] op_sel:[0,0,1] op_sel_hi:[1,0,0]
	v_pk_add_f32 v[10:11], v[4:5], v[12:13]
	v_pk_add_f32 v[4:5], v[4:5], v[12:13] neg_lo:[0,1] neg_hi:[0,1]
	v_pk_add_f32 v[12:13], v[6:7], v[14:15]
	v_pk_add_f32 v[6:7], v[6:7], v[14:15] neg_lo:[0,1] neg_hi:[0,1]
	v_pk_mul_f32 v[14:15], v[6:7], s[10:11]
	v_pk_fma_f32 v[6:7], v[6:7], s[14:15], v[14:15] op_sel:[0,0,1] op_sel_hi:[1,0,0] neg_lo:[1,0,0] neg_hi:[1,0,0]
	v_pk_add_f32 v[14:15], v[24:25], v[26:27]
	v_pk_add_f32 v[24:25], v[24:25], v[26:27] neg_lo:[0,1] neg_hi:[0,1]
	v_pk_add_f32 v[26:27], v[86:87], v[28:29]
	v_pk_add_f32 v[28:29], v[86:87], v[28:29] neg_lo:[0,1] neg_hi:[0,1]
	v_pk_add_f32 v[86:87], v[22:23], v[18:19] op_sel:[0,1] op_sel_hi:[1,0] neg_hi:[0,1]
	v_pk_add_f32 v[18:19], v[22:23], v[18:19] op_sel:[0,1] op_sel_hi:[1,0] neg_lo:[0,1]
	v_pk_add_f32 v[22:23], v[16:17], v[20:21]
	v_pk_add_f32 v[16:17], v[16:17], v[20:21] neg_lo:[0,1] neg_hi:[0,1]
	v_pk_add_f32 v[20:21], v[30:31], v[10:11]
	v_pk_add_f32 v[10:11], v[30:31], v[10:11] neg_lo:[0,1] neg_hi:[0,1]
	v_pk_add_f32 v[30:31], v[8:9], v[12:13]
	v_pk_add_f32 v[8:9], v[8:9], v[12:13] neg_lo:[0,1] neg_hi:[0,1]
	v_pk_add_f32 v[12:13], v[0:1], v[4:5] op_sel:[0,1] op_sel_hi:[1,0] neg_hi:[0,1]
	v_pk_add_f32 v[0:1], v[0:1], v[4:5] op_sel:[0,1] op_sel_hi:[1,0] neg_lo:[0,1]
	v_pk_add_f32 v[4:5], v[2:3], v[6:7]
	v_pk_add_f32 v[2:3], v[2:3], v[6:7] neg_lo:[0,1] neg_hi:[0,1]
	v_pk_mul_f32 v[2:3], v[2:3], s[22:23]
	v_pk_add_f32 v[6:7], v[14:15], v[26:27]
	v_pk_add_f32 v[14:15], v[14:15], v[26:27] neg_lo:[0,1] neg_hi:[0,1]
	v_pk_add_f32 v[26:27], v[24:25], v[28:29] op_sel:[0,1] op_sel_hi:[1,0] neg_hi:[0,1]
	v_pk_add_f32 v[24:25], v[24:25], v[28:29] op_sel:[0,1] op_sel_hi:[1,0] neg_lo:[0,1]
	v_pk_add_f32 v[28:29], v[86:87], v[22:23]
	v_pk_add_f32 v[22:23], v[86:87], v[22:23] neg_lo:[0,1] neg_hi:[0,1]
	v_pk_add_f32 v[86:87], v[18:19], v[16:17] op_sel:[0,1] op_sel_hi:[1,0] neg_hi:[0,1]
	v_pk_add_f32 v[16:17], v[18:19], v[16:17] op_sel:[0,1] op_sel_hi:[1,0] neg_lo:[0,1]
	v_pk_add_f32 v[18:19], v[20:21], v[30:31]
	v_pk_add_f32 v[20:21], v[20:21], v[30:31] neg_lo:[0,1] neg_hi:[0,1]
	v_pk_add_f32 v[30:31], v[10:11], v[8:9] op_sel:[0,1] op_sel_hi:[1,0] neg_hi:[0,1]
	v_pk_add_f32 v[8:9], v[10:11], v[8:9] op_sel:[0,1] op_sel_hi:[1,0] neg_lo:[0,1]
	v_pk_add_f32 v[10:11], v[12:13], v[4:5]
	v_pk_add_f32 v[4:5], v[12:13], v[4:5] neg_lo:[0,1] neg_hi:[0,1]
	v_pk_add_f32 v[12:13], v[0:1], v[2:3] op_sel:[0,1] op_sel_hi:[1,0]
	v_pk_add_f32 v[0:1], v[0:1], v[2:3] op_sel:[0,1] op_sel_hi:[1,0] neg_lo:[0,1] neg_hi:[0,1]
	v_lshlrev_b32_e32 v2, 4, v41
	v_and_or_b32 v2, v2, s7, v98
	v_ashrrev_i32_e32 v3, 4, v2
	v_lshlrev_b32_e32 v3, 3, v3
	v_lshlrev_b32_e32 v2, 3, v2
	v_add3_u32 v2, 0, v3, v2
	v_add_u32_e32 v3, 0x800, v2
	v_mov_b32_e32 v41, v32
	ds_write2_b64 v2, v[6:7], v[18:19] offset1:34
	ds_write2_b64 v3, v[14:15], v[20:21] offset0:16 offset1:50
	ds_write2_b64 v2, v[26:27], v[30:31] offset0:136 offset1:170
	ds_write2_b64 v3, v[24:25], v[8:9] offset0:152 offset1:186
	ds_write2_b64 v2, v[28:29], v[10:11] offset0:68 offset1:102
	ds_write2_b64 v3, v[22:23], v[4:5] offset0:84 offset1:118
	ds_write2_b64 v2, v[86:87], v[12:13] offset0:204 offset1:238
	ds_write2_b64 v3, v[16:17], v[0:1] offset0:220 offset1:254
	s_waitcnt lgkmcnt(0)
	s_barrier
	s_nop 0
	v_and_b32_e32 v98, 0x1ff, v41
	v_cvt_f32_u32_e32 v24, v98
	v_ashrrev_i32_e32 v0, 4, v41
	v_lshlrev_b32_e32 v0, 3, v0
	v_lshlrev_b32_e32 v1, 3, v41
	v_mul_f32_e32 v92, 0x39000000, v24
	v_sin_f32_e32 v24, v92
	v_cos_f32_e32 v92, v92
	v_add3_u32 v25, 0, v0, v1
	ds_read_b64 v[0:1], v25
	ds_read_b64 v[2:3], v25 offset:4352
	ds_read_b64 v[4:5], v25 offset:8704
	ds_read_b64 v[6:7], v25 offset:13056
	ds_read_b64 v[8:9], v25 offset:17408
	ds_read_b64 v[10:11], v25 offset:21760
	ds_read_b64 v[12:13], v25 offset:26112
	ds_read_b64 v[14:15], v25 offset:30464
	v_xor_b32_e32 v93, 0x80000000, v24
	s_waitcnt lgkmcnt(6)
	v_pk_mul_f32 v[94:95], v[2:3], v[24:25] op_sel:[1,0] op_sel_hi:[0,0] neg_hi:[0,1]
	v_pk_fma_f32 v[2:3], v[2:3], v[92:93], v[94:95] op_sel_hi:[1,0,1]
	v_pk_mul_f32 v[94:95], v[24:25], v[92:93] op_sel:[0,1] op_sel_hi:[0,0] neg_hi:[1,0]
	v_pk_fma_f32 v[94:95], v[92:93], v[92:93], v[94:95] op_sel_hi:[0,1,1]
	ds_read_b64 v[16:17], v25 offset:34816
	ds_read_b64 v[18:19], v25 offset:39168
	ds_read_b64 v[20:21], v25 offset:43520
	ds_read_b64 v[22:23], v25 offset:47872
	s_waitcnt lgkmcnt(9)
	v_pk_mul_f32 v[96:97], v[4:5], v[94:95] op_sel:[1,1] op_sel_hi:[0,1] neg_lo:[0,1]
	v_pk_fma_f32 v[4:5], v[4:5], v[94:95], v[96:97] op_sel_hi:[1,0,1]
	v_pk_mul_f32 v[96:97], v[24:25], v[94:95] op_sel:[0,1] op_sel_hi:[0,0] neg_hi:[1,0]
	v_pk_fma_f32 v[94:95], v[92:93], v[94:95], v[96:97] op_sel_hi:[0,1,1]
	ds_read_b64 v[26:27], v25 offset:52224
	ds_read_b64 v[28:29], v25 offset:56576
	ds_read_b64 v[30:31], v25 offset:60928
	ds_read_b64 v[86:87], v25 offset:65280
	s_waitcnt lgkmcnt(12)
	v_pk_mul_f32 v[96:97], v[6:7], v[94:95] op_sel:[1,1] op_sel_hi:[0,1] neg_lo:[0,1]
	v_pk_fma_f32 v[6:7], v[6:7], v[94:95], v[96:97] op_sel_hi:[1,0,1]
	v_pk_mul_f32 v[96:97], v[24:25], v[94:95] op_sel:[0,1] op_sel_hi:[0,0] neg_hi:[1,0]
	v_pk_fma_f32 v[94:95], v[92:93], v[94:95], v[96:97] op_sel_hi:[0,1,1]
	s_waitcnt lgkmcnt(0)
	v_pk_mul_f32 v[96:97], v[8:9], v[94:95] op_sel:[1,1] op_sel_hi:[0,1] neg_lo:[0,1]
	v_pk_fma_f32 v[8:9], v[8:9], v[94:95], v[96:97] op_sel_hi:[1,0,1]
	v_pk_mul_f32 v[96:97], v[24:25], v[94:95] op_sel:[0,1] op_sel_hi:[0,0] neg_hi:[1,0]
	v_pk_fma_f32 v[94:95], v[92:93], v[94:95], v[96:97] op_sel_hi:[0,1,1]
	s_barrier
	v_pk_mul_f32 v[96:97], v[10:11], v[94:95] op_sel:[1,1] op_sel_hi:[0,1] neg_lo:[0,1]
	v_pk_fma_f32 v[10:11], v[10:11], v[94:95], v[96:97] op_sel_hi:[1,0,1]
	v_pk_mul_f32 v[96:97], v[24:25], v[94:95] op_sel:[0,1] op_sel_hi:[0,0] neg_hi:[1,0]
	v_pk_fma_f32 v[94:95], v[92:93], v[94:95], v[96:97] op_sel_hi:[0,1,1]
	v_pk_mul_f32 v[96:97], v[12:13], v[94:95] op_sel:[1,1] op_sel_hi:[0,1] neg_lo:[0,1]
	v_pk_fma_f32 v[12:13], v[12:13], v[94:95], v[96:97] op_sel_hi:[1,0,1]
	v_pk_mul_f32 v[96:97], v[24:25], v[94:95] op_sel:[0,1] op_sel_hi:[0,0] neg_hi:[1,0]
	v_pk_fma_f32 v[94:95], v[92:93], v[94:95], v[96:97] op_sel_hi:[0,1,1]
	v_pk_mul_f32 v[96:97], v[14:15], v[94:95] op_sel:[1,1] op_sel_hi:[0,1] neg_lo:[0,1]
	v_pk_fma_f32 v[14:15], v[14:15], v[94:95], v[96:97] op_sel_hi:[1,0,1]
	v_pk_mul_f32 v[96:97], v[24:25], v[94:95] op_sel:[0,1] op_sel_hi:[0,0] neg_hi:[1,0]
	v_pk_fma_f32 v[94:95], v[92:93], v[94:95], v[96:97] op_sel_hi:[0,1,1]
	v_pk_mul_f32 v[96:97], v[16:17], v[94:95] op_sel:[1,1] op_sel_hi:[0,1] neg_lo:[0,1]
	v_pk_fma_f32 v[16:17], v[16:17], v[94:95], v[96:97] op_sel_hi:[1,0,1]
	v_pk_mul_f32 v[96:97], v[24:25], v[94:95] op_sel:[0,1] op_sel_hi:[0,0] neg_hi:[1,0]
	v_pk_fma_f32 v[94:95], v[92:93], v[94:95], v[96:97] op_sel_hi:[0,1,1]
	v_pk_mul_f32 v[96:97], v[18:19], v[94:95] op_sel:[1,1] op_sel_hi:[0,1] neg_lo:[0,1]
	v_pk_fma_f32 v[18:19], v[18:19], v[94:95], v[96:97] op_sel_hi:[1,0,1]
	v_pk_mul_f32 v[96:97], v[24:25], v[94:95] op_sel:[0,1] op_sel_hi:[0,0] neg_hi:[1,0]
	v_pk_fma_f32 v[94:95], v[92:93], v[94:95], v[96:97] op_sel_hi:[0,1,1]
	v_pk_mul_f32 v[96:97], v[20:21], v[94:95] op_sel:[1,1] op_sel_hi:[0,1] neg_lo:[0,1]
	v_pk_fma_f32 v[20:21], v[20:21], v[94:95], v[96:97] op_sel_hi:[1,0,1]
	v_pk_mul_f32 v[96:97], v[24:25], v[94:95] op_sel:[0,1] op_sel_hi:[0,0] neg_hi:[1,0]
	v_pk_fma_f32 v[94:95], v[92:93], v[94:95], v[96:97] op_sel_hi:[0,1,1]
	v_pk_mul_f32 v[96:97], v[22:23], v[94:95] op_sel:[1,1] op_sel_hi:[0,1] neg_lo:[0,1]
	v_pk_fma_f32 v[22:23], v[22:23], v[94:95], v[96:97] op_sel_hi:[1,0,1]
	v_pk_mul_f32 v[96:97], v[24:25], v[94:95] op_sel:[0,1] op_sel_hi:[0,0] neg_hi:[1,0]
	v_pk_fma_f32 v[94:95], v[92:93], v[94:95], v[96:97] op_sel_hi:[0,1,1]
	v_pk_mul_f32 v[96:97], v[26:27], v[94:95] op_sel:[1,1] op_sel_hi:[0,1] neg_lo:[0,1]
	v_pk_fma_f32 v[26:27], v[26:27], v[94:95], v[96:97] op_sel_hi:[1,0,1]
	v_pk_mul_f32 v[96:97], v[24:25], v[94:95] op_sel:[0,1] op_sel_hi:[0,0] neg_hi:[1,0]
	v_pk_fma_f32 v[94:95], v[92:93], v[94:95], v[96:97] op_sel_hi:[0,1,1]
	v_pk_mul_f32 v[96:97], v[28:29], v[94:95] op_sel:[1,1] op_sel_hi:[0,1] neg_lo:[0,1]
	v_pk_fma_f32 v[28:29], v[28:29], v[94:95], v[96:97] op_sel_hi:[1,0,1]
	v_pk_mul_f32 v[96:97], v[24:25], v[94:95] op_sel:[0,1] op_sel_hi:[0,0] neg_hi:[1,0]
	v_pk_fma_f32 v[94:95], v[92:93], v[94:95], v[96:97] op_sel_hi:[0,1,1]
	v_pk_mul_f32 v[24:25], v[24:25], v[94:95] op_sel:[0,1] op_sel_hi:[0,0] neg_hi:[1,0]
	v_pk_fma_f32 v[24:25], v[92:93], v[94:95], v[24:25] op_sel_hi:[0,1,1]
	v_pk_mul_f32 v[92:93], v[86:87], v[24:25] op_sel:[1,1] op_sel_hi:[0,1] neg_lo:[0,1]
	v_pk_fma_f32 v[24:25], v[86:87], v[24:25], v[92:93] op_sel_hi:[1,0,1]
	v_pk_add_f32 v[86:87], v[0:1], v[16:17]
	v_pk_add_f32 v[0:1], v[0:1], v[16:17] neg_lo:[0,1] neg_hi:[0,1]
	v_pk_add_f32 v[16:17], v[2:3], v[18:19]
	v_pk_add_f32 v[2:3], v[2:3], v[18:19] neg_lo:[0,1] neg_hi:[0,1]
	v_pk_mul_f32 v[96:97], v[30:31], v[94:95] op_sel:[1,1] op_sel_hi:[0,1] neg_lo:[0,1]
	v_pk_mul_f32 v[18:19], v[2:3], s[18:19]
	v_pk_fma_f32 v[30:31], v[30:31], v[94:95], v[96:97] op_sel_hi:[1,0,1]
	v_pk_fma_f32 v[2:3], v[2:3], s[30:31], v[18:19] op_sel:[0,0,1] op_sel_hi:[1,0,0]
	v_pk_add_f32 v[18:19], v[4:5], v[20:21]
	v_pk_add_f32 v[4:5], v[4:5], v[20:21] neg_lo:[0,1] neg_hi:[0,1]
	v_pk_mul_f32 v[20:21], v[4:5], s[10:11]
	v_pk_fma_f32 v[4:5], v[4:5], s[14:15], v[20:21] op_sel:[0,0,1] op_sel_hi:[1,0,0]
	v_pk_add_f32 v[20:21], v[6:7], v[22:23]
	v_pk_add_f32 v[6:7], v[6:7], v[22:23] neg_lo:[0,1] neg_hi:[0,1]
	v_pk_mul_f32 v[22:23], v[6:7], s[34:35]
	v_pk_fma_f32 v[6:7], v[6:7], s[26:27], v[22:23] op_sel:[0,0,1] op_sel_hi:[1,0,0]
	v_pk_add_f32 v[22:23], v[8:9], v[26:27]
	v_pk_add_f32 v[8:9], v[8:9], v[26:27] neg_lo:[0,1] neg_hi:[0,1]
	v_pk_add_f32 v[26:27], v[10:11], v[28:29]
	v_pk_add_f32 v[10:11], v[10:11], v[28:29] neg_lo:[0,1] neg_hi:[0,1]
	v_pk_mul_f32 v[28:29], v[10:11], s[34:35]
	v_pk_fma_f32 v[10:11], v[10:11], s[26:27], v[28:29] op_sel:[0,0,1] op_sel_hi:[1,0,0] neg_lo:[1,0,0] neg_hi:[1,0,0]
	v_pk_add_f32 v[28:29], v[12:13], v[30:31]
	v_pk_add_f32 v[12:13], v[12:13], v[30:31] neg_lo:[0,1] neg_hi:[0,1]
	v_pk_mul_f32 v[30:31], v[12:13], s[10:11]
	v_pk_fma_f32 v[12:13], v[12:13], s[14:15], v[30:31] op_sel:[0,0,1] op_sel_hi:[1,0,0] neg_lo:[1,0,0] neg_hi:[1,0,0]
	v_pk_add_f32 v[30:31], v[14:15], v[24:25]
	v_pk_add_f32 v[14:15], v[14:15], v[24:25] neg_lo:[0,1] neg_hi:[0,1]
	v_pk_mul_f32 v[24:25], v[14:15], s[18:19]
	v_pk_fma_f32 v[14:15], v[14:15], s[30:31], v[24:25] op_sel:[0,0,1] op_sel_hi:[1,0,0] neg_lo:[1,0,0] neg_hi:[1,0,0]
	v_pk_add_f32 v[24:25], v[86:87], v[22:23]
	v_pk_add_f32 v[22:23], v[86:87], v[22:23] neg_lo:[0,1] neg_hi:[0,1]
	v_pk_add_f32 v[86:87], v[16:17], v[26:27]
	v_pk_add_f32 v[16:17], v[16:17], v[26:27] neg_lo:[0,1] neg_hi:[0,1]
	v_pk_mul_f32 v[26:27], v[16:17], s[10:11]
	v_pk_fma_f32 v[16:17], v[16:17], s[14:15], v[26:27] op_sel:[0,0,1] op_sel_hi:[1,0,0]
	v_pk_add_f32 v[26:27], v[18:19], v[28:29]
	v_pk_add_f32 v[18:19], v[18:19], v[28:29] neg_lo:[0,1] neg_hi:[0,1]
	v_pk_add_f32 v[28:29], v[20:21], v[30:31]
	v_pk_add_f32 v[20:21], v[20:21], v[30:31] neg_lo:[0,1] neg_hi:[0,1]
	v_pk_mul_f32 v[30:31], v[20:21], s[10:11]
	v_pk_fma_f32 v[20:21], v[20:21], s[14:15], v[30:31] op_sel:[0,0,1] op_sel_hi:[1,0,0] neg_lo:[1,0,0] neg_hi:[1,0,0]
	v_pk_add_f32 v[30:31], v[0:1], v[8:9] op_sel:[0,1] op_sel_hi:[1,0] neg_hi:[0,1]
	v_pk_add_f32 v[0:1], v[0:1], v[8:9] op_sel:[0,1] op_sel_hi:[1,0] neg_lo:[0,1]
	v_pk_add_f32 v[8:9], v[2:3], v[10:11]
	v_pk_add_f32 v[2:3], v[2:3], v[10:11] neg_lo:[0,1] neg_hi:[0,1]
	v_pk_mul_f32 v[10:11], v[2:3], s[10:11]
	v_pk_fma_f32 v[2:3], v[2:3], s[14:15], v[10:11] op_sel:[0,0,1] op_sel_hi:[1,0,0]
	v_pk_add_f32 v[10:11], v[4:5], v[12:13]
	v_pk_add_f32 v[4:5], v[4:5], v[12:13] neg_lo:[0,1] neg_hi:[0,1]
	v_pk_add_f32 v[12:13], v[6:7], v[14:15]
	v_pk_add_f32 v[6:7], v[6:7], v[14:15] neg_lo:[0,1] neg_hi:[0,1]
	v_pk_mul_f32 v[14:15], v[6:7], s[10:11]
	v_pk_fma_f32 v[6:7], v[6:7], s[14:15], v[14:15] op_sel:[0,0,1] op_sel_hi:[1,0,0] neg_lo:[1,0,0] neg_hi:[1,0,0]
	v_pk_add_f32 v[14:15], v[24:25], v[26:27]
	v_pk_add_f32 v[24:25], v[24:25], v[26:27] neg_lo:[0,1] neg_hi:[0,1]
	v_pk_add_f32 v[26:27], v[86:87], v[28:29]
	v_pk_add_f32 v[28:29], v[86:87], v[28:29] neg_lo:[0,1] neg_hi:[0,1]
	v_pk_add_f32 v[86:87], v[22:23], v[18:19] op_sel:[0,1] op_sel_hi:[1,0] neg_hi:[0,1]
	v_pk_add_f32 v[18:19], v[22:23], v[18:19] op_sel:[0,1] op_sel_hi:[1,0] neg_lo:[0,1]
	v_pk_add_f32 v[22:23], v[16:17], v[20:21]
	v_pk_add_f32 v[16:17], v[16:17], v[20:21] neg_lo:[0,1] neg_hi:[0,1]
	v_pk_add_f32 v[20:21], v[30:31], v[10:11]
	v_pk_add_f32 v[10:11], v[30:31], v[10:11] neg_lo:[0,1] neg_hi:[0,1]
	v_pk_add_f32 v[30:31], v[8:9], v[12:13]
	v_pk_add_f32 v[8:9], v[8:9], v[12:13] neg_lo:[0,1] neg_hi:[0,1]
	v_pk_add_f32 v[12:13], v[0:1], v[4:5] op_sel:[0,1] op_sel_hi:[1,0] neg_hi:[0,1]
	v_pk_add_f32 v[0:1], v[0:1], v[4:5] op_sel:[0,1] op_sel_hi:[1,0] neg_lo:[0,1]
	v_pk_add_f32 v[4:5], v[2:3], v[6:7]
	v_pk_add_f32 v[2:3], v[2:3], v[6:7] neg_lo:[0,1] neg_hi:[0,1]
	v_pk_mul_f32 v[2:3], v[2:3], s[22:23]
	v_pk_add_f32 v[6:7], v[14:15], v[26:27]
	v_pk_add_f32 v[14:15], v[14:15], v[26:27] neg_lo:[0,1] neg_hi:[0,1]
	v_pk_add_f32 v[26:27], v[24:25], v[28:29] op_sel:[0,1] op_sel_hi:[1,0] neg_hi:[0,1]
	v_pk_add_f32 v[24:25], v[24:25], v[28:29] op_sel:[0,1] op_sel_hi:[1,0] neg_lo:[0,1]
	v_pk_add_f32 v[28:29], v[86:87], v[22:23]
	v_pk_add_f32 v[22:23], v[86:87], v[22:23] neg_lo:[0,1] neg_hi:[0,1]
	v_pk_add_f32 v[86:87], v[18:19], v[16:17] op_sel:[0,1] op_sel_hi:[1,0] neg_hi:[0,1]
	v_pk_add_f32 v[16:17], v[18:19], v[16:17] op_sel:[0,1] op_sel_hi:[1,0] neg_lo:[0,1]
	v_pk_add_f32 v[18:19], v[20:21], v[30:31]
	v_pk_add_f32 v[20:21], v[20:21], v[30:31] neg_lo:[0,1] neg_hi:[0,1]
	v_pk_add_f32 v[30:31], v[10:11], v[8:9] op_sel:[0,1] op_sel_hi:[1,0] neg_hi:[0,1]
	v_pk_add_f32 v[8:9], v[10:11], v[8:9] op_sel:[0,1] op_sel_hi:[1,0] neg_lo:[0,1]
	v_pk_add_f32 v[10:11], v[12:13], v[4:5]
	v_pk_add_f32 v[4:5], v[12:13], v[4:5] neg_lo:[0,1] neg_hi:[0,1]
	v_pk_add_f32 v[12:13], v[0:1], v[2:3] op_sel:[0,1] op_sel_hi:[1,0]
	v_pk_add_f32 v[0:1], v[0:1], v[2:3] op_sel:[0,1] op_sel_hi:[1,0] neg_lo:[0,1] neg_hi:[0,1]
	v_lshlrev_b32_e32 v2, 4, v41
	v_and_or_b32 v2, v2, s15, v98
	v_ashrrev_i32_e32 v3, 4, v2
	v_lshlrev_b32_e32 v3, 3, v3
	v_lshlrev_b32_e32 v2, 3, v2
	v_add3_u32 v2, 0, v3, v2
	ds_write_b64 v2, v[6:7]
	ds_write_b64 v2, v[14:15] offset:34816
	ds_write_b64 v2, v[26:27] offset:17408
	ds_write_b64 v2, v[24:25] offset:52224
	ds_write_b64 v2, v[28:29] offset:8704
	ds_write_b64 v2, v[22:23] offset:43520
	ds_write_b64 v2, v[86:87] offset:26112
	ds_write_b64 v2, v[16:17] offset:60928
	ds_write_b64 v2, v[18:19] offset:4352
	ds_write_b64 v2, v[20:21] offset:39168
	ds_write_b64 v2, v[30:31] offset:21760
	ds_write_b64 v2, v[8:9] offset:56576
	ds_write_b64 v2, v[10:11] offset:13056
	ds_write_b64 v2, v[4:5] offset:47872
	ds_write_b64 v2, v[12:13] offset:30464
	ds_write_b64 v2, v[0:1] offset:65280
	s_waitcnt lgkmcnt(0)
	s_barrier
	s_and_saveexec_b64 s[28:29], s[40:41]
	s_cbranch_execz .LBB0_633
	s_add_u32 s4, s38, 0x400000
	s_addc_u32 s5, s39, 0
	v_lshl_add_u64 v[0:1], v[48:49], 1, s[4:5]
	global_load_dwordx4 v[8:11], v[0:1], off offset:16
	global_load_dwordx4 v[12:15], v[0:1], off
	v_mov_b32_e32 v19, 0
	v_mov_b32_e32 v18, 0
	s_and_saveexec_b64 s[8:9], s[42:43]
	s_cbranch_execz .LBB0_626
	v_lshl_add_u64 v[2:3], v[172:173], 1, s[4:5]
	global_load_ushort v2, v[2:3], off offset:-2
	s_waitcnt vmcnt(0)
	v_lshlrev_b32_e32 v18, 16, v2

.LBB0_665:
	s_or_b64 exec, exec, s[4:5]
	s_barrier
	ds_write2_b64 v152, v[92:93], v[86:87] offset1:1
	ds_write2_b64 v152, v[76:77], v[70:71] offset0:2 offset1:3
	ds_write2_b64 v152, v[90:91], v[82:83] offset0:4 offset1:5
	ds_write2_b64 v152, v[74:75], v[66:67] offset0:6 offset1:7
	ds_write2_b64 v152, v[88:89], v[80:81] offset0:8 offset1:9
	ds_write2_b64 v152, v[72:73], v[64:65] offset0:10 offset1:11
	ds_write2_b64 v152, v[84:85], v[78:79] offset0:12 offset1:13
	ds_write2_b64 v152, v[68:69], v[62:63] offset0:14 offset1:15
	s_waitcnt lgkmcnt(0)
	s_barrier
	s_and_saveexec_b64 s[28:29], s[40:41]
	s_cbranch_execz .LBB0_667
	ds_read_b64 v[0:1], v153
	ds_read_b64 v[2:3], v153 offset:2176
	ds_read_b64 v[4:5], v153 offset:4352
	ds_read_b64 v[6:7], v153 offset:6528
	ds_read_b64 v[8:9], v153 offset:8704
	ds_read_b64 v[10:11], v153 offset:10880
	ds_read_b64 v[12:13], v153 offset:13056
	ds_read_b64 v[14:15], v153 offset:15232
	ds_read_b64 v[16:17], v153 offset:17408
	ds_read_b64 v[18:19], v153 offset:19584
	ds_read_b64 v[20:21], v153 offset:21760
	ds_read_b64 v[22:23], v153 offset:23936
	ds_read_b64 v[24:25], v153 offset:26112
	ds_read_b64 v[26:27], v153 offset:28288
	ds_read_b64 v[28:29], v153 offset:30464
	ds_read_b64 v[30:31], v153 offset:32640
	ds_read_b64 v[58:59], v153 offset:34816
	ds_read_b64 v[60:61], v153 offset:41344
	ds_read_b64 v[94:95], v153 offset:43520
	ds_read_b64 v[96:97], v153 offset:45696
	ds_read_b64 v[98:99], v153 offset:47872
	ds_read_b64 v[100:101], v153 offset:50048
	ds_read_b64 v[102:103], v153 offset:52224
	ds_read_b64 v[104:105], v153 offset:54400
	ds_read_b64 v[106:107], v153 offset:56576
	ds_read_b64 v[108:109], v153 offset:58752
	ds_read_b64 v[110:111], v153 offset:60928
	ds_read_b64 v[112:113], v153 offset:63104
	ds_read_b64 v[114:115], v153 offset:65280
	ds_read_b64 v[116:117], v153 offset:36992
	ds_read_b64 v[118:119], v153 offset:39168
	ds_read_b64 v[120:121], v33
	s_waitcnt lgkmcnt(14)
	v_pk_add_f32 v[124:125], v[0:1], v[58:59]
	v_pk_add_f32 v[0:1], v[0:1], v[58:59] neg_lo:[0,1] neg_hi:[0,1]
	s_waitcnt lgkmcnt(2)
	v_pk_add_f32 v[58:59], v[2:3], v[116:117]
	v_pk_add_f32 v[2:3], v[2:3], v[116:117] neg_lo:[0,1] neg_hi:[0,1]
	s_mov_b32 s11, s14
	v_pk_mul_f32 v[116:117], v[2:3], s[16:17]
	s_mov_b32 s13, s86
	v_pk_fma_f32 v[2:3], v[2:3], s[6:7], v[116:117] op_sel:[0,0,1] op_sel_hi:[1,0,0]
	s_waitcnt lgkmcnt(1)
	v_pk_add_f32 v[116:117], v[4:5], v[118:119]
	v_pk_add_f32 v[4:5], v[4:5], v[118:119] neg_lo:[0,1] neg_hi:[0,1]
	s_mov_b32 s4, s21
	v_pk_mul_f32 v[118:119], v[4:5], s[18:19]
	s_mov_b32 s35, s30
	v_pk_fma_f32 v[4:5], v[4:5], s[30:31], v[118:119] op_sel:[0,0,1] op_sel_hi:[1,0,0]
	v_pk_add_f32 v[118:119], v[6:7], v[60:61]
	v_pk_add_f32 v[6:7], v[6:7], v[60:61] neg_lo:[0,1] neg_hi:[0,1]
	s_mov_b32 s8, s19
	v_pk_mul_f32 v[60:61], v[6:7], s[20:21]
	s_mov_b32 s77, s6
	v_pk_fma_f32 v[6:7], v[6:7], s[86:87], v[60:61] op_sel:[0,0,1] op_sel_hi:[1,0,0]
	v_pk_add_f32 v[60:61], v[8:9], v[94:95]
	v_pk_add_f32 v[8:9], v[8:9], v[94:95] neg_lo:[0,1] neg_hi:[0,1]
	s_mov_b32 s26, s17
	v_pk_mul_f32 v[94:95], v[8:9], s[10:11]
	s_nop 0
	v_pk_fma_f32 v[8:9], v[8:9], s[14:15], v[94:95] op_sel:[0,0,1] op_sel_hi:[1,0,0]
	v_pk_add_f32 v[94:95], v[10:11], v[96:97]
	v_pk_add_f32 v[10:11], v[10:11], v[96:97] neg_lo:[0,1] neg_hi:[0,1]
	v_pk_mul_f32 v[96:97], v[10:11], s[12:13]
	v_pk_fma_f32 v[10:11], v[10:11], s[4:5], v[96:97] op_sel:[0,0,1] op_sel_hi:[1,0,0]
	v_pk_add_f32 v[96:97], v[12:13], v[98:99]
	v_pk_add_f32 v[12:13], v[12:13], v[98:99] neg_lo:[0,1] neg_hi:[0,1]
	v_pk_mul_f32 v[98:99], v[12:13], s[34:35]
	v_pk_fma_f32 v[12:13], v[12:13], s[8:9], v[98:99] op_sel:[0,0,1] op_sel_hi:[1,0,0]
	v_pk_add_f32 v[98:99], v[14:15], v[100:101]
	v_pk_add_f32 v[14:15], v[14:15], v[100:101] neg_lo:[0,1] neg_hi:[0,1]
	v_pk_mul_f32 v[100:101], v[14:15], s[76:77]
	v_pk_fma_f32 v[14:15], v[14:15], s[26:27], v[100:101] op_sel:[0,0,1] op_sel_hi:[1,0,0]
	v_pk_add_f32 v[100:101], v[16:17], v[102:103]
	v_pk_add_f32 v[16:17], v[16:17], v[102:103] neg_lo:[0,1] neg_hi:[0,1]
	v_pk_add_f32 v[102:103], v[18:19], v[104:105]
	v_pk_add_f32 v[18:19], v[18:19], v[104:105] neg_lo:[0,1] neg_hi:[0,1]
	v_pk_mul_f32 v[104:105], v[18:19], s[76:77]
	v_pk_fma_f32 v[18:19], v[18:19], s[26:27], v[104:105] op_sel:[0,0,1] op_sel_hi:[1,0,0] neg_lo:[1,0,0] neg_hi:[1,0,0]
	v_pk_add_f32 v[104:105], v[20:21], v[106:107]
	v_pk_add_f32 v[20:21], v[20:21], v[106:107] neg_lo:[0,1] neg_hi:[0,1]
	v_pk_mul_f32 v[106:107], v[20:21], s[34:35]
	v_pk_fma_f32 v[20:21], v[20:21], s[8:9], v[106:107] op_sel:[0,0,1] op_sel_hi:[1,0,0] neg_lo:[1,0,0] neg_hi:[1,0,0]
	v_pk_add_f32 v[106:107], v[22:23], v[108:109]
	v_pk_add_f32 v[22:23], v[22:23], v[108:109] neg_lo:[0,1] neg_hi:[0,1]
	v_pk_mul_f32 v[108:109], v[22:23], s[12:13]
	v_pk_fma_f32 v[22:23], v[22:23], s[4:5], v[108:109] op_sel:[0,0,1] op_sel_hi:[1,0,0] neg_lo:[1,0,0] neg_hi:[1,0,0]
	v_pk_add_f32 v[108:109], v[24:25], v[110:111]
	v_pk_add_f32 v[24:25], v[24:25], v[110:111] neg_lo:[0,1] neg_hi:[0,1]
	v_pk_mul_f32 v[110:111], v[24:25], s[10:11]
	v_pk_fma_f32 v[24:25], v[24:25], s[14:15], v[110:111] op_sel:[0,0,1] op_sel_hi:[1,0,0] neg_lo:[1,0,0] neg_hi:[1,0,0]
	v_pk_add_f32 v[110:111], v[26:27], v[112:113]
	v_pk_add_f32 v[26:27], v[26:27], v[112:113] neg_lo:[0,1] neg_hi:[0,1]
	v_pk_mul_f32 v[112:113], v[26:27], s[20:21]
	v_pk_fma_f32 v[26:27], v[26:27], s[86:87], v[112:113] op_sel:[0,0,1] op_sel_hi:[1,0,0] neg_lo:[1,0,0] neg_hi:[1,0,0]
	v_pk_add_f32 v[112:113], v[28:29], v[114:115]
	v_pk_add_f32 v[28:29], v[28:29], v[114:115] neg_lo:[0,1] neg_hi:[0,1]
	v_pk_mul_f32 v[114:115], v[28:29], s[18:19]
	v_pk_fma_f32 v[28:29], v[28:29], s[30:31], v[114:115] op_sel:[0,0,1] op_sel_hi:[1,0,0] neg_lo:[1,0,0] neg_hi:[1,0,0]
	s_waitcnt lgkmcnt(0)
	v_pk_add_f32 v[114:115], v[30:31], v[120:121]
	v_pk_add_f32 v[30:31], v[30:31], v[120:121] neg_lo:[0,1] neg_hi:[0,1]
	s_nop 0
	v_pk_mul_f32 v[120:121], v[30:31], s[16:17]
	v_pk_fma_f32 v[30:31], v[30:31], s[6:7], v[120:121] op_sel:[0,0,1] op_sel_hi:[1,0,0] neg_lo:[1,0,0] neg_hi:[1,0,0]
	v_pk_add_f32 v[120:121], v[124:125], v[100:101]
	v_pk_add_f32 v[100:101], v[124:125], v[100:101] neg_lo:[0,1] neg_hi:[0,1]
	v_pk_add_f32 v[124:125], v[58:59], v[102:103]
	v_pk_add_f32 v[58:59], v[58:59], v[102:103] neg_lo:[0,1] neg_hi:[0,1]
	v_pk_mul_f32 v[102:103], v[58:59], s[18:19]
	v_pk_fma_f32 v[58:59], v[58:59], s[30:31], v[102:103] op_sel:[0,0,1] op_sel_hi:[1,0,0]
	v_pk_add_f32 v[102:103], v[116:117], v[104:105]
	v_pk_add_f32 v[104:105], v[116:117], v[104:105] neg_lo:[0,1] neg_hi:[0,1]
	v_pk_mul_f32 v[116:117], v[104:105], s[10:11]
	v_pk_fma_f32 v[104:105], v[104:105], s[14:15], v[116:117] op_sel:[0,0,1] op_sel_hi:[1,0,0]
	v_pk_add_f32 v[116:117], v[118:119], v[106:107]
	v_pk_add_f32 v[106:107], v[118:119], v[106:107] neg_lo:[0,1] neg_hi:[0,1]
	v_pk_mul_f32 v[118:119], v[106:107], s[34:35]
	v_pk_fma_f32 v[106:107], v[106:107], s[8:9], v[118:119] op_sel:[0,0,1] op_sel_hi:[1,0,0]
	v_pk_add_f32 v[118:119], v[60:61], v[108:109]
	v_pk_add_f32 v[60:61], v[60:61], v[108:109] neg_lo:[0,1] neg_hi:[0,1]
	v_pk_add_f32 v[108:109], v[94:95], v[110:111]
	v_pk_add_f32 v[94:95], v[94:95], v[110:111] neg_lo:[0,1] neg_hi:[0,1]
	v_pk_mul_f32 v[110:111], v[94:95], s[34:35]
	v_pk_fma_f32 v[94:95], v[94:95], s[8:9], v[110:111] op_sel:[0,0,1] op_sel_hi:[1,0,0] neg_lo:[1,0,0] neg_hi:[1,0,0]
	v_pk_add_f32 v[110:111], v[96:97], v[112:113]
	v_pk_add_f32 v[96:97], v[96:97], v[112:113] neg_lo:[0,1] neg_hi:[0,1]
	v_pk_mul_f32 v[112:113], v[96:97], s[10:11]
	v_pk_fma_f32 v[96:97], v[96:97], s[14:15], v[112:113] op_sel:[0,0,1] op_sel_hi:[1,0,0] neg_lo:[1,0,0] neg_hi:[1,0,0]
	v_pk_add_f32 v[112:113], v[98:99], v[114:115]
	v_pk_add_f32 v[98:99], v[98:99], v[114:115] neg_lo:[0,1] neg_hi:[0,1]
	v_pk_mul_f32 v[114:115], v[98:99], s[18:19]
	v_pk_fma_f32 v[98:99], v[98:99], s[30:31], v[114:115] op_sel:[0,0,1] op_sel_hi:[1,0,0] neg_lo:[1,0,0] neg_hi:[1,0,0]
	v_pk_add_f32 v[114:115], v[0:1], v[16:17] op_sel:[0,1] op_sel_hi:[1,0] neg_hi:[0,1]
	v_pk_add_f32 v[0:1], v[0:1], v[16:17] op_sel:[0,1] op_sel_hi:[1,0] neg_lo:[0,1]
	v_pk_add_f32 v[16:17], v[2:3], v[18:19]
	v_pk_add_f32 v[2:3], v[2:3], v[18:19] neg_lo:[0,1] neg_hi:[0,1]
	v_pk_mul_f32 v[18:19], v[2:3], s[18:19]
	v_pk_fma_f32 v[2:3], v[2:3], s[30:31], v[18:19] op_sel:[0,0,1] op_sel_hi:[1,0,0]
	v_pk_add_f32 v[18:19], v[4:5], v[20:21]
	v_pk_add_f32 v[4:5], v[4:5], v[20:21] neg_lo:[0,1] neg_hi:[0,1]
	v_pk_mul_f32 v[20:21], v[4:5], s[10:11]
	v_pk_fma_f32 v[4:5], v[4:5], s[14:15], v[20:21] op_sel:[0,0,1] op_sel_hi:[1,0,0]
	v_pk_add_f32 v[20:21], v[6:7], v[22:23]
	v_pk_add_f32 v[6:7], v[6:7], v[22:23] neg_lo:[0,1] neg_hi:[0,1]
	v_pk_mul_f32 v[22:23], v[6:7], s[34:35]
	v_pk_fma_f32 v[6:7], v[6:7], s[8:9], v[22:23] op_sel:[0,0,1] op_sel_hi:[1,0,0]
	v_pk_add_f32 v[22:23], v[8:9], v[24:25]
	v_pk_add_f32 v[8:9], v[8:9], v[24:25] neg_lo:[0,1] neg_hi:[0,1]
	v_pk_add_f32 v[24:25], v[10:11], v[26:27]
	v_pk_add_f32 v[10:11], v[10:11], v[26:27] neg_lo:[0,1] neg_hi:[0,1]
	v_pk_mul_f32 v[26:27], v[10:11], s[34:35]
	v_pk_fma_f32 v[10:11], v[10:11], s[8:9], v[26:27] op_sel:[0,0,1] op_sel_hi:[1,0,0] neg_lo:[1,0,0] neg_hi:[1,0,0]
	v_pk_add_f32 v[26:27], v[12:13], v[28:29]
	v_pk_add_f32 v[12:13], v[12:13], v[28:29] neg_lo:[0,1] neg_hi:[0,1]
	v_pk_mul_f32 v[28:29], v[12:13], s[10:11]
	v_pk_fma_f32 v[12:13], v[12:13], s[14:15], v[28:29] op_sel:[0,0,1] op_sel_hi:[1,0,0] neg_lo:[1,0,0] neg_hi:[1,0,0]
	v_pk_add_f32 v[28:29], v[14:15], v[30:31]
	v_pk_add_f32 v[14:15], v[14:15], v[30:31] neg_lo:[0,1] neg_hi:[0,1]
	v_pk_mul_f32 v[30:31], v[14:15], s[18:19]
	v_pk_fma_f32 v[14:15], v[14:15], s[30:31], v[30:31] op_sel:[0,0,1] op_sel_hi:[1,0,0] neg_lo:[1,0,0] neg_hi:[1,0,0]
	v_pk_add_f32 v[30:31], v[120:121], v[118:119]
	v_pk_add_f32 v[118:119], v[120:121], v[118:119] neg_lo:[0,1] neg_hi:[0,1]
	v_pk_add_f32 v[120:121], v[124:125], v[108:109]
	v_pk_add_f32 v[108:109], v[124:125], v[108:109] neg_lo:[0,1] neg_hi:[0,1]
	v_pk_mul_f32 v[124:125], v[108:109], s[10:11]
	v_pk_fma_f32 v[108:109], v[108:109], s[14:15], v[124:125] op_sel:[0,0,1] op_sel_hi:[1,0,0]
	v_pk_add_f32 v[124:125], v[102:103], v[110:111]
	v_pk_add_f32 v[102:103], v[102:103], v[110:111] neg_lo:[0,1] neg_hi:[0,1]
	v_pk_add_f32 v[110:111], v[116:117], v[112:113]
	v_pk_add_f32 v[112:113], v[116:117], v[112:113] neg_lo:[0,1] neg_hi:[0,1]
	v_pk_mul_f32 v[116:117], v[112:113], s[10:11]
	v_pk_fma_f32 v[112:113], v[112:113], s[14:15], v[116:117] op_sel:[0,0,1] op_sel_hi:[1,0,0] neg_lo:[1,0,0] neg_hi:[1,0,0]
	v_pk_add_f32 v[116:117], v[100:101], v[60:61] op_sel:[0,1] op_sel_hi:[1,0] neg_hi:[0,1]
	v_pk_add_f32 v[60:61], v[100:101], v[60:61] op_sel:[0,1] op_sel_hi:[1,0] neg_lo:[0,1]
	v_pk_add_f32 v[100:101], v[58:59], v[94:95]
	v_pk_add_f32 v[58:59], v[58:59], v[94:95] neg_lo:[0,1] neg_hi:[0,1]
	v_pk_add_f32 v[126:127], v[108:109], v[112:113]
	v_pk_mul_f32 v[94:95], v[58:59], s[10:11]
	v_pk_fma_f32 v[58:59], v[58:59], s[14:15], v[94:95] op_sel:[0,0,1] op_sel_hi:[1,0,0]
	v_pk_add_f32 v[94:95], v[104:105], v[96:97]
	v_pk_add_f32 v[96:97], v[104:105], v[96:97] neg_lo:[0,1] neg_hi:[0,1]
	v_pk_add_f32 v[104:105], v[106:107], v[98:99]
	v_pk_add_f32 v[98:99], v[106:107], v[98:99] neg_lo:[0,1] neg_hi:[0,1]
	v_pk_mul_f32 v[106:107], v[98:99], s[10:11]
	v_pk_add_f32 v[130:131], v[60:61], v[96:97] op_sel:[0,1] op_sel_hi:[1,0] neg_hi:[0,1]
	v_pk_fma_f32 v[98:99], v[98:99], s[14:15], v[106:107] op_sel:[0,0,1] op_sel_hi:[1,0,0] neg_lo:[1,0,0] neg_hi:[1,0,0]
	v_pk_add_f32 v[106:107], v[114:115], v[22:23]
	v_pk_add_f32 v[22:23], v[114:115], v[22:23] neg_lo:[0,1] neg_hi:[0,1]
	v_pk_add_f32 v[114:115], v[16:17], v[24:25]
	v_pk_add_f32 v[16:17], v[16:17], v[24:25] neg_lo:[0,1] neg_hi:[0,1]
	v_pk_add_f32 v[132:133], v[60:61], v[96:97] op_sel:[0,1] op_sel_hi:[1,0] neg_lo:[0,1]
	v_pk_mul_f32 v[24:25], v[16:17], s[10:11]
	v_pk_add_f32 v[60:61], v[58:59], v[98:99]
	v_pk_fma_f32 v[16:17], v[16:17], s[14:15], v[24:25] op_sel:[0,0,1] op_sel_hi:[1,0,0]
	v_pk_add_f32 v[24:25], v[18:19], v[26:27]
	v_pk_add_f32 v[18:19], v[18:19], v[26:27] neg_lo:[0,1] neg_hi:[0,1]
	v_pk_add_f32 v[26:27], v[20:21], v[28:29]
	v_pk_add_f32 v[20:21], v[20:21], v[28:29] neg_lo:[0,1] neg_hi:[0,1]
	v_pk_mul_f32 v[28:29], v[20:21], s[10:11]
	v_pk_add_f32 v[58:59], v[58:59], v[98:99] neg_lo:[0,1] neg_hi:[0,1]
	v_pk_fma_f32 v[20:21], v[20:21], s[14:15], v[28:29] op_sel:[0,0,1] op_sel_hi:[1,0,0] neg_lo:[1,0,0] neg_hi:[1,0,0]
	v_pk_add_f32 v[28:29], v[0:1], v[8:9] op_sel:[0,1] op_sel_hi:[1,0] neg_hi:[0,1]
	v_pk_add_f32 v[0:1], v[0:1], v[8:9] op_sel:[0,1] op_sel_hi:[1,0] neg_lo:[0,1]
	v_pk_add_f32 v[8:9], v[2:3], v[10:11]
	v_pk_add_f32 v[2:3], v[2:3], v[10:11] neg_lo:[0,1] neg_hi:[0,1]
	v_pk_add_f32 v[134:135], v[106:107], v[24:25]
	v_pk_mul_f32 v[10:11], v[2:3], s[10:11]
	v_pk_add_f32 v[106:107], v[106:107], v[24:25] neg_lo:[0,1] neg_hi:[0,1]
	v_pk_fma_f32 v[2:3], v[2:3], s[14:15], v[10:11] op_sel:[0,0,1] op_sel_hi:[1,0,0]
	v_pk_add_f32 v[10:11], v[4:5], v[12:13]
	v_pk_add_f32 v[4:5], v[4:5], v[12:13] neg_lo:[0,1] neg_hi:[0,1]
	v_pk_add_f32 v[12:13], v[6:7], v[14:15]
	v_pk_add_f32 v[6:7], v[6:7], v[14:15] neg_lo:[0,1] neg_hi:[0,1]
	v_pk_mul_f32 v[14:15], v[6:7], s[10:11]
	v_pk_add_f32 v[24:25], v[114:115], v[26:27] neg_lo:[0,1] neg_hi:[0,1]
	v_pk_fma_f32 v[6:7], v[6:7], s[14:15], v[14:15] op_sel:[0,0,1] op_sel_hi:[1,0,0] neg_lo:[1,0,0] neg_hi:[1,0,0]
	v_pk_add_f32 v[14:15], v[30:31], v[124:125]
	v_pk_add_f32 v[30:31], v[30:31], v[124:125] neg_lo:[0,1] neg_hi:[0,1]
	v_pk_add_f32 v[124:125], v[120:121], v[110:111]
	v_pk_add_f32 v[110:111], v[120:121], v[110:111] neg_lo:[0,1] neg_hi:[0,1]
	v_pk_add_f32 v[120:121], v[118:119], v[102:103] op_sel:[0,1] op_sel_hi:[1,0] neg_hi:[0,1]
	v_pk_add_f32 v[118:119], v[118:119], v[102:103] op_sel:[0,1] op_sel_hi:[1,0] neg_lo:[0,1]
	v_pk_add_f32 v[102:103], v[108:109], v[112:113] neg_lo:[0,1] neg_hi:[0,1]
	v_pk_add_f32 v[112:113], v[116:117], v[94:95]
	v_pk_add_f32 v[94:95], v[116:117], v[94:95] neg_lo:[0,1] neg_hi:[0,1]
	v_pk_add_f32 v[116:117], v[100:101], v[104:105]
	v_pk_add_f32 v[100:101], v[100:101], v[104:105] neg_lo:[0,1] neg_hi:[0,1]
	v_pk_add_f32 v[138:139], v[22:23], v[18:19] op_sel:[0,1] op_sel_hi:[1,0] neg_hi:[0,1]
	v_pk_add_f32 v[140:141], v[22:23], v[18:19] op_sel:[0,1] op_sel_hi:[1,0] neg_lo:[0,1]
	v_pk_add_f32 v[18:19], v[16:17], v[20:21]
	v_pk_add_f32 v[16:17], v[16:17], v[20:21] neg_lo:[0,1] neg_hi:[0,1]
	v_pk_add_f32 v[144:145], v[28:29], v[10:11]
	v_pk_add_f32 v[158:159], v[28:29], v[10:11] neg_lo:[0,1] neg_hi:[0,1]
	v_pk_add_f32 v[10:11], v[8:9], v[12:13]
	v_pk_add_f32 v[8:9], v[8:9], v[12:13] neg_lo:[0,1] neg_hi:[0,1]
	v_pk_add_f32 v[162:163], v[0:1], v[4:5] op_sel:[0,1] op_sel_hi:[1,0] neg_hi:[0,1]
	v_pk_add_f32 v[164:165], v[0:1], v[4:5] op_sel:[0,1] op_sel_hi:[1,0] neg_lo:[0,1]
	v_pk_add_f32 v[0:1], v[2:3], v[6:7] neg_lo:[0,1] neg_hi:[0,1]
	v_pk_mul_f32 v[108:109], v[102:103], s[22:23]
	v_pk_mul_f32 v[128:129], v[100:101], s[22:23]
	v_pk_add_f32 v[136:137], v[114:115], v[26:27]
	v_pk_mul_f32 v[114:115], v[24:25], s[22:23]
	v_pk_mul_f32 v[142:143], v[16:17], s[22:23]
	v_pk_mul_f32 v[160:161], v[8:9], s[22:23]
	v_pk_add_f32 v[166:167], v[2:3], v[6:7]
	v_pk_mul_f32 v[168:169], v[0:1], s[22:23]
	v_pk_add_f32 v[28:29], v[14:15], v[124:125]
	v_pk_add_f32 v[104:105], v[14:15], v[124:125] neg_lo:[0,1] neg_hi:[0,1]
	v_pk_add_f32 v[24:25], v[30:31], v[110:111] op_sel:[0,1] op_sel_hi:[1,0] neg_hi:[0,1]
	v_pk_add_f32 v[102:103], v[30:31], v[110:111] op_sel:[0,1] op_sel_hi:[1,0] neg_lo:[0,1]
	v_pk_add_f32 v[20:21], v[120:121], v[126:127]
	v_pk_add_f32 v[100:101], v[120:121], v[126:127] neg_lo:[0,1] neg_hi:[0,1]
	v_pk_add_f32 v[16:17], v[118:119], v[108:109] op_sel:[0,1] op_sel_hi:[1,0]
	v_pk_add_f32 v[98:99], v[118:119], v[108:109] op_sel:[0,1] op_sel_hi:[1,0] neg_lo:[0,1] neg_hi:[0,1]
	v_pk_add_f32 v[12:13], v[112:113], v[116:117]
	v_pk_add_f32 v[96:97], v[112:113], v[116:117] neg_lo:[0,1] neg_hi:[0,1]
	v_pk_add_f32 v[8:9], v[94:95], v[128:129] op_sel:[0,1] op_sel_hi:[1,0]
	v_pk_add_f32 v[94:95], v[94:95], v[128:129] op_sel:[0,1] op_sel_hi:[1,0] neg_lo:[0,1] neg_hi:[0,1]
	v_pk_add_f32 v[4:5], v[130:131], v[60:61]
	v_pk_add_f32 v[60:61], v[130:131], v[60:61] neg_lo:[0,1] neg_hi:[0,1]
	v_pk_add_f32 v[0:1], v[132:133], v[58:59] op_sel:[0,1] op_sel_hi:[1,0] neg_hi:[0,1]
	v_pk_add_f32 v[58:59], v[132:133], v[58:59] op_sel:[0,1] op_sel_hi:[1,0] neg_lo:[0,1]
	v_pk_add_f32 v[30:31], v[134:135], v[136:137]
	v_pk_add_f32 v[120:121], v[134:135], v[136:137] neg_lo:[0,1] neg_hi:[0,1]
	v_pk_add_f32 v[26:27], v[106:107], v[114:115] op_sel:[0,1] op_sel_hi:[1,0]
	v_pk_add_f32 v[118:119], v[106:107], v[114:115] op_sel:[0,1] op_sel_hi:[1,0] neg_lo:[0,1] neg_hi:[0,1]
	v_pk_add_f32 v[22:23], v[138:139], v[18:19]
	v_pk_add_f32 v[116:117], v[138:139], v[18:19] neg_lo:[0,1] neg_hi:[0,1]
	v_pk_add_f32 v[18:19], v[140:141], v[142:143] op_sel:[0,1] op_sel_hi:[1,0]
	v_pk_add_f32 v[114:115], v[140:141], v[142:143] op_sel:[0,1] op_sel_hi:[1,0] neg_lo:[0,1] neg_hi:[0,1]
	v_pk_add_f32 v[14:15], v[144:145], v[10:11]
	v_pk_add_f32 v[112:113], v[144:145], v[10:11] neg_lo:[0,1] neg_hi:[0,1]
	v_pk_add_f32 v[10:11], v[158:159], v[160:161] op_sel:[0,1] op_sel_hi:[1,0]
	v_pk_add_f32 v[110:111], v[158:159], v[160:161] op_sel:[0,1] op_sel_hi:[1,0] neg_lo:[0,1] neg_hi:[0,1]
	v_pk_add_f32 v[6:7], v[162:163], v[166:167]
	v_pk_add_f32 v[108:109], v[162:163], v[166:167] neg_lo:[0,1] neg_hi:[0,1]
	v_pk_add_f32 v[2:3], v[164:165], v[168:169] op_sel:[0,1] op_sel_hi:[1,0]
	v_pk_add_f32 v[106:107], v[164:165], v[168:169] op_sel:[0,1] op_sel_hi:[1,0] neg_lo:[0,1] neg_hi:[0,1]

.LBB0_669:
	s_or_b64 exec, exec, s[4:5]
	v_mov_b32_e32 v41, v32
	s_waitcnt lgkmcnt(0)
	s_barrier
	s_mov_b32 s11, s14
	v_and_b32_e32 v98, 31, v41
	v_cvt_f32_ubyte0_e32 v24, v98
	v_mul_f32_e32 v60, 0x3b000000, v24
	v_sin_f32_e32 v24, v60
	v_ashrrev_i32_e32 v0, 4, v41
	v_lshlrev_b32_e32 v0, 3, v0
	v_lshlrev_b32_e32 v1, 3, v41
	v_cos_f32_e32 v60, v60
	v_add3_u32 v25, 0, v0, v1
	ds_read_b64 v[0:1], v25
	ds_read_b64 v[2:3], v25 offset:4352
	ds_read_b64 v[4:5], v25 offset:8704
	ds_read_b64 v[6:7], v25 offset:13056
	ds_read_b64 v[8:9], v25 offset:17408
	ds_read_b64 v[10:11], v25 offset:21760
	ds_read_b64 v[12:13], v25 offset:26112
	ds_read_b64 v[14:15], v25 offset:30464
	ds_read_b64 v[16:17], v25 offset:34816
	ds_read_b64 v[18:19], v25 offset:39168
	ds_read_b64 v[20:21], v25 offset:43520
	ds_read_b64 v[22:23], v25 offset:47872
	v_xor_b32_e32 v61, 0x80000000, v24
	s_waitcnt lgkmcnt(10)
	v_pk_mul_f32 v[94:95], v[2:3], v[24:25] op_sel:[1,0] op_sel_hi:[0,0] neg_hi:[0,1]
	v_pk_fma_f32 v[2:3], v[2:3], v[60:61], v[94:95] op_sel_hi:[1,0,1]
	v_pk_mul_f32 v[94:95], v[24:25], v[60:61] op_sel:[0,1] op_sel_hi:[0,0] neg_hi:[1,0]
	v_pk_fma_f32 v[94:95], v[60:61], v[60:61], v[94:95] op_sel_hi:[0,1,1]
	ds_read_b64 v[26:27], v25 offset:52224
	ds_read_b64 v[28:29], v25 offset:56576
	ds_read_b64 v[30:31], v25 offset:60928
	ds_read_b64 v[58:59], v25 offset:65280
	s_waitcnt lgkmcnt(13)
	v_pk_mul_f32 v[96:97], v[4:5], v[94:95] op_sel:[1,1] op_sel_hi:[0,1] neg_lo:[0,1]
	v_pk_fma_f32 v[4:5], v[4:5], v[94:95], v[96:97] op_sel_hi:[1,0,1]
	v_pk_mul_f32 v[96:97], v[24:25], v[94:95] op_sel:[0,1] op_sel_hi:[0,0] neg_hi:[1,0]
	v_pk_fma_f32 v[94:95], v[60:61], v[94:95], v[96:97] op_sel_hi:[0,1,1]
	s_mov_b32 s35, s30
	s_waitcnt lgkmcnt(12)
	v_pk_mul_f32 v[96:97], v[6:7], v[94:95] op_sel:[1,1] op_sel_hi:[0,1] neg_lo:[0,1]
	v_pk_fma_f32 v[6:7], v[6:7], v[94:95], v[96:97] op_sel_hi:[1,0,1]
	v_pk_mul_f32 v[96:97], v[24:25], v[94:95] op_sel:[0,1] op_sel_hi:[0,0] neg_hi:[1,0]
	v_pk_fma_f32 v[94:95], v[60:61], v[94:95], v[96:97] op_sel_hi:[0,1,1]
	s_mov_b32 s26, s19
	s_waitcnt lgkmcnt(11)
	v_pk_mul_f32 v[96:97], v[8:9], v[94:95] op_sel:[1,1] op_sel_hi:[0,1] neg_lo:[0,1]
	v_pk_fma_f32 v[8:9], v[8:9], v[94:95], v[96:97] op_sel_hi:[1,0,1]
	v_pk_mul_f32 v[96:97], v[24:25], v[94:95] op_sel:[0,1] op_sel_hi:[0,0] neg_hi:[1,0]
	v_pk_fma_f32 v[94:95], v[60:61], v[94:95], v[96:97] op_sel_hi:[0,1,1]
	s_waitcnt lgkmcnt(0)
	v_pk_mul_f32 v[96:97], v[10:11], v[94:95] op_sel:[1,1] op_sel_hi:[0,1] neg_lo:[0,1]
	v_pk_fma_f32 v[10:11], v[10:11], v[94:95], v[96:97] op_sel_hi:[1,0,1]
	v_pk_mul_f32 v[96:97], v[24:25], v[94:95] op_sel:[0,1] op_sel_hi:[0,0] neg_hi:[1,0]
	v_pk_fma_f32 v[94:95], v[60:61], v[94:95], v[96:97] op_sel_hi:[0,1,1]
	s_barrier
	v_pk_mul_f32 v[96:97], v[12:13], v[94:95] op_sel:[1,1] op_sel_hi:[0,1] neg_lo:[0,1]
	v_pk_fma_f32 v[12:13], v[12:13], v[94:95], v[96:97] op_sel_hi:[1,0,1]
	v_pk_mul_f32 v[96:97], v[24:25], v[94:95] op_sel:[0,1] op_sel_hi:[0,0] neg_hi:[1,0]
	v_pk_fma_f32 v[94:95], v[60:61], v[94:95], v[96:97] op_sel_hi:[0,1,1]
	v_pk_mul_f32 v[96:97], v[14:15], v[94:95] op_sel:[1,1] op_sel_hi:[0,1] neg_lo:[0,1]
	v_pk_fma_f32 v[14:15], v[14:15], v[94:95], v[96:97] op_sel_hi:[1,0,1]
	v_pk_mul_f32 v[96:97], v[24:25], v[94:95] op_sel:[0,1] op_sel_hi:[0,0] neg_hi:[1,0]
	v_pk_fma_f32 v[94:95], v[60:61], v[94:95], v[96:97] op_sel_hi:[0,1,1]
	s_mov_b32 s4, 0
	v_pk_mul_f32 v[96:97], v[16:17], v[94:95] op_sel:[1,1] op_sel_hi:[0,1] neg_lo:[0,1]
	v_pk_fma_f32 v[16:17], v[16:17], v[94:95], v[96:97] op_sel_hi:[1,0,1]
	v_pk_mul_f32 v[96:97], v[24:25], v[94:95] op_sel:[0,1] op_sel_hi:[0,0] neg_hi:[1,0]
	v_pk_fma_f32 v[94:95], v[60:61], v[94:95], v[96:97] op_sel_hi:[0,1,1]
	v_pk_mul_f32 v[96:97], v[18:19], v[94:95] op_sel:[1,1] op_sel_hi:[0,1] neg_lo:[0,1]
	v_pk_fma_f32 v[18:19], v[18:19], v[94:95], v[96:97] op_sel_hi:[1,0,1]
	v_pk_mul_f32 v[96:97], v[24:25], v[94:95] op_sel:[0,1] op_sel_hi:[0,0] neg_hi:[1,0]
	v_pk_fma_f32 v[94:95], v[60:61], v[94:95], v[96:97] op_sel_hi:[0,1,1]
	v_pk_mul_f32 v[96:97], v[20:21], v[94:95] op_sel:[1,1] op_sel_hi:[0,1] neg_lo:[0,1]
	v_pk_fma_f32 v[20:21], v[20:21], v[94:95], v[96:97] op_sel_hi:[1,0,1]
	v_pk_mul_f32 v[96:97], v[24:25], v[94:95] op_sel:[0,1] op_sel_hi:[0,0] neg_hi:[1,0]
	v_pk_fma_f32 v[94:95], v[60:61], v[94:95], v[96:97] op_sel_hi:[0,1,1]
	v_pk_mul_f32 v[96:97], v[22:23], v[94:95] op_sel:[1,1] op_sel_hi:[0,1] neg_lo:[0,1]
	v_pk_fma_f32 v[22:23], v[22:23], v[94:95], v[96:97] op_sel_hi:[1,0,1]
	v_pk_mul_f32 v[96:97], v[24:25], v[94:95] op_sel:[0,1] op_sel_hi:[0,0] neg_hi:[1,0]
	v_pk_fma_f32 v[94:95], v[60:61], v[94:95], v[96:97] op_sel_hi:[0,1,1]
	v_pk_mul_f32 v[96:97], v[26:27], v[94:95] op_sel:[1,1] op_sel_hi:[0,1] neg_lo:[0,1]
	v_pk_fma_f32 v[26:27], v[26:27], v[94:95], v[96:97] op_sel_hi:[1,0,1]
	v_pk_mul_f32 v[96:97], v[24:25], v[94:95] op_sel:[0,1] op_sel_hi:[0,0] neg_hi:[1,0]
	v_pk_fma_f32 v[94:95], v[60:61], v[94:95], v[96:97] op_sel_hi:[0,1,1]
	v_pk_mul_f32 v[96:97], v[28:29], v[94:95] op_sel:[1,1] op_sel_hi:[0,1] neg_lo:[0,1]
	v_pk_fma_f32 v[28:29], v[28:29], v[94:95], v[96:97] op_sel_hi:[1,0,1]
	v_pk_mul_f32 v[96:97], v[24:25], v[94:95] op_sel:[0,1] op_sel_hi:[0,0] neg_hi:[1,0]
	v_pk_fma_f32 v[94:95], v[60:61], v[94:95], v[96:97] op_sel_hi:[0,1,1]
	v_pk_mul_f32 v[24:25], v[24:25], v[94:95] op_sel:[0,1] op_sel_hi:[0,0] neg_hi:[1,0]
	v_pk_fma_f32 v[24:25], v[60:61], v[94:95], v[24:25] op_sel_hi:[0,1,1]
	v_pk_mul_f32 v[60:61], v[58:59], v[24:25] op_sel:[1,1] op_sel_hi:[0,1] neg_lo:[0,1]
	v_pk_fma_f32 v[24:25], v[58:59], v[24:25], v[60:61] op_sel_hi:[1,0,1]
	v_pk_add_f32 v[58:59], v[0:1], v[16:17]
	v_pk_add_f32 v[0:1], v[0:1], v[16:17] neg_lo:[0,1] neg_hi:[0,1]
	v_pk_add_f32 v[16:17], v[2:3], v[18:19]
	v_pk_add_f32 v[2:3], v[2:3], v[18:19] neg_lo:[0,1] neg_hi:[0,1]
	v_pk_mul_f32 v[96:97], v[30:31], v[94:95] op_sel:[1,1] op_sel_hi:[0,1] neg_lo:[0,1]
	v_pk_mul_f32 v[18:19], v[2:3], s[18:19]
	v_pk_fma_f32 v[30:31], v[30:31], v[94:95], v[96:97] op_sel_hi:[1,0,1]
	v_pk_fma_f32 v[2:3], v[2:3], s[30:31], v[18:19] op_sel:[0,0,1] op_sel_hi:[1,0,0]
	v_pk_add_f32 v[18:19], v[4:5], v[20:21]
	v_pk_add_f32 v[4:5], v[4:5], v[20:21] neg_lo:[0,1] neg_hi:[0,1]
	v_pk_mul_f32 v[20:21], v[4:5], s[10:11]
	v_pk_fma_f32 v[4:5], v[4:5], s[14:15], v[20:21] op_sel:[0,0,1] op_sel_hi:[1,0,0]
	v_pk_add_f32 v[20:21], v[6:7], v[22:23]
	v_pk_add_f32 v[6:7], v[6:7], v[22:23] neg_lo:[0,1] neg_hi:[0,1]
	v_pk_mul_f32 v[22:23], v[6:7], s[34:35]
	v_pk_fma_f32 v[6:7], v[6:7], s[26:27], v[22:23] op_sel:[0,0,1] op_sel_hi:[1,0,0]
	v_pk_add_f32 v[22:23], v[8:9], v[26:27]
	v_pk_add_f32 v[8:9], v[8:9], v[26:27] neg_lo:[0,1] neg_hi:[0,1]
	v_pk_add_f32 v[26:27], v[10:11], v[28:29]
	v_pk_add_f32 v[10:11], v[10:11], v[28:29] neg_lo:[0,1] neg_hi:[0,1]
	v_pk_mul_f32 v[28:29], v[10:11], s[34:35]
	v_pk_fma_f32 v[10:11], v[10:11], s[26:27], v[28:29] op_sel:[0,0,1] op_sel_hi:[1,0,0] neg_lo:[1,0,0] neg_hi:[1,0,0]
	v_pk_add_f32 v[28:29], v[12:13], v[30:31]
	v_pk_add_f32 v[12:13], v[12:13], v[30:31] neg_lo:[0,1] neg_hi:[0,1]
	v_pk_mul_f32 v[30:31], v[12:13], s[10:11]
	v_pk_fma_f32 v[12:13], v[12:13], s[14:15], v[30:31] op_sel:[0,0,1] op_sel_hi:[1,0,0] neg_lo:[1,0,0] neg_hi:[1,0,0]
	v_pk_add_f32 v[30:31], v[14:15], v[24:25]
	v_pk_add_f32 v[14:15], v[14:15], v[24:25] neg_lo:[0,1] neg_hi:[0,1]
	v_pk_mul_f32 v[24:25], v[14:15], s[18:19]
	v_pk_fma_f32 v[14:15], v[14:15], s[30:31], v[24:25] op_sel:[0,0,1] op_sel_hi:[1,0,0] neg_lo:[1,0,0] neg_hi:[1,0,0]
	v_pk_add_f32 v[24:25], v[58:59], v[22:23]
	v_pk_add_f32 v[22:23], v[58:59], v[22:23] neg_lo:[0,1] neg_hi:[0,1]
	v_pk_add_f32 v[58:59], v[16:17], v[26:27]
	v_pk_add_f32 v[16:17], v[16:17], v[26:27] neg_lo:[0,1] neg_hi:[0,1]
	v_pk_mul_f32 v[26:27], v[16:17], s[10:11]
	v_pk_fma_f32 v[16:17], v[16:17], s[14:15], v[26:27] op_sel:[0,0,1] op_sel_hi:[1,0,0]
	v_pk_add_f32 v[26:27], v[18:19], v[28:29]
	v_pk_add_f32 v[18:19], v[18:19], v[28:29] neg_lo:[0,1] neg_hi:[0,1]
	v_pk_add_f32 v[28:29], v[20:21], v[30:31]
	v_pk_add_f32 v[20:21], v[20:21], v[30:31] neg_lo:[0,1] neg_hi:[0,1]
	v_pk_mul_f32 v[30:31], v[20:21], s[10:11]
	v_pk_fma_f32 v[20:21], v[20:21], s[14:15], v[30:31] op_sel:[0,0,1] op_sel_hi:[1,0,0] neg_lo:[1,0,0] neg_hi:[1,0,0]
	v_pk_add_f32 v[30:31], v[0:1], v[8:9] op_sel:[0,1] op_sel_hi:[1,0] neg_hi:[0,1]
	v_pk_add_f32 v[0:1], v[0:1], v[8:9] op_sel:[0,1] op_sel_hi:[1,0] neg_lo:[0,1]
	v_pk_add_f32 v[8:9], v[2:3], v[10:11]
	v_pk_add_f32 v[2:3], v[2:3], v[10:11] neg_lo:[0,1] neg_hi:[0,1]
	v_pk_mul_f32 v[10:11], v[2:3], s[10:11]
	v_pk_fma_f32 v[2:3], v[2:3], s[14:15], v[10:11] op_sel:[0,0,1] op_sel_hi:[1,0,0]
	v_pk_add_f32 v[10:11], v[4:5], v[12:13]
	v_pk_add_f32 v[4:5], v[4:5], v[12:13] neg_lo:[0,1] neg_hi:[0,1]
	v_pk_add_f32 v[12:13], v[6:7], v[14:15]
	v_pk_add_f32 v[6:7], v[6:7], v[14:15] neg_lo:[0,1] neg_hi:[0,1]
	v_pk_mul_f32 v[14:15], v[6:7], s[10:11]
	v_pk_fma_f32 v[6:7], v[6:7], s[14:15], v[14:15] op_sel:[0,0,1] op_sel_hi:[1,0,0] neg_lo:[1,0,0] neg_hi:[1,0,0]
	v_pk_add_f32 v[14:15], v[24:25], v[26:27]
	v_pk_add_f32 v[24:25], v[24:25], v[26:27] neg_lo:[0,1] neg_hi:[0,1]
	v_pk_add_f32 v[26:27], v[58:59], v[28:29]
	v_pk_add_f32 v[28:29], v[58:59], v[28:29] neg_lo:[0,1] neg_hi:[0,1]
	v_pk_add_f32 v[58:59], v[22:23], v[18:19] op_sel:[0,1] op_sel_hi:[1,0] neg_hi:[0,1]
	v_pk_add_f32 v[18:19], v[22:23], v[18:19] op_sel:[0,1] op_sel_hi:[1,0] neg_lo:[0,1]
	v_pk_add_f32 v[22:23], v[16:17], v[20:21]
	v_pk_add_f32 v[16:17], v[16:17], v[20:21] neg_lo:[0,1] neg_hi:[0,1]
	v_pk_add_f32 v[20:21], v[30:31], v[10:11]
	v_pk_add_f32 v[10:11], v[30:31], v[10:11] neg_lo:[0,1] neg_hi:[0,1]
	v_pk_add_f32 v[30:31], v[8:9], v[12:13]
	v_pk_add_f32 v[8:9], v[8:9], v[12:13] neg_lo:[0,1] neg_hi:[0,1]
	v_pk_add_f32 v[12:13], v[0:1], v[4:5] op_sel:[0,1] op_sel_hi:[1,0] neg_hi:[0,1]
	v_pk_add_f32 v[0:1], v[0:1], v[4:5] op_sel:[0,1] op_sel_hi:[1,0] neg_lo:[0,1]
	v_pk_add_f32 v[4:5], v[2:3], v[6:7]
	v_pk_add_f32 v[2:3], v[2:3], v[6:7] neg_lo:[0,1] neg_hi:[0,1]
	v_pk_mul_f32 v[2:3], v[2:3], s[22:23]
	v_pk_add_f32 v[6:7], v[14:15], v[26:27]
	v_pk_add_f32 v[14:15], v[14:15], v[26:27] neg_lo:[0,1] neg_hi:[0,1]
	v_pk_add_f32 v[26:27], v[24:25], v[28:29] op_sel:[0,1] op_sel_hi:[1,0] neg_hi:[0,1]
	v_pk_add_f32 v[24:25], v[24:25], v[28:29] op_sel:[0,1] op_sel_hi:[1,0] neg_lo:[0,1]
	v_pk_add_f32 v[28:29], v[58:59], v[22:23]
	v_pk_add_f32 v[22:23], v[58:59], v[22:23] neg_lo:[0,1] neg_hi:[0,1]
	v_pk_add_f32 v[58:59], v[18:19], v[16:17] op_sel:[0,1] op_sel_hi:[1,0] neg_hi:[0,1]
	v_pk_add_f32 v[16:17], v[18:19], v[16:17] op_sel:[0,1] op_sel_hi:[1,0] neg_lo:[0,1]
	v_pk_add_f32 v[18:19], v[20:21], v[30:31]
	v_pk_add_f32 v[20:21], v[20:21], v[30:31] neg_lo:[0,1] neg_hi:[0,1]
	v_pk_add_f32 v[30:31], v[10:11], v[8:9] op_sel:[0,1] op_sel_hi:[1,0] neg_hi:[0,1]
	v_pk_add_f32 v[8:9], v[10:11], v[8:9] op_sel:[0,1] op_sel_hi:[1,0] neg_lo:[0,1]
	v_pk_add_f32 v[10:11], v[12:13], v[4:5]
	v_pk_add_f32 v[4:5], v[12:13], v[4:5] neg_lo:[0,1] neg_hi:[0,1]
	v_pk_add_f32 v[12:13], v[0:1], v[2:3] op_sel:[0,1] op_sel_hi:[1,0]
	v_pk_add_f32 v[0:1], v[0:1], v[2:3] op_sel:[0,1] op_sel_hi:[1,0] neg_lo:[0,1] neg_hi:[0,1]
	v_lshlrev_b32_e32 v2, 4, v41
	v_and_or_b32 v2, v2, s7, v98
	v_ashrrev_i32_e32 v3, 4, v2
	v_lshlrev_b32_e32 v3, 3, v3
	v_lshlrev_b32_e32 v2, 3, v2
	v_add3_u32 v2, 0, v3, v2
	v_add_u32_e32 v3, 0x800, v2
	v_mov_b32_e32 v41, v32
	ds_write2_b64 v2, v[6:7], v[18:19] offset1:34
	ds_write2_b64 v3, v[14:15], v[20:21] offset0:16 offset1:50
	ds_write2_b64 v2, v[26:27], v[30:31] offset0:136 offset1:170
	ds_write2_b64 v3, v[24:25], v[8:9] offset0:152 offset1:186
	ds_write2_b64 v2, v[28:29], v[10:11] offset0:68 offset1:102
	ds_write2_b64 v3, v[22:23], v[4:5] offset0:84 offset1:118
	ds_write2_b64 v2, v[58:59], v[12:13] offset0:204 offset1:238
	ds_write2_b64 v3, v[16:17], v[0:1] offset0:220 offset1:254
	s_waitcnt lgkmcnt(0)
	s_barrier
	s_nop 0
	v_and_b32_e32 v98, 0x1ff, v41
	v_cvt_f32_u32_e32 v24, v98
	v_ashrrev_i32_e32 v0, 4, v41
	v_lshlrev_b32_e32 v0, 3, v0
	v_lshlrev_b32_e32 v1, 3, v41
	v_mul_f32_e32 v60, 0x39000000, v24
	v_sin_f32_e32 v24, v60
	v_cos_f32_e32 v60, v60
	v_add3_u32 v25, 0, v0, v1
	ds_read_b64 v[0:1], v25
	ds_read_b64 v[2:3], v25 offset:4352
	ds_read_b64 v[4:5], v25 offset:8704
	ds_read_b64 v[6:7], v25 offset:13056
	ds_read_b64 v[8:9], v25 offset:17408
	ds_read_b64 v[10:11], v25 offset:21760
	ds_read_b64 v[12:13], v25 offset:26112
	ds_read_b64 v[14:15], v25 offset:30464
	v_xor_b32_e32 v61, 0x80000000, v24
	s_waitcnt lgkmcnt(6)
	v_pk_mul_f32 v[94:95], v[2:3], v[24:25] op_sel:[1,0] op_sel_hi:[0,0] neg_hi:[0,1]
	v_pk_fma_f32 v[2:3], v[2:3], v[60:61], v[94:95] op_sel_hi:[1,0,1]
	v_pk_mul_f32 v[94:95], v[24:25], v[60:61] op_sel:[0,1] op_sel_hi:[0,0] neg_hi:[1,0]
	v_pk_fma_f32 v[94:95], v[60:61], v[60:61], v[94:95] op_sel_hi:[0,1,1]
	ds_read_b64 v[16:17], v25 offset:34816
	ds_read_b64 v[18:19], v25 offset:39168
	ds_read_b64 v[20:21], v25 offset:43520
	ds_read_b64 v[22:23], v25 offset:47872
	s_waitcnt lgkmcnt(9)
	v_pk_mul_f32 v[96:97], v[4:5], v[94:95] op_sel:[1,1] op_sel_hi:[0,1] neg_lo:[0,1]
	v_pk_fma_f32 v[4:5], v[4:5], v[94:95], v[96:97] op_sel_hi:[1,0,1]
	v_pk_mul_f32 v[96:97], v[24:25], v[94:95] op_sel:[0,1] op_sel_hi:[0,0] neg_hi:[1,0]
	v_pk_fma_f32 v[94:95], v[60:61], v[94:95], v[96:97] op_sel_hi:[0,1,1]
	ds_read_b64 v[26:27], v25 offset:52224
	ds_read_b64 v[28:29], v25 offset:56576
	ds_read_b64 v[30:31], v25 offset:60928
	ds_read_b64 v[58:59], v25 offset:65280
	s_waitcnt lgkmcnt(12)
	v_pk_mul_f32 v[96:97], v[6:7], v[94:95] op_sel:[1,1] op_sel_hi:[0,1] neg_lo:[0,1]
	v_pk_fma_f32 v[6:7], v[6:7], v[94:95], v[96:97] op_sel_hi:[1,0,1]
	v_pk_mul_f32 v[96:97], v[24:25], v[94:95] op_sel:[0,1] op_sel_hi:[0,0] neg_hi:[1,0]
	v_pk_fma_f32 v[94:95], v[60:61], v[94:95], v[96:97] op_sel_hi:[0,1,1]
	s_waitcnt lgkmcnt(0)
	v_pk_mul_f32 v[96:97], v[8:9], v[94:95] op_sel:[1,1] op_sel_hi:[0,1] neg_lo:[0,1]
	v_pk_fma_f32 v[8:9], v[8:9], v[94:95], v[96:97] op_sel_hi:[1,0,1]
	v_pk_mul_f32 v[96:97], v[24:25], v[94:95] op_sel:[0,1] op_sel_hi:[0,0] neg_hi:[1,0]
	v_pk_fma_f32 v[94:95], v[60:61], v[94:95], v[96:97] op_sel_hi:[0,1,1]
	s_barrier
	v_pk_mul_f32 v[96:97], v[10:11], v[94:95] op_sel:[1,1] op_sel_hi:[0,1] neg_lo:[0,1]
	v_pk_fma_f32 v[10:11], v[10:11], v[94:95], v[96:97] op_sel_hi:[1,0,1]
	v_pk_mul_f32 v[96:97], v[24:25], v[94:95] op_sel:[0,1] op_sel_hi:[0,0] neg_hi:[1,0]
	v_pk_fma_f32 v[94:95], v[60:61], v[94:95], v[96:97] op_sel_hi:[0,1,1]
	v_pk_mul_f32 v[96:97], v[12:13], v[94:95] op_sel:[1,1] op_sel_hi:[0,1] neg_lo:[0,1]
	v_pk_fma_f32 v[12:13], v[12:13], v[94:95], v[96:97] op_sel_hi:[1,0,1]
	v_pk_mul_f32 v[96:97], v[24:25], v[94:95] op_sel:[0,1] op_sel_hi:[0,0] neg_hi:[1,0]
	v_pk_fma_f32 v[94:95], v[60:61], v[94:95], v[96:97] op_sel_hi:[0,1,1]
	v_pk_mul_f32 v[96:97], v[14:15], v[94:95] op_sel:[1,1] op_sel_hi:[0,1] neg_lo:[0,1]
	v_pk_fma_f32 v[14:15], v[14:15], v[94:95], v[96:97] op_sel_hi:[1,0,1]
	v_pk_mul_f32 v[96:97], v[24:25], v[94:95] op_sel:[0,1] op_sel_hi:[0,0] neg_hi:[1,0]
	v_pk_fma_f32 v[94:95], v[60:61], v[94:95], v[96:97] op_sel_hi:[0,1,1]
	v_pk_mul_f32 v[96:97], v[16:17], v[94:95] op_sel:[1,1] op_sel_hi:[0,1] neg_lo:[0,1]
	v_pk_fma_f32 v[16:17], v[16:17], v[94:95], v[96:97] op_sel_hi:[1,0,1]
	v_pk_mul_f32 v[96:97], v[24:25], v[94:95] op_sel:[0,1] op_sel_hi:[0,0] neg_hi:[1,0]
	v_pk_fma_f32 v[94:95], v[60:61], v[94:95], v[96:97] op_sel_hi:[0,1,1]
	v_pk_mul_f32 v[96:97], v[18:19], v[94:95] op_sel:[1,1] op_sel_hi:[0,1] neg_lo:[0,1]
	v_pk_fma_f32 v[18:19], v[18:19], v[94:95], v[96:97] op_sel_hi:[1,0,1]
	v_pk_mul_f32 v[96:97], v[24:25], v[94:95] op_sel:[0,1] op_sel_hi:[0,0] neg_hi:[1,0]
	v_pk_fma_f32 v[94:95], v[60:61], v[94:95], v[96:97] op_sel_hi:[0,1,1]
	v_pk_mul_f32 v[96:97], v[20:21], v[94:95] op_sel:[1,1] op_sel_hi:[0,1] neg_lo:[0,1]
	v_pk_fma_f32 v[20:21], v[20:21], v[94:95], v[96:97] op_sel_hi:[1,0,1]
	v_pk_mul_f32 v[96:97], v[24:25], v[94:95] op_sel:[0,1] op_sel_hi:[0,0] neg_hi:[1,0]
	v_pk_fma_f32 v[94:95], v[60:61], v[94:95], v[96:97] op_sel_hi:[0,1,1]
	v_pk_mul_f32 v[96:97], v[22:23], v[94:95] op_sel:[1,1] op_sel_hi:[0,1] neg_lo:[0,1]
	v_pk_fma_f32 v[22:23], v[22:23], v[94:95], v[96:97] op_sel_hi:[1,0,1]
	v_pk_mul_f32 v[96:97], v[24:25], v[94:95] op_sel:[0,1] op_sel_hi:[0,0] neg_hi:[1,0]
	v_pk_fma_f32 v[94:95], v[60:61], v[94:95], v[96:97] op_sel_hi:[0,1,1]
	v_pk_mul_f32 v[96:97], v[26:27], v[94:95] op_sel:[1,1] op_sel_hi:[0,1] neg_lo:[0,1]
	v_pk_fma_f32 v[26:27], v[26:27], v[94:95], v[96:97] op_sel_hi:[1,0,1]
	v_pk_mul_f32 v[96:97], v[24:25], v[94:95] op_sel:[0,1] op_sel_hi:[0,0] neg_hi:[1,0]
	v_pk_fma_f32 v[94:95], v[60:61], v[94:95], v[96:97] op_sel_hi:[0,1,1]
	v_pk_mul_f32 v[96:97], v[28:29], v[94:95] op_sel:[1,1] op_sel_hi:[0,1] neg_lo:[0,1]
	v_pk_fma_f32 v[28:29], v[28:29], v[94:95], v[96:97] op_sel_hi:[1,0,1]
	v_pk_mul_f32 v[96:97], v[24:25], v[94:95] op_sel:[0,1] op_sel_hi:[0,0] neg_hi:[1,0]
	v_pk_fma_f32 v[94:95], v[60:61], v[94:95], v[96:97] op_sel_hi:[0,1,1]
	v_pk_mul_f32 v[24:25], v[24:25], v[94:95] op_sel:[0,1] op_sel_hi:[0,0] neg_hi:[1,0]
	v_pk_fma_f32 v[24:25], v[60:61], v[94:95], v[24:25] op_sel_hi:[0,1,1]
	v_pk_mul_f32 v[60:61], v[58:59], v[24:25] op_sel:[1,1] op_sel_hi:[0,1] neg_lo:[0,1]
	v_pk_fma_f32 v[24:25], v[58:59], v[24:25], v[60:61] op_sel_hi:[1,0,1]
	v_pk_add_f32 v[58:59], v[0:1], v[16:17]
	v_pk_add_f32 v[0:1], v[0:1], v[16:17] neg_lo:[0,1] neg_hi:[0,1]
	v_pk_add_f32 v[16:17], v[2:3], v[18:19]
	v_pk_add_f32 v[2:3], v[2:3], v[18:19] neg_lo:[0,1] neg_hi:[0,1]
	v_pk_mul_f32 v[96:97], v[30:31], v[94:95] op_sel:[1,1] op_sel_hi:[0,1] neg_lo:[0,1]
	v_pk_mul_f32 v[18:19], v[2:3], s[18:19]
	v_pk_fma_f32 v[30:31], v[30:31], v[94:95], v[96:97] op_sel_hi:[1,0,1]
	v_pk_fma_f32 v[2:3], v[2:3], s[30:31], v[18:19] op_sel:[0,0,1] op_sel_hi:[1,0,0]
	v_pk_add_f32 v[18:19], v[4:5], v[20:21]
	v_pk_add_f32 v[4:5], v[4:5], v[20:21] neg_lo:[0,1] neg_hi:[0,1]
	v_pk_mul_f32 v[20:21], v[4:5], s[10:11]
	v_pk_fma_f32 v[4:5], v[4:5], s[14:15], v[20:21] op_sel:[0,0,1] op_sel_hi:[1,0,0]
	v_pk_add_f32 v[20:21], v[6:7], v[22:23]
	v_pk_add_f32 v[6:7], v[6:7], v[22:23] neg_lo:[0,1] neg_hi:[0,1]
	v_pk_mul_f32 v[22:23], v[6:7], s[34:35]
	v_pk_fma_f32 v[6:7], v[6:7], s[26:27], v[22:23] op_sel:[0,0,1] op_sel_hi:[1,0,0]
	v_pk_add_f32 v[22:23], v[8:9], v[26:27]
	v_pk_add_f32 v[8:9], v[8:9], v[26:27] neg_lo:[0,1] neg_hi:[0,1]
	v_pk_add_f32 v[26:27], v[10:11], v[28:29]
	v_pk_add_f32 v[10:11], v[10:11], v[28:29] neg_lo:[0,1] neg_hi:[0,1]
	v_pk_mul_f32 v[28:29], v[10:11], s[34:35]
	v_pk_fma_f32 v[10:11], v[10:11], s[26:27], v[28:29] op_sel:[0,0,1] op_sel_hi:[1,0,0] neg_lo:[1,0,0] neg_hi:[1,0,0]
	v_pk_add_f32 v[28:29], v[12:13], v[30:31]
	v_pk_add_f32 v[12:13], v[12:13], v[30:31] neg_lo:[0,1] neg_hi:[0,1]
	v_pk_mul_f32 v[30:31], v[12:13], s[10:11]
	v_pk_fma_f32 v[12:13], v[12:13], s[14:15], v[30:31] op_sel:[0,0,1] op_sel_hi:[1,0,0] neg_lo:[1,0,0] neg_hi:[1,0,0]
	v_pk_add_f32 v[30:31], v[14:15], v[24:25]
	v_pk_add_f32 v[14:15], v[14:15], v[24:25] neg_lo:[0,1] neg_hi:[0,1]
	v_pk_mul_f32 v[24:25], v[14:15], s[18:19]
	v_pk_fma_f32 v[14:15], v[14:15], s[30:31], v[24:25] op_sel:[0,0,1] op_sel_hi:[1,0,0] neg_lo:[1,0,0] neg_hi:[1,0,0]
	v_pk_add_f32 v[24:25], v[58:59], v[22:23]
	v_pk_add_f32 v[22:23], v[58:59], v[22:23] neg_lo:[0,1] neg_hi:[0,1]
	v_pk_add_f32 v[58:59], v[16:17], v[26:27]
	v_pk_add_f32 v[16:17], v[16:17], v[26:27] neg_lo:[0,1] neg_hi:[0,1]
	v_pk_mul_f32 v[26:27], v[16:17], s[10:11]
	v_pk_fma_f32 v[16:17], v[16:17], s[14:15], v[26:27] op_sel:[0,0,1] op_sel_hi:[1,0,0]
	v_pk_add_f32 v[26:27], v[18:19], v[28:29]
	v_pk_add_f32 v[18:19], v[18:19], v[28:29] neg_lo:[0,1] neg_hi:[0,1]
	v_pk_add_f32 v[28:29], v[20:21], v[30:31]
	v_pk_add_f32 v[20:21], v[20:21], v[30:31] neg_lo:[0,1] neg_hi:[0,1]
	v_pk_mul_f32 v[30:31], v[20:21], s[10:11]
	v_pk_fma_f32 v[20:21], v[20:21], s[14:15], v[30:31] op_sel:[0,0,1] op_sel_hi:[1,0,0] neg_lo:[1,0,0] neg_hi:[1,0,0]
	v_pk_add_f32 v[30:31], v[0:1], v[8:9] op_sel:[0,1] op_sel_hi:[1,0] neg_hi:[0,1]
	v_pk_add_f32 v[0:1], v[0:1], v[8:9] op_sel:[0,1] op_sel_hi:[1,0] neg_lo:[0,1]
	v_pk_add_f32 v[8:9], v[2:3], v[10:11]
	v_pk_add_f32 v[2:3], v[2:3], v[10:11] neg_lo:[0,1] neg_hi:[0,1]
	v_pk_mul_f32 v[10:11], v[2:3], s[10:11]
	v_pk_fma_f32 v[2:3], v[2:3], s[14:15], v[10:11] op_sel:[0,0,1] op_sel_hi:[1,0,0]
	v_pk_add_f32 v[10:11], v[4:5], v[12:13]
	v_pk_add_f32 v[4:5], v[4:5], v[12:13] neg_lo:[0,1] neg_hi:[0,1]
	v_pk_add_f32 v[12:13], v[6:7], v[14:15]
	v_pk_add_f32 v[6:7], v[6:7], v[14:15] neg_lo:[0,1] neg_hi:[0,1]
	v_pk_mul_f32 v[14:15], v[6:7], s[10:11]
	v_pk_fma_f32 v[6:7], v[6:7], s[14:15], v[14:15] op_sel:[0,0,1] op_sel_hi:[1,0,0] neg_lo:[1,0,0] neg_hi:[1,0,0]
	v_pk_add_f32 v[14:15], v[24:25], v[26:27]
	v_pk_add_f32 v[24:25], v[24:25], v[26:27] neg_lo:[0,1] neg_hi:[0,1]
	v_pk_add_f32 v[26:27], v[58:59], v[28:29]
	v_pk_add_f32 v[28:29], v[58:59], v[28:29] neg_lo:[0,1] neg_hi:[0,1]
	v_pk_add_f32 v[58:59], v[22:23], v[18:19] op_sel:[0,1] op_sel_hi:[1,0] neg_hi:[0,1]
	v_pk_add_f32 v[18:19], v[22:23], v[18:19] op_sel:[0,1] op_sel_hi:[1,0] neg_lo:[0,1]
	v_pk_add_f32 v[22:23], v[16:17], v[20:21]
	v_pk_add_f32 v[16:17], v[16:17], v[20:21] neg_lo:[0,1] neg_hi:[0,1]
	v_pk_add_f32 v[20:21], v[30:31], v[10:11]
	v_pk_add_f32 v[10:11], v[30:31], v[10:11] neg_lo:[0,1] neg_hi:[0,1]
	v_pk_add_f32 v[30:31], v[8:9], v[12:13]
	v_pk_add_f32 v[8:9], v[8:9], v[12:13] neg_lo:[0,1] neg_hi:[0,1]
	v_pk_add_f32 v[12:13], v[0:1], v[4:5] op_sel:[0,1] op_sel_hi:[1,0] neg_hi:[0,1]
	v_pk_add_f32 v[0:1], v[0:1], v[4:5] op_sel:[0,1] op_sel_hi:[1,0] neg_lo:[0,1]
	v_pk_add_f32 v[4:5], v[2:3], v[6:7]
	v_pk_add_f32 v[2:3], v[2:3], v[6:7] neg_lo:[0,1] neg_hi:[0,1]
	v_pk_mul_f32 v[2:3], v[2:3], s[22:23]
	v_pk_add_f32 v[6:7], v[14:15], v[26:27]
	v_pk_add_f32 v[14:15], v[14:15], v[26:27] neg_lo:[0,1] neg_hi:[0,1]
	v_pk_add_f32 v[26:27], v[24:25], v[28:29] op_sel:[0,1] op_sel_hi:[1,0] neg_hi:[0,1]
	v_pk_add_f32 v[24:25], v[24:25], v[28:29] op_sel:[0,1] op_sel_hi:[1,0] neg_lo:[0,1]
	v_pk_add_f32 v[28:29], v[58:59], v[22:23]
	v_pk_add_f32 v[22:23], v[58:59], v[22:23] neg_lo:[0,1] neg_hi:[0,1]
	v_pk_add_f32 v[58:59], v[18:19], v[16:17] op_sel:[0,1] op_sel_hi:[1,0] neg_hi:[0,1]
	v_pk_add_f32 v[16:17], v[18:19], v[16:17] op_sel:[0,1] op_sel_hi:[1,0] neg_lo:[0,1]
	v_pk_add_f32 v[18:19], v[20:21], v[30:31]
	v_pk_add_f32 v[20:21], v[20:21], v[30:31] neg_lo:[0,1] neg_hi:[0,1]
	v_pk_add_f32 v[30:31], v[10:11], v[8:9] op_sel:[0,1] op_sel_hi:[1,0] neg_hi:[0,1]
	v_pk_add_f32 v[8:9], v[10:11], v[8:9] op_sel:[0,1] op_sel_hi:[1,0] neg_lo:[0,1]
	v_pk_add_f32 v[10:11], v[12:13], v[4:5]
	v_pk_add_f32 v[4:5], v[12:13], v[4:5] neg_lo:[0,1] neg_hi:[0,1]
	v_pk_add_f32 v[12:13], v[0:1], v[2:3] op_sel:[0,1] op_sel_hi:[1,0]
	v_pk_add_f32 v[0:1], v[0:1], v[2:3] op_sel:[0,1] op_sel_hi:[1,0] neg_lo:[0,1] neg_hi:[0,1]
	v_lshlrev_b32_e32 v2, 4, v41
	v_and_or_b32 v2, v2, s15, v98
	v_ashrrev_i32_e32 v3, 4, v2
	v_lshlrev_b32_e32 v3, 3, v3
	v_lshlrev_b32_e32 v2, 3, v2
	v_add3_u32 v2, 0, v3, v2
	ds_write_b64 v2, v[6:7]
	ds_write_b64 v2, v[14:15] offset:34816
	ds_write_b64 v2, v[26:27] offset:17408
	ds_write_b64 v2, v[24:25] offset:52224
	ds_write_b64 v2, v[28:29] offset:8704
	ds_write_b64 v2, v[22:23] offset:43520
	ds_write_b64 v2, v[58:59] offset:26112
	ds_write_b64 v2, v[16:17] offset:60928
	ds_write_b64 v2, v[18:19] offset:4352
	ds_write_b64 v2, v[20:21] offset:39168
	ds_write_b64 v2, v[30:31] offset:21760
	ds_write_b64 v2, v[8:9] offset:56576
	ds_write_b64 v2, v[10:11] offset:13056
	ds_write_b64 v2, v[4:5] offset:47872
	ds_write_b64 v2, v[12:13] offset:30464
	ds_write_b64 v2, v[0:1] offset:65280
	v_mov_b32_e32 v0, v154
	v_mov_b32_e32 v1, v156
	v_mov_b32_e32 v2, v155
	s_waitcnt lgkmcnt(0)
	s_barrier
.LBB0_670:
	v_or_b32_e32 v3, s4, v32
	v_cmp_ne_u32_e32 vcc, 0, v3
	v_add_u32_e32 v9, 0, v2
	v_add_u32_e32 v4, 0x11000, v9
	v_cndmask_b32_e32 v3, 0, v0, vcc
	v_lshl_add_u32 v3, v3, 3, 0
	v_add_u32_e32 v3, 0x11000, v3
	ds_read_b64 v[4:5], v4
	ds_read_b64 v[6:7], v3
	s_add_i32 s4, s4, 2
	v_add_u32_e32 v2, 0x2200, v2
	v_add_u32_e32 v0, 0xfffffbc0, v0
	s_cmp_lg_u32 s4, 16
	s_waitcnt lgkmcnt(0)
	v_add_f32_e32 v3, v5, v7
	v_mul_f32_e32 v8, 0.5, v3
	v_sub_f32_e32 v3, v4, v6
	ds_read_b64 v[6:7], v9
	v_mul_f32_e32 v4, -0.5, v3
	v_add_u32_e32 v3, 0x12100, v9
	s_waitcnt lgkmcnt(0)
	v_pk_mul_f32 v[4:5], v[6:7], v[4:5] op_sel:[1,0] op_sel_hi:[0,0]
	v_pk_fma_f32 v[10:11], v[6:7], v[8:9], v[4:5] neg_lo:[0,0,1] neg_hi:[0,0,1]
	v_pk_fma_f32 v[4:5], v[6:7], v[8:9], v[4:5] op_sel_hi:[1,0,1]
	s_nop 0
	v_mov_b32_e32 v11, v5
	v_pk_mul_f32 v[4:5], v[10:11], s[24:25]
	ds_write_b64 v9, v[4:5]
	ds_read_b64 v[4:5], v3
	v_add_u32_e32 v3, 0, v1
	v_add_u32_e32 v3, 0x1ff00, v3
	ds_read_b64 v[6:7], v3
	v_add_u32_e32 v1, 0xffffde00, v1
	s_waitcnt lgkmcnt(0)
	v_add_f32_e32 v3, v5, v7
	v_mul_f32_e32 v8, 0.5, v3
	v_sub_f32_e32 v3, v4, v6
	ds_read_b64 v[6:7], v9 offset:4352
	v_mul_f32_e32 v4, -0.5, v3
	s_waitcnt lgkmcnt(0)
	v_pk_mul_f32 v[4:5], v[6:7], v[4:5] op_sel:[1,0] op_sel_hi:[0,0]
	v_pk_fma_f32 v[10:11], v[6:7], v[8:9], v[4:5] neg_lo:[0,0,1] neg_hi:[0,0,1]
	v_pk_fma_f32 v[4:5], v[6:7], v[8:9], v[4:5] op_sel_hi:[1,0,1]
	s_nop 0
	v_mov_b32_e32 v11, v5
	v_pk_mul_f32 v[4:5], v[10:11], s[24:25]
	ds_write_b64 v9, v[4:5] offset:4352
	s_cbranch_scc1 .LBB0_670
	s_waitcnt lgkmcnt(0)
	s_barrier
	s_and_saveexec_b64 s[28:29], s[40:41]
	s_cbranch_execz .LBB0_673
	ds_read_b64 v[0:1], v153
	ds_read_b64 v[2:3], v153 offset:2176
	ds_read_b64 v[4:5], v153 offset:4352
	ds_read_b64 v[6:7], v153 offset:6528
	ds_read_b64 v[8:9], v153 offset:8704
	ds_read_b64 v[10:11], v153 offset:10880
	ds_read_b64 v[12:13], v153 offset:13056
	ds_read_b64 v[14:15], v153 offset:15232
	ds_read_b64 v[16:17], v153 offset:17408
	ds_read_b64 v[18:19], v153 offset:19584
	ds_read_b64 v[20:21], v153 offset:21760
	ds_read_b64 v[22:23], v153 offset:23936
	ds_read_b64 v[24:25], v153 offset:26112
	ds_read_b64 v[26:27], v153 offset:28288
	ds_read_b64 v[28:29], v153 offset:30464
	ds_read_b64 v[30:31], v153 offset:32640
	ds_read_b64 v[58:59], v153 offset:34816
	ds_read_b64 v[60:61], v153 offset:41344
	ds_read_b64 v[94:95], v153 offset:43520
	ds_read_b64 v[96:97], v153 offset:45696
	ds_read_b64 v[98:99], v153 offset:47872
	ds_read_b64 v[100:101], v153 offset:50048
	ds_read_b64 v[102:103], v153 offset:52224
	ds_read_b64 v[104:105], v153 offset:54400
	ds_read_b64 v[106:107], v153 offset:56576
	ds_read_b64 v[108:109], v153 offset:58752
	ds_read_b64 v[110:111], v153 offset:60928
	ds_read_b64 v[112:113], v153 offset:63104
	ds_read_b64 v[114:115], v153 offset:65280
	ds_read_b64 v[116:117], v153 offset:36992
	ds_read_b64 v[118:119], v153 offset:39168
	ds_read_b64 v[120:121], v33
	s_waitcnt lgkmcnt(14)
	v_pk_add_f32 v[124:125], v[0:1], v[58:59]
	v_pk_add_f32 v[0:1], v[0:1], v[58:59] neg_lo:[0,1] neg_hi:[0,1]
	s_waitcnt lgkmcnt(2)
	v_pk_add_f32 v[58:59], v[2:3], v[116:117]
	v_pk_add_f32 v[2:3], v[2:3], v[116:117] neg_lo:[0,1] neg_hi:[0,1]
	s_mov_b32 s11, s14
	v_pk_mul_f32 v[116:117], v[2:3], s[16:17]
	s_mov_b32 s13, s86
	v_pk_fma_f32 v[2:3], v[2:3], s[6:7], v[116:117] op_sel:[0,0,1] op_sel_hi:[1,0,0]
	s_waitcnt lgkmcnt(1)
	v_pk_add_f32 v[116:117], v[4:5], v[118:119]
	v_pk_add_f32 v[4:5], v[4:5], v[118:119] neg_lo:[0,1] neg_hi:[0,1]
	s_mov_b32 s4, s21
	v_pk_mul_f32 v[118:119], v[4:5], s[18:19]
	s_mov_b32 s35, s30
	v_pk_fma_f32 v[4:5], v[4:5], s[30:31], v[118:119] op_sel:[0,0,1] op_sel_hi:[1,0,0]
	v_pk_add_f32 v[118:119], v[6:7], v[60:61]
	v_pk_add_f32 v[6:7], v[6:7], v[60:61] neg_lo:[0,1] neg_hi:[0,1]
	s_mov_b32 s8, s19
	v_pk_mul_f32 v[60:61], v[6:7], s[20:21]
	s_mov_b32 s77, s6
	v_pk_fma_f32 v[6:7], v[6:7], s[86:87], v[60:61] op_sel:[0,0,1] op_sel_hi:[1,0,0]
	v_pk_add_f32 v[60:61], v[8:9], v[94:95]
	v_pk_add_f32 v[8:9], v[8:9], v[94:95] neg_lo:[0,1] neg_hi:[0,1]
	s_mov_b32 s26, s17
	v_pk_mul_f32 v[94:95], v[8:9], s[10:11]
	s_nop 0
	v_pk_fma_f32 v[8:9], v[8:9], s[14:15], v[94:95] op_sel:[0,0,1] op_sel_hi:[1,0,0]
	v_pk_add_f32 v[94:95], v[10:11], v[96:97]
	v_pk_add_f32 v[10:11], v[10:11], v[96:97] neg_lo:[0,1] neg_hi:[0,1]
	v_pk_mul_f32 v[96:97], v[10:11], s[12:13]
	v_pk_fma_f32 v[10:11], v[10:11], s[4:5], v[96:97] op_sel:[0,0,1] op_sel_hi:[1,0,0]
	v_pk_add_f32 v[96:97], v[12:13], v[98:99]
	v_pk_add_f32 v[12:13], v[12:13], v[98:99] neg_lo:[0,1] neg_hi:[0,1]
	v_pk_mul_f32 v[98:99], v[12:13], s[34:35]
	v_pk_fma_f32 v[12:13], v[12:13], s[8:9], v[98:99] op_sel:[0,0,1] op_sel_hi:[1,0,0]
	v_pk_add_f32 v[98:99], v[14:15], v[100:101]
	v_pk_add_f32 v[14:15], v[14:15], v[100:101] neg_lo:[0,1] neg_hi:[0,1]
	v_pk_mul_f32 v[100:101], v[14:15], s[76:77]
	v_pk_fma_f32 v[14:15], v[14:15], s[26:27], v[100:101] op_sel:[0,0,1] op_sel_hi:[1,0,0]
	v_pk_add_f32 v[100:101], v[16:17], v[102:103]
	v_pk_add_f32 v[16:17], v[16:17], v[102:103] neg_lo:[0,1] neg_hi:[0,1]
	v_pk_add_f32 v[102:103], v[18:19], v[104:105]
	v_pk_add_f32 v[18:19], v[18:19], v[104:105] neg_lo:[0,1] neg_hi:[0,1]
	v_pk_mul_f32 v[104:105], v[18:19], s[76:77]
	v_pk_fma_f32 v[18:19], v[18:19], s[26:27], v[104:105] op_sel:[0,0,1] op_sel_hi:[1,0,0] neg_lo:[1,0,0] neg_hi:[1,0,0]
	v_pk_add_f32 v[104:105], v[20:21], v[106:107]
	v_pk_add_f32 v[20:21], v[20:21], v[106:107] neg_lo:[0,1] neg_hi:[0,1]
	v_pk_mul_f32 v[106:107], v[20:21], s[34:35]
	v_pk_fma_f32 v[20:21], v[20:21], s[8:9], v[106:107] op_sel:[0,0,1] op_sel_hi:[1,0,0] neg_lo:[1,0,0] neg_hi:[1,0,0]
	v_pk_add_f32 v[106:107], v[22:23], v[108:109]
	v_pk_add_f32 v[22:23], v[22:23], v[108:109] neg_lo:[0,1] neg_hi:[0,1]
	v_pk_mul_f32 v[108:109], v[22:23], s[12:13]
	v_pk_fma_f32 v[22:23], v[22:23], s[4:5], v[108:109] op_sel:[0,0,1] op_sel_hi:[1,0,0] neg_lo:[1,0,0] neg_hi:[1,0,0]
	v_pk_add_f32 v[108:109], v[24:25], v[110:111]
	v_pk_add_f32 v[24:25], v[24:25], v[110:111] neg_lo:[0,1] neg_hi:[0,1]
	v_pk_mul_f32 v[110:111], v[24:25], s[10:11]
	v_pk_fma_f32 v[24:25], v[24:25], s[14:15], v[110:111] op_sel:[0,0,1] op_sel_hi:[1,0,0] neg_lo:[1,0,0] neg_hi:[1,0,0]
	v_pk_add_f32 v[110:111], v[26:27], v[112:113]
	v_pk_add_f32 v[26:27], v[26:27], v[112:113] neg_lo:[0,1] neg_hi:[0,1]
	v_pk_mul_f32 v[112:113], v[26:27], s[20:21]
	v_pk_fma_f32 v[26:27], v[26:27], s[86:87], v[112:113] op_sel:[0,0,1] op_sel_hi:[1,0,0] neg_lo:[1,0,0] neg_hi:[1,0,0]
	v_pk_add_f32 v[112:113], v[28:29], v[114:115]
	v_pk_add_f32 v[28:29], v[28:29], v[114:115] neg_lo:[0,1] neg_hi:[0,1]
	v_pk_mul_f32 v[114:115], v[28:29], s[18:19]
	v_pk_fma_f32 v[28:29], v[28:29], s[30:31], v[114:115] op_sel:[0,0,1] op_sel_hi:[1,0,0] neg_lo:[1,0,0] neg_hi:[1,0,0]
	s_waitcnt lgkmcnt(0)
	v_pk_add_f32 v[114:115], v[30:31], v[120:121]
	v_pk_add_f32 v[30:31], v[30:31], v[120:121] neg_lo:[0,1] neg_hi:[0,1]
	s_nop 0
	v_pk_mul_f32 v[120:121], v[30:31], s[16:17]
	v_pk_fma_f32 v[30:31], v[30:31], s[6:7], v[120:121] op_sel:[0,0,1] op_sel_hi:[1,0,0] neg_lo:[1,0,0] neg_hi:[1,0,0]
	v_pk_add_f32 v[120:121], v[124:125], v[100:101]
	v_pk_add_f32 v[100:101], v[124:125], v[100:101] neg_lo:[0,1] neg_hi:[0,1]
	v_pk_add_f32 v[124:125], v[58:59], v[102:103]
	v_pk_add_f32 v[58:59], v[58:59], v[102:103] neg_lo:[0,1] neg_hi:[0,1]
	v_pk_mul_f32 v[102:103], v[58:59], s[18:19]
	v_pk_fma_f32 v[58:59], v[58:59], s[30:31], v[102:103] op_sel:[0,0,1] op_sel_hi:[1,0,0]
	v_pk_add_f32 v[102:103], v[116:117], v[104:105]
	v_pk_add_f32 v[104:105], v[116:117], v[104:105] neg_lo:[0,1] neg_hi:[0,1]
	v_pk_mul_f32 v[116:117], v[104:105], s[10:11]
	v_pk_fma_f32 v[104:105], v[104:105], s[14:15], v[116:117] op_sel:[0,0,1] op_sel_hi:[1,0,0]
	v_pk_add_f32 v[116:117], v[118:119], v[106:107]
	v_pk_add_f32 v[106:107], v[118:119], v[106:107] neg_lo:[0,1] neg_hi:[0,1]
	v_pk_mul_f32 v[118:119], v[106:107], s[34:35]
	v_pk_fma_f32 v[106:107], v[106:107], s[8:9], v[118:119] op_sel:[0,0,1] op_sel_hi:[1,0,0]
	v_pk_add_f32 v[118:119], v[60:61], v[108:109]
	v_pk_add_f32 v[60:61], v[60:61], v[108:109] neg_lo:[0,1] neg_hi:[0,1]
	v_pk_add_f32 v[108:109], v[94:95], v[110:111]
	v_pk_add_f32 v[94:95], v[94:95], v[110:111] neg_lo:[0,1] neg_hi:[0,1]
	v_pk_mul_f32 v[110:111], v[94:95], s[34:35]
	v_pk_fma_f32 v[94:95], v[94:95], s[8:9], v[110:111] op_sel:[0,0,1] op_sel_hi:[1,0,0] neg_lo:[1,0,0] neg_hi:[1,0,0]
	v_pk_add_f32 v[110:111], v[96:97], v[112:113]
	v_pk_add_f32 v[96:97], v[96:97], v[112:113] neg_lo:[0,1] neg_hi:[0,1]
	v_pk_mul_f32 v[112:113], v[96:97], s[10:11]
	v_pk_fma_f32 v[96:97], v[96:97], s[14:15], v[112:113] op_sel:[0,0,1] op_sel_hi:[1,0,0] neg_lo:[1,0,0] neg_hi:[1,0,0]
	v_pk_add_f32 v[112:113], v[98:99], v[114:115]
	v_pk_add_f32 v[98:99], v[98:99], v[114:115] neg_lo:[0,1] neg_hi:[0,1]
	v_pk_mul_f32 v[114:115], v[98:99], s[18:19]
	v_pk_fma_f32 v[98:99], v[98:99], s[30:31], v[114:115] op_sel:[0,0,1] op_sel_hi:[1,0,0] neg_lo:[1,0,0] neg_hi:[1,0,0]
	v_pk_add_f32 v[114:115], v[0:1], v[16:17] op_sel:[0,1] op_sel_hi:[1,0] neg_hi:[0,1]
	v_pk_add_f32 v[0:1], v[0:1], v[16:17] op_sel:[0,1] op_sel_hi:[1,0] neg_lo:[0,1]
	v_pk_add_f32 v[16:17], v[2:3], v[18:19]
	v_pk_add_f32 v[2:3], v[2:3], v[18:19] neg_lo:[0,1] neg_hi:[0,1]
	v_pk_mul_f32 v[18:19], v[2:3], s[18:19]
	v_pk_fma_f32 v[2:3], v[2:3], s[30:31], v[18:19] op_sel:[0,0,1] op_sel_hi:[1,0,0]
	v_pk_add_f32 v[18:19], v[4:5], v[20:21]
	v_pk_add_f32 v[4:5], v[4:5], v[20:21] neg_lo:[0,1] neg_hi:[0,1]
	v_pk_mul_f32 v[20:21], v[4:5], s[10:11]
	v_pk_fma_f32 v[4:5], v[4:5], s[14:15], v[20:21] op_sel:[0,0,1] op_sel_hi:[1,0,0]
	v_pk_add_f32 v[20:21], v[6:7], v[22:23]
	v_pk_add_f32 v[6:7], v[6:7], v[22:23] neg_lo:[0,1] neg_hi:[0,1]
	v_pk_mul_f32 v[22:23], v[6:7], s[34:35]
	v_pk_fma_f32 v[6:7], v[6:7], s[8:9], v[22:23] op_sel:[0,0,1] op_sel_hi:[1,0,0]
	v_pk_add_f32 v[22:23], v[8:9], v[24:25]
	v_pk_add_f32 v[8:9], v[8:9], v[24:25] neg_lo:[0,1] neg_hi:[0,1]
	v_pk_add_f32 v[24:25], v[10:11], v[26:27]
	v_pk_add_f32 v[10:11], v[10:11], v[26:27] neg_lo:[0,1] neg_hi:[0,1]
	v_pk_mul_f32 v[26:27], v[10:11], s[34:35]
	v_pk_fma_f32 v[10:11], v[10:11], s[8:9], v[26:27] op_sel:[0,0,1] op_sel_hi:[1,0,0] neg_lo:[1,0,0] neg_hi:[1,0,0]
	v_pk_add_f32 v[26:27], v[12:13], v[28:29]
	v_pk_add_f32 v[12:13], v[12:13], v[28:29] neg_lo:[0,1] neg_hi:[0,1]
	v_pk_mul_f32 v[28:29], v[12:13], s[10:11]
	v_pk_fma_f32 v[12:13], v[12:13], s[14:15], v[28:29] op_sel:[0,0,1] op_sel_hi:[1,0,0] neg_lo:[1,0,0] neg_hi:[1,0,0]
	v_pk_add_f32 v[28:29], v[14:15], v[30:31]
	v_pk_add_f32 v[14:15], v[14:15], v[30:31] neg_lo:[0,1] neg_hi:[0,1]
	v_pk_mul_f32 v[30:31], v[14:15], s[18:19]
	v_pk_fma_f32 v[14:15], v[14:15], s[30:31], v[30:31] op_sel:[0,0,1] op_sel_hi:[1,0,0] neg_lo:[1,0,0] neg_hi:[1,0,0]
	v_pk_add_f32 v[30:31], v[120:121], v[118:119]
	v_pk_add_f32 v[118:119], v[120:121], v[118:119] neg_lo:[0,1] neg_hi:[0,1]
	v_pk_add_f32 v[120:121], v[124:125], v[108:109]
	v_pk_add_f32 v[108:109], v[124:125], v[108:109] neg_lo:[0,1] neg_hi:[0,1]
	v_pk_mul_f32 v[124:125], v[108:109], s[10:11]
	v_pk_fma_f32 v[108:109], v[108:109], s[14:15], v[124:125] op_sel:[0,0,1] op_sel_hi:[1,0,0]
	v_pk_add_f32 v[124:125], v[102:103], v[110:111]
	v_pk_add_f32 v[102:103], v[102:103], v[110:111] neg_lo:[0,1] neg_hi:[0,1]
	v_pk_add_f32 v[110:111], v[116:117], v[112:113]
	v_pk_add_f32 v[112:113], v[116:117], v[112:113] neg_lo:[0,1] neg_hi:[0,1]
	v_pk_mul_f32 v[116:117], v[112:113], s[10:11]
	v_pk_fma_f32 v[112:113], v[112:113], s[14:15], v[116:117] op_sel:[0,0,1] op_sel_hi:[1,0,0] neg_lo:[1,0,0] neg_hi:[1,0,0]
	v_pk_add_f32 v[116:117], v[100:101], v[60:61] op_sel:[0,1] op_sel_hi:[1,0] neg_hi:[0,1]
	v_pk_add_f32 v[60:61], v[100:101], v[60:61] op_sel:[0,1] op_sel_hi:[1,0] neg_lo:[0,1]
	v_pk_add_f32 v[100:101], v[58:59], v[94:95]
	v_pk_add_f32 v[58:59], v[58:59], v[94:95] neg_lo:[0,1] neg_hi:[0,1]
	v_pk_add_f32 v[126:127], v[108:109], v[112:113]
	v_pk_mul_f32 v[94:95], v[58:59], s[10:11]
	v_pk_fma_f32 v[58:59], v[58:59], s[14:15], v[94:95] op_sel:[0,0,1] op_sel_hi:[1,0,0]
	v_pk_add_f32 v[94:95], v[104:105], v[96:97]
	v_pk_add_f32 v[96:97], v[104:105], v[96:97] neg_lo:[0,1] neg_hi:[0,1]
	v_pk_add_f32 v[104:105], v[106:107], v[98:99]
	v_pk_add_f32 v[98:99], v[106:107], v[98:99] neg_lo:[0,1] neg_hi:[0,1]
	v_pk_mul_f32 v[106:107], v[98:99], s[10:11]
	v_pk_add_f32 v[130:131], v[60:61], v[96:97] op_sel:[0,1] op_sel_hi:[1,0] neg_hi:[0,1]
	v_pk_fma_f32 v[98:99], v[98:99], s[14:15], v[106:107] op_sel:[0,0,1] op_sel_hi:[1,0,0] neg_lo:[1,0,0] neg_hi:[1,0,0]
	v_pk_add_f32 v[106:107], v[114:115], v[22:23]
	v_pk_add_f32 v[22:23], v[114:115], v[22:23] neg_lo:[0,1] neg_hi:[0,1]
	v_pk_add_f32 v[114:115], v[16:17], v[24:25]
	v_pk_add_f32 v[16:17], v[16:17], v[24:25] neg_lo:[0,1] neg_hi:[0,1]
	v_pk_add_f32 v[132:133], v[60:61], v[96:97] op_sel:[0,1] op_sel_hi:[1,0] neg_lo:[0,1]
	v_pk_mul_f32 v[24:25], v[16:17], s[10:11]
	v_pk_add_f32 v[60:61], v[58:59], v[98:99]
	v_pk_fma_f32 v[16:17], v[16:17], s[14:15], v[24:25] op_sel:[0,0,1] op_sel_hi:[1,0,0]
	v_pk_add_f32 v[24:25], v[18:19], v[26:27]
	v_pk_add_f32 v[18:19], v[18:19], v[26:27] neg_lo:[0,1] neg_hi:[0,1]
	v_pk_add_f32 v[26:27], v[20:21], v[28:29]
	v_pk_add_f32 v[20:21], v[20:21], v[28:29] neg_lo:[0,1] neg_hi:[0,1]
	v_pk_mul_f32 v[28:29], v[20:21], s[10:11]
	v_pk_add_f32 v[58:59], v[58:59], v[98:99] neg_lo:[0,1] neg_hi:[0,1]
	v_pk_fma_f32 v[20:21], v[20:21], s[14:15], v[28:29] op_sel:[0,0,1] op_sel_hi:[1,0,0] neg_lo:[1,0,0] neg_hi:[1,0,0]
	v_pk_add_f32 v[28:29], v[0:1], v[8:9] op_sel:[0,1] op_sel_hi:[1,0] neg_hi:[0,1]
	v_pk_add_f32 v[0:1], v[0:1], v[8:9] op_sel:[0,1] op_sel_hi:[1,0] neg_lo:[0,1]
	v_pk_add_f32 v[8:9], v[2:3], v[10:11]
	v_pk_add_f32 v[2:3], v[2:3], v[10:11] neg_lo:[0,1] neg_hi:[0,1]
	v_pk_add_f32 v[134:135], v[106:107], v[24:25]
	v_pk_mul_f32 v[10:11], v[2:3], s[10:11]
	v_pk_add_f32 v[106:107], v[106:107], v[24:25] neg_lo:[0,1] neg_hi:[0,1]
	v_pk_fma_f32 v[2:3], v[2:3], s[14:15], v[10:11] op_sel:[0,0,1] op_sel_hi:[1,0,0]
	v_pk_add_f32 v[10:11], v[4:5], v[12:13]
	v_pk_add_f32 v[4:5], v[4:5], v[12:13] neg_lo:[0,1] neg_hi:[0,1]
	v_pk_add_f32 v[12:13], v[6:7], v[14:15]
	v_pk_add_f32 v[6:7], v[6:7], v[14:15] neg_lo:[0,1] neg_hi:[0,1]
	v_pk_mul_f32 v[14:15], v[6:7], s[10:11]
	v_pk_add_f32 v[24:25], v[114:115], v[26:27] neg_lo:[0,1] neg_hi:[0,1]
	v_pk_fma_f32 v[6:7], v[6:7], s[14:15], v[14:15] op_sel:[0,0,1] op_sel_hi:[1,0,0] neg_lo:[1,0,0] neg_hi:[1,0,0]
	v_pk_add_f32 v[14:15], v[30:31], v[124:125]
	v_pk_add_f32 v[30:31], v[30:31], v[124:125] neg_lo:[0,1] neg_hi:[0,1]
	v_pk_add_f32 v[124:125], v[120:121], v[110:111]
	v_pk_add_f32 v[110:111], v[120:121], v[110:111] neg_lo:[0,1] neg_hi:[0,1]
	v_pk_add_f32 v[120:121], v[118:119], v[102:103] op_sel:[0,1] op_sel_hi:[1,0] neg_hi:[0,1]
	v_pk_add_f32 v[118:119], v[118:119], v[102:103] op_sel:[0,1] op_sel_hi:[1,0] neg_lo:[0,1]
	v_pk_add_f32 v[102:103], v[108:109], v[112:113] neg_lo:[0,1] neg_hi:[0,1]
	v_pk_add_f32 v[112:113], v[116:117], v[94:95]
	v_pk_add_f32 v[94:95], v[116:117], v[94:95] neg_lo:[0,1] neg_hi:[0,1]
	v_pk_add_f32 v[116:117], v[100:101], v[104:105]
	v_pk_add_f32 v[100:101], v[100:101], v[104:105] neg_lo:[0,1] neg_hi:[0,1]
	v_pk_add_f32 v[138:139], v[22:23], v[18:19] op_sel:[0,1] op_sel_hi:[1,0] neg_hi:[0,1]
	v_pk_add_f32 v[140:141], v[22:23], v[18:19] op_sel:[0,1] op_sel_hi:[1,0] neg_lo:[0,1]
	v_pk_add_f32 v[18:19], v[16:17], v[20:21]
	v_pk_add_f32 v[16:17], v[16:17], v[20:21] neg_lo:[0,1] neg_hi:[0,1]
	v_pk_add_f32 v[144:145], v[28:29], v[10:11]
	v_pk_add_f32 v[158:159], v[28:29], v[10:11] neg_lo:[0,1] neg_hi:[0,1]
	v_pk_add_f32 v[10:11], v[8:9], v[12:13]
	v_pk_add_f32 v[8:9], v[8:9], v[12:13] neg_lo:[0,1] neg_hi:[0,1]
	v_pk_add_f32 v[162:163], v[0:1], v[4:5] op_sel:[0,1] op_sel_hi:[1,0] neg_hi:[0,1]
	v_pk_add_f32 v[164:165], v[0:1], v[4:5] op_sel:[0,1] op_sel_hi:[1,0] neg_lo:[0,1]
	v_pk_add_f32 v[0:1], v[2:3], v[6:7] neg_lo:[0,1] neg_hi:[0,1]
	v_pk_mul_f32 v[108:109], v[102:103], s[22:23]
	v_pk_mul_f32 v[128:129], v[100:101], s[22:23]
	v_pk_add_f32 v[136:137], v[114:115], v[26:27]
	v_pk_mul_f32 v[114:115], v[24:25], s[22:23]
	v_pk_mul_f32 v[142:143], v[16:17], s[22:23]
	v_pk_mul_f32 v[160:161], v[8:9], s[22:23]
	v_pk_add_f32 v[166:167], v[2:3], v[6:7]
	v_pk_mul_f32 v[168:169], v[0:1], s[22:23]
	v_pk_add_f32 v[28:29], v[14:15], v[124:125]
	v_pk_add_f32 v[104:105], v[14:15], v[124:125] neg_lo:[0,1] neg_hi:[0,1]
	v_pk_add_f32 v[24:25], v[30:31], v[110:111] op_sel:[0,1] op_sel_hi:[1,0] neg_hi:[0,1]
	v_pk_add_f32 v[102:103], v[30:31], v[110:111] op_sel:[0,1] op_sel_hi:[1,0] neg_lo:[0,1]
	v_pk_add_f32 v[20:21], v[120:121], v[126:127]
	v_pk_add_f32 v[100:101], v[120:121], v[126:127] neg_lo:[0,1] neg_hi:[0,1]
	v_pk_add_f32 v[16:17], v[118:119], v[108:109] op_sel:[0,1] op_sel_hi:[1,0]
	v_pk_add_f32 v[98:99], v[118:119], v[108:109] op_sel:[0,1] op_sel_hi:[1,0] neg_lo:[0,1] neg_hi:[0,1]
	v_pk_add_f32 v[12:13], v[112:113], v[116:117]
	v_pk_add_f32 v[96:97], v[112:113], v[116:117] neg_lo:[0,1] neg_hi:[0,1]
	v_pk_add_f32 v[8:9], v[94:95], v[128:129] op_sel:[0,1] op_sel_hi:[1,0]
	v_pk_add_f32 v[94:95], v[94:95], v[128:129] op_sel:[0,1] op_sel_hi:[1,0] neg_lo:[0,1] neg_hi:[0,1]
	v_pk_add_f32 v[4:5], v[130:131], v[60:61]
	v_pk_add_f32 v[60:61], v[130:131], v[60:61] neg_lo:[0,1] neg_hi:[0,1]
	v_pk_add_f32 v[0:1], v[132:133], v[58:59] op_sel:[0,1] op_sel_hi:[1,0] neg_hi:[0,1]
	v_pk_add_f32 v[58:59], v[132:133], v[58:59] op_sel:[0,1] op_sel_hi:[1,0] neg_lo:[0,1]
	v_pk_add_f32 v[30:31], v[134:135], v[136:137]
	v_pk_add_f32 v[120:121], v[134:135], v[136:137] neg_lo:[0,1] neg_hi:[0,1]
	v_pk_add_f32 v[26:27], v[106:107], v[114:115] op_sel:[0,1] op_sel_hi:[1,0]
	v_pk_add_f32 v[118:119], v[106:107], v[114:115] op_sel:[0,1] op_sel_hi:[1,0] neg_lo:[0,1] neg_hi:[0,1]
	v_pk_add_f32 v[22:23], v[138:139], v[18:19]
	v_pk_add_f32 v[116:117], v[138:139], v[18:19] neg_lo:[0,1] neg_hi:[0,1]
	v_pk_add_f32 v[18:19], v[140:141], v[142:143] op_sel:[0,1] op_sel_hi:[1,0]
	v_pk_add_f32 v[114:115], v[140:141], v[142:143] op_sel:[0,1] op_sel_hi:[1,0] neg_lo:[0,1] neg_hi:[0,1]
	v_pk_add_f32 v[14:15], v[144:145], v[10:11]
	v_pk_add_f32 v[112:113], v[144:145], v[10:11] neg_lo:[0,1] neg_hi:[0,1]
	v_pk_add_f32 v[10:11], v[158:159], v[160:161] op_sel:[0,1] op_sel_hi:[1,0]
	v_pk_add_f32 v[110:111], v[158:159], v[160:161] op_sel:[0,1] op_sel_hi:[1,0] neg_lo:[0,1] neg_hi:[0,1]
	v_pk_add_f32 v[6:7], v[162:163], v[166:167]
	v_pk_add_f32 v[108:109], v[162:163], v[166:167] neg_lo:[0,1] neg_hi:[0,1]
	v_pk_add_f32 v[2:3], v[164:165], v[168:169] op_sel:[0,1] op_sel_hi:[1,0]
	v_pk_add_f32 v[106:107], v[164:165], v[168:169] op_sel:[0,1] op_sel_hi:[1,0] neg_lo:[0,1] neg_hi:[0,1]

.LBB0_675:
	s_or_b64 exec, exec, s[4:5]
	v_mov_b32_e32 v41, v32
	s_waitcnt lgkmcnt(0)
	s_barrier
	s_mov_b32 s11, s14
	v_and_b32_e32 v98, 31, v41
	v_cvt_f32_ubyte0_e32 v24, v98
	v_mul_f32_e32 v60, 0x3b000000, v24
	v_sin_f32_e32 v24, v60
	v_ashrrev_i32_e32 v0, 4, v41
	v_lshlrev_b32_e32 v0, 3, v0
	v_lshlrev_b32_e32 v1, 3, v41
	v_cos_f32_e32 v60, v60
	v_add3_u32 v25, 0, v0, v1
	ds_read_b64 v[0:1], v25
	ds_read_b64 v[2:3], v25 offset:4352
	ds_read_b64 v[4:5], v25 offset:8704
	ds_read_b64 v[6:7], v25 offset:13056
	ds_read_b64 v[8:9], v25 offset:17408
	ds_read_b64 v[10:11], v25 offset:21760
	ds_read_b64 v[12:13], v25 offset:26112
	ds_read_b64 v[14:15], v25 offset:30464
	ds_read_b64 v[16:17], v25 offset:34816
	ds_read_b64 v[18:19], v25 offset:39168
	ds_read_b64 v[20:21], v25 offset:43520
	ds_read_b64 v[22:23], v25 offset:47872
	v_xor_b32_e32 v61, 0x80000000, v24
	s_waitcnt lgkmcnt(10)
	v_pk_mul_f32 v[94:95], v[2:3], v[24:25] op_sel:[1,0] op_sel_hi:[0,0] neg_hi:[0,1]
	v_pk_fma_f32 v[2:3], v[2:3], v[60:61], v[94:95] op_sel_hi:[1,0,1]
	v_pk_mul_f32 v[94:95], v[24:25], v[60:61] op_sel:[0,1] op_sel_hi:[0,0] neg_hi:[1,0]
	v_pk_fma_f32 v[94:95], v[60:61], v[60:61], v[94:95] op_sel_hi:[0,1,1]
	ds_read_b64 v[26:27], v25 offset:52224
	ds_read_b64 v[28:29], v25 offset:56576
	ds_read_b64 v[30:31], v25 offset:60928
	ds_read_b64 v[58:59], v25 offset:65280
	s_waitcnt lgkmcnt(13)
	v_pk_mul_f32 v[96:97], v[4:5], v[94:95] op_sel:[1,1] op_sel_hi:[0,1] neg_lo:[0,1]
	v_pk_fma_f32 v[4:5], v[4:5], v[94:95], v[96:97] op_sel_hi:[1,0,1]
	v_pk_mul_f32 v[96:97], v[24:25], v[94:95] op_sel:[0,1] op_sel_hi:[0,0] neg_hi:[1,0]
	v_pk_fma_f32 v[94:95], v[60:61], v[94:95], v[96:97] op_sel_hi:[0,1,1]
	s_mov_b32 s35, s30
	s_waitcnt lgkmcnt(12)
	v_pk_mul_f32 v[96:97], v[6:7], v[94:95] op_sel:[1,1] op_sel_hi:[0,1] neg_lo:[0,1]
	v_pk_fma_f32 v[6:7], v[6:7], v[94:95], v[96:97] op_sel_hi:[1,0,1]
	v_pk_mul_f32 v[96:97], v[24:25], v[94:95] op_sel:[0,1] op_sel_hi:[0,0] neg_hi:[1,0]
	v_pk_fma_f32 v[94:95], v[60:61], v[94:95], v[96:97] op_sel_hi:[0,1,1]
	s_mov_b32 s26, s19
	s_waitcnt lgkmcnt(11)
	v_pk_mul_f32 v[96:97], v[8:9], v[94:95] op_sel:[1,1] op_sel_hi:[0,1] neg_lo:[0,1]
	v_pk_fma_f32 v[8:9], v[8:9], v[94:95], v[96:97] op_sel_hi:[1,0,1]
	v_pk_mul_f32 v[96:97], v[24:25], v[94:95] op_sel:[0,1] op_sel_hi:[0,0] neg_hi:[1,0]
	v_pk_fma_f32 v[94:95], v[60:61], v[94:95], v[96:97] op_sel_hi:[0,1,1]
	s_waitcnt lgkmcnt(0)
	v_pk_mul_f32 v[96:97], v[10:11], v[94:95] op_sel:[1,1] op_sel_hi:[0,1] neg_lo:[0,1]
	v_pk_fma_f32 v[10:11], v[10:11], v[94:95], v[96:97] op_sel_hi:[1,0,1]
	v_pk_mul_f32 v[96:97], v[24:25], v[94:95] op_sel:[0,1] op_sel_hi:[0,0] neg_hi:[1,0]
	v_pk_fma_f32 v[94:95], v[60:61], v[94:95], v[96:97] op_sel_hi:[0,1,1]
	s_barrier
	v_pk_mul_f32 v[96:97], v[12:13], v[94:95] op_sel:[1,1] op_sel_hi:[0,1] neg_lo:[0,1]
	v_pk_fma_f32 v[12:13], v[12:13], v[94:95], v[96:97] op_sel_hi:[1,0,1]
	v_pk_mul_f32 v[96:97], v[24:25], v[94:95] op_sel:[0,1] op_sel_hi:[0,0] neg_hi:[1,0]
	v_pk_fma_f32 v[94:95], v[60:61], v[94:95], v[96:97] op_sel_hi:[0,1,1]
	v_pk_mul_f32 v[96:97], v[14:15], v[94:95] op_sel:[1,1] op_sel_hi:[0,1] neg_lo:[0,1]
	v_pk_fma_f32 v[14:15], v[14:15], v[94:95], v[96:97] op_sel_hi:[1,0,1]
	v_pk_mul_f32 v[96:97], v[24:25], v[94:95] op_sel:[0,1] op_sel_hi:[0,0] neg_hi:[1,0]
	v_pk_fma_f32 v[94:95], v[60:61], v[94:95], v[96:97] op_sel_hi:[0,1,1]
	v_pk_mul_f32 v[96:97], v[16:17], v[94:95] op_sel:[1,1] op_sel_hi:[0,1] neg_lo:[0,1]
	v_pk_fma_f32 v[16:17], v[16:17], v[94:95], v[96:97] op_sel_hi:[1,0,1]
	v_pk_mul_f32 v[96:97], v[24:25], v[94:95] op_sel:[0,1] op_sel_hi:[0,0] neg_hi:[1,0]
	v_pk_fma_f32 v[94:95], v[60:61], v[94:95], v[96:97] op_sel_hi:[0,1,1]
	v_pk_mul_f32 v[96:97], v[18:19], v[94:95] op_sel:[1,1] op_sel_hi:[0,1] neg_lo:[0,1]
	v_pk_fma_f32 v[18:19], v[18:19], v[94:95], v[96:97] op_sel_hi:[1,0,1]
	v_pk_mul_f32 v[96:97], v[24:25], v[94:95] op_sel:[0,1] op_sel_hi:[0,0] neg_hi:[1,0]
	v_pk_fma_f32 v[94:95], v[60:61], v[94:95], v[96:97] op_sel_hi:[0,1,1]
	v_pk_mul_f32 v[96:97], v[20:21], v[94:95] op_sel:[1,1] op_sel_hi:[0,1] neg_lo:[0,1]
	v_pk_fma_f32 v[20:21], v[20:21], v[94:95], v[96:97] op_sel_hi:[1,0,1]
	v_pk_mul_f32 v[96:97], v[24:25], v[94:95] op_sel:[0,1] op_sel_hi:[0,0] neg_hi:[1,0]
	v_pk_fma_f32 v[94:95], v[60:61], v[94:95], v[96:97] op_sel_hi:[0,1,1]
	v_pk_mul_f32 v[96:97], v[22:23], v[94:95] op_sel:[1,1] op_sel_hi:[0,1] neg_lo:[0,1]
	v_pk_fma_f32 v[22:23], v[22:23], v[94:95], v[96:97] op_sel_hi:[1,0,1]
	v_pk_mul_f32 v[96:97], v[24:25], v[94:95] op_sel:[0,1] op_sel_hi:[0,0] neg_hi:[1,0]
	v_pk_fma_f32 v[94:95], v[60:61], v[94:95], v[96:97] op_sel_hi:[0,1,1]
	v_pk_mul_f32 v[96:97], v[26:27], v[94:95] op_sel:[1,1] op_sel_hi:[0,1] neg_lo:[0,1]
	v_pk_fma_f32 v[26:27], v[26:27], v[94:95], v[96:97] op_sel_hi:[1,0,1]
	v_pk_mul_f32 v[96:97], v[24:25], v[94:95] op_sel:[0,1] op_sel_hi:[0,0] neg_hi:[1,0]
	v_pk_fma_f32 v[94:95], v[60:61], v[94:95], v[96:97] op_sel_hi:[0,1,1]
	v_pk_mul_f32 v[96:97], v[28:29], v[94:95] op_sel:[1,1] op_sel_hi:[0,1] neg_lo:[0,1]
	v_pk_fma_f32 v[28:29], v[28:29], v[94:95], v[96:97] op_sel_hi:[1,0,1]
	v_pk_mul_f32 v[96:97], v[24:25], v[94:95] op_sel:[0,1] op_sel_hi:[0,0] neg_hi:[1,0]
	v_pk_fma_f32 v[94:95], v[60:61], v[94:95], v[96:97] op_sel_hi:[0,1,1]
	v_pk_mul_f32 v[24:25], v[24:25], v[94:95] op_sel:[0,1] op_sel_hi:[0,0] neg_hi:[1,0]
	v_pk_fma_f32 v[24:25], v[60:61], v[94:95], v[24:25] op_sel_hi:[0,1,1]
	v_pk_mul_f32 v[60:61], v[58:59], v[24:25] op_sel:[1,1] op_sel_hi:[0,1] neg_lo:[0,1]
	v_pk_fma_f32 v[24:25], v[58:59], v[24:25], v[60:61] op_sel_hi:[1,0,1]
	v_pk_add_f32 v[58:59], v[0:1], v[16:17]
	v_pk_add_f32 v[0:1], v[0:1], v[16:17] neg_lo:[0,1] neg_hi:[0,1]
	v_pk_add_f32 v[16:17], v[2:3], v[18:19]
	v_pk_add_f32 v[2:3], v[2:3], v[18:19] neg_lo:[0,1] neg_hi:[0,1]
	v_pk_mul_f32 v[96:97], v[30:31], v[94:95] op_sel:[1,1] op_sel_hi:[0,1] neg_lo:[0,1]
	v_pk_mul_f32 v[18:19], v[2:3], s[18:19]
	v_pk_fma_f32 v[30:31], v[30:31], v[94:95], v[96:97] op_sel_hi:[1,0,1]
	v_pk_fma_f32 v[2:3], v[2:3], s[30:31], v[18:19] op_sel:[0,0,1] op_sel_hi:[1,0,0]
	v_pk_add_f32 v[18:19], v[4:5], v[20:21]
	v_pk_add_f32 v[4:5], v[4:5], v[20:21] neg_lo:[0,1] neg_hi:[0,1]
	v_pk_mul_f32 v[20:21], v[4:5], s[10:11]
	v_pk_fma_f32 v[4:5], v[4:5], s[14:15], v[20:21] op_sel:[0,0,1] op_sel_hi:[1,0,0]
	v_pk_add_f32 v[20:21], v[6:7], v[22:23]
	v_pk_add_f32 v[6:7], v[6:7], v[22:23] neg_lo:[0,1] neg_hi:[0,1]
	v_pk_mul_f32 v[22:23], v[6:7], s[34:35]
	v_pk_fma_f32 v[6:7], v[6:7], s[26:27], v[22:23] op_sel:[0,0,1] op_sel_hi:[1,0,0]
	v_pk_add_f32 v[22:23], v[8:9], v[26:27]
	v_pk_add_f32 v[8:9], v[8:9], v[26:27] neg_lo:[0,1] neg_hi:[0,1]
	v_pk_add_f32 v[26:27], v[10:11], v[28:29]
	v_pk_add_f32 v[10:11], v[10:11], v[28:29] neg_lo:[0,1] neg_hi:[0,1]
	v_pk_mul_f32 v[28:29], v[10:11], s[34:35]
	v_pk_fma_f32 v[10:11], v[10:11], s[26:27], v[28:29] op_sel:[0,0,1] op_sel_hi:[1,0,0] neg_lo:[1,0,0] neg_hi:[1,0,0]
	v_pk_add_f32 v[28:29], v[12:13], v[30:31]
	v_pk_add_f32 v[12:13], v[12:13], v[30:31] neg_lo:[0,1] neg_hi:[0,1]
	v_pk_mul_f32 v[30:31], v[12:13], s[10:11]
	v_pk_fma_f32 v[12:13], v[12:13], s[14:15], v[30:31] op_sel:[0,0,1] op_sel_hi:[1,0,0] neg_lo:[1,0,0] neg_hi:[1,0,0]
	v_pk_add_f32 v[30:31], v[14:15], v[24:25]
	v_pk_add_f32 v[14:15], v[14:15], v[24:25] neg_lo:[0,1] neg_hi:[0,1]
	v_pk_mul_f32 v[24:25], v[14:15], s[18:19]
	v_pk_fma_f32 v[14:15], v[14:15], s[30:31], v[24:25] op_sel:[0,0,1] op_sel_hi:[1,0,0] neg_lo:[1,0,0] neg_hi:[1,0,0]
	v_pk_add_f32 v[24:25], v[58:59], v[22:23]
	v_pk_add_f32 v[22:23], v[58:59], v[22:23] neg_lo:[0,1] neg_hi:[0,1]
	v_pk_add_f32 v[58:59], v[16:17], v[26:27]
	v_pk_add_f32 v[16:17], v[16:17], v[26:27] neg_lo:[0,1] neg_hi:[0,1]
	v_pk_mul_f32 v[26:27], v[16:17], s[10:11]
	v_pk_fma_f32 v[16:17], v[16:17], s[14:15], v[26:27] op_sel:[0,0,1] op_sel_hi:[1,0,0]
	v_pk_add_f32 v[26:27], v[18:19], v[28:29]
	v_pk_add_f32 v[18:19], v[18:19], v[28:29] neg_lo:[0,1] neg_hi:[0,1]
	v_pk_add_f32 v[28:29], v[20:21], v[30:31]
	v_pk_add_f32 v[20:21], v[20:21], v[30:31] neg_lo:[0,1] neg_hi:[0,1]
	v_pk_mul_f32 v[30:31], v[20:21], s[10:11]
	v_pk_fma_f32 v[20:21], v[20:21], s[14:15], v[30:31] op_sel:[0,0,1] op_sel_hi:[1,0,0] neg_lo:[1,0,0] neg_hi:[1,0,0]
	v_pk_add_f32 v[30:31], v[0:1], v[8:9] op_sel:[0,1] op_sel_hi:[1,0] neg_hi:[0,1]
	v_pk_add_f32 v[0:1], v[0:1], v[8:9] op_sel:[0,1] op_sel_hi:[1,0] neg_lo:[0,1]
	v_pk_add_f32 v[8:9], v[2:3], v[10:11]
	v_pk_add_f32 v[2:3], v[2:3], v[10:11] neg_lo:[0,1] neg_hi:[0,1]
	v_pk_mul_f32 v[10:11], v[2:3], s[10:11]
	v_pk_fma_f32 v[2:3], v[2:3], s[14:15], v[10:11] op_sel:[0,0,1] op_sel_hi:[1,0,0]
	v_pk_add_f32 v[10:11], v[4:5], v[12:13]
	v_pk_add_f32 v[4:5], v[4:5], v[12:13] neg_lo:[0,1] neg_hi:[0,1]
	v_pk_add_f32 v[12:13], v[6:7], v[14:15]
	v_pk_add_f32 v[6:7], v[6:7], v[14:15] neg_lo:[0,1] neg_hi:[0,1]
	v_pk_mul_f32 v[14:15], v[6:7], s[10:11]
	v_pk_fma_f32 v[6:7], v[6:7], s[14:15], v[14:15] op_sel:[0,0,1] op_sel_hi:[1,0,0] neg_lo:[1,0,0] neg_hi:[1,0,0]
	v_pk_add_f32 v[14:15], v[24:25], v[26:27]
	v_pk_add_f32 v[24:25], v[24:25], v[26:27] neg_lo:[0,1] neg_hi:[0,1]
	v_pk_add_f32 v[26:27], v[58:59], v[28:29]
	v_pk_add_f32 v[28:29], v[58:59], v[28:29] neg_lo:[0,1] neg_hi:[0,1]
	v_pk_add_f32 v[58:59], v[22:23], v[18:19] op_sel:[0,1] op_sel_hi:[1,0] neg_hi:[0,1]
	v_pk_add_f32 v[18:19], v[22:23], v[18:19] op_sel:[0,1] op_sel_hi:[1,0] neg_lo:[0,1]
	v_pk_add_f32 v[22:23], v[16:17], v[20:21]
	v_pk_add_f32 v[16:17], v[16:17], v[20:21] neg_lo:[0,1] neg_hi:[0,1]
	v_pk_add_f32 v[20:21], v[30:31], v[10:11]
	v_pk_add_f32 v[10:11], v[30:31], v[10:11] neg_lo:[0,1] neg_hi:[0,1]
	v_pk_add_f32 v[30:31], v[8:9], v[12:13]
	v_pk_add_f32 v[8:9], v[8:9], v[12:13] neg_lo:[0,1] neg_hi:[0,1]
	v_pk_add_f32 v[12:13], v[0:1], v[4:5] op_sel:[0,1] op_sel_hi:[1,0] neg_hi:[0,1]
	v_pk_add_f32 v[0:1], v[0:1], v[4:5] op_sel:[0,1] op_sel_hi:[1,0] neg_lo:[0,1]
	v_pk_add_f32 v[4:5], v[2:3], v[6:7]
	v_pk_add_f32 v[2:3], v[2:3], v[6:7] neg_lo:[0,1] neg_hi:[0,1]
	v_pk_mul_f32 v[2:3], v[2:3], s[22:23]
	v_pk_add_f32 v[6:7], v[14:15], v[26:27]
	v_pk_add_f32 v[14:15], v[14:15], v[26:27] neg_lo:[0,1] neg_hi:[0,1]
	v_pk_add_f32 v[26:27], v[24:25], v[28:29] op_sel:[0,1] op_sel_hi:[1,0] neg_hi:[0,1]
	v_pk_add_f32 v[24:25], v[24:25], v[28:29] op_sel:[0,1] op_sel_hi:[1,0] neg_lo:[0,1]
	v_pk_add_f32 v[28:29], v[58:59], v[22:23]
	v_pk_add_f32 v[22:23], v[58:59], v[22:23] neg_lo:[0,1] neg_hi:[0,1]
	v_pk_add_f32 v[58:59], v[18:19], v[16:17] op_sel:[0,1] op_sel_hi:[1,0] neg_hi:[0,1]
	v_pk_add_f32 v[16:17], v[18:19], v[16:17] op_sel:[0,1] op_sel_hi:[1,0] neg_lo:[0,1]
	v_pk_add_f32 v[18:19], v[20:21], v[30:31]
	v_pk_add_f32 v[20:21], v[20:21], v[30:31] neg_lo:[0,1] neg_hi:[0,1]
	v_pk_add_f32 v[30:31], v[10:11], v[8:9] op_sel:[0,1] op_sel_hi:[1,0] neg_hi:[0,1]
	v_pk_add_f32 v[8:9], v[10:11], v[8:9] op_sel:[0,1] op_sel_hi:[1,0] neg_lo:[0,1]
	v_pk_add_f32 v[10:11], v[12:13], v[4:5]
	v_pk_add_f32 v[4:5], v[12:13], v[4:5] neg_lo:[0,1] neg_hi:[0,1]
	v_pk_add_f32 v[12:13], v[0:1], v[2:3] op_sel:[0,1] op_sel_hi:[1,0]
	v_pk_add_f32 v[0:1], v[0:1], v[2:3] op_sel:[0,1] op_sel_hi:[1,0] neg_lo:[0,1] neg_hi:[0,1]
	v_lshlrev_b32_e32 v2, 4, v41
	v_and_or_b32 v2, v2, s7, v98
	v_ashrrev_i32_e32 v3, 4, v2
	v_lshlrev_b32_e32 v3, 3, v3
	v_lshlrev_b32_e32 v2, 3, v2
	v_add3_u32 v2, 0, v3, v2
	v_add_u32_e32 v3, 0x800, v2
	v_mov_b32_e32 v41, v32
	ds_write2_b64 v2, v[6:7], v[18:19] offset1:34
	ds_write2_b64 v3, v[14:15], v[20:21] offset0:16 offset1:50
	ds_write2_b64 v2, v[26:27], v[30:31] offset0:136 offset1:170
	ds_write2_b64 v3, v[24:25], v[8:9] offset0:152 offset1:186
	ds_write2_b64 v2, v[28:29], v[10:11] offset0:68 offset1:102
	ds_write2_b64 v3, v[22:23], v[4:5] offset0:84 offset1:118
	ds_write2_b64 v2, v[58:59], v[12:13] offset0:204 offset1:238
	ds_write2_b64 v3, v[16:17], v[0:1] offset0:220 offset1:254
	s_waitcnt lgkmcnt(0)
	s_barrier
	s_nop 0
	v_and_b32_e32 v98, 0x1ff, v41
	v_cvt_f32_u32_e32 v24, v98
	v_ashrrev_i32_e32 v0, 4, v41
	v_lshlrev_b32_e32 v0, 3, v0
	v_lshlrev_b32_e32 v1, 3, v41
	v_mul_f32_e32 v60, 0x39000000, v24
	v_sin_f32_e32 v24, v60
	v_cos_f32_e32 v60, v60
	v_add3_u32 v25, 0, v0, v1
	ds_read_b64 v[0:1], v25
	ds_read_b64 v[2:3], v25 offset:4352
	ds_read_b64 v[4:5], v25 offset:8704
	ds_read_b64 v[6:7], v25 offset:13056
	ds_read_b64 v[8:9], v25 offset:17408
	ds_read_b64 v[10:11], v25 offset:21760
	ds_read_b64 v[12:13], v25 offset:26112
	ds_read_b64 v[14:15], v25 offset:30464
	v_xor_b32_e32 v61, 0x80000000, v24
	s_waitcnt lgkmcnt(6)
	v_pk_mul_f32 v[94:95], v[2:3], v[24:25] op_sel:[1,0] op_sel_hi:[0,0] neg_hi:[0,1]
	v_pk_fma_f32 v[2:3], v[2:3], v[60:61], v[94:95] op_sel_hi:[1,0,1]
	v_pk_mul_f32 v[94:95], v[24:25], v[60:61] op_sel:[0,1] op_sel_hi:[0,0] neg_hi:[1,0]
	v_pk_fma_f32 v[94:95], v[60:61], v[60:61], v[94:95] op_sel_hi:[0,1,1]
	ds_read_b64 v[16:17], v25 offset:34816
	ds_read_b64 v[18:19], v25 offset:39168
	ds_read_b64 v[20:21], v25 offset:43520
	ds_read_b64 v[22:23], v25 offset:47872
	s_waitcnt lgkmcnt(9)
	v_pk_mul_f32 v[96:97], v[4:5], v[94:95] op_sel:[1,1] op_sel_hi:[0,1] neg_lo:[0,1]
	v_pk_fma_f32 v[4:5], v[4:5], v[94:95], v[96:97] op_sel_hi:[1,0,1]
	v_pk_mul_f32 v[96:97], v[24:25], v[94:95] op_sel:[0,1] op_sel_hi:[0,0] neg_hi:[1,0]
	v_pk_fma_f32 v[94:95], v[60:61], v[94:95], v[96:97] op_sel_hi:[0,1,1]
	ds_read_b64 v[26:27], v25 offset:52224
	ds_read_b64 v[28:29], v25 offset:56576
	ds_read_b64 v[30:31], v25 offset:60928
	ds_read_b64 v[58:59], v25 offset:65280
	s_waitcnt lgkmcnt(12)
	v_pk_mul_f32 v[96:97], v[6:7], v[94:95] op_sel:[1,1] op_sel_hi:[0,1] neg_lo:[0,1]
	v_pk_fma_f32 v[6:7], v[6:7], v[94:95], v[96:97] op_sel_hi:[1,0,1]
	v_pk_mul_f32 v[96:97], v[24:25], v[94:95] op_sel:[0,1] op_sel_hi:[0,0] neg_hi:[1,0]
	v_pk_fma_f32 v[94:95], v[60:61], v[94:95], v[96:97] op_sel_hi:[0,1,1]
	s_waitcnt lgkmcnt(0)
	v_pk_mul_f32 v[96:97], v[8:9], v[94:95] op_sel:[1,1] op_sel_hi:[0,1] neg_lo:[0,1]
	v_pk_fma_f32 v[8:9], v[8:9], v[94:95], v[96:97] op_sel_hi:[1,0,1]
	v_pk_mul_f32 v[96:97], v[24:25], v[94:95] op_sel:[0,1] op_sel_hi:[0,0] neg_hi:[1,0]
	v_pk_fma_f32 v[94:95], v[60:61], v[94:95], v[96:97] op_sel_hi:[0,1,1]
	s_barrier
	v_pk_mul_f32 v[96:97], v[10:11], v[94:95] op_sel:[1,1] op_sel_hi:[0,1] neg_lo:[0,1]
	v_pk_fma_f32 v[10:11], v[10:11], v[94:95], v[96:97] op_sel_hi:[1,0,1]
	v_pk_mul_f32 v[96:97], v[24:25], v[94:95] op_sel:[0,1] op_sel_hi:[0,0] neg_hi:[1,0]
	v_pk_fma_f32 v[94:95], v[60:61], v[94:95], v[96:97] op_sel_hi:[0,1,1]
	v_pk_mul_f32 v[96:97], v[12:13], v[94:95] op_sel:[1,1] op_sel_hi:[0,1] neg_lo:[0,1]
	v_pk_fma_f32 v[12:13], v[12:13], v[94:95], v[96:97] op_sel_hi:[1,0,1]
	v_pk_mul_f32 v[96:97], v[24:25], v[94:95] op_sel:[0,1] op_sel_hi:[0,0] neg_hi:[1,0]
	v_pk_fma_f32 v[94:95], v[60:61], v[94:95], v[96:97] op_sel_hi:[0,1,1]
	v_pk_mul_f32 v[96:97], v[14:15], v[94:95] op_sel:[1,1] op_sel_hi:[0,1] neg_lo:[0,1]
	v_pk_fma_f32 v[14:15], v[14:15], v[94:95], v[96:97] op_sel_hi:[1,0,1]
	v_pk_mul_f32 v[96:97], v[24:25], v[94:95] op_sel:[0,1] op_sel_hi:[0,0] neg_hi:[1,0]
	v_pk_fma_f32 v[94:95], v[60:61], v[94:95], v[96:97] op_sel_hi:[0,1,1]
	v_pk_mul_f32 v[96:97], v[16:17], v[94:95] op_sel:[1,1] op_sel_hi:[0,1] neg_lo:[0,1]
	v_pk_fma_f32 v[16:17], v[16:17], v[94:95], v[96:97] op_sel_hi:[1,0,1]
	v_pk_mul_f32 v[96:97], v[24:25], v[94:95] op_sel:[0,1] op_sel_hi:[0,0] neg_hi:[1,0]
	v_pk_fma_f32 v[94:95], v[60:61], v[94:95], v[96:97] op_sel_hi:[0,1,1]
	v_pk_mul_f32 v[96:97], v[18:19], v[94:95] op_sel:[1,1] op_sel_hi:[0,1] neg_lo:[0,1]
	v_pk_fma_f32 v[18:19], v[18:19], v[94:95], v[96:97] op_sel_hi:[1,0,1]
	v_pk_mul_f32 v[96:97], v[24:25], v[94:95] op_sel:[0,1] op_sel_hi:[0,0] neg_hi:[1,0]
	v_pk_fma_f32 v[94:95], v[60:61], v[94:95], v[96:97] op_sel_hi:[0,1,1]
	v_pk_mul_f32 v[96:97], v[20:21], v[94:95] op_sel:[1,1] op_sel_hi:[0,1] neg_lo:[0,1]
	v_pk_fma_f32 v[20:21], v[20:21], v[94:95], v[96:97] op_sel_hi:[1,0,1]
	v_pk_mul_f32 v[96:97], v[24:25], v[94:95] op_sel:[0,1] op_sel_hi:[0,0] neg_hi:[1,0]
	v_pk_fma_f32 v[94:95], v[60:61], v[94:95], v[96:97] op_sel_hi:[0,1,1]
	v_pk_mul_f32 v[96:97], v[22:23], v[94:95] op_sel:[1,1] op_sel_hi:[0,1] neg_lo:[0,1]
	v_pk_fma_f32 v[22:23], v[22:23], v[94:95], v[96:97] op_sel_hi:[1,0,1]
	v_pk_mul_f32 v[96:97], v[24:25], v[94:95] op_sel:[0,1] op_sel_hi:[0,0] neg_hi:[1,0]
	v_pk_fma_f32 v[94:95], v[60:61], v[94:95], v[96:97] op_sel_hi:[0,1,1]
	v_pk_mul_f32 v[96:97], v[26:27], v[94:95] op_sel:[1,1] op_sel_hi:[0,1] neg_lo:[0,1]
	v_pk_fma_f32 v[26:27], v[26:27], v[94:95], v[96:97] op_sel_hi:[1,0,1]
	v_pk_mul_f32 v[96:97], v[24:25], v[94:95] op_sel:[0,1] op_sel_hi:[0,0] neg_hi:[1,0]
	v_pk_fma_f32 v[94:95], v[60:61], v[94:95], v[96:97] op_sel_hi:[0,1,1]
	v_pk_mul_f32 v[96:97], v[28:29], v[94:95] op_sel:[1,1] op_sel_hi:[0,1] neg_lo:[0,1]
	v_pk_fma_f32 v[28:29], v[28:29], v[94:95], v[96:97] op_sel_hi:[1,0,1]
	v_pk_mul_f32 v[96:97], v[24:25], v[94:95] op_sel:[0,1] op_sel_hi:[0,0] neg_hi:[1,0]
	v_pk_fma_f32 v[94:95], v[60:61], v[94:95], v[96:97] op_sel_hi:[0,1,1]
	v_pk_mul_f32 v[24:25], v[24:25], v[94:95] op_sel:[0,1] op_sel_hi:[0,0] neg_hi:[1,0]
	v_pk_fma_f32 v[24:25], v[60:61], v[94:95], v[24:25] op_sel_hi:[0,1,1]
	v_pk_mul_f32 v[60:61], v[58:59], v[24:25] op_sel:[1,1] op_sel_hi:[0,1] neg_lo:[0,1]
	v_pk_fma_f32 v[24:25], v[58:59], v[24:25], v[60:61] op_sel_hi:[1,0,1]
	v_pk_add_f32 v[58:59], v[0:1], v[16:17]
	v_pk_add_f32 v[0:1], v[0:1], v[16:17] neg_lo:[0,1] neg_hi:[0,1]
	v_pk_add_f32 v[16:17], v[2:3], v[18:19]
	v_pk_add_f32 v[2:3], v[2:3], v[18:19] neg_lo:[0,1] neg_hi:[0,1]
	v_pk_mul_f32 v[96:97], v[30:31], v[94:95] op_sel:[1,1] op_sel_hi:[0,1] neg_lo:[0,1]
	v_pk_mul_f32 v[18:19], v[2:3], s[18:19]
	v_pk_fma_f32 v[30:31], v[30:31], v[94:95], v[96:97] op_sel_hi:[1,0,1]
	v_pk_fma_f32 v[2:3], v[2:3], s[30:31], v[18:19] op_sel:[0,0,1] op_sel_hi:[1,0,0]
	v_pk_add_f32 v[18:19], v[4:5], v[20:21]
	v_pk_add_f32 v[4:5], v[4:5], v[20:21] neg_lo:[0,1] neg_hi:[0,1]
	v_pk_mul_f32 v[20:21], v[4:5], s[10:11]
	v_pk_fma_f32 v[4:5], v[4:5], s[14:15], v[20:21] op_sel:[0,0,1] op_sel_hi:[1,0,0]
	v_pk_add_f32 v[20:21], v[6:7], v[22:23]
	v_pk_add_f32 v[6:7], v[6:7], v[22:23] neg_lo:[0,1] neg_hi:[0,1]
	v_pk_mul_f32 v[22:23], v[6:7], s[34:35]
	v_pk_fma_f32 v[6:7], v[6:7], s[26:27], v[22:23] op_sel:[0,0,1] op_sel_hi:[1,0,0]
	v_pk_add_f32 v[22:23], v[8:9], v[26:27]
	v_pk_add_f32 v[8:9], v[8:9], v[26:27] neg_lo:[0,1] neg_hi:[0,1]
	v_pk_add_f32 v[26:27], v[10:11], v[28:29]
	v_pk_add_f32 v[10:11], v[10:11], v[28:29] neg_lo:[0,1] neg_hi:[0,1]
	v_pk_mul_f32 v[28:29], v[10:11], s[34:35]
	v_pk_fma_f32 v[10:11], v[10:11], s[26:27], v[28:29] op_sel:[0,0,1] op_sel_hi:[1,0,0] neg_lo:[1,0,0] neg_hi:[1,0,0]
	v_pk_add_f32 v[28:29], v[12:13], v[30:31]
	v_pk_add_f32 v[12:13], v[12:13], v[30:31] neg_lo:[0,1] neg_hi:[0,1]
	v_pk_mul_f32 v[30:31], v[12:13], s[10:11]
	v_pk_fma_f32 v[12:13], v[12:13], s[14:15], v[30:31] op_sel:[0,0,1] op_sel_hi:[1,0,0] neg_lo:[1,0,0] neg_hi:[1,0,0]
	v_pk_add_f32 v[30:31], v[14:15], v[24:25]
	v_pk_add_f32 v[14:15], v[14:15], v[24:25] neg_lo:[0,1] neg_hi:[0,1]
	v_pk_mul_f32 v[24:25], v[14:15], s[18:19]
	v_pk_fma_f32 v[14:15], v[14:15], s[30:31], v[24:25] op_sel:[0,0,1] op_sel_hi:[1,0,0] neg_lo:[1,0,0] neg_hi:[1,0,0]
	v_pk_add_f32 v[24:25], v[58:59], v[22:23]
	v_pk_add_f32 v[22:23], v[58:59], v[22:23] neg_lo:[0,1] neg_hi:[0,1]
	v_pk_add_f32 v[58:59], v[16:17], v[26:27]
	v_pk_add_f32 v[16:17], v[16:17], v[26:27] neg_lo:[0,1] neg_hi:[0,1]
	v_pk_mul_f32 v[26:27], v[16:17], s[10:11]
	v_pk_fma_f32 v[16:17], v[16:17], s[14:15], v[26:27] op_sel:[0,0,1] op_sel_hi:[1,0,0]
	v_pk_add_f32 v[26:27], v[18:19], v[28:29]
	v_pk_add_f32 v[18:19], v[18:19], v[28:29] neg_lo:[0,1] neg_hi:[0,1]
	v_pk_add_f32 v[28:29], v[20:21], v[30:31]
	v_pk_add_f32 v[20:21], v[20:21], v[30:31] neg_lo:[0,1] neg_hi:[0,1]
	v_pk_mul_f32 v[30:31], v[20:21], s[10:11]
	v_pk_fma_f32 v[20:21], v[20:21], s[14:15], v[30:31] op_sel:[0,0,1] op_sel_hi:[1,0,0] neg_lo:[1,0,0] neg_hi:[1,0,0]
	v_pk_add_f32 v[30:31], v[0:1], v[8:9] op_sel:[0,1] op_sel_hi:[1,0] neg_hi:[0,1]
	v_pk_add_f32 v[0:1], v[0:1], v[8:9] op_sel:[0,1] op_sel_hi:[1,0] neg_lo:[0,1]
	v_pk_add_f32 v[8:9], v[2:3], v[10:11]
	v_pk_add_f32 v[2:3], v[2:3], v[10:11] neg_lo:[0,1] neg_hi:[0,1]
	v_pk_mul_f32 v[10:11], v[2:3], s[10:11]
	v_pk_fma_f32 v[2:3], v[2:3], s[14:15], v[10:11] op_sel:[0,0,1] op_sel_hi:[1,0,0]
	v_pk_add_f32 v[10:11], v[4:5], v[12:13]
	v_pk_add_f32 v[4:5], v[4:5], v[12:13] neg_lo:[0,1] neg_hi:[0,1]
	v_pk_add_f32 v[12:13], v[6:7], v[14:15]
	v_pk_add_f32 v[6:7], v[6:7], v[14:15] neg_lo:[0,1] neg_hi:[0,1]
	v_pk_mul_f32 v[14:15], v[6:7], s[10:11]
	v_pk_fma_f32 v[6:7], v[6:7], s[14:15], v[14:15] op_sel:[0,0,1] op_sel_hi:[1,0,0] neg_lo:[1,0,0] neg_hi:[1,0,0]
	v_pk_add_f32 v[14:15], v[24:25], v[26:27]
	v_pk_add_f32 v[24:25], v[24:25], v[26:27] neg_lo:[0,1] neg_hi:[0,1]
	v_pk_add_f32 v[26:27], v[58:59], v[28:29]
	v_pk_add_f32 v[28:29], v[58:59], v[28:29] neg_lo:[0,1] neg_hi:[0,1]
	v_pk_add_f32 v[58:59], v[22:23], v[18:19] op_sel:[0,1] op_sel_hi:[1,0] neg_hi:[0,1]
	v_pk_add_f32 v[18:19], v[22:23], v[18:19] op_sel:[0,1] op_sel_hi:[1,0] neg_lo:[0,1]
	v_pk_add_f32 v[22:23], v[16:17], v[20:21]
	v_pk_add_f32 v[16:17], v[16:17], v[20:21] neg_lo:[0,1] neg_hi:[0,1]
	v_pk_add_f32 v[20:21], v[30:31], v[10:11]
	v_pk_add_f32 v[10:11], v[30:31], v[10:11] neg_lo:[0,1] neg_hi:[0,1]
	v_pk_add_f32 v[30:31], v[8:9], v[12:13]
	v_pk_add_f32 v[8:9], v[8:9], v[12:13] neg_lo:[0,1] neg_hi:[0,1]
	v_pk_add_f32 v[12:13], v[0:1], v[4:5] op_sel:[0,1] op_sel_hi:[1,0] neg_hi:[0,1]
	v_pk_add_f32 v[0:1], v[0:1], v[4:5] op_sel:[0,1] op_sel_hi:[1,0] neg_lo:[0,1]
	v_pk_add_f32 v[4:5], v[2:3], v[6:7]
	v_pk_add_f32 v[2:3], v[2:3], v[6:7] neg_lo:[0,1] neg_hi:[0,1]
	v_pk_mul_f32 v[2:3], v[2:3], s[22:23]
	v_pk_add_f32 v[6:7], v[14:15], v[26:27]
	v_pk_add_f32 v[14:15], v[14:15], v[26:27] neg_lo:[0,1] neg_hi:[0,1]
	v_pk_add_f32 v[26:27], v[24:25], v[28:29] op_sel:[0,1] op_sel_hi:[1,0] neg_hi:[0,1]
	v_pk_add_f32 v[24:25], v[24:25], v[28:29] op_sel:[0,1] op_sel_hi:[1,0] neg_lo:[0,1]
	v_pk_add_f32 v[28:29], v[58:59], v[22:23]
	v_pk_add_f32 v[22:23], v[58:59], v[22:23] neg_lo:[0,1] neg_hi:[0,1]
	v_pk_add_f32 v[58:59], v[18:19], v[16:17] op_sel:[0,1] op_sel_hi:[1,0] neg_hi:[0,1]
	v_pk_add_f32 v[16:17], v[18:19], v[16:17] op_sel:[0,1] op_sel_hi:[1,0] neg_lo:[0,1]
	v_pk_add_f32 v[18:19], v[20:21], v[30:31]
	v_pk_add_f32 v[20:21], v[20:21], v[30:31] neg_lo:[0,1] neg_hi:[0,1]
	v_pk_add_f32 v[30:31], v[10:11], v[8:9] op_sel:[0,1] op_sel_hi:[1,0] neg_hi:[0,1]
	v_pk_add_f32 v[8:9], v[10:11], v[8:9] op_sel:[0,1] op_sel_hi:[1,0] neg_lo:[0,1]
	v_pk_add_f32 v[10:11], v[12:13], v[4:5]
	v_pk_add_f32 v[4:5], v[12:13], v[4:5] neg_lo:[0,1] neg_hi:[0,1]
	v_pk_add_f32 v[12:13], v[0:1], v[2:3] op_sel:[0,1] op_sel_hi:[1,0]
	v_pk_add_f32 v[0:1], v[0:1], v[2:3] op_sel:[0,1] op_sel_hi:[1,0] neg_lo:[0,1] neg_hi:[0,1]
	v_lshlrev_b32_e32 v2, 4, v41
	v_and_or_b32 v2, v2, s15, v98
	v_ashrrev_i32_e32 v3, 4, v2
	v_lshlrev_b32_e32 v3, 3, v3
	v_lshlrev_b32_e32 v2, 3, v2
	v_add3_u32 v2, 0, v3, v2
	ds_write_b64 v2, v[6:7]
	ds_write_b64 v2, v[14:15] offset:34816
	ds_write_b64 v2, v[26:27] offset:17408
	ds_write_b64 v2, v[24:25] offset:52224
	ds_write_b64 v2, v[28:29] offset:8704
	ds_write_b64 v2, v[22:23] offset:43520
	ds_write_b64 v2, v[58:59] offset:26112
	ds_write_b64 v2, v[16:17] offset:60928
	ds_write_b64 v2, v[18:19] offset:4352
	ds_write_b64 v2, v[20:21] offset:39168
	ds_write_b64 v2, v[30:31] offset:21760
	ds_write_b64 v2, v[8:9] offset:56576
	ds_write_b64 v2, v[10:11] offset:13056
	ds_write_b64 v2, v[4:5] offset:47872
	ds_write_b64 v2, v[12:13] offset:30464
	ds_write_b64 v2, v[0:1] offset:65280
	s_waitcnt lgkmcnt(0)
	s_barrier
	s_and_saveexec_b64 s[28:29], s[40:41]
	s_cbranch_execz .LBB0_602
	s_add_u32 s4, s38, 0x800000
	s_addc_u32 s5, s39, 0
	v_lshl_add_u64 v[0:1], v[48:49], 1, s[4:5]
	global_load_dwordx4 v[8:11], v[0:1], off offset:16
	global_load_dwordx4 v[12:15], v[0:1], off
	v_mov_b32_e32 v19, 0
	v_mov_b32_e32 v21, 0
	s_and_saveexec_b64 s[8:9], s[42:43]
	s_cbranch_execz .LBB0_678
	v_lshl_add_u64 v[2:3], v[172:173], 1, s[4:5]
	global_load_ushort v2, v[2:3], off offset:-2
	s_waitcnt vmcnt(0)
	v_lshlrev_b32_e32 v21, 16, v2
